# row phases: each lane holds 8 consecutive columns per half row, so H is stored with two dwordx4 per row instead of four dwordx2
# baseline (speedup 1.0000x reference)
; DI const float* modp(const Frame& F, int l, int mr, int which) { return (const float*)(F.ws + WS_MOD) + ((size_t)(l * 9 + mr) * 6 + which) * 1024; }
; DI void ln_row_v(const Frame& F, f32x4 (&v)[4], float* xout, const float* g, const float* b, const float* sh, const float* sc, bf16_t* hout, const float* slab, const float* gres, float* stat = nullptr) {
;     ...
;     if (g) {
;         float s = 0.f, s2 = 0.f;
; #pragma unroll
;         for (int j = 0; j < 4; ++j) { s += (v[j][0] + v[j][1]) + (v[j][2] + v[j][3]); s2 += (v[j][0] * v[j][0] + v[j][1] * v[j][1]) + (v[j][2] * v[j][2] + v[j][3] * v[j][3]); }
;         wave_sum2(s, s2, F.lane);
;         const float mean = s * (1.f / D); const float rstd = 1.f / sqrtf(fmaxf(s2 * (1.f / D) - mean * mean, 0.f) + EPS);
; DI void ln_phase(const Frame& F, int which) {
;     const int gw = F.vcu * 8 + F.wave, NGW = F.G * 8; const int l = F.l;
;     const int nrows = (l == NL - 1) ? ML : MT;
;     bf16_t* H = (bf16_t*)(F.ws + WS_HB);
;     const float* g = pin(F, which == 0 ? I_LN1G : I_LN2G) + l * 1024; const float* b = pin(F, which == 0 ? I_LN1B : I_LN2B) + l * 1024;
;     const bool wh = !(which == 1 && l == NL - 1);
;     f32x4 vc[4], vn[4];
;     if (gw < nrows) ln_load(F, xrow_ptr(F, gw), vc);
;     for (int row = gw; row < nrows; row += NGW) {
;         if (row + NGW < nrows) ln_load(F, xrow_ptr(F, row + NGW), vn);
;         const int mr = row < ML ? (row >> 11) : 8;
;         const float* sh = which == 0 ? modp(F, l, mr, 3) : modp(F, l + 1 < NL ? l + 1 : l, mr, 0);
;         const float* sc = which == 0 ? modp(F, l, mr, 4) : modp(F, l + 1 < NL ? l + 1 : l, mr, 1);
;         const bool sl = (which == 1 && row >= ML);
;         const bool st_only = row < ML && !(which == 1 && l == NL - 1);
;         float* stp = st_only ? (float*)(F.ws + (which == 0 ? WS_ST1 : WS_ST2)) + 2 * (size_t)row : nullptr;
;         ln_row_v(F, vc, st_only ? nullptr : xrow_ptr(F, row), g, b, sh, sc, wh ? H + (size_t)row * D : nullptr, sl ? (const float*)(F.ws + WS_KN) + (size_t)(row - ML) * 1024 : nullptr, modp(F, l, mr, 5), stp);
.LBB0_107:
	s_cmp_gt_i32 s28, 4
	s_mov_b64 s[2:3], -1
	s_cbranch_scc0 .LBB0_125
	v_readlane_b32 s2, v255, 29
	s_lshl_b32 s2, s2, 3
	v_readlane_b32 s3, v255, 31
	s_add_i32 s16, s3, s2
	v_lshlrev_b32_e32 v0, 5, v186
	v_lshlrev_b32_e32 v1, 4, v186
	v_lshlrev_b32_e32 v96, 2, v186
	v_xor_b32_e32 v3, 4, v96
	v_xor_b32_e32 v4, 8, v96
	v_xor_b32_e32 v5, 16, v96
	v_xor_b32_e32 v6, 32, v96
	v_xor_b32_e32 v7, 64, v96
	v_xor_b32_e32 v8, 128, v96
	s_load_dwordx4 s[4:7], s[62:63], 0x98
	v_readlane_b32 s22, v255, 35
	v_readlane_b32 s8, v255, 17
	v_readlane_b32 s9, v255, 18
	s_add_u32 s20, s94, 0x3600000
	s_addc_u32 s21, s95, 0
	s_lshl_b32 s2, s16, 12
	s_lshl_b32 s3, s16, 15
	s_add_u32 s8, s8, s3
	s_addc_u32 s9, s9, 0
	s_add_u32 s20, s20, s2
	s_addc_u32 s21, s21, 0
	s_lshl_b32 s2, s16, 14
	s_add_u32 s10, s94, s2
	s_addc_u32 s11, s95, 0
	s_add_u32 s10, s10, 0x3e00000
	s_addc_u32 s11, s11, 0
	s_lshl_b32 s2, s16, 6
	s_add_u32 s12, s94, s2
	s_addc_u32 s13, s95, 0
	s_add_u32 s12, s12, 0x480000
	s_addc_u32 s13, s13, 0
	s_mov_b32 s3, s22
	s_mul_i32 s3, s3, 0x36000
	s_add_u32 s14, s94, s3
	s_addc_u32 s15, s95, 0
	s_add_u32 s14, s14, 0x103000
	s_addc_u32 s15, s15, 0
	s_add_u32 s18, s14, 0x1000
	s_addc_u32 s19, s15, 0
	s_lshl_b32 s2, s22, 12
	s_waitcnt lgkmcnt(0)
	s_add_u32 s4, s4, s2
	s_addc_u32 s5, s5, 0
	s_add_u32 s6, s6, s2
	s_addc_u32 s7, s7, 0
	global_load_dwordx4 v[10:13], v0, s[4:5]
	global_load_dwordx4 v[14:17], v0, s[4:5] offset:16
	global_load_dwordx4 v[18:21], v0, s[4:5] offset:2048
	global_load_dwordx4 v[22:25], v0, s[4:5] offset:2064
	global_load_dwordx4 v[26:29], v0, s[6:7]
	global_load_dwordx4 v[30:33], v0, s[6:7] offset:16
	global_load_dwordx4 v[34:37], v0, s[6:7] offset:2048
	global_load_dwordx4 v[38:41], v0, s[6:7] offset:2064
	s_add_u32 s2, s8, 0x0
	s_addc_u32 s3, s9, 0
	global_load_dwordx4 v[42:45], v0, s[2:3]
	global_load_dwordx4 v[46:49], v0, s[2:3] offset:16
	global_load_dwordx4 v[50:53], v0, s[2:3] offset:2048
	global_load_dwordx4 v[54:57], v0, s[2:3] offset:2064
	s_lshr_b32 s23, s16, 8
	s_mul_i32 s23, s23, 0x6000
	s_add_u32 s2, s14, s23
	s_addc_u32 s3, s15, 0
	global_load_dwordx4 v[114:117], v0, s[2:3]
	global_load_dwordx4 v[118:121], v0, s[2:3] offset:16
	global_load_dwordx4 v[122:125], v0, s[2:3] offset:2048
	global_load_dwordx4 v[126:129], v0, s[2:3] offset:2064
	s_add_u32 s2, s18, s23
	s_addc_u32 s3, s19, 0
	global_load_dwordx4 v[130:133], v0, s[2:3]
	global_load_dwordx4 v[134:137], v0, s[2:3] offset:16
	global_load_dwordx4 v[138:141], v0, s[2:3] offset:2048
	global_load_dwordx4 v[142:145], v0, s[2:3] offset:2064
	s_add_u32 s2, s8, 0x1000
	s_addc_u32 s3, s9, 0
	global_load_dwordx4 v[58:61], v0, s[2:3]
	global_load_dwordx4 v[62:65], v0, s[2:3] offset:16
	global_load_dwordx4 v[66:69], v0, s[2:3] offset:2048
	global_load_dwordx4 v[70:73], v0, s[2:3] offset:2064
	s_mov_b32 s23, 0x30000
	s_add_u32 s2, s14, s23
	s_addc_u32 s3, s15, 0
	global_load_dwordx4 v[146:149], v0, s[2:3]
	global_load_dwordx4 v[150:153], v0, s[2:3] offset:16
	global_load_dwordx4 v[154:157], v0, s[2:3] offset:2048
	global_load_dwordx4 v[158:161], v0, s[2:3] offset:2064
	s_add_u32 s2, s18, s23
	s_addc_u32 s3, s19, 0
	global_load_dwordx4 v[162:165], v0, s[2:3]
	global_load_dwordx4 v[166:169], v0, s[2:3] offset:16
	global_load_dwordx4 v[170:173], v0, s[2:3] offset:2048
	global_load_dwordx4 v[174:177], v0, s[2:3] offset:2064
	s_add_u32 s2, s8, 0x2000
	s_addc_u32 s3, s9, 0
	global_load_dwordx4 v[74:77], v0, s[2:3]
	global_load_dwordx4 v[78:81], v0, s[2:3] offset:16
	global_load_dwordx4 v[82:85], v0, s[2:3] offset:2048
	global_load_dwordx4 v[86:89], v0, s[2:3] offset:2064
	s_add_u32 s2, s8, 0x3000
	s_addc_u32 s3, s9, 0
	global_load_dwordx4 v[98:101], v0, s[2:3]
	global_load_dwordx4 v[102:105], v0, s[2:3] offset:16
	global_load_dwordx4 v[106:109], v0, s[2:3] offset:2048
	global_load_dwordx4 v[110:113], v0, s[2:3] offset:2064
	s_waitcnt vmcnt(28)
	v_add_f32_e32 v9, v42, v43
	v_add_f32_e32 v91, v44, v45
	v_mul_f32_e32 v90, v42, v42
	v_mul_f32_e32 v92, v43, v43
	v_add_f32_e32 v9, v9, v46
	v_add_f32_e32 v91, v91, v47
	v_add_f32_e32 v9, v9, v48
	v_add_f32_e32 v91, v91, v49
	v_add_f32_e32 v9, v9, v50
	v_add_f32_e32 v91, v91, v51
	v_add_f32_e32 v9, v9, v52
	v_add_f32_e32 v91, v91, v53
	v_add_f32_e32 v9, v9, v54
	v_add_f32_e32 v91, v91, v55
	v_add_f32_e32 v9, v9, v56
	v_add_f32_e32 v91, v91, v57
	v_fmac_f32_e32 v90, v44, v44
	v_fmac_f32_e32 v92, v45, v45
	v_fmac_f32_e32 v90, v46, v46
	v_fmac_f32_e32 v92, v47, v47
	v_fmac_f32_e32 v90, v48, v48
	v_fmac_f32_e32 v92, v49, v49
	v_fmac_f32_e32 v90, v50, v50
	v_fmac_f32_e32 v92, v51, v51
	v_fmac_f32_e32 v90, v52, v52
	v_fmac_f32_e32 v92, v53, v53
	v_fmac_f32_e32 v90, v54, v54
	v_fmac_f32_e32 v92, v55, v55
	v_fmac_f32_e32 v90, v56, v56
	v_fmac_f32_e32 v92, v57, v57
	v_add_f32_e32 v9, v9, v91
	v_add_f32_e32 v90, v90, v92
	s_nop 1
	v_add_f32_dpp v9, v9, v9 quad_perm:[1,0,3,2] row_mask:0xf bank_mask:0xf
	v_add_f32_dpp v90, v90, v90 quad_perm:[1,0,3,2] row_mask:0xf bank_mask:0xf
	s_nop 0
	v_add_f32_dpp v9, v9, v9 quad_perm:[2,3,0,1] row_mask:0xf bank_mask:0xf
	v_add_f32_dpp v90, v90, v90 quad_perm:[2,3,0,1] row_mask:0xf bank_mask:0xf
	s_nop 0
	v_add_f32_dpp v9, v9, v9 row_half_mirror row_mask:0xf bank_mask:0xf
	v_add_f32_dpp v90, v90, v90 row_half_mirror row_mask:0xf bank_mask:0xf
	s_nop 0
	v_add_f32_dpp v9, v9, v9 row_mirror row_mask:0xf bank_mask:0xf
	v_add_f32_dpp v90, v90, v90 row_mirror row_mask:0xf bank_mask:0xf
	s_nop 0
	v_add_f32_dpp v9, v9, v9 row_bcast:15 row_mask:0xa bank_mask:0xf
	v_add_f32_dpp v90, v90, v90 row_bcast:15 row_mask:0xa bank_mask:0xf
	s_nop 0
	v_add_f32_dpp v9, v9, v9 row_bcast:31 row_mask:0xc bank_mask:0xf
; DI void ln_row_v(const Frame& F, f32x4 (&v)[4], float* xout, const float* g, const float* b, const float* sh, const float* sc, bf16_t* hout, const float* slab, const float* gres, float* stat = nullptr) {
;     ...
;         float s = 0.f, s2 = 0.f;
; #pragma unroll
;         for (int j = 0; j < 4; ++j) { s += (v[j][0] + v[j][1]) + (v[j][2] + v[j][3]); s2 += (v[j][0] * v[j][0] + v[j][1] * v[j][1]) + (v[j][2] * v[j][2] + v[j][3] * v[j][3]); }
;         wave_sum2(s, s2, F.lane);
;         const float mean = s * (1.f / D); const float rstd = 1.f / sqrtf(fmaxf(s2 * (1.f / D) - mean * mean, 0.f) + EPS);
;         if (stat && F.lane == 0) { f32x2 sv = {mean, rstd}; *(f32x2*)stat = sv; }
; #pragma unroll
;         for (int j = 0; j < 4; ++j) { const f32x4 gg = ((const f32x4*)g)[F.lane + 64 * j], bb = ((const f32x4*)b)[F.lane + 64 * j];
;             v[j] = (v[j] - mean) * rstd * gg + bb; if (xout) ((f32x4*)xout)[F.lane + 64 * j] = v[j]; }
;     }
;     if (hout) {
;         float s = 0.f, s2 = 0.f;
; #pragma unroll
;         for (int j = 0; j < 4; ++j) { s += (v[j][0] + v[j][1]) + (v[j][2] + v[j][3]); s2 += (v[j][0] * v[j][0] + v[j][1] * v[j][1]) + (v[j][2] * v[j][2] + v[j][3] * v[j][3]); }
;         wave_sum2(s, s2, F.lane);
;         const float mean = s * (1.f / D); const float rstd = 1.f / sqrtf(fmaxf(s2 * (1.f / D) - mean * mean, 0.f) + EPS);
	v_add_f32_dpp v90, v90, v90 row_bcast:31 row_mask:0xc bank_mask:0xf
	s_nop 0
	v_readlane_b32 s2, v9, 63
	v_readlane_b32 s3, v90, 63
	s_nop 1
	v_mov_b32_e32 v9, s2
	v_mov_b32_e32 v90, s3
	v_mul_f32_e32 v93, 0x3a800000, v9
	v_mul_f32_e32 v91, 0x3a800000, v90
	v_fma_f32 v91, -v93, v93, v91
	v_max_f32_e32 v91, 0, v91
	v_add_f32_e32 v91, 0x358637bd, v91
	v_rsq_f32_e32 v94, v91
	v_mul_f32_e32 v91, 0.5, v91
	v_mul_f32_e32 v92, v94, v94
	v_fma_f32 v92, -v91, v92, 0.5
	v_fma_f32 v94, v94, v92, v94
	s_add_u32 s2, s12, 0x0
	s_addc_u32 s3, s13, 0
	v_mov_b32_e32 v188, v93
	v_mov_b32_e32 v189, v94
	s_mov_b64 exec, 1
	global_store_dwordx2 v97, v[188:189], s[2:3]
	s_mov_b64 exec, -1
	v_sub_f32_e32 v42, v42, v93
	v_sub_f32_e32 v43, v43, v93
	v_sub_f32_e32 v44, v44, v93
	v_sub_f32_e32 v45, v45, v93
	v_sub_f32_e32 v46, v46, v93
	v_sub_f32_e32 v47, v47, v93
	v_sub_f32_e32 v48, v48, v93
	v_sub_f32_e32 v49, v49, v93
	v_sub_f32_e32 v50, v50, v93
	v_sub_f32_e32 v51, v51, v93
	v_sub_f32_e32 v52, v52, v93
	v_sub_f32_e32 v53, v53, v93
	v_sub_f32_e32 v54, v54, v93
	v_sub_f32_e32 v55, v55, v93
	v_sub_f32_e32 v56, v56, v93
	v_sub_f32_e32 v57, v57, v93
	v_mul_f32_e32 v42, v94, v42
	v_mul_f32_e32 v43, v94, v43
	v_mul_f32_e32 v44, v94, v44
	v_mul_f32_e32 v45, v94, v45
	v_mul_f32_e32 v46, v94, v46
	v_mul_f32_e32 v47, v94, v47
	v_mul_f32_e32 v48, v94, v48
	v_mul_f32_e32 v49, v94, v49
	v_mul_f32_e32 v50, v94, v50
	v_mul_f32_e32 v51, v94, v51
	v_mul_f32_e32 v52, v94, v52
	v_mul_f32_e32 v53, v94, v53
	v_mul_f32_e32 v54, v94, v54
	v_mul_f32_e32 v55, v94, v55
	v_mul_f32_e32 v56, v94, v56
	v_mul_f32_e32 v57, v94, v57
	v_fma_f32 v42, v42, v10, v26
	v_fma_f32 v43, v43, v11, v27
	v_fma_f32 v44, v44, v12, v28
	v_fma_f32 v45, v45, v13, v29
	v_fma_f32 v46, v46, v14, v30
	v_fma_f32 v47, v47, v15, v31
	v_fma_f32 v48, v48, v16, v32
	v_fma_f32 v49, v49, v17, v33
	v_fma_f32 v50, v50, v18, v34
	v_fma_f32 v51, v51, v19, v35
	v_fma_f32 v52, v52, v20, v36
	v_fma_f32 v53, v53, v21, v37
	v_fma_f32 v54, v54, v22, v38
	v_fma_f32 v55, v55, v23, v39
	v_fma_f32 v56, v56, v24, v40
	v_fma_f32 v57, v57, v25, v41
	v_add_f32_e32 v9, v42, v43
	v_add_f32_e32 v91, v44, v45
	v_mul_f32_e32 v90, v42, v42
	v_mul_f32_e32 v92, v43, v43
	v_add_f32_e32 v9, v9, v46
	v_add_f32_e32 v91, v91, v47
	v_add_f32_e32 v9, v9, v48
	v_add_f32_e32 v91, v91, v49
	v_add_f32_e32 v9, v9, v50
	v_add_f32_e32 v91, v91, v51
	v_add_f32_e32 v9, v9, v52
	v_add_f32_e32 v91, v91, v53
	v_add_f32_e32 v9, v9, v54
	v_add_f32_e32 v91, v91, v55
	v_add_f32_e32 v9, v9, v56
	v_add_f32_e32 v91, v91, v57
	v_fmac_f32_e32 v90, v44, v44
	v_fmac_f32_e32 v92, v45, v45
	v_fmac_f32_e32 v90, v46, v46
	v_fmac_f32_e32 v92, v47, v47
	v_fmac_f32_e32 v90, v48, v48
	v_fmac_f32_e32 v92, v49, v49
	v_fmac_f32_e32 v90, v50, v50
	v_fmac_f32_e32 v92, v51, v51
	v_fmac_f32_e32 v90, v52, v52
	v_fmac_f32_e32 v92, v53, v53
	v_fmac_f32_e32 v90, v54, v54
	v_fmac_f32_e32 v92, v55, v55
	v_fmac_f32_e32 v90, v56, v56
	v_fmac_f32_e32 v92, v57, v57
	v_add_f32_e32 v9, v9, v91
	v_add_f32_e32 v90, v90, v92
	s_nop 1
	v_add_f32_dpp v9, v9, v9 quad_perm:[1,0,3,2] row_mask:0xf bank_mask:0xf
	v_add_f32_dpp v90, v90, v90 quad_perm:[1,0,3,2] row_mask:0xf bank_mask:0xf
	s_nop 0
	v_add_f32_dpp v9, v9, v9 quad_perm:[2,3,0,1] row_mask:0xf bank_mask:0xf
	v_add_f32_dpp v90, v90, v90 quad_perm:[2,3,0,1] row_mask:0xf bank_mask:0xf
	s_nop 0
	v_add_f32_dpp v9, v9, v9 row_half_mirror row_mask:0xf bank_mask:0xf
	v_add_f32_dpp v90, v90, v90 row_half_mirror row_mask:0xf bank_mask:0xf
	s_nop 0
	v_add_f32_dpp v9, v9, v9 row_mirror row_mask:0xf bank_mask:0xf
	v_add_f32_dpp v90, v90, v90 row_mirror row_mask:0xf bank_mask:0xf
	s_nop 0
	v_add_f32_dpp v9, v9, v9 row_bcast:15 row_mask:0xa bank_mask:0xf
	v_add_f32_dpp v90, v90, v90 row_bcast:15 row_mask:0xa bank_mask:0xf
	s_nop 0
	v_add_f32_dpp v9, v9, v9 row_bcast:31 row_mask:0xc bank_mask:0xf
	v_add_f32_dpp v90, v90, v90 row_bcast:31 row_mask:0xc bank_mask:0xf
	s_nop 0
	v_readlane_b32 s2, v9, 63
	v_readlane_b32 s3, v90, 63
	s_nop 1
	v_mov_b32_e32 v9, s2
	v_mov_b32_e32 v90, s3
	v_mul_f32_e32 v93, 0x3a800000, v9
	v_mul_f32_e32 v91, 0x3a800000, v90
	v_fma_f32 v91, -v93, v93, v91
	v_max_f32_e32 v91, 0, v91
	v_add_f32_e32 v91, 0x358637bd, v91
	v_rsq_f32_e32 v94, v91
	v_mul_f32_e32 v91, 0.5, v91
	v_mul_f32_e32 v92, v94, v94
	v_fma_f32 v92, -v91, v92, 0.5
	v_fma_f32 v94, v94, v92, v94
	s_waitcnt vmcnt(21)
; DI unsigned pk2(float lo, float hi) { f32x2 v = {lo, hi}; bf16x2_t b = __builtin_convertvector(v, bf16x2_t); return __builtin_bit_cast(unsigned, b); }
; DI void ln_row_v(const Frame& F, f32x4 (&v)[4], float* xout, const float* g, const float* b, const float* sh, const float* sc, bf16_t* hout, const float* slab, const float* gres, float* stat = nullptr) {
;     ...
;         const float mean = s * (1.f / D); const float rstd = 1.f / sqrtf(fmaxf(s2 * (1.f / D) - mean * mean, 0.f) + EPS);
; #pragma unroll
;         for (int j = 0; j < 4; ++j) { const f32x4 hh = ((const f32x4*)sh)[F.lane + 64 * j], cc = ((const f32x4*)sc)[F.lane + 64 * j];
;             const f32x4 o = (v[j] - mean) * rstd * (cc + 1.f) + hh; u32x2 wv; wv.x = pk2(o[0], o[1]); wv.y = pk2(o[2], o[3]);
;             ((u32x2*)hout)[F.lane + 64 * j] = wv; }
;     }
; DI void ln_phase(const Frame& F, int which) {
;     ...
;         if (row + NGW < nrows) ln_load(F, xrow_ptr(F, row + NGW), vn);
	v_sub_f32_e32 v42, v42, v93
	v_sub_f32_e32 v43, v43, v93
	v_sub_f32_e32 v44, v44, v93
	v_sub_f32_e32 v45, v45, v93
	v_sub_f32_e32 v46, v46, v93
	v_sub_f32_e32 v47, v47, v93
	v_sub_f32_e32 v48, v48, v93
	v_sub_f32_e32 v49, v49, v93
	v_sub_f32_e32 v50, v50, v93
	v_sub_f32_e32 v51, v51, v93
	v_sub_f32_e32 v52, v52, v93
	v_sub_f32_e32 v53, v53, v93
	v_sub_f32_e32 v54, v54, v93
	v_sub_f32_e32 v55, v55, v93
	v_sub_f32_e32 v56, v56, v93
	v_sub_f32_e32 v57, v57, v93
	v_add_f32_e32 v130, 1.0, v130
	v_add_f32_e32 v131, 1.0, v131
	v_add_f32_e32 v132, 1.0, v132
	v_add_f32_e32 v133, 1.0, v133
	v_add_f32_e32 v134, 1.0, v134
	v_add_f32_e32 v135, 1.0, v135
	v_add_f32_e32 v136, 1.0, v136
	v_add_f32_e32 v137, 1.0, v137
	v_add_f32_e32 v138, 1.0, v138
	v_add_f32_e32 v139, 1.0, v139
	v_add_f32_e32 v140, 1.0, v140
	v_add_f32_e32 v141, 1.0, v141
	v_add_f32_e32 v142, 1.0, v142
	v_add_f32_e32 v143, 1.0, v143
	v_add_f32_e32 v144, 1.0, v144
	v_add_f32_e32 v145, 1.0, v145
	v_mul_f32_e32 v42, v94, v42
	v_mul_f32_e32 v43, v94, v43
	v_mul_f32_e32 v44, v94, v44
	v_mul_f32_e32 v45, v94, v45
	v_mul_f32_e32 v46, v94, v46
	v_mul_f32_e32 v47, v94, v47
	v_mul_f32_e32 v48, v94, v48
	v_mul_f32_e32 v49, v94, v49
	v_mul_f32_e32 v50, v94, v50
	v_mul_f32_e32 v51, v94, v51
	v_mul_f32_e32 v52, v94, v52
	v_mul_f32_e32 v53, v94, v53
	v_mul_f32_e32 v54, v94, v54
	v_mul_f32_e32 v55, v94, v55
	v_mul_f32_e32 v56, v94, v56
	v_mul_f32_e32 v57, v94, v57
	v_fma_f32 v42, v42, v130, v114
	v_fma_f32 v43, v43, v131, v115
	v_fma_f32 v44, v44, v132, v116
	v_fma_f32 v45, v45, v133, v117
	v_fma_f32 v46, v46, v134, v118
	v_fma_f32 v47, v47, v135, v119
	v_fma_f32 v48, v48, v136, v120
	v_fma_f32 v49, v49, v137, v121
	v_fma_f32 v50, v50, v138, v122
	v_fma_f32 v51, v51, v139, v123
	v_fma_f32 v52, v52, v140, v124
	v_fma_f32 v53, v53, v141, v125
	v_fma_f32 v54, v54, v142, v126
	v_fma_f32 v55, v55, v143, v127
	v_fma_f32 v56, v56, v144, v128
	v_fma_f32 v57, v57, v145, v129
	v_cvt_pk_bf16_f32 v190, v42, v43
	v_cvt_pk_bf16_f32 v191, v44, v45
	v_cvt_pk_bf16_f32 v192, v46, v47
	v_cvt_pk_bf16_f32 v193, v48, v49
	v_cvt_pk_bf16_f32 v194, v50, v51
	v_cvt_pk_bf16_f32 v195, v52, v53
	v_cvt_pk_bf16_f32 v196, v54, v55
	v_cvt_pk_bf16_f32 v197, v56, v57
	s_add_u32 s2, s10, 0x0
	s_addc_u32 s3, s11, 0
	global_store_dwordx4 v1, v[190:193], s[2:3]
	global_store_dwordx4 v1, v[194:197], s[2:3] offset:1024
	s_add_u32 s2, s8, 0x4000
	s_addc_u32 s3, s9, 0
	global_load_dwordx4 v[42:45], v0, s[2:3]
	global_load_dwordx4 v[46:49], v0, s[2:3] offset:16
	global_load_dwordx4 v[50:53], v0, s[2:3] offset:2048
	global_load_dwordx4 v[54:57], v0, s[2:3] offset:2064
	s_waitcnt vmcnt(23)
	v_add_f32_e32 v9, v58, v59
	v_add_f32_e32 v91, v60, v61
	v_mul_f32_e32 v90, v58, v58
	v_mul_f32_e32 v92, v59, v59
	v_add_f32_e32 v9, v9, v62
	v_add_f32_e32 v91, v91, v63
	v_add_f32_e32 v9, v9, v64
	v_add_f32_e32 v91, v91, v65
	v_add_f32_e32 v9, v9, v66
	v_add_f32_e32 v91, v91, v67
	v_add_f32_e32 v9, v9, v68
	v_add_f32_e32 v91, v91, v69
	v_add_f32_e32 v9, v9, v70
	v_add_f32_e32 v91, v91, v71
	v_add_f32_e32 v9, v9, v72
	v_add_f32_e32 v91, v91, v73
	v_fmac_f32_e32 v90, v60, v60
	v_fmac_f32_e32 v92, v61, v61
	v_fmac_f32_e32 v90, v62, v62
	v_fmac_f32_e32 v92, v63, v63
	v_fmac_f32_e32 v90, v64, v64
	v_fmac_f32_e32 v92, v65, v65
	v_fmac_f32_e32 v90, v66, v66
	v_fmac_f32_e32 v92, v67, v67
	v_fmac_f32_e32 v90, v68, v68
	v_fmac_f32_e32 v92, v69, v69
	v_fmac_f32_e32 v90, v70, v70
	v_fmac_f32_e32 v92, v71, v71
	v_fmac_f32_e32 v90, v72, v72
	v_fmac_f32_e32 v92, v73, v73
	v_add_f32_e32 v9, v9, v91
	v_add_f32_e32 v90, v90, v92
	s_nop 1
	v_add_f32_dpp v9, v9, v9 quad_perm:[1,0,3,2] row_mask:0xf bank_mask:0xf
	v_add_f32_dpp v90, v90, v90 quad_perm:[1,0,3,2] row_mask:0xf bank_mask:0xf
	s_nop 0
	v_add_f32_dpp v9, v9, v9 quad_perm:[2,3,0,1] row_mask:0xf bank_mask:0xf
	v_add_f32_dpp v90, v90, v90 quad_perm:[2,3,0,1] row_mask:0xf bank_mask:0xf
	s_nop 0
	v_add_f32_dpp v9, v9, v9 row_half_mirror row_mask:0xf bank_mask:0xf
	v_add_f32_dpp v90, v90, v90 row_half_mirror row_mask:0xf bank_mask:0xf
	s_nop 0
	v_add_f32_dpp v9, v9, v9 row_mirror row_mask:0xf bank_mask:0xf
	v_add_f32_dpp v90, v90, v90 row_mirror row_mask:0xf bank_mask:0xf
	s_nop 0
	v_add_f32_dpp v9, v9, v9 row_bcast:15 row_mask:0xa bank_mask:0xf
	v_add_f32_dpp v90, v90, v90 row_bcast:15 row_mask:0xa bank_mask:0xf
	s_nop 0
	v_add_f32_dpp v9, v9, v9 row_bcast:31 row_mask:0xc bank_mask:0xf
	v_add_f32_dpp v90, v90, v90 row_bcast:31 row_mask:0xc bank_mask:0xf
	s_nop 0
	v_readlane_b32 s2, v9, 63
	v_readlane_b32 s3, v90, 63
	s_nop 1
	v_mov_b32_e32 v9, s2
	v_mov_b32_e32 v90, s3
	v_mul_f32_e32 v93, 0x3a800000, v9
	v_mul_f32_e32 v91, 0x3a800000, v90
	v_fma_f32 v91, -v93, v93, v91
	v_max_f32_e32 v91, 0, v91
	v_add_f32_e32 v91, 0x358637bd, v91
	v_rsq_f32_e32 v94, v91
	v_mul_f32_e32 v91, 0.5, v91
	v_mul_f32_e32 v92, v94, v94
	v_fma_f32 v92, -v91, v92, 0.5
	v_fma_f32 v94, v94, v92, v94
	s_add_u32 s2, s12, 0x8
	s_addc_u32 s3, s13, 0
	v_mov_b32_e32 v188, v93
	v_mov_b32_e32 v189, v94
	s_mov_b64 exec, 1
	global_store_dwordx2 v97, v[188:189], s[2:3]
	s_mov_b64 exec, -1
	v_sub_f32_e32 v58, v58, v93
	v_sub_f32_e32 v59, v59, v93
	v_sub_f32_e32 v60, v60, v93
	v_sub_f32_e32 v61, v61, v93
	v_sub_f32_e32 v62, v62, v93
	v_sub_f32_e32 v63, v63, v93
	v_sub_f32_e32 v64, v64, v93
	v_sub_f32_e32 v65, v65, v93
	v_sub_f32_e32 v66, v66, v93
	v_sub_f32_e32 v67, v67, v93
	v_sub_f32_e32 v68, v68, v93
	v_sub_f32_e32 v69, v69, v93
	v_sub_f32_e32 v70, v70, v93
	v_sub_f32_e32 v71, v71, v93
	v_sub_f32_e32 v72, v72, v93
	v_sub_f32_e32 v73, v73, v93
	v_mul_f32_e32 v58, v94, v58
	v_mul_f32_e32 v59, v94, v59
	v_mul_f32_e32 v60, v94, v60
	v_mul_f32_e32 v61, v94, v61
; DI unsigned pk2(float lo, float hi) { f32x2 v = {lo, hi}; bf16x2_t b = __builtin_convertvector(v, bf16x2_t); return __builtin_bit_cast(unsigned, b); }
; DI void ln_row_v(const Frame& F, f32x4 (&v)[4], float* xout, const float* g, const float* b, const float* sh, const float* sc, bf16_t* hout, const float* slab, const float* gres, float* stat = nullptr) {
;     ...
;         float s = 0.f, s2 = 0.f;
; #pragma unroll
;         for (int j = 0; j < 4; ++j) { s += (v[j][0] + v[j][1]) + (v[j][2] + v[j][3]); s2 += (v[j][0] * v[j][0] + v[j][1] * v[j][1]) + (v[j][2] * v[j][2] + v[j][3] * v[j][3]); }
;         wave_sum2(s, s2, F.lane);
;         const float mean = s * (1.f / D); const float rstd = 1.f / sqrtf(fmaxf(s2 * (1.f / D) - mean * mean, 0.f) + EPS);
;         if (stat && F.lane == 0) { f32x2 sv = {mean, rstd}; *(f32x2*)stat = sv; }
; #pragma unroll
;         for (int j = 0; j < 4; ++j) { const f32x4 gg = ((const f32x4*)g)[F.lane + 64 * j], bb = ((const f32x4*)b)[F.lane + 64 * j];
;             v[j] = (v[j] - mean) * rstd * gg + bb; if (xout) ((f32x4*)xout)[F.lane + 64 * j] = v[j]; }
;     }
;     if (hout) {
;         float s = 0.f, s2 = 0.f;
; #pragma unroll
;         for (int j = 0; j < 4; ++j) { s += (v[j][0] + v[j][1]) + (v[j][2] + v[j][3]); s2 += (v[j][0] * v[j][0] + v[j][1] * v[j][1]) + (v[j][2] * v[j][2] + v[j][3] * v[j][3]); }
;         wave_sum2(s, s2, F.lane);
;         const float mean = s * (1.f / D); const float rstd = 1.f / sqrtf(fmaxf(s2 * (1.f / D) - mean * mean, 0.f) + EPS);
; #pragma unroll
;         for (int j = 0; j < 4; ++j) { const f32x4 hh = ((const f32x4*)sh)[F.lane + 64 * j], cc = ((const f32x4*)sc)[F.lane + 64 * j];
;             const f32x4 o = (v[j] - mean) * rstd * (cc + 1.f) + hh; u32x2 wv; wv.x = pk2(o[0], o[1]); wv.y = pk2(o[2], o[3]);
;             ((u32x2*)hout)[F.lane + 64 * j] = wv; }
;     }
; DI void ln_phase(const Frame& F, int which) {
;     ...
;         if (row + NGW < nrows) ln_load(F, xrow_ptr(F, row + NGW), vn);
	v_mul_f32_e32 v62, v94, v62
	v_mul_f32_e32 v63, v94, v63
	v_mul_f32_e32 v64, v94, v64
	v_mul_f32_e32 v65, v94, v65
	v_mul_f32_e32 v66, v94, v66
	v_mul_f32_e32 v67, v94, v67
	v_mul_f32_e32 v68, v94, v68
	v_mul_f32_e32 v69, v94, v69
	v_mul_f32_e32 v70, v94, v70
	v_mul_f32_e32 v71, v94, v71
	v_mul_f32_e32 v72, v94, v72
	v_mul_f32_e32 v73, v94, v73
	v_fma_f32 v58, v58, v10, v26
	v_fma_f32 v59, v59, v11, v27
	v_fma_f32 v60, v60, v12, v28
	v_fma_f32 v61, v61, v13, v29
	v_fma_f32 v62, v62, v14, v30
	v_fma_f32 v63, v63, v15, v31
	v_fma_f32 v64, v64, v16, v32
	v_fma_f32 v65, v65, v17, v33
	v_fma_f32 v66, v66, v18, v34
	v_fma_f32 v67, v67, v19, v35
	v_fma_f32 v68, v68, v20, v36
	v_fma_f32 v69, v69, v21, v37
	v_fma_f32 v70, v70, v22, v38
	v_fma_f32 v71, v71, v23, v39
	v_fma_f32 v72, v72, v24, v40
	v_fma_f32 v73, v73, v25, v41
	v_add_f32_e32 v9, v58, v59
	v_add_f32_e32 v91, v60, v61
	v_mul_f32_e32 v90, v58, v58
	v_mul_f32_e32 v92, v59, v59
	v_add_f32_e32 v9, v9, v62
	v_add_f32_e32 v91, v91, v63
	v_add_f32_e32 v9, v9, v64
	v_add_f32_e32 v91, v91, v65
	v_add_f32_e32 v9, v9, v66
	v_add_f32_e32 v91, v91, v67
	v_add_f32_e32 v9, v9, v68
	v_add_f32_e32 v91, v91, v69
	v_add_f32_e32 v9, v9, v70
	v_add_f32_e32 v91, v91, v71
	v_add_f32_e32 v9, v9, v72
	v_add_f32_e32 v91, v91, v73
	v_fmac_f32_e32 v90, v60, v60
	v_fmac_f32_e32 v92, v61, v61
	v_fmac_f32_e32 v90, v62, v62
	v_fmac_f32_e32 v92, v63, v63
	v_fmac_f32_e32 v90, v64, v64
	v_fmac_f32_e32 v92, v65, v65
	v_fmac_f32_e32 v90, v66, v66
	v_fmac_f32_e32 v92, v67, v67
	v_fmac_f32_e32 v90, v68, v68
	v_fmac_f32_e32 v92, v69, v69
	v_fmac_f32_e32 v90, v70, v70
	v_fmac_f32_e32 v92, v71, v71
	v_fmac_f32_e32 v90, v72, v72
	v_fmac_f32_e32 v92, v73, v73
	v_add_f32_e32 v9, v9, v91
	v_add_f32_e32 v90, v90, v92
	s_nop 1
	v_add_f32_dpp v9, v9, v9 quad_perm:[1,0,3,2] row_mask:0xf bank_mask:0xf
	v_add_f32_dpp v90, v90, v90 quad_perm:[1,0,3,2] row_mask:0xf bank_mask:0xf
	s_nop 0
	v_add_f32_dpp v9, v9, v9 quad_perm:[2,3,0,1] row_mask:0xf bank_mask:0xf
	v_add_f32_dpp v90, v90, v90 quad_perm:[2,3,0,1] row_mask:0xf bank_mask:0xf
	s_nop 0
	v_add_f32_dpp v9, v9, v9 row_half_mirror row_mask:0xf bank_mask:0xf
	v_add_f32_dpp v90, v90, v90 row_half_mirror row_mask:0xf bank_mask:0xf
	s_nop 0
	v_add_f32_dpp v9, v9, v9 row_mirror row_mask:0xf bank_mask:0xf
	v_add_f32_dpp v90, v90, v90 row_mirror row_mask:0xf bank_mask:0xf
	s_nop 0
	v_add_f32_dpp v9, v9, v9 row_bcast:15 row_mask:0xa bank_mask:0xf
	v_add_f32_dpp v90, v90, v90 row_bcast:15 row_mask:0xa bank_mask:0xf
	s_nop 0
	v_add_f32_dpp v9, v9, v9 row_bcast:31 row_mask:0xc bank_mask:0xf
	v_add_f32_dpp v90, v90, v90 row_bcast:31 row_mask:0xc bank_mask:0xf
	s_nop 0
	v_readlane_b32 s2, v9, 63
	v_readlane_b32 s3, v90, 63
	s_nop 1
	v_mov_b32_e32 v9, s2
	v_mov_b32_e32 v90, s3
	v_mul_f32_e32 v93, 0x3a800000, v9
	v_mul_f32_e32 v91, 0x3a800000, v90
	v_fma_f32 v91, -v93, v93, v91
	v_max_f32_e32 v91, 0, v91
	v_add_f32_e32 v91, 0x358637bd, v91
	v_rsq_f32_e32 v94, v91
	v_mul_f32_e32 v91, 0.5, v91
	v_mul_f32_e32 v92, v94, v94
	v_fma_f32 v92, -v91, v92, 0.5
	v_fma_f32 v94, v94, v92, v94
	v_sub_f32_e32 v58, v58, v93
	v_sub_f32_e32 v59, v59, v93
	v_sub_f32_e32 v60, v60, v93
	v_sub_f32_e32 v61, v61, v93
	v_sub_f32_e32 v62, v62, v93
	v_sub_f32_e32 v63, v63, v93
	v_sub_f32_e32 v64, v64, v93
	v_sub_f32_e32 v65, v65, v93
	v_sub_f32_e32 v66, v66, v93
	v_sub_f32_e32 v67, v67, v93
	v_sub_f32_e32 v68, v68, v93
	v_sub_f32_e32 v69, v69, v93
	v_sub_f32_e32 v70, v70, v93
	v_sub_f32_e32 v71, v71, v93
	v_sub_f32_e32 v72, v72, v93
	v_sub_f32_e32 v73, v73, v93
	v_mul_f32_e32 v58, v94, v58
	v_mul_f32_e32 v59, v94, v59
	v_mul_f32_e32 v60, v94, v60
	v_mul_f32_e32 v61, v94, v61
	v_mul_f32_e32 v62, v94, v62
	v_mul_f32_e32 v63, v94, v63
	v_mul_f32_e32 v64, v94, v64
	v_mul_f32_e32 v65, v94, v65
	v_mul_f32_e32 v66, v94, v66
	v_mul_f32_e32 v67, v94, v67
	v_mul_f32_e32 v68, v94, v68
	v_mul_f32_e32 v69, v94, v69
	v_mul_f32_e32 v70, v94, v70
	v_mul_f32_e32 v71, v94, v71
	v_mul_f32_e32 v72, v94, v72
	v_mul_f32_e32 v73, v94, v73
	v_fma_f32 v58, v58, v130, v114
	v_fma_f32 v59, v59, v131, v115
	v_fma_f32 v60, v60, v132, v116
	v_fma_f32 v61, v61, v133, v117
	v_fma_f32 v62, v62, v134, v118
	v_fma_f32 v63, v63, v135, v119
	v_fma_f32 v64, v64, v136, v120
	v_fma_f32 v65, v65, v137, v121
	v_fma_f32 v66, v66, v138, v122
	v_fma_f32 v67, v67, v139, v123
	v_fma_f32 v68, v68, v140, v124
	v_fma_f32 v69, v69, v141, v125
	v_fma_f32 v70, v70, v142, v126
	v_fma_f32 v71, v71, v143, v127
	v_fma_f32 v72, v72, v144, v128
	v_fma_f32 v73, v73, v145, v129
	v_cvt_pk_bf16_f32 v190, v58, v59
	v_cvt_pk_bf16_f32 v191, v60, v61
	v_cvt_pk_bf16_f32 v192, v62, v63
	v_cvt_pk_bf16_f32 v193, v64, v65
	v_cvt_pk_bf16_f32 v194, v66, v67
	v_cvt_pk_bf16_f32 v195, v68, v69
	v_cvt_pk_bf16_f32 v196, v70, v71
	v_cvt_pk_bf16_f32 v197, v72, v73
	s_add_u32 s2, s10, 0x800
	s_addc_u32 s3, s11, 0
	global_store_dwordx4 v1, v[190:193], s[2:3]
	global_store_dwordx4 v1, v[194:197], s[2:3] offset:1024
	s_add_u32 s2, s8, 0x5000
	s_addc_u32 s3, s9, 0
	global_load_dwordx4 v[58:61], v0, s[2:3]
	global_load_dwordx4 v[62:65], v0, s[2:3] offset:16
	global_load_dwordx4 v[66:69], v0, s[2:3] offset:2048
	global_load_dwordx4 v[70:73], v0, s[2:3] offset:2064
	s_waitcnt vmcnt(18)
; DI void ln_row_v(const Frame& F, f32x4 (&v)[4], float* xout, const float* g, const float* b, const float* sh, const float* sc, bf16_t* hout, const float* slab, const float* gres, float* stat = nullptr) {
;     ...
;         float s = 0.f, s2 = 0.f;
; #pragma unroll
;         for (int j = 0; j < 4; ++j) { s += (v[j][0] + v[j][1]) + (v[j][2] + v[j][3]); s2 += (v[j][0] * v[j][0] + v[j][1] * v[j][1]) + (v[j][2] * v[j][2] + v[j][3] * v[j][3]); }
;         wave_sum2(s, s2, F.lane);
;         const float mean = s * (1.f / D); const float rstd = 1.f / sqrtf(fmaxf(s2 * (1.f / D) - mean * mean, 0.f) + EPS);
;         if (stat && F.lane == 0) { f32x2 sv = {mean, rstd}; *(f32x2*)stat = sv; }
; #pragma unroll
;         for (int j = 0; j < 4; ++j) { const f32x4 gg = ((const f32x4*)g)[F.lane + 64 * j], bb = ((const f32x4*)b)[F.lane + 64 * j];
;             v[j] = (v[j] - mean) * rstd * gg + bb; if (xout) ((f32x4*)xout)[F.lane + 64 * j] = v[j]; }
;     }
;     if (hout) {
;         float s = 0.f, s2 = 0.f;
; #pragma unroll
;         for (int j = 0; j < 4; ++j) { s += (v[j][0] + v[j][1]) + (v[j][2] + v[j][3]); s2 += (v[j][0] * v[j][0] + v[j][1] * v[j][1]) + (v[j][2] * v[j][2] + v[j][3] * v[j][3]); }
;         wave_sum2(s, s2, F.lane);
;         const float mean = s * (1.f / D); const float rstd = 1.f / sqrtf(fmaxf(s2 * (1.f / D) - mean * mean, 0.f) + EPS);
	v_add_f32_e32 v9, v74, v75
	v_add_f32_e32 v91, v76, v77
	v_mul_f32_e32 v90, v74, v74
	v_mul_f32_e32 v92, v75, v75
	v_add_f32_e32 v9, v9, v78
	v_add_f32_e32 v91, v91, v79
	v_add_f32_e32 v9, v9, v80
	v_add_f32_e32 v91, v91, v81
	v_add_f32_e32 v9, v9, v82
	v_add_f32_e32 v91, v91, v83
	v_add_f32_e32 v9, v9, v84
	v_add_f32_e32 v91, v91, v85
	v_add_f32_e32 v9, v9, v86
	v_add_f32_e32 v91, v91, v87
	v_add_f32_e32 v9, v9, v88
	v_add_f32_e32 v91, v91, v89
	v_fmac_f32_e32 v90, v76, v76
	v_fmac_f32_e32 v92, v77, v77
	v_fmac_f32_e32 v90, v78, v78
	v_fmac_f32_e32 v92, v79, v79
	v_fmac_f32_e32 v90, v80, v80
	v_fmac_f32_e32 v92, v81, v81
	v_fmac_f32_e32 v90, v82, v82
	v_fmac_f32_e32 v92, v83, v83
	v_fmac_f32_e32 v90, v84, v84
	v_fmac_f32_e32 v92, v85, v85
	v_fmac_f32_e32 v90, v86, v86
	v_fmac_f32_e32 v92, v87, v87
	v_fmac_f32_e32 v90, v88, v88
	v_fmac_f32_e32 v92, v89, v89
	v_add_f32_e32 v9, v9, v91
	v_add_f32_e32 v90, v90, v92
	s_nop 1
	v_add_f32_dpp v9, v9, v9 quad_perm:[1,0,3,2] row_mask:0xf bank_mask:0xf
	v_add_f32_dpp v90, v90, v90 quad_perm:[1,0,3,2] row_mask:0xf bank_mask:0xf
	s_nop 0
	v_add_f32_dpp v9, v9, v9 quad_perm:[2,3,0,1] row_mask:0xf bank_mask:0xf
	v_add_f32_dpp v90, v90, v90 quad_perm:[2,3,0,1] row_mask:0xf bank_mask:0xf
	s_nop 0
	v_add_f32_dpp v9, v9, v9 row_half_mirror row_mask:0xf bank_mask:0xf
	v_add_f32_dpp v90, v90, v90 row_half_mirror row_mask:0xf bank_mask:0xf
	s_nop 0
	v_add_f32_dpp v9, v9, v9 row_mirror row_mask:0xf bank_mask:0xf
	v_add_f32_dpp v90, v90, v90 row_mirror row_mask:0xf bank_mask:0xf
	s_nop 0
	v_add_f32_dpp v9, v9, v9 row_bcast:15 row_mask:0xa bank_mask:0xf
	v_add_f32_dpp v90, v90, v90 row_bcast:15 row_mask:0xa bank_mask:0xf
	s_nop 0
	v_add_f32_dpp v9, v9, v9 row_bcast:31 row_mask:0xc bank_mask:0xf
	v_add_f32_dpp v90, v90, v90 row_bcast:31 row_mask:0xc bank_mask:0xf
	s_nop 0
	v_readlane_b32 s2, v9, 63
	v_readlane_b32 s3, v90, 63
	s_nop 1
	v_mov_b32_e32 v9, s2
	v_mov_b32_e32 v90, s3
	v_mul_f32_e32 v93, 0x3a800000, v9
	v_mul_f32_e32 v91, 0x3a800000, v90
	v_fma_f32 v91, -v93, v93, v91
	v_max_f32_e32 v91, 0, v91
	v_add_f32_e32 v91, 0x358637bd, v91
	v_rsq_f32_e32 v94, v91
	v_mul_f32_e32 v91, 0.5, v91
	v_mul_f32_e32 v92, v94, v94
	v_fma_f32 v92, -v91, v92, 0.5
	v_fma_f32 v94, v94, v92, v94
	s_add_u32 s2, s12, 0x10
	s_addc_u32 s3, s13, 0
	v_mov_b32_e32 v188, v93
	v_mov_b32_e32 v189, v94
	s_mov_b64 exec, 1
	global_store_dwordx2 v97, v[188:189], s[2:3]
	s_mov_b64 exec, -1
	v_sub_f32_e32 v74, v74, v93
	v_sub_f32_e32 v75, v75, v93
	v_sub_f32_e32 v76, v76, v93
	v_sub_f32_e32 v77, v77, v93
	v_sub_f32_e32 v78, v78, v93
	v_sub_f32_e32 v79, v79, v93
	v_sub_f32_e32 v80, v80, v93
	v_sub_f32_e32 v81, v81, v93
	v_sub_f32_e32 v82, v82, v93
	v_sub_f32_e32 v83, v83, v93
	v_sub_f32_e32 v84, v84, v93
	v_sub_f32_e32 v85, v85, v93
	v_sub_f32_e32 v86, v86, v93
	v_sub_f32_e32 v87, v87, v93
	v_sub_f32_e32 v88, v88, v93
	v_sub_f32_e32 v89, v89, v93
	v_mul_f32_e32 v74, v94, v74
	v_mul_f32_e32 v75, v94, v75
	v_mul_f32_e32 v76, v94, v76
	v_mul_f32_e32 v77, v94, v77
	v_mul_f32_e32 v78, v94, v78
	v_mul_f32_e32 v79, v94, v79
	v_mul_f32_e32 v80, v94, v80
	v_mul_f32_e32 v81, v94, v81
	v_mul_f32_e32 v82, v94, v82
	v_mul_f32_e32 v83, v94, v83
	v_mul_f32_e32 v84, v94, v84
	v_mul_f32_e32 v85, v94, v85
	v_mul_f32_e32 v86, v94, v86
	v_mul_f32_e32 v87, v94, v87
	v_mul_f32_e32 v88, v94, v88
	v_mul_f32_e32 v89, v94, v89
	v_fma_f32 v74, v74, v10, v26
	v_fma_f32 v75, v75, v11, v27
	v_fma_f32 v76, v76, v12, v28
	v_fma_f32 v77, v77, v13, v29
	v_fma_f32 v78, v78, v14, v30
	v_fma_f32 v79, v79, v15, v31
	v_fma_f32 v80, v80, v16, v32
	v_fma_f32 v81, v81, v17, v33
	v_fma_f32 v82, v82, v18, v34
	v_fma_f32 v83, v83, v19, v35
	v_fma_f32 v84, v84, v20, v36
	v_fma_f32 v85, v85, v21, v37
	v_fma_f32 v86, v86, v22, v38
	v_fma_f32 v87, v87, v23, v39
	v_fma_f32 v88, v88, v24, v40
	v_fma_f32 v89, v89, v25, v41
	v_add_f32_e32 v9, v74, v75
	v_add_f32_e32 v91, v76, v77
	v_mul_f32_e32 v90, v74, v74
	v_mul_f32_e32 v92, v75, v75
	v_add_f32_e32 v9, v9, v78
	v_add_f32_e32 v91, v91, v79
	v_add_f32_e32 v9, v9, v80
	v_add_f32_e32 v91, v91, v81
	v_add_f32_e32 v9, v9, v82
	v_add_f32_e32 v91, v91, v83
	v_add_f32_e32 v9, v9, v84
	v_add_f32_e32 v91, v91, v85
	v_add_f32_e32 v9, v9, v86
	v_add_f32_e32 v91, v91, v87
	v_add_f32_e32 v9, v9, v88
	v_add_f32_e32 v91, v91, v89
	v_fmac_f32_e32 v90, v76, v76
	v_fmac_f32_e32 v92, v77, v77
	v_fmac_f32_e32 v90, v78, v78
	v_fmac_f32_e32 v92, v79, v79
	v_fmac_f32_e32 v90, v80, v80
	v_fmac_f32_e32 v92, v81, v81
	v_fmac_f32_e32 v90, v82, v82
	v_fmac_f32_e32 v92, v83, v83
	v_fmac_f32_e32 v90, v84, v84
	v_fmac_f32_e32 v92, v85, v85
	v_fmac_f32_e32 v90, v86, v86
	v_fmac_f32_e32 v92, v87, v87
	v_fmac_f32_e32 v90, v88, v88
	v_fmac_f32_e32 v92, v89, v89
	v_add_f32_e32 v9, v9, v91
	v_add_f32_e32 v90, v90, v92
	s_nop 1
	v_add_f32_dpp v9, v9, v9 quad_perm:[1,0,3,2] row_mask:0xf bank_mask:0xf
	v_add_f32_dpp v90, v90, v90 quad_perm:[1,0,3,2] row_mask:0xf bank_mask:0xf
	s_nop 0
	v_add_f32_dpp v9, v9, v9 quad_perm:[2,3,0,1] row_mask:0xf bank_mask:0xf
	v_add_f32_dpp v90, v90, v90 quad_perm:[2,3,0,1] row_mask:0xf bank_mask:0xf
	s_nop 0
	v_add_f32_dpp v9, v9, v9 row_half_mirror row_mask:0xf bank_mask:0xf
	v_add_f32_dpp v90, v90, v90 row_half_mirror row_mask:0xf bank_mask:0xf
	s_nop 0
	v_add_f32_dpp v9, v9, v9 row_mirror row_mask:0xf bank_mask:0xf
	v_add_f32_dpp v90, v90, v90 row_mirror row_mask:0xf bank_mask:0xf
	s_nop 0
	v_add_f32_dpp v9, v9, v9 row_bcast:15 row_mask:0xa bank_mask:0xf
	v_add_f32_dpp v90, v90, v90 row_bcast:15 row_mask:0xa bank_mask:0xf
	s_nop 0
	v_add_f32_dpp v9, v9, v9 row_bcast:31 row_mask:0xc bank_mask:0xf
	v_add_f32_dpp v90, v90, v90 row_bcast:31 row_mask:0xc bank_mask:0xf
; DI unsigned pk2(float lo, float hi) { f32x2 v = {lo, hi}; bf16x2_t b = __builtin_convertvector(v, bf16x2_t); return __builtin_bit_cast(unsigned, b); }
; DI void ln_row_v(const Frame& F, f32x4 (&v)[4], float* xout, const float* g, const float* b, const float* sh, const float* sc, bf16_t* hout, const float* slab, const float* gres, float* stat = nullptr) {
;     ...
;         float s = 0.f, s2 = 0.f;
; #pragma unroll
;         for (int j = 0; j < 4; ++j) { s += (v[j][0] + v[j][1]) + (v[j][2] + v[j][3]); s2 += (v[j][0] * v[j][0] + v[j][1] * v[j][1]) + (v[j][2] * v[j][2] + v[j][3] * v[j][3]); }
;         wave_sum2(s, s2, F.lane);
;         const float mean = s * (1.f / D); const float rstd = 1.f / sqrtf(fmaxf(s2 * (1.f / D) - mean * mean, 0.f) + EPS);
;         if (stat && F.lane == 0) { f32x2 sv = {mean, rstd}; *(f32x2*)stat = sv; }
;     ...
;         const float mean = s * (1.f / D); const float rstd = 1.f / sqrtf(fmaxf(s2 * (1.f / D) - mean * mean, 0.f) + EPS);
; #pragma unroll
;         for (int j = 0; j < 4; ++j) { const f32x4 hh = ((const f32x4*)sh)[F.lane + 64 * j], cc = ((const f32x4*)sc)[F.lane + 64 * j];
;             const f32x4 o = (v[j] - mean) * rstd * (cc + 1.f) + hh; u32x2 wv; wv.x = pk2(o[0], o[1]); wv.y = pk2(o[2], o[3]);
;             ((u32x2*)hout)[F.lane + 64 * j] = wv; }
;     }
	s_nop 0
	v_readlane_b32 s2, v9, 63
	v_readlane_b32 s3, v90, 63
	s_nop 1
	v_mov_b32_e32 v9, s2
	v_mov_b32_e32 v90, s3
	v_mul_f32_e32 v93, 0x3a800000, v9
	v_mul_f32_e32 v91, 0x3a800000, v90
	v_fma_f32 v91, -v93, v93, v91
	v_max_f32_e32 v91, 0, v91
	v_add_f32_e32 v91, 0x358637bd, v91
	v_rsq_f32_e32 v94, v91
	v_mul_f32_e32 v91, 0.5, v91
	v_mul_f32_e32 v92, v94, v94
	v_fma_f32 v92, -v91, v92, 0.5
	v_fma_f32 v94, v94, v92, v94
	v_sub_f32_e32 v74, v74, v93
	v_sub_f32_e32 v75, v75, v93
	v_sub_f32_e32 v76, v76, v93
	v_sub_f32_e32 v77, v77, v93
	v_sub_f32_e32 v78, v78, v93
	v_sub_f32_e32 v79, v79, v93
	v_sub_f32_e32 v80, v80, v93
	v_sub_f32_e32 v81, v81, v93
	v_sub_f32_e32 v82, v82, v93
	v_sub_f32_e32 v83, v83, v93
	v_sub_f32_e32 v84, v84, v93
	v_sub_f32_e32 v85, v85, v93
	v_sub_f32_e32 v86, v86, v93
	v_sub_f32_e32 v87, v87, v93
	v_sub_f32_e32 v88, v88, v93
	v_sub_f32_e32 v89, v89, v93
	v_mul_f32_e32 v74, v94, v74
	v_mul_f32_e32 v75, v94, v75
	v_mul_f32_e32 v76, v94, v76
	v_mul_f32_e32 v77, v94, v77
	v_mul_f32_e32 v78, v94, v78
	v_mul_f32_e32 v79, v94, v79
	v_mul_f32_e32 v80, v94, v80
	v_mul_f32_e32 v81, v94, v81
	v_mul_f32_e32 v82, v94, v82
	v_mul_f32_e32 v83, v94, v83
	v_mul_f32_e32 v84, v94, v84
	v_mul_f32_e32 v85, v94, v85
	v_mul_f32_e32 v86, v94, v86
	v_mul_f32_e32 v87, v94, v87
	v_mul_f32_e32 v88, v94, v88
	v_mul_f32_e32 v89, v94, v89
	v_fma_f32 v74, v74, v130, v114
	v_fma_f32 v75, v75, v131, v115
	v_fma_f32 v76, v76, v132, v116
	v_fma_f32 v77, v77, v133, v117
	v_fma_f32 v78, v78, v134, v118
	v_fma_f32 v79, v79, v135, v119
	v_fma_f32 v80, v80, v136, v120
	v_fma_f32 v81, v81, v137, v121
	v_fma_f32 v82, v82, v138, v122
	v_fma_f32 v83, v83, v139, v123
	v_fma_f32 v84, v84, v140, v124
	v_fma_f32 v85, v85, v141, v125
	v_fma_f32 v86, v86, v142, v126
	v_fma_f32 v87, v87, v143, v127
	v_fma_f32 v88, v88, v144, v128
	v_fma_f32 v89, v89, v145, v129
	v_cvt_pk_bf16_f32 v190, v74, v75
	v_cvt_pk_bf16_f32 v191, v76, v77
	v_cvt_pk_bf16_f32 v192, v78, v79
	v_cvt_pk_bf16_f32 v193, v80, v81
	v_cvt_pk_bf16_f32 v194, v82, v83
	v_cvt_pk_bf16_f32 v195, v84, v85
	v_cvt_pk_bf16_f32 v196, v86, v87
	v_cvt_pk_bf16_f32 v197, v88, v89
	s_add_u32 s2, s10, 0x1000
	s_addc_u32 s3, s11, 0
	global_store_dwordx4 v1, v[190:193], s[2:3]
	global_store_dwordx4 v1, v[194:197], s[2:3] offset:1024
	s_add_u32 s2, s8, 0x6000
	s_addc_u32 s3, s9, 0
	global_load_dwordx4 v[74:77], v0, s[2:3]
	global_load_dwordx4 v[78:81], v0, s[2:3] offset:16
	global_load_dwordx4 v[82:85], v0, s[2:3] offset:2048
	global_load_dwordx4 v[86:89], v0, s[2:3] offset:2064
	s_waitcnt vmcnt(21)
	v_add_f32_e32 v9, v98, v99
	v_add_f32_e32 v91, v100, v101
	v_mul_f32_e32 v90, v98, v98
	v_mul_f32_e32 v92, v99, v99
	v_add_f32_e32 v9, v9, v102
	v_add_f32_e32 v91, v91, v103
	v_add_f32_e32 v9, v9, v104
	v_add_f32_e32 v91, v91, v105
	v_add_f32_e32 v9, v9, v106
	v_add_f32_e32 v91, v91, v107
	v_add_f32_e32 v9, v9, v108
	v_add_f32_e32 v91, v91, v109
	v_add_f32_e32 v9, v9, v110
	v_add_f32_e32 v91, v91, v111
	v_add_f32_e32 v9, v9, v112
	v_add_f32_e32 v91, v91, v113
	v_fmac_f32_e32 v90, v100, v100
	v_fmac_f32_e32 v92, v101, v101
	v_fmac_f32_e32 v90, v102, v102
	v_fmac_f32_e32 v92, v103, v103
	v_fmac_f32_e32 v90, v104, v104
	v_fmac_f32_e32 v92, v105, v105
	v_fmac_f32_e32 v90, v106, v106
	v_fmac_f32_e32 v92, v107, v107
	v_fmac_f32_e32 v90, v108, v108
	v_fmac_f32_e32 v92, v109, v109
	v_fmac_f32_e32 v90, v110, v110
	v_fmac_f32_e32 v92, v111, v111
	v_fmac_f32_e32 v90, v112, v112
	v_fmac_f32_e32 v92, v113, v113
	v_add_f32_e32 v9, v9, v91
	v_add_f32_e32 v90, v90, v92
	s_nop 1
	v_add_f32_dpp v9, v9, v9 quad_perm:[1,0,3,2] row_mask:0xf bank_mask:0xf
	v_add_f32_dpp v90, v90, v90 quad_perm:[1,0,3,2] row_mask:0xf bank_mask:0xf
	s_nop 0
	v_add_f32_dpp v9, v9, v9 quad_perm:[2,3,0,1] row_mask:0xf bank_mask:0xf
	v_add_f32_dpp v90, v90, v90 quad_perm:[2,3,0,1] row_mask:0xf bank_mask:0xf
	s_nop 0
	v_add_f32_dpp v9, v9, v9 row_half_mirror row_mask:0xf bank_mask:0xf
	v_add_f32_dpp v90, v90, v90 row_half_mirror row_mask:0xf bank_mask:0xf
	s_nop 0
	v_add_f32_dpp v9, v9, v9 row_mirror row_mask:0xf bank_mask:0xf
	v_add_f32_dpp v90, v90, v90 row_mirror row_mask:0xf bank_mask:0xf
	s_nop 0
	v_add_f32_dpp v9, v9, v9 row_bcast:15 row_mask:0xa bank_mask:0xf
	v_add_f32_dpp v90, v90, v90 row_bcast:15 row_mask:0xa bank_mask:0xf
	s_nop 0
	v_add_f32_dpp v9, v9, v9 row_bcast:31 row_mask:0xc bank_mask:0xf
	v_add_f32_dpp v90, v90, v90 row_bcast:31 row_mask:0xc bank_mask:0xf
	s_nop 0
	v_readlane_b32 s2, v9, 63
	v_readlane_b32 s3, v90, 63
	s_nop 1
	v_mov_b32_e32 v9, s2
	v_mov_b32_e32 v90, s3
	v_mul_f32_e32 v93, 0x3a800000, v9
	v_mul_f32_e32 v91, 0x3a800000, v90
	v_fma_f32 v91, -v93, v93, v91
	v_max_f32_e32 v91, 0, v91
	v_add_f32_e32 v91, 0x358637bd, v91
	v_rsq_f32_e32 v94, v91
	v_mul_f32_e32 v91, 0.5, v91
	v_mul_f32_e32 v92, v94, v94
	v_fma_f32 v92, -v91, v92, 0.5
	v_fma_f32 v94, v94, v92, v94
	s_add_u32 s2, s12, 0x18
	s_addc_u32 s3, s13, 0
	v_mov_b32_e32 v188, v93
	v_mov_b32_e32 v189, v94
	s_mov_b64 exec, 1
	global_store_dwordx2 v97, v[188:189], s[2:3]
	s_mov_b64 exec, -1
	v_sub_f32_e32 v98, v98, v93
	v_sub_f32_e32 v99, v99, v93
	v_sub_f32_e32 v100, v100, v93
	v_sub_f32_e32 v101, v101, v93
	v_sub_f32_e32 v102, v102, v93
	v_sub_f32_e32 v103, v103, v93
	v_sub_f32_e32 v104, v104, v93
	v_sub_f32_e32 v105, v105, v93
	v_sub_f32_e32 v106, v106, v93
	v_sub_f32_e32 v107, v107, v93
	v_sub_f32_e32 v108, v108, v93
	v_sub_f32_e32 v109, v109, v93
	v_sub_f32_e32 v110, v110, v93
	v_sub_f32_e32 v111, v111, v93
	v_sub_f32_e32 v112, v112, v93
	v_sub_f32_e32 v113, v113, v93
	v_mul_f32_e32 v98, v94, v98
	v_mul_f32_e32 v99, v94, v99
	v_mul_f32_e32 v100, v94, v100
	v_mul_f32_e32 v101, v94, v101
; DI unsigned pk2(float lo, float hi) { f32x2 v = {lo, hi}; bf16x2_t b = __builtin_convertvector(v, bf16x2_t); return __builtin_bit_cast(unsigned, b); }
; DI void ln_row_v(const Frame& F, f32x4 (&v)[4], float* xout, const float* g, const float* b, const float* sh, const float* sc, bf16_t* hout, const float* slab, const float* gres, float* stat = nullptr) {
;     ...
;         for (int j = 0; j < 4; ++j) { const f32x4 gg = ((const f32x4*)g)[F.lane + 64 * j], bb = ((const f32x4*)b)[F.lane + 64 * j];
;             v[j] = (v[j] - mean) * rstd * gg + bb; if (xout) ((f32x4*)xout)[F.lane + 64 * j] = v[j]; }
;     }
;     if (hout) {
;         float s = 0.f, s2 = 0.f;
; #pragma unroll
;         for (int j = 0; j < 4; ++j) { s += (v[j][0] + v[j][1]) + (v[j][2] + v[j][3]); s2 += (v[j][0] * v[j][0] + v[j][1] * v[j][1]) + (v[j][2] * v[j][2] + v[j][3] * v[j][3]); }
;         wave_sum2(s, s2, F.lane);
;         const float mean = s * (1.f / D); const float rstd = 1.f / sqrtf(fmaxf(s2 * (1.f / D) - mean * mean, 0.f) + EPS);
; #pragma unroll
;         for (int j = 0; j < 4; ++j) { const f32x4 hh = ((const f32x4*)sh)[F.lane + 64 * j], cc = ((const f32x4*)sc)[F.lane + 64 * j];
;             const f32x4 o = (v[j] - mean) * rstd * (cc + 1.f) + hh; u32x2 wv; wv.x = pk2(o[0], o[1]); wv.y = pk2(o[2], o[3]);
;             ((u32x2*)hout)[F.lane + 64 * j] = wv; }
;     }
; DI void ln_phase(const Frame& F, int which) {
;     ...
;         if (row + NGW < nrows) ln_load(F, xrow_ptr(F, row + NGW), vn);
	v_mul_f32_e32 v102, v94, v102
	v_mul_f32_e32 v103, v94, v103
	v_mul_f32_e32 v104, v94, v104
	v_mul_f32_e32 v105, v94, v105
	v_mul_f32_e32 v106, v94, v106
	v_mul_f32_e32 v107, v94, v107
	v_mul_f32_e32 v108, v94, v108
	v_mul_f32_e32 v109, v94, v109
	v_mul_f32_e32 v110, v94, v110
	v_mul_f32_e32 v111, v94, v111
	v_mul_f32_e32 v112, v94, v112
	v_mul_f32_e32 v113, v94, v113
	v_fma_f32 v98, v98, v10, v26
	v_fma_f32 v99, v99, v11, v27
	v_fma_f32 v100, v100, v12, v28
	v_fma_f32 v101, v101, v13, v29
	v_fma_f32 v102, v102, v14, v30
	v_fma_f32 v103, v103, v15, v31
	v_fma_f32 v104, v104, v16, v32
	v_fma_f32 v105, v105, v17, v33
	v_fma_f32 v106, v106, v18, v34
	v_fma_f32 v107, v107, v19, v35
	v_fma_f32 v108, v108, v20, v36
	v_fma_f32 v109, v109, v21, v37
	v_fma_f32 v110, v110, v22, v38
	v_fma_f32 v111, v111, v23, v39
	v_fma_f32 v112, v112, v24, v40
	v_fma_f32 v113, v113, v25, v41
	v_add_f32_e32 v9, v98, v99
	v_add_f32_e32 v91, v100, v101
	v_mul_f32_e32 v90, v98, v98
	v_mul_f32_e32 v92, v99, v99
	v_add_f32_e32 v9, v9, v102
	v_add_f32_e32 v91, v91, v103
	v_add_f32_e32 v9, v9, v104
	v_add_f32_e32 v91, v91, v105
	v_add_f32_e32 v9, v9, v106
	v_add_f32_e32 v91, v91, v107
	v_add_f32_e32 v9, v9, v108
	v_add_f32_e32 v91, v91, v109
	v_add_f32_e32 v9, v9, v110
	v_add_f32_e32 v91, v91, v111
	v_add_f32_e32 v9, v9, v112
	v_add_f32_e32 v91, v91, v113
	v_fmac_f32_e32 v90, v100, v100
	v_fmac_f32_e32 v92, v101, v101
	v_fmac_f32_e32 v90, v102, v102
	v_fmac_f32_e32 v92, v103, v103
	v_fmac_f32_e32 v90, v104, v104
	v_fmac_f32_e32 v92, v105, v105
	v_fmac_f32_e32 v90, v106, v106
	v_fmac_f32_e32 v92, v107, v107
	v_fmac_f32_e32 v90, v108, v108
	v_fmac_f32_e32 v92, v109, v109
	v_fmac_f32_e32 v90, v110, v110
	v_fmac_f32_e32 v92, v111, v111
	v_fmac_f32_e32 v90, v112, v112
	v_fmac_f32_e32 v92, v113, v113
	v_add_f32_e32 v9, v9, v91
	v_add_f32_e32 v90, v90, v92
	s_nop 1
	v_add_f32_dpp v9, v9, v9 quad_perm:[1,0,3,2] row_mask:0xf bank_mask:0xf
	v_add_f32_dpp v90, v90, v90 quad_perm:[1,0,3,2] row_mask:0xf bank_mask:0xf
	s_nop 0
	v_add_f32_dpp v9, v9, v9 quad_perm:[2,3,0,1] row_mask:0xf bank_mask:0xf
	v_add_f32_dpp v90, v90, v90 quad_perm:[2,3,0,1] row_mask:0xf bank_mask:0xf
	s_nop 0
	v_add_f32_dpp v9, v9, v9 row_half_mirror row_mask:0xf bank_mask:0xf
	v_add_f32_dpp v90, v90, v90 row_half_mirror row_mask:0xf bank_mask:0xf
	s_nop 0
	v_add_f32_dpp v9, v9, v9 row_mirror row_mask:0xf bank_mask:0xf
	v_add_f32_dpp v90, v90, v90 row_mirror row_mask:0xf bank_mask:0xf
	s_nop 0
	v_add_f32_dpp v9, v9, v9 row_bcast:15 row_mask:0xa bank_mask:0xf
	v_add_f32_dpp v90, v90, v90 row_bcast:15 row_mask:0xa bank_mask:0xf
	s_nop 0
	v_add_f32_dpp v9, v9, v9 row_bcast:31 row_mask:0xc bank_mask:0xf
	v_add_f32_dpp v90, v90, v90 row_bcast:31 row_mask:0xc bank_mask:0xf
	s_nop 0
	v_readlane_b32 s2, v9, 63
	v_readlane_b32 s3, v90, 63
	s_nop 1
	v_mov_b32_e32 v9, s2
	v_mov_b32_e32 v90, s3
	v_mul_f32_e32 v93, 0x3a800000, v9
	v_mul_f32_e32 v91, 0x3a800000, v90
	v_fma_f32 v91, -v93, v93, v91
	v_max_f32_e32 v91, 0, v91
	v_add_f32_e32 v91, 0x358637bd, v91
	v_rsq_f32_e32 v94, v91
	v_mul_f32_e32 v91, 0.5, v91
	v_mul_f32_e32 v92, v94, v94
	v_fma_f32 v92, -v91, v92, 0.5
	v_fma_f32 v94, v94, v92, v94
	v_sub_f32_e32 v98, v98, v93
	v_sub_f32_e32 v99, v99, v93
	v_sub_f32_e32 v100, v100, v93
	v_sub_f32_e32 v101, v101, v93
	v_sub_f32_e32 v102, v102, v93
	v_sub_f32_e32 v103, v103, v93
	v_sub_f32_e32 v104, v104, v93
	v_sub_f32_e32 v105, v105, v93
	v_sub_f32_e32 v106, v106, v93
	v_sub_f32_e32 v107, v107, v93
	v_sub_f32_e32 v108, v108, v93
	v_sub_f32_e32 v109, v109, v93
	v_sub_f32_e32 v110, v110, v93
	v_sub_f32_e32 v111, v111, v93
	v_sub_f32_e32 v112, v112, v93
	v_sub_f32_e32 v113, v113, v93
	v_mul_f32_e32 v98, v94, v98
	v_mul_f32_e32 v99, v94, v99
	v_mul_f32_e32 v100, v94, v100
	v_mul_f32_e32 v101, v94, v101
	v_mul_f32_e32 v102, v94, v102
	v_mul_f32_e32 v103, v94, v103
	v_mul_f32_e32 v104, v94, v104
	v_mul_f32_e32 v105, v94, v105
	v_mul_f32_e32 v106, v94, v106
	v_mul_f32_e32 v107, v94, v107
	v_mul_f32_e32 v108, v94, v108
	v_mul_f32_e32 v109, v94, v109
	v_mul_f32_e32 v110, v94, v110
	v_mul_f32_e32 v111, v94, v111
	v_mul_f32_e32 v112, v94, v112
	v_mul_f32_e32 v113, v94, v113
	v_fma_f32 v98, v98, v130, v114
	v_fma_f32 v99, v99, v131, v115
	v_fma_f32 v100, v100, v132, v116
	v_fma_f32 v101, v101, v133, v117
	v_fma_f32 v102, v102, v134, v118
	v_fma_f32 v103, v103, v135, v119
	v_fma_f32 v104, v104, v136, v120
	v_fma_f32 v105, v105, v137, v121
	v_fma_f32 v106, v106, v138, v122
	v_fma_f32 v107, v107, v139, v123
	v_fma_f32 v108, v108, v140, v124
	v_fma_f32 v109, v109, v141, v125
	v_fma_f32 v110, v110, v142, v126
	v_fma_f32 v111, v111, v143, v127
	v_fma_f32 v112, v112, v144, v128
	v_fma_f32 v113, v113, v145, v129
	v_cvt_pk_bf16_f32 v190, v98, v99
	v_cvt_pk_bf16_f32 v191, v100, v101
	v_cvt_pk_bf16_f32 v192, v102, v103
	v_cvt_pk_bf16_f32 v193, v104, v105
	v_cvt_pk_bf16_f32 v194, v106, v107
	v_cvt_pk_bf16_f32 v195, v108, v109
	v_cvt_pk_bf16_f32 v196, v110, v111
	v_cvt_pk_bf16_f32 v197, v112, v113
	s_add_u32 s2, s10, 0x1800
	s_addc_u32 s3, s11, 0
	global_store_dwordx4 v1, v[190:193], s[2:3]
	global_store_dwordx4 v1, v[194:197], s[2:3] offset:1024
	s_add_u32 s2, s8, 0x7000
	s_addc_u32 s3, s9, 0
	global_load_dwordx4 v[98:101], v0, s[2:3]
	global_load_dwordx4 v[102:105], v0, s[2:3] offset:16
	global_load_dwordx4 v[106:109], v0, s[2:3] offset:2048
	global_load_dwordx4 v[110:113], v0, s[2:3] offset:2064
	s_waitcnt vmcnt(21)
; DI void ln_row_v(const Frame& F, f32x4 (&v)[4], float* xout, const float* g, const float* b, const float* sh, const float* sc, bf16_t* hout, const float* slab, const float* gres, float* stat = nullptr) {
;     ...
;         float s = 0.f, s2 = 0.f;
; #pragma unroll
;         for (int j = 0; j < 4; ++j) { s += (v[j][0] + v[j][1]) + (v[j][2] + v[j][3]); s2 += (v[j][0] * v[j][0] + v[j][1] * v[j][1]) + (v[j][2] * v[j][2] + v[j][3] * v[j][3]); }
;         wave_sum2(s, s2, F.lane);
;         const float mean = s * (1.f / D); const float rstd = 1.f / sqrtf(fmaxf(s2 * (1.f / D) - mean * mean, 0.f) + EPS);
;         if (stat && F.lane == 0) { f32x2 sv = {mean, rstd}; *(f32x2*)stat = sv; }
; #pragma unroll
;         for (int j = 0; j < 4; ++j) { const f32x4 gg = ((const f32x4*)g)[F.lane + 64 * j], bb = ((const f32x4*)b)[F.lane + 64 * j];
;             v[j] = (v[j] - mean) * rstd * gg + bb; if (xout) ((f32x4*)xout)[F.lane + 64 * j] = v[j]; }
;     }
;     if (hout) {
;         float s = 0.f, s2 = 0.f;
; #pragma unroll
;         for (int j = 0; j < 4; ++j) { s += (v[j][0] + v[j][1]) + (v[j][2] + v[j][3]); s2 += (v[j][0] * v[j][0] + v[j][1] * v[j][1]) + (v[j][2] * v[j][2] + v[j][3] * v[j][3]); }
;         wave_sum2(s, s2, F.lane);
;         const float mean = s * (1.f / D); const float rstd = 1.f / sqrtf(fmaxf(s2 * (1.f / D) - mean * mean, 0.f) + EPS);
	v_add_f32_e32 v9, v42, v43
	v_add_f32_e32 v91, v44, v45
	v_mul_f32_e32 v90, v42, v42
	v_mul_f32_e32 v92, v43, v43
	v_add_f32_e32 v9, v9, v46
	v_add_f32_e32 v91, v91, v47
	v_add_f32_e32 v9, v9, v48
	v_add_f32_e32 v91, v91, v49
	v_add_f32_e32 v9, v9, v50
	v_add_f32_e32 v91, v91, v51
	v_add_f32_e32 v9, v9, v52
	v_add_f32_e32 v91, v91, v53
	v_add_f32_e32 v9, v9, v54
	v_add_f32_e32 v91, v91, v55
	v_add_f32_e32 v9, v9, v56
	v_add_f32_e32 v91, v91, v57
	v_fmac_f32_e32 v90, v44, v44
	v_fmac_f32_e32 v92, v45, v45
	v_fmac_f32_e32 v90, v46, v46
	v_fmac_f32_e32 v92, v47, v47
	v_fmac_f32_e32 v90, v48, v48
	v_fmac_f32_e32 v92, v49, v49
	v_fmac_f32_e32 v90, v50, v50
	v_fmac_f32_e32 v92, v51, v51
	v_fmac_f32_e32 v90, v52, v52
	v_fmac_f32_e32 v92, v53, v53
	v_fmac_f32_e32 v90, v54, v54
	v_fmac_f32_e32 v92, v55, v55
	v_fmac_f32_e32 v90, v56, v56
	v_fmac_f32_e32 v92, v57, v57
	v_add_f32_e32 v9, v9, v91
	v_add_f32_e32 v90, v90, v92
	s_nop 1
	v_add_f32_dpp v9, v9, v9 quad_perm:[1,0,3,2] row_mask:0xf bank_mask:0xf
	v_add_f32_dpp v90, v90, v90 quad_perm:[1,0,3,2] row_mask:0xf bank_mask:0xf
	s_nop 0
	v_add_f32_dpp v9, v9, v9 quad_perm:[2,3,0,1] row_mask:0xf bank_mask:0xf
	v_add_f32_dpp v90, v90, v90 quad_perm:[2,3,0,1] row_mask:0xf bank_mask:0xf
	s_nop 0
	v_add_f32_dpp v9, v9, v9 row_half_mirror row_mask:0xf bank_mask:0xf
	v_add_f32_dpp v90, v90, v90 row_half_mirror row_mask:0xf bank_mask:0xf
	s_nop 0
	v_add_f32_dpp v9, v9, v9 row_mirror row_mask:0xf bank_mask:0xf
	v_add_f32_dpp v90, v90, v90 row_mirror row_mask:0xf bank_mask:0xf
	s_nop 0
	v_add_f32_dpp v9, v9, v9 row_bcast:15 row_mask:0xa bank_mask:0xf
	v_add_f32_dpp v90, v90, v90 row_bcast:15 row_mask:0xa bank_mask:0xf
	s_nop 0
	v_add_f32_dpp v9, v9, v9 row_bcast:31 row_mask:0xc bank_mask:0xf
	v_add_f32_dpp v90, v90, v90 row_bcast:31 row_mask:0xc bank_mask:0xf
	s_nop 0
	v_readlane_b32 s2, v9, 63
	v_readlane_b32 s3, v90, 63
	s_nop 1
	v_mov_b32_e32 v9, s2
	v_mov_b32_e32 v90, s3
	v_mul_f32_e32 v93, 0x3a800000, v9
	v_mul_f32_e32 v91, 0x3a800000, v90
	v_fma_f32 v91, -v93, v93, v91
	v_max_f32_e32 v91, 0, v91
	v_add_f32_e32 v91, 0x358637bd, v91
	v_rsq_f32_e32 v94, v91
	v_mul_f32_e32 v91, 0.5, v91
	v_mul_f32_e32 v92, v94, v94
	v_fma_f32 v92, -v91, v92, 0.5
	v_fma_f32 v94, v94, v92, v94
	s_add_u32 s2, s12, 0x20
	s_addc_u32 s3, s13, 0
	v_mov_b32_e32 v188, v93
	v_mov_b32_e32 v189, v94
	s_mov_b64 exec, 1
	global_store_dwordx2 v97, v[188:189], s[2:3]
	s_mov_b64 exec, -1
	v_sub_f32_e32 v42, v42, v93
	v_sub_f32_e32 v43, v43, v93
	v_sub_f32_e32 v44, v44, v93
	v_sub_f32_e32 v45, v45, v93
	v_sub_f32_e32 v46, v46, v93
	v_sub_f32_e32 v47, v47, v93
	v_sub_f32_e32 v48, v48, v93
	v_sub_f32_e32 v49, v49, v93
	v_sub_f32_e32 v50, v50, v93
	v_sub_f32_e32 v51, v51, v93
	v_sub_f32_e32 v52, v52, v93
	v_sub_f32_e32 v53, v53, v93
	v_sub_f32_e32 v54, v54, v93
	v_sub_f32_e32 v55, v55, v93
	v_sub_f32_e32 v56, v56, v93
	v_sub_f32_e32 v57, v57, v93
	v_mul_f32_e32 v42, v94, v42
	v_mul_f32_e32 v43, v94, v43
	v_mul_f32_e32 v44, v94, v44
	v_mul_f32_e32 v45, v94, v45
	v_mul_f32_e32 v46, v94, v46
	v_mul_f32_e32 v47, v94, v47
	v_mul_f32_e32 v48, v94, v48
	v_mul_f32_e32 v49, v94, v49
	v_mul_f32_e32 v50, v94, v50
	v_mul_f32_e32 v51, v94, v51
	v_mul_f32_e32 v52, v94, v52
	v_mul_f32_e32 v53, v94, v53
	v_mul_f32_e32 v54, v94, v54
	v_mul_f32_e32 v55, v94, v55
	v_mul_f32_e32 v56, v94, v56
	v_mul_f32_e32 v57, v94, v57
	v_fma_f32 v42, v42, v10, v26
	v_fma_f32 v43, v43, v11, v27
	v_fma_f32 v44, v44, v12, v28
	v_fma_f32 v45, v45, v13, v29
	v_fma_f32 v46, v46, v14, v30
	v_fma_f32 v47, v47, v15, v31
	v_fma_f32 v48, v48, v16, v32
	v_fma_f32 v49, v49, v17, v33
	v_fma_f32 v50, v50, v18, v34
	v_fma_f32 v51, v51, v19, v35
	v_fma_f32 v52, v52, v20, v36
	v_fma_f32 v53, v53, v21, v37
	v_fma_f32 v54, v54, v22, v38
	v_fma_f32 v55, v55, v23, v39
	v_fma_f32 v56, v56, v24, v40
	v_fma_f32 v57, v57, v25, v41
	v_add_f32_e32 v9, v42, v43
	v_add_f32_e32 v91, v44, v45
	v_mul_f32_e32 v90, v42, v42
	v_mul_f32_e32 v92, v43, v43
	v_add_f32_e32 v9, v9, v46
	v_add_f32_e32 v91, v91, v47
	v_add_f32_e32 v9, v9, v48
	v_add_f32_e32 v91, v91, v49
	v_add_f32_e32 v9, v9, v50
	v_add_f32_e32 v91, v91, v51
	v_add_f32_e32 v9, v9, v52
	v_add_f32_e32 v91, v91, v53
	v_add_f32_e32 v9, v9, v54
	v_add_f32_e32 v91, v91, v55
	v_add_f32_e32 v9, v9, v56
	v_add_f32_e32 v91, v91, v57
	v_fmac_f32_e32 v90, v44, v44
	v_fmac_f32_e32 v92, v45, v45
	v_fmac_f32_e32 v90, v46, v46
	v_fmac_f32_e32 v92, v47, v47
	v_fmac_f32_e32 v90, v48, v48
	v_fmac_f32_e32 v92, v49, v49
	v_fmac_f32_e32 v90, v50, v50
	v_fmac_f32_e32 v92, v51, v51
	v_fmac_f32_e32 v90, v52, v52
	v_fmac_f32_e32 v92, v53, v53
	v_fmac_f32_e32 v90, v54, v54
	v_fmac_f32_e32 v92, v55, v55
	v_fmac_f32_e32 v90, v56, v56
	v_fmac_f32_e32 v92, v57, v57
	v_add_f32_e32 v9, v9, v91
	v_add_f32_e32 v90, v90, v92
	s_nop 1
	v_add_f32_dpp v9, v9, v9 quad_perm:[1,0,3,2] row_mask:0xf bank_mask:0xf
	v_add_f32_dpp v90, v90, v90 quad_perm:[1,0,3,2] row_mask:0xf bank_mask:0xf
	s_nop 0
	v_add_f32_dpp v9, v9, v9 quad_perm:[2,3,0,1] row_mask:0xf bank_mask:0xf
	v_add_f32_dpp v90, v90, v90 quad_perm:[2,3,0,1] row_mask:0xf bank_mask:0xf
	s_nop 0
	v_add_f32_dpp v9, v9, v9 row_half_mirror row_mask:0xf bank_mask:0xf
	v_add_f32_dpp v90, v90, v90 row_half_mirror row_mask:0xf bank_mask:0xf
	s_nop 0
	v_add_f32_dpp v9, v9, v9 row_mirror row_mask:0xf bank_mask:0xf
	v_add_f32_dpp v90, v90, v90 row_mirror row_mask:0xf bank_mask:0xf
	s_nop 0
	v_add_f32_dpp v9, v9, v9 row_bcast:15 row_mask:0xa bank_mask:0xf
	v_add_f32_dpp v90, v90, v90 row_bcast:15 row_mask:0xa bank_mask:0xf
	s_nop 0
	v_add_f32_dpp v9, v9, v9 row_bcast:31 row_mask:0xc bank_mask:0xf
	v_add_f32_dpp v90, v90, v90 row_bcast:31 row_mask:0xc bank_mask:0xf
; DI unsigned pk2(float lo, float hi) { f32x2 v = {lo, hi}; bf16x2_t b = __builtin_convertvector(v, bf16x2_t); return __builtin_bit_cast(unsigned, b); }
; DI void ln_row_v(const Frame& F, f32x4 (&v)[4], float* xout, const float* g, const float* b, const float* sh, const float* sc, bf16_t* hout, const float* slab, const float* gres, float* stat = nullptr) {
;     ...
;         const float mean = s * (1.f / D); const float rstd = 1.f / sqrtf(fmaxf(s2 * (1.f / D) - mean * mean, 0.f) + EPS);
; #pragma unroll
;         for (int j = 0; j < 4; ++j) { const f32x4 hh = ((const f32x4*)sh)[F.lane + 64 * j], cc = ((const f32x4*)sc)[F.lane + 64 * j];
;             const f32x4 o = (v[j] - mean) * rstd * (cc + 1.f) + hh; u32x2 wv; wv.x = pk2(o[0], o[1]); wv.y = pk2(o[2], o[3]);
;             ((u32x2*)hout)[F.lane + 64 * j] = wv; }
;     }
; DI void ln_phase(const Frame& F, int which) {
;     ...
;     if (gw < nrows) ln_load(F, xrow_ptr(F, gw), vc);
;     for (int row = gw; row < nrows; row += NGW) {
;         if (row + NGW < nrows) ln_load(F, xrow_ptr(F, row + NGW), vn);
	s_nop 0
	v_readlane_b32 s2, v9, 63
	v_readlane_b32 s3, v90, 63
	s_nop 1
	v_mov_b32_e32 v9, s2
	v_mov_b32_e32 v90, s3
	v_mul_f32_e32 v93, 0x3a800000, v9
	v_mul_f32_e32 v91, 0x3a800000, v90
	v_fma_f32 v91, -v93, v93, v91
	v_max_f32_e32 v91, 0, v91
	v_add_f32_e32 v91, 0x358637bd, v91
	v_rsq_f32_e32 v94, v91
	v_mul_f32_e32 v91, 0.5, v91
	v_mul_f32_e32 v92, v94, v94
	v_fma_f32 v92, -v91, v92, 0.5
	v_fma_f32 v94, v94, v92, v94
	v_sub_f32_e32 v42, v42, v93
	v_sub_f32_e32 v43, v43, v93
	v_sub_f32_e32 v44, v44, v93
	v_sub_f32_e32 v45, v45, v93
	v_sub_f32_e32 v46, v46, v93
	v_sub_f32_e32 v47, v47, v93
	v_sub_f32_e32 v48, v48, v93
	v_sub_f32_e32 v49, v49, v93
	v_sub_f32_e32 v50, v50, v93
	v_sub_f32_e32 v51, v51, v93
	v_sub_f32_e32 v52, v52, v93
	v_sub_f32_e32 v53, v53, v93
	v_sub_f32_e32 v54, v54, v93
	v_sub_f32_e32 v55, v55, v93
	v_sub_f32_e32 v56, v56, v93
	v_sub_f32_e32 v57, v57, v93
	v_mul_f32_e32 v42, v94, v42
	v_mul_f32_e32 v43, v94, v43
	v_mul_f32_e32 v44, v94, v44
	v_mul_f32_e32 v45, v94, v45
	v_mul_f32_e32 v46, v94, v46
	v_mul_f32_e32 v47, v94, v47
	v_mul_f32_e32 v48, v94, v48
	v_mul_f32_e32 v49, v94, v49
	v_mul_f32_e32 v50, v94, v50
	v_mul_f32_e32 v51, v94, v51
	v_mul_f32_e32 v52, v94, v52
	v_mul_f32_e32 v53, v94, v53
	v_mul_f32_e32 v54, v94, v54
	v_mul_f32_e32 v55, v94, v55
	v_mul_f32_e32 v56, v94, v56
	v_mul_f32_e32 v57, v94, v57
	v_fma_f32 v42, v42, v130, v114
	v_fma_f32 v43, v43, v131, v115
	v_fma_f32 v44, v44, v132, v116
	v_fma_f32 v45, v45, v133, v117
	v_fma_f32 v46, v46, v134, v118
	v_fma_f32 v47, v47, v135, v119
	v_fma_f32 v48, v48, v136, v120
	v_fma_f32 v49, v49, v137, v121
	v_fma_f32 v50, v50, v138, v122
	v_fma_f32 v51, v51, v139, v123
	v_fma_f32 v52, v52, v140, v124
	v_fma_f32 v53, v53, v141, v125
	v_fma_f32 v54, v54, v142, v126
	v_fma_f32 v55, v55, v143, v127
	v_fma_f32 v56, v56, v144, v128
	v_fma_f32 v57, v57, v145, v129
	v_cvt_pk_bf16_f32 v190, v42, v43
	v_cvt_pk_bf16_f32 v191, v44, v45
	v_cvt_pk_bf16_f32 v192, v46, v47
	v_cvt_pk_bf16_f32 v193, v48, v49
	v_cvt_pk_bf16_f32 v194, v50, v51
	v_cvt_pk_bf16_f32 v195, v52, v53
	v_cvt_pk_bf16_f32 v196, v54, v55
	v_cvt_pk_bf16_f32 v197, v56, v57
	s_add_u32 s2, s10, 0x2000
	s_addc_u32 s3, s11, 0
	global_store_dwordx4 v1, v[190:193], s[2:3]
	global_store_dwordx4 v1, v[194:197], s[2:3] offset:1024
	s_mov_b64 s[2:3], s[20:21]
	global_load_dwordx4 v[42:45], v0, s[2:3]
	global_load_dwordx4 v[46:49], v0, s[2:3] offset:16
	global_load_dwordx4 v[50:53], v0, s[2:3] offset:2048
	global_load_dwordx4 v[54:57], v0, s[2:3] offset:2064
	s_waitcnt vmcnt(21)
	v_add_f32_e32 v9, v58, v59
	v_add_f32_e32 v91, v60, v61
	v_mul_f32_e32 v90, v58, v58
	v_mul_f32_e32 v92, v59, v59
	v_add_f32_e32 v9, v9, v62
	v_add_f32_e32 v91, v91, v63
	v_add_f32_e32 v9, v9, v64
	v_add_f32_e32 v91, v91, v65
	v_add_f32_e32 v9, v9, v66
	v_add_f32_e32 v91, v91, v67
	v_add_f32_e32 v9, v9, v68
	v_add_f32_e32 v91, v91, v69
	v_add_f32_e32 v9, v9, v70
	v_add_f32_e32 v91, v91, v71
	v_add_f32_e32 v9, v9, v72
	v_add_f32_e32 v91, v91, v73
	v_fmac_f32_e32 v90, v60, v60
	v_fmac_f32_e32 v92, v61, v61
	v_fmac_f32_e32 v90, v62, v62
	v_fmac_f32_e32 v92, v63, v63
	v_fmac_f32_e32 v90, v64, v64
	v_fmac_f32_e32 v92, v65, v65
	v_fmac_f32_e32 v90, v66, v66
	v_fmac_f32_e32 v92, v67, v67
	v_fmac_f32_e32 v90, v68, v68
	v_fmac_f32_e32 v92, v69, v69
	v_fmac_f32_e32 v90, v70, v70
	v_fmac_f32_e32 v92, v71, v71
	v_fmac_f32_e32 v90, v72, v72
	v_fmac_f32_e32 v92, v73, v73
	v_add_f32_e32 v9, v9, v91
	v_add_f32_e32 v90, v90, v92
	s_nop 1
	v_add_f32_dpp v9, v9, v9 quad_perm:[1,0,3,2] row_mask:0xf bank_mask:0xf
	v_add_f32_dpp v90, v90, v90 quad_perm:[1,0,3,2] row_mask:0xf bank_mask:0xf
	s_nop 0
	v_add_f32_dpp v9, v9, v9 quad_perm:[2,3,0,1] row_mask:0xf bank_mask:0xf
	v_add_f32_dpp v90, v90, v90 quad_perm:[2,3,0,1] row_mask:0xf bank_mask:0xf
	s_nop 0
	v_add_f32_dpp v9, v9, v9 row_half_mirror row_mask:0xf bank_mask:0xf
	v_add_f32_dpp v90, v90, v90 row_half_mirror row_mask:0xf bank_mask:0xf
	s_nop 0
	v_add_f32_dpp v9, v9, v9 row_mirror row_mask:0xf bank_mask:0xf
	v_add_f32_dpp v90, v90, v90 row_mirror row_mask:0xf bank_mask:0xf
	s_nop 0
	v_add_f32_dpp v9, v9, v9 row_bcast:15 row_mask:0xa bank_mask:0xf
	v_add_f32_dpp v90, v90, v90 row_bcast:15 row_mask:0xa bank_mask:0xf
	s_nop 0
	v_add_f32_dpp v9, v9, v9 row_bcast:31 row_mask:0xc bank_mask:0xf
	v_add_f32_dpp v90, v90, v90 row_bcast:31 row_mask:0xc bank_mask:0xf
	s_nop 0
	v_readlane_b32 s2, v9, 63
	v_readlane_b32 s3, v90, 63
	s_nop 1
	v_mov_b32_e32 v9, s2
	v_mov_b32_e32 v90, s3
	v_mul_f32_e32 v93, 0x3a800000, v9
	v_mul_f32_e32 v91, 0x3a800000, v90
	v_fma_f32 v91, -v93, v93, v91
	v_max_f32_e32 v91, 0, v91
	v_add_f32_e32 v91, 0x358637bd, v91
	v_rsq_f32_e32 v94, v91
	v_mul_f32_e32 v91, 0.5, v91
	v_mul_f32_e32 v92, v94, v94
	v_fma_f32 v92, -v91, v92, 0.5
	v_fma_f32 v94, v94, v92, v94
	s_add_u32 s2, s12, 0x28
	s_addc_u32 s3, s13, 0
	v_mov_b32_e32 v188, v93
	v_mov_b32_e32 v189, v94
	s_mov_b64 exec, 1
	global_store_dwordx2 v97, v[188:189], s[2:3]
	s_mov_b64 exec, -1
	v_sub_f32_e32 v58, v58, v93
	v_sub_f32_e32 v59, v59, v93
	v_sub_f32_e32 v60, v60, v93
	v_sub_f32_e32 v61, v61, v93
	v_sub_f32_e32 v62, v62, v93
	v_sub_f32_e32 v63, v63, v93
	v_sub_f32_e32 v64, v64, v93
	v_sub_f32_e32 v65, v65, v93
	v_sub_f32_e32 v66, v66, v93
	v_sub_f32_e32 v67, v67, v93
	v_sub_f32_e32 v68, v68, v93
	v_sub_f32_e32 v69, v69, v93
	v_sub_f32_e32 v70, v70, v93
	v_sub_f32_e32 v71, v71, v93
	v_sub_f32_e32 v72, v72, v93
	v_sub_f32_e32 v73, v73, v93
	v_mul_f32_e32 v58, v94, v58
	v_mul_f32_e32 v59, v94, v59
	v_mul_f32_e32 v60, v94, v60
	v_mul_f32_e32 v61, v94, v61
	v_mul_f32_e32 v62, v94, v62
	v_mul_f32_e32 v63, v94, v63
	v_mul_f32_e32 v64, v94, v64
; DI unsigned pk2(float lo, float hi) { f32x2 v = {lo, hi}; bf16x2_t b = __builtin_convertvector(v, bf16x2_t); return __builtin_bit_cast(unsigned, b); }
; DI void ln_row_v(const Frame& F, f32x4 (&v)[4], float* xout, const float* g, const float* b, const float* sh, const float* sc, bf16_t* hout, const float* slab, const float* gres, float* stat = nullptr) {
;     ...
;         for (int j = 0; j < 4; ++j) { const f32x4 gg = ((const f32x4*)g)[F.lane + 64 * j], bb = ((const f32x4*)b)[F.lane + 64 * j];
;             v[j] = (v[j] - mean) * rstd * gg + bb; if (xout) ((f32x4*)xout)[F.lane + 64 * j] = v[j]; }
;     }
;     if (hout) {
;         float s = 0.f, s2 = 0.f;
; #pragma unroll
;         for (int j = 0; j < 4; ++j) { s += (v[j][0] + v[j][1]) + (v[j][2] + v[j][3]); s2 += (v[j][0] * v[j][0] + v[j][1] * v[j][1]) + (v[j][2] * v[j][2] + v[j][3] * v[j][3]); }
;         wave_sum2(s, s2, F.lane);
;         const float mean = s * (1.f / D); const float rstd = 1.f / sqrtf(fmaxf(s2 * (1.f / D) - mean * mean, 0.f) + EPS);
; #pragma unroll
;         for (int j = 0; j < 4; ++j) { const f32x4 hh = ((const f32x4*)sh)[F.lane + 64 * j], cc = ((const f32x4*)sc)[F.lane + 64 * j];
;             const f32x4 o = (v[j] - mean) * rstd * (cc + 1.f) + hh; u32x2 wv; wv.x = pk2(o[0], o[1]); wv.y = pk2(o[2], o[3]);
;             ((u32x2*)hout)[F.lane + 64 * j] = wv; }
;     }
	v_mul_f32_e32 v65, v94, v65
	v_mul_f32_e32 v66, v94, v66
	v_mul_f32_e32 v67, v94, v67
	v_mul_f32_e32 v68, v94, v68
	v_mul_f32_e32 v69, v94, v69
	v_mul_f32_e32 v70, v94, v70
	v_mul_f32_e32 v71, v94, v71
	v_mul_f32_e32 v72, v94, v72
	v_mul_f32_e32 v73, v94, v73
	v_fma_f32 v58, v58, v10, v26
	v_fma_f32 v59, v59, v11, v27
	v_fma_f32 v60, v60, v12, v28
	v_fma_f32 v61, v61, v13, v29
	v_fma_f32 v62, v62, v14, v30
	v_fma_f32 v63, v63, v15, v31
	v_fma_f32 v64, v64, v16, v32
	v_fma_f32 v65, v65, v17, v33
	v_fma_f32 v66, v66, v18, v34
	v_fma_f32 v67, v67, v19, v35
	v_fma_f32 v68, v68, v20, v36
	v_fma_f32 v69, v69, v21, v37
	v_fma_f32 v70, v70, v22, v38
	v_fma_f32 v71, v71, v23, v39
	v_fma_f32 v72, v72, v24, v40
	v_fma_f32 v73, v73, v25, v41
	v_add_f32_e32 v9, v58, v59
	v_add_f32_e32 v91, v60, v61
	v_mul_f32_e32 v90, v58, v58
	v_mul_f32_e32 v92, v59, v59
	v_add_f32_e32 v9, v9, v62
	v_add_f32_e32 v91, v91, v63
	v_add_f32_e32 v9, v9, v64
	v_add_f32_e32 v91, v91, v65
	v_add_f32_e32 v9, v9, v66
	v_add_f32_e32 v91, v91, v67
	v_add_f32_e32 v9, v9, v68
	v_add_f32_e32 v91, v91, v69
	v_add_f32_e32 v9, v9, v70
	v_add_f32_e32 v91, v91, v71
	v_add_f32_e32 v9, v9, v72
	v_add_f32_e32 v91, v91, v73
	v_fmac_f32_e32 v90, v60, v60
	v_fmac_f32_e32 v92, v61, v61
	v_fmac_f32_e32 v90, v62, v62
	v_fmac_f32_e32 v92, v63, v63
	v_fmac_f32_e32 v90, v64, v64
	v_fmac_f32_e32 v92, v65, v65
	v_fmac_f32_e32 v90, v66, v66
	v_fmac_f32_e32 v92, v67, v67
	v_fmac_f32_e32 v90, v68, v68
	v_fmac_f32_e32 v92, v69, v69
	v_fmac_f32_e32 v90, v70, v70
	v_fmac_f32_e32 v92, v71, v71
	v_fmac_f32_e32 v90, v72, v72
	v_fmac_f32_e32 v92, v73, v73
	v_add_f32_e32 v9, v9, v91
	v_add_f32_e32 v90, v90, v92
	s_nop 1
	v_add_f32_dpp v9, v9, v9 quad_perm:[1,0,3,2] row_mask:0xf bank_mask:0xf
	v_add_f32_dpp v90, v90, v90 quad_perm:[1,0,3,2] row_mask:0xf bank_mask:0xf
	s_nop 0
	v_add_f32_dpp v9, v9, v9 quad_perm:[2,3,0,1] row_mask:0xf bank_mask:0xf
	v_add_f32_dpp v90, v90, v90 quad_perm:[2,3,0,1] row_mask:0xf bank_mask:0xf
	s_nop 0
	v_add_f32_dpp v9, v9, v9 row_half_mirror row_mask:0xf bank_mask:0xf
	v_add_f32_dpp v90, v90, v90 row_half_mirror row_mask:0xf bank_mask:0xf
	s_nop 0
	v_add_f32_dpp v9, v9, v9 row_mirror row_mask:0xf bank_mask:0xf
	v_add_f32_dpp v90, v90, v90 row_mirror row_mask:0xf bank_mask:0xf
	s_nop 0
	v_add_f32_dpp v9, v9, v9 row_bcast:15 row_mask:0xa bank_mask:0xf
	v_add_f32_dpp v90, v90, v90 row_bcast:15 row_mask:0xa bank_mask:0xf
	s_nop 0
	v_add_f32_dpp v9, v9, v9 row_bcast:31 row_mask:0xc bank_mask:0xf
	v_add_f32_dpp v90, v90, v90 row_bcast:31 row_mask:0xc bank_mask:0xf
	s_nop 0
	v_readlane_b32 s2, v9, 63
	v_readlane_b32 s3, v90, 63
	s_nop 1
	v_mov_b32_e32 v9, s2
	v_mov_b32_e32 v90, s3
	v_mul_f32_e32 v93, 0x3a800000, v9
	v_mul_f32_e32 v91, 0x3a800000, v90
	v_fma_f32 v91, -v93, v93, v91
	v_max_f32_e32 v91, 0, v91
	v_add_f32_e32 v91, 0x358637bd, v91
	v_rsq_f32_e32 v94, v91
	v_mul_f32_e32 v91, 0.5, v91
	v_mul_f32_e32 v92, v94, v94
	v_fma_f32 v92, -v91, v92, 0.5
	v_fma_f32 v94, v94, v92, v94
	v_sub_f32_e32 v58, v58, v93
	v_sub_f32_e32 v59, v59, v93
	v_sub_f32_e32 v60, v60, v93
	v_sub_f32_e32 v61, v61, v93
	v_sub_f32_e32 v62, v62, v93
	v_sub_f32_e32 v63, v63, v93
	v_sub_f32_e32 v64, v64, v93
	v_sub_f32_e32 v65, v65, v93
	v_sub_f32_e32 v66, v66, v93
	v_sub_f32_e32 v67, v67, v93
	v_sub_f32_e32 v68, v68, v93
	v_sub_f32_e32 v69, v69, v93
	v_sub_f32_e32 v70, v70, v93
	v_sub_f32_e32 v71, v71, v93
	v_sub_f32_e32 v72, v72, v93
	v_sub_f32_e32 v73, v73, v93
	v_mul_f32_e32 v58, v94, v58
	v_mul_f32_e32 v59, v94, v59
	v_mul_f32_e32 v60, v94, v60
	v_mul_f32_e32 v61, v94, v61
	v_mul_f32_e32 v62, v94, v62
	v_mul_f32_e32 v63, v94, v63
	v_mul_f32_e32 v64, v94, v64
	v_mul_f32_e32 v65, v94, v65
	v_mul_f32_e32 v66, v94, v66
	v_mul_f32_e32 v67, v94, v67
	v_mul_f32_e32 v68, v94, v68
	v_mul_f32_e32 v69, v94, v69
	v_mul_f32_e32 v70, v94, v70
	v_mul_f32_e32 v71, v94, v71
	v_mul_f32_e32 v72, v94, v72
	v_mul_f32_e32 v73, v94, v73
	v_fma_f32 v58, v58, v130, v114
	v_fma_f32 v59, v59, v131, v115
	v_fma_f32 v60, v60, v132, v116
	v_fma_f32 v61, v61, v133, v117
	v_fma_f32 v62, v62, v134, v118
	v_fma_f32 v63, v63, v135, v119
	v_fma_f32 v64, v64, v136, v120
	v_fma_f32 v65, v65, v137, v121
	v_fma_f32 v66, v66, v138, v122
	v_fma_f32 v67, v67, v139, v123
	v_fma_f32 v68, v68, v140, v124
	v_fma_f32 v69, v69, v141, v125
	v_fma_f32 v70, v70, v142, v126
	v_fma_f32 v71, v71, v143, v127
	v_fma_f32 v72, v72, v144, v128
	v_fma_f32 v73, v73, v145, v129
	v_cvt_pk_bf16_f32 v190, v58, v59
	v_cvt_pk_bf16_f32 v191, v60, v61
	v_cvt_pk_bf16_f32 v192, v62, v63
	v_cvt_pk_bf16_f32 v193, v64, v65
	v_cvt_pk_bf16_f32 v194, v66, v67
	v_cvt_pk_bf16_f32 v195, v68, v69
	v_cvt_pk_bf16_f32 v196, v70, v71
	v_cvt_pk_bf16_f32 v197, v72, v73
	s_add_u32 s2, s10, 0x2800
	s_addc_u32 s3, s11, 0
	global_store_dwordx4 v1, v[190:193], s[2:3]
	global_store_dwordx4 v1, v[194:197], s[2:3] offset:1024
	s_waitcnt vmcnt(17)
; DI void ln_row_v(const Frame& F, f32x4 (&v)[4], float* xout, const float* g, const float* b, const float* sh, const float* sc, bf16_t* hout, const float* slab, const float* gres, float* stat = nullptr) {
;     ...
;         float s = 0.f, s2 = 0.f;
; #pragma unroll
;         for (int j = 0; j < 4; ++j) { s += (v[j][0] + v[j][1]) + (v[j][2] + v[j][3]); s2 += (v[j][0] * v[j][0] + v[j][1] * v[j][1]) + (v[j][2] * v[j][2] + v[j][3] * v[j][3]); }
;         wave_sum2(s, s2, F.lane);
;         const float mean = s * (1.f / D); const float rstd = 1.f / sqrtf(fmaxf(s2 * (1.f / D) - mean * mean, 0.f) + EPS);
;         if (stat && F.lane == 0) { f32x2 sv = {mean, rstd}; *(f32x2*)stat = sv; }
; #pragma unroll
;         for (int j = 0; j < 4; ++j) { const f32x4 gg = ((const f32x4*)g)[F.lane + 64 * j], bb = ((const f32x4*)b)[F.lane + 64 * j];
;             v[j] = (v[j] - mean) * rstd * gg + bb; if (xout) ((f32x4*)xout)[F.lane + 64 * j] = v[j]; }
;     }
;     if (hout) {
;         float s = 0.f, s2 = 0.f;
; #pragma unroll
;         for (int j = 0; j < 4; ++j) { s += (v[j][0] + v[j][1]) + (v[j][2] + v[j][3]); s2 += (v[j][0] * v[j][0] + v[j][1] * v[j][1]) + (v[j][2] * v[j][2] + v[j][3] * v[j][3]); }
;         wave_sum2(s, s2, F.lane);
;         const float mean = s * (1.f / D); const float rstd = 1.f / sqrtf(fmaxf(s2 * (1.f / D) - mean * mean, 0.f) + EPS);
	v_add_f32_e32 v9, v74, v75
	v_add_f32_e32 v91, v76, v77
	v_mul_f32_e32 v90, v74, v74
	v_mul_f32_e32 v92, v75, v75
	v_add_f32_e32 v9, v9, v78
	v_add_f32_e32 v91, v91, v79
	v_add_f32_e32 v9, v9, v80
	v_add_f32_e32 v91, v91, v81
	v_add_f32_e32 v9, v9, v82
	v_add_f32_e32 v91, v91, v83
	v_add_f32_e32 v9, v9, v84
	v_add_f32_e32 v91, v91, v85
	v_add_f32_e32 v9, v9, v86
	v_add_f32_e32 v91, v91, v87
	v_add_f32_e32 v9, v9, v88
	v_add_f32_e32 v91, v91, v89
	v_fmac_f32_e32 v90, v76, v76
	v_fmac_f32_e32 v92, v77, v77
	v_fmac_f32_e32 v90, v78, v78
	v_fmac_f32_e32 v92, v79, v79
	v_fmac_f32_e32 v90, v80, v80
	v_fmac_f32_e32 v92, v81, v81
	v_fmac_f32_e32 v90, v82, v82
	v_fmac_f32_e32 v92, v83, v83
	v_fmac_f32_e32 v90, v84, v84
	v_fmac_f32_e32 v92, v85, v85
	v_fmac_f32_e32 v90, v86, v86
	v_fmac_f32_e32 v92, v87, v87
	v_fmac_f32_e32 v90, v88, v88
	v_fmac_f32_e32 v92, v89, v89
	v_add_f32_e32 v9, v9, v91
	v_add_f32_e32 v90, v90, v92
	s_nop 1
	v_add_f32_dpp v9, v9, v9 quad_perm:[1,0,3,2] row_mask:0xf bank_mask:0xf
	v_add_f32_dpp v90, v90, v90 quad_perm:[1,0,3,2] row_mask:0xf bank_mask:0xf
	s_nop 0
	v_add_f32_dpp v9, v9, v9 quad_perm:[2,3,0,1] row_mask:0xf bank_mask:0xf
	v_add_f32_dpp v90, v90, v90 quad_perm:[2,3,0,1] row_mask:0xf bank_mask:0xf
	s_nop 0
	v_add_f32_dpp v9, v9, v9 row_half_mirror row_mask:0xf bank_mask:0xf
	v_add_f32_dpp v90, v90, v90 row_half_mirror row_mask:0xf bank_mask:0xf
	s_nop 0
	v_add_f32_dpp v9, v9, v9 row_mirror row_mask:0xf bank_mask:0xf
	v_add_f32_dpp v90, v90, v90 row_mirror row_mask:0xf bank_mask:0xf
	s_nop 0
	v_add_f32_dpp v9, v9, v9 row_bcast:15 row_mask:0xa bank_mask:0xf
	v_add_f32_dpp v90, v90, v90 row_bcast:15 row_mask:0xa bank_mask:0xf
	s_nop 0
	v_add_f32_dpp v9, v9, v9 row_bcast:31 row_mask:0xc bank_mask:0xf
	v_add_f32_dpp v90, v90, v90 row_bcast:31 row_mask:0xc bank_mask:0xf
	s_nop 0
	v_readlane_b32 s2, v9, 63
	v_readlane_b32 s3, v90, 63
	s_nop 1
	v_mov_b32_e32 v9, s2
	v_mov_b32_e32 v90, s3
	v_mul_f32_e32 v93, 0x3a800000, v9
	v_mul_f32_e32 v91, 0x3a800000, v90
	v_fma_f32 v91, -v93, v93, v91
	v_max_f32_e32 v91, 0, v91
	v_add_f32_e32 v91, 0x358637bd, v91
	v_rsq_f32_e32 v94, v91
	v_mul_f32_e32 v91, 0.5, v91
	v_mul_f32_e32 v92, v94, v94
	v_fma_f32 v92, -v91, v92, 0.5
	v_fma_f32 v94, v94, v92, v94
	s_add_u32 s2, s12, 0x30
	s_addc_u32 s3, s13, 0
	v_mov_b32_e32 v188, v93
	v_mov_b32_e32 v189, v94
	s_mov_b64 exec, 1
	global_store_dwordx2 v97, v[188:189], s[2:3]
	s_mov_b64 exec, -1
	v_sub_f32_e32 v74, v74, v93
	v_sub_f32_e32 v75, v75, v93
	v_sub_f32_e32 v76, v76, v93
	v_sub_f32_e32 v77, v77, v93
	v_sub_f32_e32 v78, v78, v93
	v_sub_f32_e32 v79, v79, v93
	v_sub_f32_e32 v80, v80, v93
	v_sub_f32_e32 v81, v81, v93
	v_sub_f32_e32 v82, v82, v93
	v_sub_f32_e32 v83, v83, v93
	v_sub_f32_e32 v84, v84, v93
	v_sub_f32_e32 v85, v85, v93
	v_sub_f32_e32 v86, v86, v93
	v_sub_f32_e32 v87, v87, v93
	v_sub_f32_e32 v88, v88, v93
	v_sub_f32_e32 v89, v89, v93
	v_mul_f32_e32 v74, v94, v74
	v_mul_f32_e32 v75, v94, v75
	v_mul_f32_e32 v76, v94, v76
	v_mul_f32_e32 v77, v94, v77
	v_mul_f32_e32 v78, v94, v78
	v_mul_f32_e32 v79, v94, v79
	v_mul_f32_e32 v80, v94, v80
	v_mul_f32_e32 v81, v94, v81
	v_mul_f32_e32 v82, v94, v82
	v_mul_f32_e32 v83, v94, v83
	v_mul_f32_e32 v84, v94, v84
	v_mul_f32_e32 v85, v94, v85
	v_mul_f32_e32 v86, v94, v86
	v_mul_f32_e32 v87, v94, v87
	v_mul_f32_e32 v88, v94, v88
	v_mul_f32_e32 v89, v94, v89
	v_fma_f32 v74, v74, v10, v26
	v_fma_f32 v75, v75, v11, v27
	v_fma_f32 v76, v76, v12, v28
	v_fma_f32 v77, v77, v13, v29
	v_fma_f32 v78, v78, v14, v30
	v_fma_f32 v79, v79, v15, v31
	v_fma_f32 v80, v80, v16, v32
	v_fma_f32 v81, v81, v17, v33
	v_fma_f32 v82, v82, v18, v34
	v_fma_f32 v83, v83, v19, v35
	v_fma_f32 v84, v84, v20, v36
	v_fma_f32 v85, v85, v21, v37
	v_fma_f32 v86, v86, v22, v38
	v_fma_f32 v87, v87, v23, v39
	v_fma_f32 v88, v88, v24, v40
	v_fma_f32 v89, v89, v25, v41
	v_add_f32_e32 v9, v74, v75
	v_add_f32_e32 v91, v76, v77
	v_mul_f32_e32 v90, v74, v74
	v_mul_f32_e32 v92, v75, v75
	v_add_f32_e32 v9, v9, v78
	v_add_f32_e32 v91, v91, v79
	v_add_f32_e32 v9, v9, v80
	v_add_f32_e32 v91, v91, v81
	v_add_f32_e32 v9, v9, v82
	v_add_f32_e32 v91, v91, v83
	v_add_f32_e32 v9, v9, v84
	v_add_f32_e32 v91, v91, v85
	v_add_f32_e32 v9, v9, v86
	v_add_f32_e32 v91, v91, v87
	v_add_f32_e32 v9, v9, v88
	v_add_f32_e32 v91, v91, v89
	v_fmac_f32_e32 v90, v76, v76
	v_fmac_f32_e32 v92, v77, v77
	v_fmac_f32_e32 v90, v78, v78
	v_fmac_f32_e32 v92, v79, v79
	v_fmac_f32_e32 v90, v80, v80
	v_fmac_f32_e32 v92, v81, v81
	v_fmac_f32_e32 v90, v82, v82
	v_fmac_f32_e32 v92, v83, v83
	v_fmac_f32_e32 v90, v84, v84
	v_fmac_f32_e32 v92, v85, v85
	v_fmac_f32_e32 v90, v86, v86
	v_fmac_f32_e32 v92, v87, v87
	v_fmac_f32_e32 v90, v88, v88
	v_fmac_f32_e32 v92, v89, v89
	v_add_f32_e32 v9, v9, v91
	v_add_f32_e32 v90, v90, v92
	s_nop 1
	v_add_f32_dpp v9, v9, v9 quad_perm:[1,0,3,2] row_mask:0xf bank_mask:0xf
	v_add_f32_dpp v90, v90, v90 quad_perm:[1,0,3,2] row_mask:0xf bank_mask:0xf
	s_nop 0
	v_add_f32_dpp v9, v9, v9 quad_perm:[2,3,0,1] row_mask:0xf bank_mask:0xf
	v_add_f32_dpp v90, v90, v90 quad_perm:[2,3,0,1] row_mask:0xf bank_mask:0xf
	s_nop 0
	v_add_f32_dpp v9, v9, v9 row_half_mirror row_mask:0xf bank_mask:0xf
	v_add_f32_dpp v90, v90, v90 row_half_mirror row_mask:0xf bank_mask:0xf
	s_nop 0
	v_add_f32_dpp v9, v9, v9 row_mirror row_mask:0xf bank_mask:0xf
	v_add_f32_dpp v90, v90, v90 row_mirror row_mask:0xf bank_mask:0xf
	s_nop 0
	v_add_f32_dpp v9, v9, v9 row_bcast:15 row_mask:0xa bank_mask:0xf
	v_add_f32_dpp v90, v90, v90 row_bcast:15 row_mask:0xa bank_mask:0xf
	s_nop 0
	v_add_f32_dpp v9, v9, v9 row_bcast:31 row_mask:0xc bank_mask:0xf
	v_add_f32_dpp v90, v90, v90 row_bcast:31 row_mask:0xc bank_mask:0xf
; DI unsigned pk2(float lo, float hi) { f32x2 v = {lo, hi}; bf16x2_t b = __builtin_convertvector(v, bf16x2_t); return __builtin_bit_cast(unsigned, b); }
; DI void ln_row_v(const Frame& F, f32x4 (&v)[4], float* xout, const float* g, const float* b, const float* sh, const float* sc, bf16_t* hout, const float* slab, const float* gres, float* stat = nullptr) {
;     ...
;         float s = 0.f, s2 = 0.f;
; #pragma unroll
;         for (int j = 0; j < 4; ++j) { s += (v[j][0] + v[j][1]) + (v[j][2] + v[j][3]); s2 += (v[j][0] * v[j][0] + v[j][1] * v[j][1]) + (v[j][2] * v[j][2] + v[j][3] * v[j][3]); }
;         wave_sum2(s, s2, F.lane);
;         const float mean = s * (1.f / D); const float rstd = 1.f / sqrtf(fmaxf(s2 * (1.f / D) - mean * mean, 0.f) + EPS);
;         if (stat && F.lane == 0) { f32x2 sv = {mean, rstd}; *(f32x2*)stat = sv; }
;     ...
;         const float mean = s * (1.f / D); const float rstd = 1.f / sqrtf(fmaxf(s2 * (1.f / D) - mean * mean, 0.f) + EPS);
; #pragma unroll
;         for (int j = 0; j < 4; ++j) { const f32x4 hh = ((const f32x4*)sh)[F.lane + 64 * j], cc = ((const f32x4*)sc)[F.lane + 64 * j];
;             const f32x4 o = (v[j] - mean) * rstd * (cc + 1.f) + hh; u32x2 wv; wv.x = pk2(o[0], o[1]); wv.y = pk2(o[2], o[3]);
;             ((u32x2*)hout)[F.lane + 64 * j] = wv; }
;     }
	s_nop 0
	v_readlane_b32 s2, v9, 63
	v_readlane_b32 s3, v90, 63
	s_nop 1
	v_mov_b32_e32 v9, s2
	v_mov_b32_e32 v90, s3
	v_mul_f32_e32 v93, 0x3a800000, v9
	v_mul_f32_e32 v91, 0x3a800000, v90
	v_fma_f32 v91, -v93, v93, v91
	v_max_f32_e32 v91, 0, v91
	v_add_f32_e32 v91, 0x358637bd, v91
	v_rsq_f32_e32 v94, v91
	v_mul_f32_e32 v91, 0.5, v91
	v_mul_f32_e32 v92, v94, v94
	v_fma_f32 v92, -v91, v92, 0.5
	v_fma_f32 v94, v94, v92, v94
	v_sub_f32_e32 v74, v74, v93
	v_sub_f32_e32 v75, v75, v93
	v_sub_f32_e32 v76, v76, v93
	v_sub_f32_e32 v77, v77, v93
	v_sub_f32_e32 v78, v78, v93
	v_sub_f32_e32 v79, v79, v93
	v_sub_f32_e32 v80, v80, v93
	v_sub_f32_e32 v81, v81, v93
	v_sub_f32_e32 v82, v82, v93
	v_sub_f32_e32 v83, v83, v93
	v_sub_f32_e32 v84, v84, v93
	v_sub_f32_e32 v85, v85, v93
	v_sub_f32_e32 v86, v86, v93
	v_sub_f32_e32 v87, v87, v93
	v_sub_f32_e32 v88, v88, v93
	v_sub_f32_e32 v89, v89, v93
	v_mul_f32_e32 v74, v94, v74
	v_mul_f32_e32 v75, v94, v75
	v_mul_f32_e32 v76, v94, v76
	v_mul_f32_e32 v77, v94, v77
	v_mul_f32_e32 v78, v94, v78
	v_mul_f32_e32 v79, v94, v79
	v_mul_f32_e32 v80, v94, v80
	v_mul_f32_e32 v81, v94, v81
	v_mul_f32_e32 v82, v94, v82
	v_mul_f32_e32 v83, v94, v83
	v_mul_f32_e32 v84, v94, v84
	v_mul_f32_e32 v85, v94, v85
	v_mul_f32_e32 v86, v94, v86
	v_mul_f32_e32 v87, v94, v87
	v_mul_f32_e32 v88, v94, v88
	v_mul_f32_e32 v89, v94, v89
	v_fma_f32 v74, v74, v130, v114
	v_fma_f32 v75, v75, v131, v115
	v_fma_f32 v76, v76, v132, v116
	v_fma_f32 v77, v77, v133, v117
	v_fma_f32 v78, v78, v134, v118
	v_fma_f32 v79, v79, v135, v119
	v_fma_f32 v80, v80, v136, v120
	v_fma_f32 v81, v81, v137, v121
	v_fma_f32 v82, v82, v138, v122
	v_fma_f32 v83, v83, v139, v123
	v_fma_f32 v84, v84, v140, v124
	v_fma_f32 v85, v85, v141, v125
	v_fma_f32 v86, v86, v142, v126
	v_fma_f32 v87, v87, v143, v127
	v_fma_f32 v88, v88, v144, v128
	v_fma_f32 v89, v89, v145, v129
	v_cvt_pk_bf16_f32 v190, v74, v75
	v_cvt_pk_bf16_f32 v191, v76, v77
	v_cvt_pk_bf16_f32 v192, v78, v79
	v_cvt_pk_bf16_f32 v193, v80, v81
	v_cvt_pk_bf16_f32 v194, v82, v83
	v_cvt_pk_bf16_f32 v195, v84, v85
	v_cvt_pk_bf16_f32 v196, v86, v87
	v_cvt_pk_bf16_f32 v197, v88, v89
	s_add_u32 s2, s10, 0x3000
	s_addc_u32 s3, s11, 0
	global_store_dwordx4 v1, v[190:193], s[2:3]
	global_store_dwordx4 v1, v[194:197], s[2:3] offset:1024
	s_waitcnt vmcnt(13)
	v_add_f32_e32 v9, v98, v99
	v_add_f32_e32 v91, v100, v101
	v_mul_f32_e32 v90, v98, v98
	v_mul_f32_e32 v92, v99, v99
	v_add_f32_e32 v9, v9, v102
	v_add_f32_e32 v91, v91, v103
	v_add_f32_e32 v9, v9, v104
	v_add_f32_e32 v91, v91, v105
	v_add_f32_e32 v9, v9, v106
	v_add_f32_e32 v91, v91, v107
	v_add_f32_e32 v9, v9, v108
	v_add_f32_e32 v91, v91, v109
	v_add_f32_e32 v9, v9, v110
	v_add_f32_e32 v91, v91, v111
	v_add_f32_e32 v9, v9, v112
	v_add_f32_e32 v91, v91, v113
	v_fmac_f32_e32 v90, v100, v100
	v_fmac_f32_e32 v92, v101, v101
	v_fmac_f32_e32 v90, v102, v102
	v_fmac_f32_e32 v92, v103, v103
	v_fmac_f32_e32 v90, v104, v104
	v_fmac_f32_e32 v92, v105, v105
	v_fmac_f32_e32 v90, v106, v106
	v_fmac_f32_e32 v92, v107, v107
	v_fmac_f32_e32 v90, v108, v108
	v_fmac_f32_e32 v92, v109, v109
	v_fmac_f32_e32 v90, v110, v110
	v_fmac_f32_e32 v92, v111, v111
	v_fmac_f32_e32 v90, v112, v112
	v_fmac_f32_e32 v92, v113, v113
	v_add_f32_e32 v9, v9, v91
	v_add_f32_e32 v90, v90, v92
	s_nop 1
	v_add_f32_dpp v9, v9, v9 quad_perm:[1,0,3,2] row_mask:0xf bank_mask:0xf
	v_add_f32_dpp v90, v90, v90 quad_perm:[1,0,3,2] row_mask:0xf bank_mask:0xf
	s_nop 0
	v_add_f32_dpp v9, v9, v9 quad_perm:[2,3,0,1] row_mask:0xf bank_mask:0xf
	v_add_f32_dpp v90, v90, v90 quad_perm:[2,3,0,1] row_mask:0xf bank_mask:0xf
	s_nop 0
	v_add_f32_dpp v9, v9, v9 row_half_mirror row_mask:0xf bank_mask:0xf
	v_add_f32_dpp v90, v90, v90 row_half_mirror row_mask:0xf bank_mask:0xf
	s_nop 0
	v_add_f32_dpp v9, v9, v9 row_mirror row_mask:0xf bank_mask:0xf
	v_add_f32_dpp v90, v90, v90 row_mirror row_mask:0xf bank_mask:0xf
	s_nop 0
	v_add_f32_dpp v9, v9, v9 row_bcast:15 row_mask:0xa bank_mask:0xf
	v_add_f32_dpp v90, v90, v90 row_bcast:15 row_mask:0xa bank_mask:0xf
	s_nop 0
	v_add_f32_dpp v9, v9, v9 row_bcast:31 row_mask:0xc bank_mask:0xf
	v_add_f32_dpp v90, v90, v90 row_bcast:31 row_mask:0xc bank_mask:0xf
	s_nop 0
	v_readlane_b32 s2, v9, 63
	v_readlane_b32 s3, v90, 63
	s_nop 1
	v_mov_b32_e32 v9, s2
	v_mov_b32_e32 v90, s3
	v_mul_f32_e32 v93, 0x3a800000, v9
	v_mul_f32_e32 v91, 0x3a800000, v90
	v_fma_f32 v91, -v93, v93, v91
	v_max_f32_e32 v91, 0, v91
	v_add_f32_e32 v91, 0x358637bd, v91
	v_rsq_f32_e32 v94, v91
	v_mul_f32_e32 v91, 0.5, v91
	v_mul_f32_e32 v92, v94, v94
	v_fma_f32 v92, -v91, v92, 0.5
	v_fma_f32 v94, v94, v92, v94
	s_add_u32 s2, s12, 0x38
	s_addc_u32 s3, s13, 0
	v_mov_b32_e32 v188, v93
	v_mov_b32_e32 v189, v94
	s_mov_b64 exec, 1
	global_store_dwordx2 v97, v[188:189], s[2:3]
	s_mov_b64 exec, -1
	v_sub_f32_e32 v98, v98, v93
	v_sub_f32_e32 v99, v99, v93
	v_sub_f32_e32 v100, v100, v93
	v_sub_f32_e32 v101, v101, v93
	v_sub_f32_e32 v102, v102, v93
	v_sub_f32_e32 v103, v103, v93
	v_sub_f32_e32 v104, v104, v93
	v_sub_f32_e32 v105, v105, v93
	v_sub_f32_e32 v106, v106, v93
	v_sub_f32_e32 v107, v107, v93
	v_sub_f32_e32 v108, v108, v93
	v_sub_f32_e32 v109, v109, v93
	v_sub_f32_e32 v110, v110, v93
	v_sub_f32_e32 v111, v111, v93
	v_sub_f32_e32 v112, v112, v93
	v_sub_f32_e32 v113, v113, v93
	v_mul_f32_e32 v98, v94, v98
	v_mul_f32_e32 v99, v94, v99
	v_mul_f32_e32 v100, v94, v100
	v_mul_f32_e32 v101, v94, v101
	v_mul_f32_e32 v102, v94, v102
	v_mul_f32_e32 v103, v94, v103
	v_mul_f32_e32 v104, v94, v104
	v_mul_f32_e32 v105, v94, v105
	v_mul_f32_e32 v106, v94, v106
	v_mul_f32_e32 v107, v94, v107
	v_mul_f32_e32 v108, v94, v108
	v_mul_f32_e32 v109, v94, v109
; DI unsigned pk2(float lo, float hi) { f32x2 v = {lo, hi}; bf16x2_t b = __builtin_convertvector(v, bf16x2_t); return __builtin_bit_cast(unsigned, b); }
; DI void ln_row_v(const Frame& F, f32x4 (&v)[4], float* xout, const float* g, const float* b, const float* sh, const float* sc, bf16_t* hout, const float* slab, const float* gres, float* stat = nullptr) {
;     ...
;         for (int j = 0; j < 4; ++j) { const f32x4 gg = ((const f32x4*)g)[F.lane + 64 * j], bb = ((const f32x4*)b)[F.lane + 64 * j];
;             v[j] = (v[j] - mean) * rstd * gg + bb; if (xout) ((f32x4*)xout)[F.lane + 64 * j] = v[j]; }
;     }
;     if (hout) {
;         float s = 0.f, s2 = 0.f;
; #pragma unroll
;         for (int j = 0; j < 4; ++j) { s += (v[j][0] + v[j][1]) + (v[j][2] + v[j][3]); s2 += (v[j][0] * v[j][0] + v[j][1] * v[j][1]) + (v[j][2] * v[j][2] + v[j][3] * v[j][3]); }
;         wave_sum2(s, s2, F.lane);
;         const float mean = s * (1.f / D); const float rstd = 1.f / sqrtf(fmaxf(s2 * (1.f / D) - mean * mean, 0.f) + EPS);
; #pragma unroll
;         for (int j = 0; j < 4; ++j) { const f32x4 hh = ((const f32x4*)sh)[F.lane + 64 * j], cc = ((const f32x4*)sc)[F.lane + 64 * j];
;             const f32x4 o = (v[j] - mean) * rstd * (cc + 1.f) + hh; u32x2 wv; wv.x = pk2(o[0], o[1]); wv.y = pk2(o[2], o[3]);
;             ((u32x2*)hout)[F.lane + 64 * j] = wv; }
;     }
	v_mul_f32_e32 v110, v94, v110
	v_mul_f32_e32 v111, v94, v111
	v_mul_f32_e32 v112, v94, v112
	v_mul_f32_e32 v113, v94, v113
	v_fma_f32 v98, v98, v10, v26
	v_fma_f32 v99, v99, v11, v27
	v_fma_f32 v100, v100, v12, v28
	v_fma_f32 v101, v101, v13, v29
	v_fma_f32 v102, v102, v14, v30
	v_fma_f32 v103, v103, v15, v31
	v_fma_f32 v104, v104, v16, v32
	v_fma_f32 v105, v105, v17, v33
	v_fma_f32 v106, v106, v18, v34
	v_fma_f32 v107, v107, v19, v35
	v_fma_f32 v108, v108, v20, v36
	v_fma_f32 v109, v109, v21, v37
	v_fma_f32 v110, v110, v22, v38
	v_fma_f32 v111, v111, v23, v39
	v_fma_f32 v112, v112, v24, v40
	v_fma_f32 v113, v113, v25, v41
	v_add_f32_e32 v9, v98, v99
	v_add_f32_e32 v91, v100, v101
	v_mul_f32_e32 v90, v98, v98
	v_mul_f32_e32 v92, v99, v99
	v_add_f32_e32 v9, v9, v102
	v_add_f32_e32 v91, v91, v103
	v_add_f32_e32 v9, v9, v104
	v_add_f32_e32 v91, v91, v105
	v_add_f32_e32 v9, v9, v106
	v_add_f32_e32 v91, v91, v107
	v_add_f32_e32 v9, v9, v108
	v_add_f32_e32 v91, v91, v109
	v_add_f32_e32 v9, v9, v110
	v_add_f32_e32 v91, v91, v111
	v_add_f32_e32 v9, v9, v112
	v_add_f32_e32 v91, v91, v113
	v_fmac_f32_e32 v90, v100, v100
	v_fmac_f32_e32 v92, v101, v101
	v_fmac_f32_e32 v90, v102, v102
	v_fmac_f32_e32 v92, v103, v103
	v_fmac_f32_e32 v90, v104, v104
	v_fmac_f32_e32 v92, v105, v105
	v_fmac_f32_e32 v90, v106, v106
	v_fmac_f32_e32 v92, v107, v107
	v_fmac_f32_e32 v90, v108, v108
	v_fmac_f32_e32 v92, v109, v109
	v_fmac_f32_e32 v90, v110, v110
	v_fmac_f32_e32 v92, v111, v111
	v_fmac_f32_e32 v90, v112, v112
	v_fmac_f32_e32 v92, v113, v113
	v_add_f32_e32 v9, v9, v91
	v_add_f32_e32 v90, v90, v92
	s_nop 1
	v_add_f32_dpp v9, v9, v9 quad_perm:[1,0,3,2] row_mask:0xf bank_mask:0xf
	v_add_f32_dpp v90, v90, v90 quad_perm:[1,0,3,2] row_mask:0xf bank_mask:0xf
	s_nop 0
	v_add_f32_dpp v9, v9, v9 quad_perm:[2,3,0,1] row_mask:0xf bank_mask:0xf
	v_add_f32_dpp v90, v90, v90 quad_perm:[2,3,0,1] row_mask:0xf bank_mask:0xf
	s_nop 0
	v_add_f32_dpp v9, v9, v9 row_half_mirror row_mask:0xf bank_mask:0xf
	v_add_f32_dpp v90, v90, v90 row_half_mirror row_mask:0xf bank_mask:0xf
	s_nop 0
	v_add_f32_dpp v9, v9, v9 row_mirror row_mask:0xf bank_mask:0xf
	v_add_f32_dpp v90, v90, v90 row_mirror row_mask:0xf bank_mask:0xf
	s_nop 0
	v_add_f32_dpp v9, v9, v9 row_bcast:15 row_mask:0xa bank_mask:0xf
	v_add_f32_dpp v90, v90, v90 row_bcast:15 row_mask:0xa bank_mask:0xf
	s_nop 0
	v_add_f32_dpp v9, v9, v9 row_bcast:31 row_mask:0xc bank_mask:0xf
	v_add_f32_dpp v90, v90, v90 row_bcast:31 row_mask:0xc bank_mask:0xf
	s_nop 0
	v_readlane_b32 s2, v9, 63
	v_readlane_b32 s3, v90, 63
	s_nop 1
	v_mov_b32_e32 v9, s2
	v_mov_b32_e32 v90, s3
	v_mul_f32_e32 v93, 0x3a800000, v9
	v_mul_f32_e32 v91, 0x3a800000, v90
	v_fma_f32 v91, -v93, v93, v91
	v_max_f32_e32 v91, 0, v91
	v_add_f32_e32 v91, 0x358637bd, v91
	v_rsq_f32_e32 v94, v91
	v_mul_f32_e32 v91, 0.5, v91
	v_mul_f32_e32 v92, v94, v94
	v_fma_f32 v92, -v91, v92, 0.5
	v_fma_f32 v94, v94, v92, v94
	v_sub_f32_e32 v98, v98, v93
	v_sub_f32_e32 v99, v99, v93
	v_sub_f32_e32 v100, v100, v93
	v_sub_f32_e32 v101, v101, v93
	v_sub_f32_e32 v102, v102, v93
	v_sub_f32_e32 v103, v103, v93
	v_sub_f32_e32 v104, v104, v93
	v_sub_f32_e32 v105, v105, v93
	v_sub_f32_e32 v106, v106, v93
	v_sub_f32_e32 v107, v107, v93
	v_sub_f32_e32 v108, v108, v93
	v_sub_f32_e32 v109, v109, v93
	v_sub_f32_e32 v110, v110, v93
	v_sub_f32_e32 v111, v111, v93
	v_sub_f32_e32 v112, v112, v93
	v_sub_f32_e32 v113, v113, v93
	v_mul_f32_e32 v98, v94, v98
	v_mul_f32_e32 v99, v94, v99
	v_mul_f32_e32 v100, v94, v100
	v_mul_f32_e32 v101, v94, v101
	v_mul_f32_e32 v102, v94, v102
	v_mul_f32_e32 v103, v94, v103
	v_mul_f32_e32 v104, v94, v104
	v_mul_f32_e32 v105, v94, v105
	v_mul_f32_e32 v106, v94, v106
	v_mul_f32_e32 v107, v94, v107
	v_mul_f32_e32 v108, v94, v108
	v_mul_f32_e32 v109, v94, v109
	v_mul_f32_e32 v110, v94, v110
	v_mul_f32_e32 v111, v94, v111
	v_mul_f32_e32 v112, v94, v112
	v_mul_f32_e32 v113, v94, v113
	v_fma_f32 v98, v98, v130, v114
	v_fma_f32 v99, v99, v131, v115
	v_fma_f32 v100, v100, v132, v116
	v_fma_f32 v101, v101, v133, v117
	v_fma_f32 v102, v102, v134, v118
	v_fma_f32 v103, v103, v135, v119
	v_fma_f32 v104, v104, v136, v120
	v_fma_f32 v105, v105, v137, v121
	v_fma_f32 v106, v106, v138, v122
	v_fma_f32 v107, v107, v139, v123
	v_fma_f32 v108, v108, v140, v124
	v_fma_f32 v109, v109, v141, v125
	v_fma_f32 v110, v110, v142, v126
	v_fma_f32 v111, v111, v143, v127
	v_fma_f32 v112, v112, v144, v128
	v_fma_f32 v113, v113, v145, v129
	v_cvt_pk_bf16_f32 v190, v98, v99
	v_cvt_pk_bf16_f32 v191, v100, v101
	v_cvt_pk_bf16_f32 v192, v102, v103
	v_cvt_pk_bf16_f32 v193, v104, v105
	v_cvt_pk_bf16_f32 v194, v106, v107
	v_cvt_pk_bf16_f32 v195, v108, v109
	v_cvt_pk_bf16_f32 v196, v110, v111
	v_cvt_pk_bf16_f32 v197, v112, v113
	s_add_u32 s2, s10, 0x3800
	s_addc_u32 s3, s11, 0
	global_store_dwordx4 v1, v[190:193], s[2:3]
	global_store_dwordx4 v1, v[194:197], s[2:3] offset:1024
	s_cmp_eq_u32 s22, 3
	s_cbranch_scc1 .Lln_a_noctx
; DI const float* modp(const Frame& F, int l, int mr, int which) { return (const float*)(F.ws + WS_MOD) + ((size_t)(l * 9 + mr) * 6 + which) * 1024; }
; DI void ln_row_v(const Frame& F, f32x4 (&v)[4], float* xout, const float* g, const float* b, const float* sh, const float* sc, bf16_t* hout, const float* slab, const float* gres, float* stat = nullptr) {
;     ...
;         float s = 0.f, s2 = 0.f;
; #pragma unroll
;         for (int j = 0; j < 4; ++j) { s += (v[j][0] + v[j][1]) + (v[j][2] + v[j][3]); s2 += (v[j][0] * v[j][0] + v[j][1] * v[j][1]) + (v[j][2] * v[j][2] + v[j][3] * v[j][3]); }
;         wave_sum2(s, s2, F.lane);
;         const float mean = s * (1.f / D); const float rstd = 1.f / sqrtf(fmaxf(s2 * (1.f / D) - mean * mean, 0.f) + EPS);
;         if (stat && F.lane == 0) { f32x2 sv = {mean, rstd}; *(f32x2*)stat = sv; }
; #pragma unroll
;         for (int j = 0; j < 4; ++j) { const f32x4 gg = ((const f32x4*)g)[F.lane + 64 * j], bb = ((const f32x4*)b)[F.lane + 64 * j];
;             v[j] = (v[j] - mean) * rstd * gg + bb; if (xout) ((f32x4*)xout)[F.lane + 64 * j] = v[j]; }
; DI void ln_phase(const Frame& F, int which) {
;     ...
;         ln_row_v(F, vc, st_only ? nullptr : xrow_ptr(F, row), g, b, sh, sc, wh ? H + (size_t)row * D : nullptr, sl ? (const float*)(F.ws + WS_KN) + (size_t)(row - ML) * 1024 : nullptr, modp(F, l, mr, 5), stp);
	s_waitcnt vmcnt(9)
	v_add_f32_e32 v9, v42, v43
	v_add_f32_e32 v91, v44, v45
	v_mul_f32_e32 v90, v42, v42
	v_mul_f32_e32 v92, v43, v43
	v_add_f32_e32 v9, v9, v46
	v_add_f32_e32 v91, v91, v47
	v_add_f32_e32 v9, v9, v48
	v_add_f32_e32 v91, v91, v49
	v_add_f32_e32 v9, v9, v50
	v_add_f32_e32 v91, v91, v51
	v_add_f32_e32 v9, v9, v52
	v_add_f32_e32 v91, v91, v53
	v_add_f32_e32 v9, v9, v54
	v_add_f32_e32 v91, v91, v55
	v_add_f32_e32 v9, v9, v56
	v_add_f32_e32 v91, v91, v57
	v_fmac_f32_e32 v90, v44, v44
	v_fmac_f32_e32 v92, v45, v45
	v_fmac_f32_e32 v90, v46, v46
	v_fmac_f32_e32 v92, v47, v47
	v_fmac_f32_e32 v90, v48, v48
	v_fmac_f32_e32 v92, v49, v49
	v_fmac_f32_e32 v90, v50, v50
	v_fmac_f32_e32 v92, v51, v51
	v_fmac_f32_e32 v90, v52, v52
	v_fmac_f32_e32 v92, v53, v53
	v_fmac_f32_e32 v90, v54, v54
	v_fmac_f32_e32 v92, v55, v55
	v_fmac_f32_e32 v90, v56, v56
	v_fmac_f32_e32 v92, v57, v57
	v_add_f32_e32 v9, v9, v91
	v_add_f32_e32 v90, v90, v92
	s_nop 1
	v_add_f32_dpp v9, v9, v9 quad_perm:[1,0,3,2] row_mask:0xf bank_mask:0xf
	v_add_f32_dpp v90, v90, v90 quad_perm:[1,0,3,2] row_mask:0xf bank_mask:0xf
	s_nop 0
	v_add_f32_dpp v9, v9, v9 quad_perm:[2,3,0,1] row_mask:0xf bank_mask:0xf
	v_add_f32_dpp v90, v90, v90 quad_perm:[2,3,0,1] row_mask:0xf bank_mask:0xf
	s_nop 0
	v_add_f32_dpp v9, v9, v9 row_half_mirror row_mask:0xf bank_mask:0xf
	v_add_f32_dpp v90, v90, v90 row_half_mirror row_mask:0xf bank_mask:0xf
	s_nop 0
	v_add_f32_dpp v9, v9, v9 row_mirror row_mask:0xf bank_mask:0xf
	v_add_f32_dpp v90, v90, v90 row_mirror row_mask:0xf bank_mask:0xf
	s_nop 0
	v_add_f32_dpp v9, v9, v9 row_bcast:15 row_mask:0xa bank_mask:0xf
	v_add_f32_dpp v90, v90, v90 row_bcast:15 row_mask:0xa bank_mask:0xf
	s_nop 0
	v_add_f32_dpp v9, v9, v9 row_bcast:31 row_mask:0xc bank_mask:0xf
	v_add_f32_dpp v90, v90, v90 row_bcast:31 row_mask:0xc bank_mask:0xf
	s_nop 0
	v_readlane_b32 s2, v9, 63
	v_readlane_b32 s3, v90, 63
	s_nop 1
	v_mov_b32_e32 v9, s2
	v_mov_b32_e32 v90, s3
	v_mul_f32_e32 v93, 0x3a800000, v9
	v_mul_f32_e32 v91, 0x3a800000, v90
	v_fma_f32 v91, -v93, v93, v91
	v_max_f32_e32 v91, 0, v91
	v_add_f32_e32 v91, 0x358637bd, v91
	v_rsq_f32_e32 v94, v91
	v_mul_f32_e32 v91, 0.5, v91
	v_mul_f32_e32 v92, v94, v94
	v_fma_f32 v92, -v91, v92, 0.5
	v_fma_f32 v94, v94, v92, v94
	v_sub_f32_e32 v42, v42, v93
	v_sub_f32_e32 v43, v43, v93
	v_sub_f32_e32 v44, v44, v93
	v_sub_f32_e32 v45, v45, v93
	v_sub_f32_e32 v46, v46, v93
	v_sub_f32_e32 v47, v47, v93
	v_sub_f32_e32 v48, v48, v93
	v_sub_f32_e32 v49, v49, v93
	v_sub_f32_e32 v50, v50, v93
	v_sub_f32_e32 v51, v51, v93
	v_sub_f32_e32 v52, v52, v93
	v_sub_f32_e32 v53, v53, v93
	v_sub_f32_e32 v54, v54, v93
	v_sub_f32_e32 v55, v55, v93
	v_sub_f32_e32 v56, v56, v93
	v_sub_f32_e32 v57, v57, v93
	v_mul_f32_e32 v42, v94, v42
	v_mul_f32_e32 v43, v94, v43
	v_mul_f32_e32 v44, v94, v44
	v_mul_f32_e32 v45, v94, v45
	v_mul_f32_e32 v46, v94, v46
	v_mul_f32_e32 v47, v94, v47
	v_mul_f32_e32 v48, v94, v48
	v_mul_f32_e32 v49, v94, v49
	v_mul_f32_e32 v50, v94, v50
	v_mul_f32_e32 v51, v94, v51
	v_mul_f32_e32 v52, v94, v52
	v_mul_f32_e32 v53, v94, v53
	v_mul_f32_e32 v54, v94, v54
	v_mul_f32_e32 v55, v94, v55
	v_mul_f32_e32 v56, v94, v56
	v_mul_f32_e32 v57, v94, v57
	v_fma_f32 v42, v42, v10, v26
	v_fma_f32 v43, v43, v11, v27
	v_fma_f32 v44, v44, v12, v28
	v_fma_f32 v45, v45, v13, v29
	v_fma_f32 v46, v46, v14, v30
	v_fma_f32 v47, v47, v15, v31
	v_fma_f32 v48, v48, v16, v32
	v_fma_f32 v49, v49, v17, v33
	v_fma_f32 v50, v50, v18, v34
	v_fma_f32 v51, v51, v19, v35
	v_fma_f32 v52, v52, v20, v36
	v_fma_f32 v53, v53, v21, v37
	v_fma_f32 v54, v54, v22, v38
	v_fma_f32 v55, v55, v23, v39
	v_fma_f32 v56, v56, v24, v40
	v_fma_f32 v57, v57, v25, v41
	s_mov_b64 s[2:3], s[20:21]
	global_store_dwordx4 v0, v[42:45], s[2:3]
	global_store_dwordx4 v0, v[46:49], s[2:3] offset:16
	global_store_dwordx4 v0, v[50:53], s[2:3] offset:2048
	global_store_dwordx4 v0, v[54:57], s[2:3] offset:2064
	v_add_f32_e32 v9, v42, v43
	v_add_f32_e32 v91, v44, v45
	v_mul_f32_e32 v90, v42, v42
	v_mul_f32_e32 v92, v43, v43
	v_add_f32_e32 v9, v9, v46
	v_add_f32_e32 v91, v91, v47
	v_add_f32_e32 v9, v9, v48
	v_add_f32_e32 v91, v91, v49
	v_add_f32_e32 v9, v9, v50
	v_add_f32_e32 v91, v91, v51
	v_add_f32_e32 v9, v9, v52
	v_add_f32_e32 v91, v91, v53
	v_add_f32_e32 v9, v9, v54
	v_add_f32_e32 v91, v91, v55
; DI unsigned pk2(float lo, float hi) { f32x2 v = {lo, hi}; bf16x2_t b = __builtin_convertvector(v, bf16x2_t); return __builtin_bit_cast(unsigned, b); }
; DI void ln_row_v(const Frame& F, f32x4 (&v)[4], float* xout, const float* g, const float* b, const float* sh, const float* sc, bf16_t* hout, const float* slab, const float* gres, float* stat = nullptr) {
;     ...
;     if (hout) {
;         float s = 0.f, s2 = 0.f;
; #pragma unroll
;         for (int j = 0; j < 4; ++j) { s += (v[j][0] + v[j][1]) + (v[j][2] + v[j][3]); s2 += (v[j][0] * v[j][0] + v[j][1] * v[j][1]) + (v[j][2] * v[j][2] + v[j][3] * v[j][3]); }
;         wave_sum2(s, s2, F.lane);
;         const float mean = s * (1.f / D); const float rstd = 1.f / sqrtf(fmaxf(s2 * (1.f / D) - mean * mean, 0.f) + EPS);
; #pragma unroll
;         for (int j = 0; j < 4; ++j) { const f32x4 hh = ((const f32x4*)sh)[F.lane + 64 * j], cc = ((const f32x4*)sc)[F.lane + 64 * j];
;             const f32x4 o = (v[j] - mean) * rstd * (cc + 1.f) + hh; u32x2 wv; wv.x = pk2(o[0], o[1]); wv.y = pk2(o[2], o[3]);
;             ((u32x2*)hout)[F.lane + 64 * j] = wv; }
;     }
	v_add_f32_e32 v9, v9, v56
	v_add_f32_e32 v91, v91, v57
	v_fmac_f32_e32 v90, v44, v44
	v_fmac_f32_e32 v92, v45, v45
	v_fmac_f32_e32 v90, v46, v46
	v_fmac_f32_e32 v92, v47, v47
	v_fmac_f32_e32 v90, v48, v48
	v_fmac_f32_e32 v92, v49, v49
	v_fmac_f32_e32 v90, v50, v50
	v_fmac_f32_e32 v92, v51, v51
	v_fmac_f32_e32 v90, v52, v52
	v_fmac_f32_e32 v92, v53, v53
	v_fmac_f32_e32 v90, v54, v54
	v_fmac_f32_e32 v92, v55, v55
	v_fmac_f32_e32 v90, v56, v56
	v_fmac_f32_e32 v92, v57, v57
	v_add_f32_e32 v9, v9, v91
	v_add_f32_e32 v90, v90, v92
	s_nop 1
	v_add_f32_dpp v9, v9, v9 quad_perm:[1,0,3,2] row_mask:0xf bank_mask:0xf
	v_add_f32_dpp v90, v90, v90 quad_perm:[1,0,3,2] row_mask:0xf bank_mask:0xf
	s_nop 0
	v_add_f32_dpp v9, v9, v9 quad_perm:[2,3,0,1] row_mask:0xf bank_mask:0xf
	v_add_f32_dpp v90, v90, v90 quad_perm:[2,3,0,1] row_mask:0xf bank_mask:0xf
	s_nop 0
	v_add_f32_dpp v9, v9, v9 row_half_mirror row_mask:0xf bank_mask:0xf
	v_add_f32_dpp v90, v90, v90 row_half_mirror row_mask:0xf bank_mask:0xf
	s_nop 0
	v_add_f32_dpp v9, v9, v9 row_mirror row_mask:0xf bank_mask:0xf
	v_add_f32_dpp v90, v90, v90 row_mirror row_mask:0xf bank_mask:0xf
	s_nop 0
	v_add_f32_dpp v9, v9, v9 row_bcast:15 row_mask:0xa bank_mask:0xf
	v_add_f32_dpp v90, v90, v90 row_bcast:15 row_mask:0xa bank_mask:0xf
	s_nop 0
	v_add_f32_dpp v9, v9, v9 row_bcast:31 row_mask:0xc bank_mask:0xf
	v_add_f32_dpp v90, v90, v90 row_bcast:31 row_mask:0xc bank_mask:0xf
	s_nop 0
	v_readlane_b32 s2, v9, 63
	v_readlane_b32 s3, v90, 63
	s_nop 1
	v_mov_b32_e32 v9, s2
	v_mov_b32_e32 v90, s3
	v_mul_f32_e32 v93, 0x3a800000, v9
	v_mul_f32_e32 v91, 0x3a800000, v90
	v_fma_f32 v91, -v93, v93, v91
	v_max_f32_e32 v91, 0, v91
	v_add_f32_e32 v91, 0x358637bd, v91
	v_rsq_f32_e32 v94, v91
	v_mul_f32_e32 v91, 0.5, v91
	v_mul_f32_e32 v92, v94, v94
	v_fma_f32 v92, -v91, v92, 0.5
	v_fma_f32 v94, v94, v92, v94
	v_sub_f32_e32 v42, v42, v93
	v_sub_f32_e32 v43, v43, v93
	v_sub_f32_e32 v44, v44, v93
	v_sub_f32_e32 v45, v45, v93
	v_sub_f32_e32 v46, v46, v93
	v_sub_f32_e32 v47, v47, v93
	v_sub_f32_e32 v48, v48, v93
	v_sub_f32_e32 v49, v49, v93
	v_sub_f32_e32 v50, v50, v93
	v_sub_f32_e32 v51, v51, v93
	v_sub_f32_e32 v52, v52, v93
	v_sub_f32_e32 v53, v53, v93
	v_sub_f32_e32 v54, v54, v93
	v_sub_f32_e32 v55, v55, v93
	v_sub_f32_e32 v56, v56, v93
	v_sub_f32_e32 v57, v57, v93
	v_add_f32_e32 v162, 1.0, v162
	v_add_f32_e32 v163, 1.0, v163
	v_add_f32_e32 v164, 1.0, v164
	v_add_f32_e32 v165, 1.0, v165
	v_add_f32_e32 v166, 1.0, v166
	v_add_f32_e32 v167, 1.0, v167
	v_add_f32_e32 v168, 1.0, v168
	v_add_f32_e32 v169, 1.0, v169
	v_add_f32_e32 v170, 1.0, v170
	v_add_f32_e32 v171, 1.0, v171
	v_add_f32_e32 v172, 1.0, v172
	v_add_f32_e32 v173, 1.0, v173
	v_add_f32_e32 v174, 1.0, v174
	v_add_f32_e32 v175, 1.0, v175
	v_add_f32_e32 v176, 1.0, v176
	v_add_f32_e32 v177, 1.0, v177
	v_mul_f32_e32 v42, v94, v42
	v_mul_f32_e32 v43, v94, v43
	v_mul_f32_e32 v44, v94, v44
	v_mul_f32_e32 v45, v94, v45
	v_mul_f32_e32 v46, v94, v46
	v_mul_f32_e32 v47, v94, v47
	v_mul_f32_e32 v48, v94, v48
	v_mul_f32_e32 v49, v94, v49
	v_mul_f32_e32 v50, v94, v50
	v_mul_f32_e32 v51, v94, v51
	v_mul_f32_e32 v52, v94, v52
	v_mul_f32_e32 v53, v94, v53
	v_mul_f32_e32 v54, v94, v54
	v_mul_f32_e32 v55, v94, v55
	v_mul_f32_e32 v56, v94, v56
	v_mul_f32_e32 v57, v94, v57
	v_fma_f32 v42, v42, v162, v146
	v_fma_f32 v43, v43, v163, v147
	v_fma_f32 v44, v44, v164, v148
	v_fma_f32 v45, v45, v165, v149
	v_fma_f32 v46, v46, v166, v150
	v_fma_f32 v47, v47, v167, v151
	v_fma_f32 v48, v48, v168, v152
	v_fma_f32 v49, v49, v169, v153
	v_fma_f32 v50, v50, v170, v154
	v_fma_f32 v51, v51, v171, v155
	v_fma_f32 v52, v52, v172, v156
	v_fma_f32 v53, v53, v173, v157
	v_fma_f32 v54, v54, v174, v158
	v_fma_f32 v55, v55, v175, v159
	v_fma_f32 v56, v56, v176, v160
	v_fma_f32 v57, v57, v177, v161
	v_cvt_pk_bf16_f32 v190, v42, v43
	v_cvt_pk_bf16_f32 v191, v44, v45
	v_cvt_pk_bf16_f32 v192, v46, v47
	v_cvt_pk_bf16_f32 v193, v48, v49
	v_cvt_pk_bf16_f32 v194, v50, v51
	v_cvt_pk_bf16_f32 v195, v52, v53
	v_cvt_pk_bf16_f32 v196, v54, v55
	v_cvt_pk_bf16_f32 v197, v56, v57
	s_lshl_b32 s2, s16, 11
	s_add_u32 s2, s94, s2
	s_addc_u32 s3, s95, 0
	s_add_u32 s2, s2, 0x5e00000
	s_addc_u32 s3, s3, 0
	global_store_dwordx4 v1, v[190:193], s[2:3]
	global_store_dwordx4 v1, v[194:197], s[2:3] offset:1024

; DI const float* modp(const Frame& F, int l, int mr, int which) { return (const float*)(F.ws + WS_MOD) + ((size_t)(l * 9 + mr) * 6 + which) * 1024; }
; DI void ln_row_v(const Frame& F, f32x4 (&v)[4], float* xout, const float* g, const float* b, const float* sh, const float* sc, bf16_t* hout, const float* slab, const float* gres, float* stat = nullptr) {
;     ...
;         float s = 0.f, s2 = 0.f;
; #pragma unroll
;         for (int j = 0; j < 4; ++j) { s += (v[j][0] + v[j][1]) + (v[j][2] + v[j][3]); s2 += (v[j][0] * v[j][0] + v[j][1] * v[j][1]) + (v[j][2] * v[j][2] + v[j][3] * v[j][3]); }
;         wave_sum2(s, s2, F.lane);
; DI void ln_phase(const Frame& F, int which) {
;     const int gw = F.vcu * 8 + F.wave, NGW = F.G * 8; const int l = F.l;
;     const int nrows = (l == NL - 1) ? ML : MT;
;     bf16_t* H = (bf16_t*)(F.ws + WS_HB);
;     const float* g = pin(F, which == 0 ? I_LN1G : I_LN2G) + l * 1024; const float* b = pin(F, which == 0 ? I_LN1B : I_LN2B) + l * 1024;
;     const bool wh = !(which == 1 && l == NL - 1);
;     f32x4 vc[4], vn[4];
;     if (gw < nrows) ln_load(F, xrow_ptr(F, gw), vc);
;     for (int row = gw; row < nrows; row += NGW) {
;         if (row + NGW < nrows) ln_load(F, xrow_ptr(F, row + NGW), vn);
;         const int mr = row < ML ? (row >> 11) : 8;
;         const float* sh = which == 0 ? modp(F, l, mr, 3) : modp(F, l + 1 < NL ? l + 1 : l, mr, 0);
;         const float* sc = which == 0 ? modp(F, l, mr, 4) : modp(F, l + 1 < NL ? l + 1 : l, mr, 1);
;         const bool sl = (which == 1 && row >= ML);
;         const bool st_only = row < ML && !(which == 1 && l == NL - 1);
;         float* stp = st_only ? (float*)(F.ws + (which == 0 ? WS_ST1 : WS_ST2)) + 2 * (size_t)row : nullptr;
;         ln_row_v(F, vc, st_only ? nullptr : xrow_ptr(F, row), g, b, sh, sc, wh ? H + (size_t)row * D : nullptr, sl ? (const float*)(F.ws + WS_KN) + (size_t)(row - ML) * 1024 : nullptr, modp(F, l, mr, 5), stp);
.LBB0_513:
	s_and_b64 vcc, exec, s[2:3]
	s_cbranch_vccz .LBB0_537
	v_readlane_b32 s2, v255, 29
	s_lshl_b32 s2, s2, 3
	v_readlane_b32 s3, v255, 31
	s_add_i32 s16, s3, s2
	v_lshlrev_b32_e32 v0, 5, v186
	v_lshlrev_b32_e32 v1, 4, v186
	v_lshlrev_b32_e32 v96, 2, v186
	v_xor_b32_e32 v3, 4, v96
	v_xor_b32_e32 v4, 8, v96
	v_xor_b32_e32 v5, 16, v96
	v_xor_b32_e32 v6, 32, v96
	v_xor_b32_e32 v7, 64, v96
	v_xor_b32_e32 v8, 128, v96
	s_load_dwordx4 s[4:7], s[62:63], 0xb8
	v_readlane_b32 s22, v255, 35
	v_readlane_b32 s8, v255, 17
	v_readlane_b32 s9, v255, 18
	s_add_u32 s20, s94, 0x3600000
	s_addc_u32 s21, s95, 0
	s_lshl_b32 s2, s16, 12
	s_lshl_b32 s3, s16, 15
	s_add_u32 s8, s8, s3
	s_addc_u32 s9, s9, 0
	s_add_u32 s20, s20, s2
	s_addc_u32 s21, s21, 0
	s_lshl_b32 s2, s16, 14
	s_add_u32 s10, s94, s2
	s_addc_u32 s11, s95, 0
	s_add_u32 s10, s10, 0x3e00000
	s_addc_u32 s11, s11, 0
	s_lshl_b32 s2, s16, 6
	s_add_u32 s12, s94, s2
	s_addc_u32 s13, s95, 0
	s_add_u32 s12, s12, 0x4c0000
	s_addc_u32 s13, s13, 0
	s_add_i32 s3, s22, 1
	s_min_u32 s3, s3, 3
	s_mul_i32 s3, s3, 0x36000
	s_add_u32 s14, s94, s3
	s_addc_u32 s15, s95, 0
	s_add_u32 s14, s14, 0x100000
	s_addc_u32 s15, s15, 0
	s_add_u32 s18, s14, 0x1000
	s_addc_u32 s19, s15, 0
	s_lshl_b32 s2, s22, 12
	s_waitcnt lgkmcnt(0)
	s_add_u32 s4, s4, s2
	s_addc_u32 s5, s5, 0
	s_add_u32 s6, s6, s2
	s_addc_u32 s7, s7, 0
	s_lshl_b32 s2, s16, 12
	s_add_u32 s24, s94, s2
	s_addc_u32 s25, s95, 0
	s_add_u32 s24, s24, 0x9100000
	s_addc_u32 s25, s25, 0
	s_mul_i32 s2, s22, 0x36000
	s_add_u32 s26, s94, s2
	s_addc_u32 s27, s95, 0
	s_add_u32 s26, s26, 0x135000
	s_addc_u32 s27, s27, 0
	s_cmp_eq_u32 s22, 3
	s_cbranch_scc1 .Lln_b_final
	global_load_dwordx4 v[10:13], v0, s[4:5]
	global_load_dwordx4 v[14:17], v0, s[4:5] offset:16
	global_load_dwordx4 v[18:21], v0, s[4:5] offset:2048
	global_load_dwordx4 v[22:25], v0, s[4:5] offset:2064
	global_load_dwordx4 v[26:29], v0, s[6:7]
	global_load_dwordx4 v[30:33], v0, s[6:7] offset:16
	global_load_dwordx4 v[34:37], v0, s[6:7] offset:2048
	global_load_dwordx4 v[38:41], v0, s[6:7] offset:2064
	s_add_u32 s2, s8, 0x0
	s_addc_u32 s3, s9, 0
	global_load_dwordx4 v[42:45], v0, s[2:3]
	global_load_dwordx4 v[46:49], v0, s[2:3] offset:16
	global_load_dwordx4 v[50:53], v0, s[2:3] offset:2048
	global_load_dwordx4 v[54:57], v0, s[2:3] offset:2064
	s_lshr_b32 s23, s16, 8
	s_mul_i32 s23, s23, 0x6000
	s_add_u32 s2, s14, s23
	s_addc_u32 s3, s15, 0
	global_load_dwordx4 v[114:117], v0, s[2:3]
	global_load_dwordx4 v[118:121], v0, s[2:3] offset:16
	global_load_dwordx4 v[122:125], v0, s[2:3] offset:2048
	global_load_dwordx4 v[126:129], v0, s[2:3] offset:2064
	s_add_u32 s2, s18, s23
	s_addc_u32 s3, s19, 0
	global_load_dwordx4 v[130:133], v0, s[2:3]
	global_load_dwordx4 v[134:137], v0, s[2:3] offset:16
	global_load_dwordx4 v[138:141], v0, s[2:3] offset:2048
	global_load_dwordx4 v[142:145], v0, s[2:3] offset:2064
	s_add_u32 s2, s8, 0x1000
	s_addc_u32 s3, s9, 0
	global_load_dwordx4 v[58:61], v0, s[2:3]
	global_load_dwordx4 v[62:65], v0, s[2:3] offset:16
	global_load_dwordx4 v[66:69], v0, s[2:3] offset:2048
	global_load_dwordx4 v[70:73], v0, s[2:3] offset:2064
	s_add_u32 s2, s8, 0x2000
	s_addc_u32 s3, s9, 0
	global_load_dwordx4 v[74:77], v0, s[2:3]
	global_load_dwordx4 v[78:81], v0, s[2:3] offset:16
	global_load_dwordx4 v[82:85], v0, s[2:3] offset:2048
	global_load_dwordx4 v[86:89], v0, s[2:3] offset:2064
	s_add_u32 s2, s8, 0x3000
	s_addc_u32 s3, s9, 0
	global_load_dwordx4 v[98:101], v0, s[2:3]
	global_load_dwordx4 v[102:105], v0, s[2:3] offset:16
	global_load_dwordx4 v[106:109], v0, s[2:3] offset:2048
	global_load_dwordx4 v[110:113], v0, s[2:3] offset:2064
	s_waitcnt vmcnt(20)
	v_add_f32_e32 v9, v42, v43
	v_add_f32_e32 v91, v44, v45
	v_mul_f32_e32 v90, v42, v42
	v_mul_f32_e32 v92, v43, v43
	v_add_f32_e32 v9, v9, v46
	v_add_f32_e32 v91, v91, v47
	v_add_f32_e32 v9, v9, v48
	v_add_f32_e32 v91, v91, v49
	v_add_f32_e32 v9, v9, v50
	v_add_f32_e32 v91, v91, v51
	v_add_f32_e32 v9, v9, v52
	v_add_f32_e32 v91, v91, v53
	v_add_f32_e32 v9, v9, v54
	v_add_f32_e32 v91, v91, v55
	v_add_f32_e32 v9, v9, v56
	v_add_f32_e32 v91, v91, v57
	v_fmac_f32_e32 v90, v44, v44
	v_fmac_f32_e32 v92, v45, v45
	v_fmac_f32_e32 v90, v46, v46
	v_fmac_f32_e32 v92, v47, v47
	v_fmac_f32_e32 v90, v48, v48
	v_fmac_f32_e32 v92, v49, v49
	v_fmac_f32_e32 v90, v50, v50
	v_fmac_f32_e32 v92, v51, v51
	v_fmac_f32_e32 v90, v52, v52
	v_fmac_f32_e32 v92, v53, v53
	v_fmac_f32_e32 v90, v54, v54
	v_fmac_f32_e32 v92, v55, v55
	v_fmac_f32_e32 v90, v56, v56
	v_fmac_f32_e32 v92, v57, v57
	v_add_f32_e32 v9, v9, v91
	v_add_f32_e32 v90, v90, v92
	s_nop 1
	v_add_f32_dpp v9, v9, v9 quad_perm:[1,0,3,2] row_mask:0xf bank_mask:0xf
	v_add_f32_dpp v90, v90, v90 quad_perm:[1,0,3,2] row_mask:0xf bank_mask:0xf
	s_nop 0
	v_add_f32_dpp v9, v9, v9 quad_perm:[2,3,0,1] row_mask:0xf bank_mask:0xf
	v_add_f32_dpp v90, v90, v90 quad_perm:[2,3,0,1] row_mask:0xf bank_mask:0xf
	s_nop 0
	v_add_f32_dpp v9, v9, v9 row_half_mirror row_mask:0xf bank_mask:0xf
	v_add_f32_dpp v90, v90, v90 row_half_mirror row_mask:0xf bank_mask:0xf
	s_nop 0
	v_add_f32_dpp v9, v9, v9 row_mirror row_mask:0xf bank_mask:0xf
	v_add_f32_dpp v90, v90, v90 row_mirror row_mask:0xf bank_mask:0xf
	s_nop 0
	v_add_f32_dpp v9, v9, v9 row_bcast:15 row_mask:0xa bank_mask:0xf
	v_add_f32_dpp v90, v90, v90 row_bcast:15 row_mask:0xa bank_mask:0xf
	s_nop 0
	v_add_f32_dpp v9, v9, v9 row_bcast:31 row_mask:0xc bank_mask:0xf
	v_add_f32_dpp v90, v90, v90 row_bcast:31 row_mask:0xc bank_mask:0xf
	s_nop 0
	v_readlane_b32 s2, v9, 63
	v_readlane_b32 s3, v90, 63
	s_nop 1
	v_mov_b32_e32 v9, s2
	v_mov_b32_e32 v90, s3
	v_mul_f32_e32 v93, 0x3a800000, v9
; DI unsigned pk2(float lo, float hi) { f32x2 v = {lo, hi}; bf16x2_t b = __builtin_convertvector(v, bf16x2_t); return __builtin_bit_cast(unsigned, b); }
; DI void ln_row_v(const Frame& F, f32x4 (&v)[4], float* xout, const float* g, const float* b, const float* sh, const float* sc, bf16_t* hout, const float* slab, const float* gres, float* stat = nullptr) {
;     ...
;         float s = 0.f, s2 = 0.f;
; #pragma unroll
;         for (int j = 0; j < 4; ++j) { s += (v[j][0] + v[j][1]) + (v[j][2] + v[j][3]); s2 += (v[j][0] * v[j][0] + v[j][1] * v[j][1]) + (v[j][2] * v[j][2] + v[j][3] * v[j][3]); }
;         wave_sum2(s, s2, F.lane);
;         const float mean = s * (1.f / D); const float rstd = 1.f / sqrtf(fmaxf(s2 * (1.f / D) - mean * mean, 0.f) + EPS);
;         if (stat && F.lane == 0) { f32x2 sv = {mean, rstd}; *(f32x2*)stat = sv; }
; #pragma unroll
;         for (int j = 0; j < 4; ++j) { const f32x4 gg = ((const f32x4*)g)[F.lane + 64 * j], bb = ((const f32x4*)b)[F.lane + 64 * j];
;             v[j] = (v[j] - mean) * rstd * gg + bb; if (xout) ((f32x4*)xout)[F.lane + 64 * j] = v[j]; }
;     }
;     if (hout) {
;         float s = 0.f, s2 = 0.f;
; #pragma unroll
;         for (int j = 0; j < 4; ++j) { s += (v[j][0] + v[j][1]) + (v[j][2] + v[j][3]); s2 += (v[j][0] * v[j][0] + v[j][1] * v[j][1]) + (v[j][2] * v[j][2] + v[j][3] * v[j][3]); }
;         wave_sum2(s, s2, F.lane);
;         const float mean = s * (1.f / D); const float rstd = 1.f / sqrtf(fmaxf(s2 * (1.f / D) - mean * mean, 0.f) + EPS);
; #pragma unroll
;         for (int j = 0; j < 4; ++j) { const f32x4 hh = ((const f32x4*)sh)[F.lane + 64 * j], cc = ((const f32x4*)sc)[F.lane + 64 * j];
;             const f32x4 o = (v[j] - mean) * rstd * (cc + 1.f) + hh; u32x2 wv; wv.x = pk2(o[0], o[1]); wv.y = pk2(o[2], o[3]);
;             ((u32x2*)hout)[F.lane + 64 * j] = wv; }
;     }
	v_mul_f32_e32 v91, 0x3a800000, v90
	v_fma_f32 v91, -v93, v93, v91
	v_max_f32_e32 v91, 0, v91
	v_add_f32_e32 v91, 0x358637bd, v91
	v_rsq_f32_e32 v94, v91
	v_mul_f32_e32 v91, 0.5, v91
	v_mul_f32_e32 v92, v94, v94
	v_fma_f32 v92, -v91, v92, 0.5
	v_fma_f32 v94, v94, v92, v94
	s_add_u32 s2, s12, 0x0
	s_addc_u32 s3, s13, 0
	v_mov_b32_e32 v188, v93
	v_mov_b32_e32 v189, v94
	s_mov_b64 exec, 1
	global_store_dwordx2 v97, v[188:189], s[2:3]
	s_mov_b64 exec, -1
	v_sub_f32_e32 v42, v42, v93
	v_sub_f32_e32 v43, v43, v93
	v_sub_f32_e32 v44, v44, v93
	v_sub_f32_e32 v45, v45, v93
	v_sub_f32_e32 v46, v46, v93
	v_sub_f32_e32 v47, v47, v93
	v_sub_f32_e32 v48, v48, v93
	v_sub_f32_e32 v49, v49, v93
	v_sub_f32_e32 v50, v50, v93
	v_sub_f32_e32 v51, v51, v93
	v_sub_f32_e32 v52, v52, v93
	v_sub_f32_e32 v53, v53, v93
	v_sub_f32_e32 v54, v54, v93
	v_sub_f32_e32 v55, v55, v93
	v_sub_f32_e32 v56, v56, v93
	v_sub_f32_e32 v57, v57, v93
	v_mul_f32_e32 v42, v94, v42
	v_mul_f32_e32 v43, v94, v43
	v_mul_f32_e32 v44, v94, v44
	v_mul_f32_e32 v45, v94, v45
	v_mul_f32_e32 v46, v94, v46
	v_mul_f32_e32 v47, v94, v47
	v_mul_f32_e32 v48, v94, v48
	v_mul_f32_e32 v49, v94, v49
	v_mul_f32_e32 v50, v94, v50
	v_mul_f32_e32 v51, v94, v51
	v_mul_f32_e32 v52, v94, v52
	v_mul_f32_e32 v53, v94, v53
	v_mul_f32_e32 v54, v94, v54
	v_mul_f32_e32 v55, v94, v55
	v_mul_f32_e32 v56, v94, v56
	v_mul_f32_e32 v57, v94, v57
	v_fma_f32 v42, v42, v10, v26
	v_fma_f32 v43, v43, v11, v27
	v_fma_f32 v44, v44, v12, v28
	v_fma_f32 v45, v45, v13, v29
	v_fma_f32 v46, v46, v14, v30
	v_fma_f32 v47, v47, v15, v31
	v_fma_f32 v48, v48, v16, v32
	v_fma_f32 v49, v49, v17, v33
	v_fma_f32 v50, v50, v18, v34
	v_fma_f32 v51, v51, v19, v35
	v_fma_f32 v52, v52, v20, v36
	v_fma_f32 v53, v53, v21, v37
	v_fma_f32 v54, v54, v22, v38
	v_fma_f32 v55, v55, v23, v39
	v_fma_f32 v56, v56, v24, v40
	v_fma_f32 v57, v57, v25, v41
	v_add_f32_e32 v9, v42, v43
	v_add_f32_e32 v91, v44, v45
	v_mul_f32_e32 v90, v42, v42
	v_mul_f32_e32 v92, v43, v43
	v_add_f32_e32 v9, v9, v46
	v_add_f32_e32 v91, v91, v47
	v_add_f32_e32 v9, v9, v48
	v_add_f32_e32 v91, v91, v49
	v_add_f32_e32 v9, v9, v50
	v_add_f32_e32 v91, v91, v51
	v_add_f32_e32 v9, v9, v52
	v_add_f32_e32 v91, v91, v53
	v_add_f32_e32 v9, v9, v54
	v_add_f32_e32 v91, v91, v55
	v_add_f32_e32 v9, v9, v56
	v_add_f32_e32 v91, v91, v57
	v_fmac_f32_e32 v90, v44, v44
	v_fmac_f32_e32 v92, v45, v45
	v_fmac_f32_e32 v90, v46, v46
	v_fmac_f32_e32 v92, v47, v47
	v_fmac_f32_e32 v90, v48, v48
	v_fmac_f32_e32 v92, v49, v49
	v_fmac_f32_e32 v90, v50, v50
	v_fmac_f32_e32 v92, v51, v51
	v_fmac_f32_e32 v90, v52, v52
	v_fmac_f32_e32 v92, v53, v53
	v_fmac_f32_e32 v90, v54, v54
	v_fmac_f32_e32 v92, v55, v55
	v_fmac_f32_e32 v90, v56, v56
	v_fmac_f32_e32 v92, v57, v57
	v_add_f32_e32 v9, v9, v91
	v_add_f32_e32 v90, v90, v92
	s_nop 1
	v_add_f32_dpp v9, v9, v9 quad_perm:[1,0,3,2] row_mask:0xf bank_mask:0xf
	v_add_f32_dpp v90, v90, v90 quad_perm:[1,0,3,2] row_mask:0xf bank_mask:0xf
	s_nop 0
	v_add_f32_dpp v9, v9, v9 quad_perm:[2,3,0,1] row_mask:0xf bank_mask:0xf
	v_add_f32_dpp v90, v90, v90 quad_perm:[2,3,0,1] row_mask:0xf bank_mask:0xf
	s_nop 0
	v_add_f32_dpp v9, v9, v9 row_half_mirror row_mask:0xf bank_mask:0xf
	v_add_f32_dpp v90, v90, v90 row_half_mirror row_mask:0xf bank_mask:0xf
	s_nop 0
	v_add_f32_dpp v9, v9, v9 row_mirror row_mask:0xf bank_mask:0xf
	v_add_f32_dpp v90, v90, v90 row_mirror row_mask:0xf bank_mask:0xf
	s_nop 0
	v_add_f32_dpp v9, v9, v9 row_bcast:15 row_mask:0xa bank_mask:0xf
	v_add_f32_dpp v90, v90, v90 row_bcast:15 row_mask:0xa bank_mask:0xf
	s_nop 0
	v_add_f32_dpp v9, v9, v9 row_bcast:31 row_mask:0xc bank_mask:0xf
	v_add_f32_dpp v90, v90, v90 row_bcast:31 row_mask:0xc bank_mask:0xf
	s_nop 0
	v_readlane_b32 s2, v9, 63
	v_readlane_b32 s3, v90, 63
	s_nop 1
	v_mov_b32_e32 v9, s2
	v_mov_b32_e32 v90, s3
	v_mul_f32_e32 v93, 0x3a800000, v9
	v_mul_f32_e32 v91, 0x3a800000, v90
	v_fma_f32 v91, -v93, v93, v91
	v_max_f32_e32 v91, 0, v91
	v_add_f32_e32 v91, 0x358637bd, v91
	v_rsq_f32_e32 v94, v91
	v_mul_f32_e32 v91, 0.5, v91
	v_mul_f32_e32 v92, v94, v94
	v_fma_f32 v92, -v91, v92, 0.5
	v_fma_f32 v94, v94, v92, v94
	s_waitcnt vmcnt(13)
	v_sub_f32_e32 v42, v42, v93
	v_sub_f32_e32 v43, v43, v93
	v_sub_f32_e32 v44, v44, v93
	v_sub_f32_e32 v45, v45, v93
	v_sub_f32_e32 v46, v46, v93
	v_sub_f32_e32 v47, v47, v93
	v_sub_f32_e32 v48, v48, v93
	v_sub_f32_e32 v49, v49, v93
	v_sub_f32_e32 v50, v50, v93
	v_sub_f32_e32 v51, v51, v93
	v_sub_f32_e32 v52, v52, v93
	v_sub_f32_e32 v53, v53, v93
	v_sub_f32_e32 v54, v54, v93
	v_sub_f32_e32 v55, v55, v93
	v_sub_f32_e32 v56, v56, v93
	v_sub_f32_e32 v57, v57, v93
	v_add_f32_e32 v130, 1.0, v130
	v_add_f32_e32 v131, 1.0, v131
	v_add_f32_e32 v132, 1.0, v132
	v_add_f32_e32 v133, 1.0, v133
	v_add_f32_e32 v134, 1.0, v134
	v_add_f32_e32 v135, 1.0, v135
	v_add_f32_e32 v136, 1.0, v136
	v_add_f32_e32 v137, 1.0, v137
	v_add_f32_e32 v138, 1.0, v138
	v_add_f32_e32 v139, 1.0, v139
	v_add_f32_e32 v140, 1.0, v140
	v_add_f32_e32 v141, 1.0, v141
	v_add_f32_e32 v142, 1.0, v142
	v_add_f32_e32 v143, 1.0, v143
	v_add_f32_e32 v144, 1.0, v144
	v_add_f32_e32 v145, 1.0, v145
	v_mul_f32_e32 v42, v94, v42
	v_mul_f32_e32 v43, v94, v43
	v_mul_f32_e32 v44, v94, v44
	v_mul_f32_e32 v45, v94, v45
	v_mul_f32_e32 v46, v94, v46
	v_mul_f32_e32 v47, v94, v47
	v_mul_f32_e32 v48, v94, v48
	v_mul_f32_e32 v49, v94, v49
	v_mul_f32_e32 v50, v94, v50
	v_mul_f32_e32 v51, v94, v51
	v_mul_f32_e32 v52, v94, v52
	v_mul_f32_e32 v53, v94, v53
	v_mul_f32_e32 v54, v94, v54
	v_mul_f32_e32 v55, v94, v55
	v_mul_f32_e32 v56, v94, v56
	v_mul_f32_e32 v57, v94, v57
	v_fma_f32 v42, v42, v130, v114
	v_fma_f32 v43, v43, v131, v115
	v_fma_f32 v44, v44, v132, v116
	v_fma_f32 v45, v45, v133, v117
	v_fma_f32 v46, v46, v134, v118
	v_fma_f32 v47, v47, v135, v119
	v_fma_f32 v48, v48, v136, v120
	v_fma_f32 v49, v49, v137, v121
	v_fma_f32 v50, v50, v138, v122
	v_fma_f32 v51, v51, v139, v123
	v_fma_f32 v52, v52, v140, v124
	v_fma_f32 v53, v53, v141, v125
	v_fma_f32 v54, v54, v142, v126
	v_fma_f32 v55, v55, v143, v127
	v_fma_f32 v56, v56, v144, v128
	v_fma_f32 v57, v57, v145, v129
	v_cvt_pk_bf16_f32 v190, v42, v43
	v_cvt_pk_bf16_f32 v191, v44, v45
	v_cvt_pk_bf16_f32 v192, v46, v47
	v_cvt_pk_bf16_f32 v193, v48, v49
	v_cvt_pk_bf16_f32 v194, v50, v51
	v_cvt_pk_bf16_f32 v195, v52, v53
	v_cvt_pk_bf16_f32 v196, v54, v55
	v_cvt_pk_bf16_f32 v197, v56, v57
	s_add_u32 s2, s10, 0x0
	s_addc_u32 s3, s11, 0
	global_store_dwordx4 v1, v[190:193], s[2:3]
	global_store_dwordx4 v1, v[194:197], s[2:3] offset:1024
	s_add_u32 s2, s8, 0x4000
	s_addc_u32 s3, s9, 0
	global_load_dwordx4 v[42:45], v0, s[2:3]
	global_load_dwordx4 v[46:49], v0, s[2:3] offset:16
	global_load_dwordx4 v[50:53], v0, s[2:3] offset:2048
	global_load_dwordx4 v[54:57], v0, s[2:3] offset:2064
	s_waitcnt vmcnt(15)
; DI void ln_row_v(const Frame& F, f32x4 (&v)[4], float* xout, const float* g, const float* b, const float* sh, const float* sc, bf16_t* hout, const float* slab, const float* gres, float* stat = nullptr) {
;     ...
;         float s = 0.f, s2 = 0.f;
; #pragma unroll
;         for (int j = 0; j < 4; ++j) { s += (v[j][0] + v[j][1]) + (v[j][2] + v[j][3]); s2 += (v[j][0] * v[j][0] + v[j][1] * v[j][1]) + (v[j][2] * v[j][2] + v[j][3] * v[j][3]); }
;         wave_sum2(s, s2, F.lane);
;         const float mean = s * (1.f / D); const float rstd = 1.f / sqrtf(fmaxf(s2 * (1.f / D) - mean * mean, 0.f) + EPS);
;         if (stat && F.lane == 0) { f32x2 sv = {mean, rstd}; *(f32x2*)stat = sv; }
	v_add_f32_e32 v9, v58, v59
	v_add_f32_e32 v91, v60, v61
	v_mul_f32_e32 v90, v58, v58
	v_mul_f32_e32 v92, v59, v59
	v_add_f32_e32 v9, v9, v62
	v_add_f32_e32 v91, v91, v63
	v_add_f32_e32 v9, v9, v64
	v_add_f32_e32 v91, v91, v65
	v_add_f32_e32 v9, v9, v66
	v_add_f32_e32 v91, v91, v67
	v_add_f32_e32 v9, v9, v68
	v_add_f32_e32 v91, v91, v69
	v_add_f32_e32 v9, v9, v70
	v_add_f32_e32 v91, v91, v71
	v_add_f32_e32 v9, v9, v72
	v_add_f32_e32 v91, v91, v73
	v_fmac_f32_e32 v90, v60, v60
	v_fmac_f32_e32 v92, v61, v61
	v_fmac_f32_e32 v90, v62, v62
	v_fmac_f32_e32 v92, v63, v63
	v_fmac_f32_e32 v90, v64, v64
	v_fmac_f32_e32 v92, v65, v65
	v_fmac_f32_e32 v90, v66, v66
	v_fmac_f32_e32 v92, v67, v67
	v_fmac_f32_e32 v90, v68, v68
	v_fmac_f32_e32 v92, v69, v69
	v_fmac_f32_e32 v90, v70, v70
	v_fmac_f32_e32 v92, v71, v71
	v_fmac_f32_e32 v90, v72, v72
	v_fmac_f32_e32 v92, v73, v73
	v_add_f32_e32 v9, v9, v91
	v_add_f32_e32 v90, v90, v92
	s_nop 1
	v_add_f32_dpp v9, v9, v9 quad_perm:[1,0,3,2] row_mask:0xf bank_mask:0xf
	v_add_f32_dpp v90, v90, v90 quad_perm:[1,0,3,2] row_mask:0xf bank_mask:0xf
	s_nop 0
	v_add_f32_dpp v9, v9, v9 quad_perm:[2,3,0,1] row_mask:0xf bank_mask:0xf
	v_add_f32_dpp v90, v90, v90 quad_perm:[2,3,0,1] row_mask:0xf bank_mask:0xf
	s_nop 0
	v_add_f32_dpp v9, v9, v9 row_half_mirror row_mask:0xf bank_mask:0xf
	v_add_f32_dpp v90, v90, v90 row_half_mirror row_mask:0xf bank_mask:0xf
	s_nop 0
	v_add_f32_dpp v9, v9, v9 row_mirror row_mask:0xf bank_mask:0xf
	v_add_f32_dpp v90, v90, v90 row_mirror row_mask:0xf bank_mask:0xf
	s_nop 0
	v_add_f32_dpp v9, v9, v9 row_bcast:15 row_mask:0xa bank_mask:0xf
	v_add_f32_dpp v90, v90, v90 row_bcast:15 row_mask:0xa bank_mask:0xf
	s_nop 0
	v_add_f32_dpp v9, v9, v9 row_bcast:31 row_mask:0xc bank_mask:0xf
	v_add_f32_dpp v90, v90, v90 row_bcast:31 row_mask:0xc bank_mask:0xf
	s_nop 0
	v_readlane_b32 s2, v9, 63
	v_readlane_b32 s3, v90, 63
	s_nop 1
	v_mov_b32_e32 v9, s2
	v_mov_b32_e32 v90, s3
	v_mul_f32_e32 v93, 0x3a800000, v9
	v_mul_f32_e32 v91, 0x3a800000, v90
	v_fma_f32 v91, -v93, v93, v91
	v_max_f32_e32 v91, 0, v91
	v_add_f32_e32 v91, 0x358637bd, v91
	v_rsq_f32_e32 v94, v91
	v_mul_f32_e32 v91, 0.5, v91
	v_mul_f32_e32 v92, v94, v94
	v_fma_f32 v92, -v91, v92, 0.5
	v_fma_f32 v94, v94, v92, v94
	s_add_u32 s2, s12, 0x8
	s_addc_u32 s3, s13, 0
	v_mov_b32_e32 v188, v93
	v_mov_b32_e32 v189, v94
	s_mov_b64 exec, 1
	global_store_dwordx2 v97, v[188:189], s[2:3]
	s_mov_b64 exec, -1
	v_sub_f32_e32 v58, v58, v93
	v_sub_f32_e32 v59, v59, v93
	v_sub_f32_e32 v60, v60, v93
	v_sub_f32_e32 v61, v61, v93
	v_sub_f32_e32 v62, v62, v93
	v_sub_f32_e32 v63, v63, v93
	v_sub_f32_e32 v64, v64, v93
	v_sub_f32_e32 v65, v65, v93
	v_sub_f32_e32 v66, v66, v93
	v_sub_f32_e32 v67, v67, v93
	v_sub_f32_e32 v68, v68, v93
	v_sub_f32_e32 v69, v69, v93
	v_sub_f32_e32 v70, v70, v93
	v_sub_f32_e32 v71, v71, v93
	v_sub_f32_e32 v72, v72, v93
	v_sub_f32_e32 v73, v73, v93
	v_mul_f32_e32 v58, v94, v58
	v_mul_f32_e32 v59, v94, v59
	v_mul_f32_e32 v60, v94, v60
	v_mul_f32_e32 v61, v94, v61
	v_mul_f32_e32 v62, v94, v62
	v_mul_f32_e32 v63, v94, v63
	v_mul_f32_e32 v64, v94, v64
	v_mul_f32_e32 v65, v94, v65
	v_mul_f32_e32 v66, v94, v66
	v_mul_f32_e32 v67, v94, v67
	v_mul_f32_e32 v68, v94, v68
	v_mul_f32_e32 v69, v94, v69
	v_mul_f32_e32 v70, v94, v70
	v_mul_f32_e32 v71, v94, v71
	v_mul_f32_e32 v72, v94, v72
	v_mul_f32_e32 v73, v94, v73
	v_fma_f32 v58, v58, v10, v26
	v_fma_f32 v59, v59, v11, v27
	v_fma_f32 v60, v60, v12, v28
	v_fma_f32 v61, v61, v13, v29
	v_fma_f32 v62, v62, v14, v30
	v_fma_f32 v63, v63, v15, v31
	v_fma_f32 v64, v64, v16, v32
	v_fma_f32 v65, v65, v17, v33
	v_fma_f32 v66, v66, v18, v34
	v_fma_f32 v67, v67, v19, v35
	v_fma_f32 v68, v68, v20, v36
	v_fma_f32 v69, v69, v21, v37
	v_fma_f32 v70, v70, v22, v38
	v_fma_f32 v71, v71, v23, v39
	v_fma_f32 v72, v72, v24, v40
	v_fma_f32 v73, v73, v25, v41
	v_add_f32_e32 v9, v58, v59
	v_add_f32_e32 v91, v60, v61
	v_mul_f32_e32 v90, v58, v58
	v_mul_f32_e32 v92, v59, v59
	v_add_f32_e32 v9, v9, v62
	v_add_f32_e32 v91, v91, v63
	v_add_f32_e32 v9, v9, v64
	v_add_f32_e32 v91, v91, v65
	v_add_f32_e32 v9, v9, v66
	v_add_f32_e32 v91, v91, v67
	v_add_f32_e32 v9, v9, v68
	v_add_f32_e32 v91, v91, v69
	v_add_f32_e32 v9, v9, v70
	v_add_f32_e32 v91, v91, v71
	v_add_f32_e32 v9, v9, v72
	v_add_f32_e32 v91, v91, v73
	v_fmac_f32_e32 v90, v60, v60
	v_fmac_f32_e32 v92, v61, v61
	v_fmac_f32_e32 v90, v62, v62
	v_fmac_f32_e32 v92, v63, v63
	v_fmac_f32_e32 v90, v64, v64
	v_fmac_f32_e32 v92, v65, v65
	v_fmac_f32_e32 v90, v66, v66
	v_fmac_f32_e32 v92, v67, v67
	v_fmac_f32_e32 v90, v68, v68
	v_fmac_f32_e32 v92, v69, v69
	v_fmac_f32_e32 v90, v70, v70
	v_fmac_f32_e32 v92, v71, v71
	v_fmac_f32_e32 v90, v72, v72
	v_fmac_f32_e32 v92, v73, v73
	v_add_f32_e32 v9, v9, v91
	v_add_f32_e32 v90, v90, v92
	s_nop 1
	v_add_f32_dpp v9, v9, v9 quad_perm:[1,0,3,2] row_mask:0xf bank_mask:0xf
	v_add_f32_dpp v90, v90, v90 quad_perm:[1,0,3,2] row_mask:0xf bank_mask:0xf
	s_nop 0
	v_add_f32_dpp v9, v9, v9 quad_perm:[2,3,0,1] row_mask:0xf bank_mask:0xf
	v_add_f32_dpp v90, v90, v90 quad_perm:[2,3,0,1] row_mask:0xf bank_mask:0xf
	s_nop 0
	v_add_f32_dpp v9, v9, v9 row_half_mirror row_mask:0xf bank_mask:0xf
	v_add_f32_dpp v90, v90, v90 row_half_mirror row_mask:0xf bank_mask:0xf
	s_nop 0
	v_add_f32_dpp v9, v9, v9 row_mirror row_mask:0xf bank_mask:0xf
	v_add_f32_dpp v90, v90, v90 row_mirror row_mask:0xf bank_mask:0xf
	s_nop 0
	v_add_f32_dpp v9, v9, v9 row_bcast:15 row_mask:0xa bank_mask:0xf
	v_add_f32_dpp v90, v90, v90 row_bcast:15 row_mask:0xa bank_mask:0xf
	s_nop 0
	v_add_f32_dpp v9, v9, v9 row_bcast:31 row_mask:0xc bank_mask:0xf
	v_add_f32_dpp v90, v90, v90 row_bcast:31 row_mask:0xc bank_mask:0xf
; DI unsigned pk2(float lo, float hi) { f32x2 v = {lo, hi}; bf16x2_t b = __builtin_convertvector(v, bf16x2_t); return __builtin_bit_cast(unsigned, b); }
; DI void ln_row_v(const Frame& F, f32x4 (&v)[4], float* xout, const float* g, const float* b, const float* sh, const float* sc, bf16_t* hout, const float* slab, const float* gres, float* stat = nullptr) {
;     ...
;         float s = 0.f, s2 = 0.f;
; #pragma unroll
;         for (int j = 0; j < 4; ++j) { s += (v[j][0] + v[j][1]) + (v[j][2] + v[j][3]); s2 += (v[j][0] * v[j][0] + v[j][1] * v[j][1]) + (v[j][2] * v[j][2] + v[j][3] * v[j][3]); }
;         wave_sum2(s, s2, F.lane);
;         const float mean = s * (1.f / D); const float rstd = 1.f / sqrtf(fmaxf(s2 * (1.f / D) - mean * mean, 0.f) + EPS);
;         if (stat && F.lane == 0) { f32x2 sv = {mean, rstd}; *(f32x2*)stat = sv; }
;     ...
;     if (hout) {
;         float s = 0.f, s2 = 0.f;
; #pragma unroll
;         for (int j = 0; j < 4; ++j) { s += (v[j][0] + v[j][1]) + (v[j][2] + v[j][3]); s2 += (v[j][0] * v[j][0] + v[j][1] * v[j][1]) + (v[j][2] * v[j][2] + v[j][3] * v[j][3]); }
;         wave_sum2(s, s2, F.lane);
;         const float mean = s * (1.f / D); const float rstd = 1.f / sqrtf(fmaxf(s2 * (1.f / D) - mean * mean, 0.f) + EPS);
; #pragma unroll
;         for (int j = 0; j < 4; ++j) { const f32x4 hh = ((const f32x4*)sh)[F.lane + 64 * j], cc = ((const f32x4*)sc)[F.lane + 64 * j];
;             const f32x4 o = (v[j] - mean) * rstd * (cc + 1.f) + hh; u32x2 wv; wv.x = pk2(o[0], o[1]); wv.y = pk2(o[2], o[3]);
;             ((u32x2*)hout)[F.lane + 64 * j] = wv; }
;     }
	s_nop 0
	v_readlane_b32 s2, v9, 63
	v_readlane_b32 s3, v90, 63
	s_nop 1
	v_mov_b32_e32 v9, s2
	v_mov_b32_e32 v90, s3
	v_mul_f32_e32 v93, 0x3a800000, v9
	v_mul_f32_e32 v91, 0x3a800000, v90
	v_fma_f32 v91, -v93, v93, v91
	v_max_f32_e32 v91, 0, v91
	v_add_f32_e32 v91, 0x358637bd, v91
	v_rsq_f32_e32 v94, v91
	v_mul_f32_e32 v91, 0.5, v91
	v_mul_f32_e32 v92, v94, v94
	v_fma_f32 v92, -v91, v92, 0.5
	v_fma_f32 v94, v94, v92, v94
	v_sub_f32_e32 v58, v58, v93
	v_sub_f32_e32 v59, v59, v93
	v_sub_f32_e32 v60, v60, v93
	v_sub_f32_e32 v61, v61, v93
	v_sub_f32_e32 v62, v62, v93
	v_sub_f32_e32 v63, v63, v93
	v_sub_f32_e32 v64, v64, v93
	v_sub_f32_e32 v65, v65, v93
	v_sub_f32_e32 v66, v66, v93
	v_sub_f32_e32 v67, v67, v93
	v_sub_f32_e32 v68, v68, v93
	v_sub_f32_e32 v69, v69, v93
	v_sub_f32_e32 v70, v70, v93
	v_sub_f32_e32 v71, v71, v93
	v_sub_f32_e32 v72, v72, v93
	v_sub_f32_e32 v73, v73, v93
	v_mul_f32_e32 v58, v94, v58
	v_mul_f32_e32 v59, v94, v59
	v_mul_f32_e32 v60, v94, v60
	v_mul_f32_e32 v61, v94, v61
	v_mul_f32_e32 v62, v94, v62
	v_mul_f32_e32 v63, v94, v63
	v_mul_f32_e32 v64, v94, v64
	v_mul_f32_e32 v65, v94, v65
	v_mul_f32_e32 v66, v94, v66
	v_mul_f32_e32 v67, v94, v67
	v_mul_f32_e32 v68, v94, v68
	v_mul_f32_e32 v69, v94, v69
	v_mul_f32_e32 v70, v94, v70
	v_mul_f32_e32 v71, v94, v71
	v_mul_f32_e32 v72, v94, v72
	v_mul_f32_e32 v73, v94, v73
	v_fma_f32 v58, v58, v130, v114
	v_fma_f32 v59, v59, v131, v115
	v_fma_f32 v60, v60, v132, v116
	v_fma_f32 v61, v61, v133, v117
	v_fma_f32 v62, v62, v134, v118
	v_fma_f32 v63, v63, v135, v119
	v_fma_f32 v64, v64, v136, v120
	v_fma_f32 v65, v65, v137, v121
	v_fma_f32 v66, v66, v138, v122
	v_fma_f32 v67, v67, v139, v123
	v_fma_f32 v68, v68, v140, v124
	v_fma_f32 v69, v69, v141, v125
	v_fma_f32 v70, v70, v142, v126
	v_fma_f32 v71, v71, v143, v127
	v_fma_f32 v72, v72, v144, v128
	v_fma_f32 v73, v73, v145, v129
	v_cvt_pk_bf16_f32 v190, v58, v59
	v_cvt_pk_bf16_f32 v191, v60, v61
	v_cvt_pk_bf16_f32 v192, v62, v63
	v_cvt_pk_bf16_f32 v193, v64, v65
	v_cvt_pk_bf16_f32 v194, v66, v67
	v_cvt_pk_bf16_f32 v195, v68, v69
	v_cvt_pk_bf16_f32 v196, v70, v71
	v_cvt_pk_bf16_f32 v197, v72, v73
	s_add_u32 s2, s10, 0x800
	s_addc_u32 s3, s11, 0
	global_store_dwordx4 v1, v[190:193], s[2:3]
	global_store_dwordx4 v1, v[194:197], s[2:3] offset:1024
	s_add_u32 s2, s8, 0x5000
	s_addc_u32 s3, s9, 0
	global_load_dwordx4 v[58:61], v0, s[2:3]
	global_load_dwordx4 v[62:65], v0, s[2:3] offset:16
	global_load_dwordx4 v[66:69], v0, s[2:3] offset:2048
	global_load_dwordx4 v[70:73], v0, s[2:3] offset:2064
	s_waitcnt vmcnt(18)
	v_add_f32_e32 v9, v74, v75
	v_add_f32_e32 v91, v76, v77
	v_mul_f32_e32 v90, v74, v74
	v_mul_f32_e32 v92, v75, v75
	v_add_f32_e32 v9, v9, v78
	v_add_f32_e32 v91, v91, v79
	v_add_f32_e32 v9, v9, v80
	v_add_f32_e32 v91, v91, v81
	v_add_f32_e32 v9, v9, v82
	v_add_f32_e32 v91, v91, v83
	v_add_f32_e32 v9, v9, v84
	v_add_f32_e32 v91, v91, v85
	v_add_f32_e32 v9, v9, v86
	v_add_f32_e32 v91, v91, v87
	v_add_f32_e32 v9, v9, v88
	v_add_f32_e32 v91, v91, v89
	v_fmac_f32_e32 v90, v76, v76
	v_fmac_f32_e32 v92, v77, v77
	v_fmac_f32_e32 v90, v78, v78
	v_fmac_f32_e32 v92, v79, v79
	v_fmac_f32_e32 v90, v80, v80
	v_fmac_f32_e32 v92, v81, v81
	v_fmac_f32_e32 v90, v82, v82
	v_fmac_f32_e32 v92, v83, v83
	v_fmac_f32_e32 v90, v84, v84
	v_fmac_f32_e32 v92, v85, v85
	v_fmac_f32_e32 v90, v86, v86
	v_fmac_f32_e32 v92, v87, v87
	v_fmac_f32_e32 v90, v88, v88
	v_fmac_f32_e32 v92, v89, v89
	v_add_f32_e32 v9, v9, v91
	v_add_f32_e32 v90, v90, v92
	s_nop 1
	v_add_f32_dpp v9, v9, v9 quad_perm:[1,0,3,2] row_mask:0xf bank_mask:0xf
	v_add_f32_dpp v90, v90, v90 quad_perm:[1,0,3,2] row_mask:0xf bank_mask:0xf
	s_nop 0
	v_add_f32_dpp v9, v9, v9 quad_perm:[2,3,0,1] row_mask:0xf bank_mask:0xf
	v_add_f32_dpp v90, v90, v90 quad_perm:[2,3,0,1] row_mask:0xf bank_mask:0xf
	s_nop 0
	v_add_f32_dpp v9, v9, v9 row_half_mirror row_mask:0xf bank_mask:0xf
	v_add_f32_dpp v90, v90, v90 row_half_mirror row_mask:0xf bank_mask:0xf
	s_nop 0
	v_add_f32_dpp v9, v9, v9 row_mirror row_mask:0xf bank_mask:0xf
	v_add_f32_dpp v90, v90, v90 row_mirror row_mask:0xf bank_mask:0xf
	s_nop 0
	v_add_f32_dpp v9, v9, v9 row_bcast:15 row_mask:0xa bank_mask:0xf
	v_add_f32_dpp v90, v90, v90 row_bcast:15 row_mask:0xa bank_mask:0xf
	s_nop 0
	v_add_f32_dpp v9, v9, v9 row_bcast:31 row_mask:0xc bank_mask:0xf
	v_add_f32_dpp v90, v90, v90 row_bcast:31 row_mask:0xc bank_mask:0xf
	s_nop 0
	v_readlane_b32 s2, v9, 63
	v_readlane_b32 s3, v90, 63
	s_nop 1
	v_mov_b32_e32 v9, s2
	v_mov_b32_e32 v90, s3
	v_mul_f32_e32 v93, 0x3a800000, v9
	v_mul_f32_e32 v91, 0x3a800000, v90
	v_fma_f32 v91, -v93, v93, v91
	v_max_f32_e32 v91, 0, v91
	v_add_f32_e32 v91, 0x358637bd, v91
	v_rsq_f32_e32 v94, v91
	v_mul_f32_e32 v91, 0.5, v91
	v_mul_f32_e32 v92, v94, v94
	v_fma_f32 v92, -v91, v92, 0.5
	v_fma_f32 v94, v94, v92, v94
	s_add_u32 s2, s12, 0x10
	s_addc_u32 s3, s13, 0
	v_mov_b32_e32 v188, v93
	v_mov_b32_e32 v189, v94
	s_mov_b64 exec, 1
	global_store_dwordx2 v97, v[188:189], s[2:3]
	s_mov_b64 exec, -1
	v_sub_f32_e32 v74, v74, v93
	v_sub_f32_e32 v75, v75, v93
	v_sub_f32_e32 v76, v76, v93
	v_sub_f32_e32 v77, v77, v93
	v_sub_f32_e32 v78, v78, v93
	v_sub_f32_e32 v79, v79, v93
	v_sub_f32_e32 v80, v80, v93
	v_sub_f32_e32 v81, v81, v93
	v_sub_f32_e32 v82, v82, v93
	v_sub_f32_e32 v83, v83, v93
	v_sub_f32_e32 v84, v84, v93
	v_sub_f32_e32 v85, v85, v93
	v_sub_f32_e32 v86, v86, v93
	v_sub_f32_e32 v87, v87, v93
	v_sub_f32_e32 v88, v88, v93
	v_sub_f32_e32 v89, v89, v93
	v_mul_f32_e32 v74, v94, v74
	v_mul_f32_e32 v75, v94, v75
	v_mul_f32_e32 v76, v94, v76
	v_mul_f32_e32 v77, v94, v77
	v_mul_f32_e32 v78, v94, v78
	v_mul_f32_e32 v79, v94, v79
; DI unsigned pk2(float lo, float hi) { f32x2 v = {lo, hi}; bf16x2_t b = __builtin_convertvector(v, bf16x2_t); return __builtin_bit_cast(unsigned, b); }
; DI void ln_row_v(const Frame& F, f32x4 (&v)[4], float* xout, const float* g, const float* b, const float* sh, const float* sc, bf16_t* hout, const float* slab, const float* gres, float* stat = nullptr) {
;     ...
;         float s = 0.f, s2 = 0.f;
; #pragma unroll
;         for (int j = 0; j < 4; ++j) { s += (v[j][0] + v[j][1]) + (v[j][2] + v[j][3]); s2 += (v[j][0] * v[j][0] + v[j][1] * v[j][1]) + (v[j][2] * v[j][2] + v[j][3] * v[j][3]); }
;         wave_sum2(s, s2, F.lane);
;         const float mean = s * (1.f / D); const float rstd = 1.f / sqrtf(fmaxf(s2 * (1.f / D) - mean * mean, 0.f) + EPS);
;         if (stat && F.lane == 0) { f32x2 sv = {mean, rstd}; *(f32x2*)stat = sv; }
; #pragma unroll
;         for (int j = 0; j < 4; ++j) { const f32x4 gg = ((const f32x4*)g)[F.lane + 64 * j], bb = ((const f32x4*)b)[F.lane + 64 * j];
;             v[j] = (v[j] - mean) * rstd * gg + bb; if (xout) ((f32x4*)xout)[F.lane + 64 * j] = v[j]; }
;     }
;     if (hout) {
;         float s = 0.f, s2 = 0.f;
; #pragma unroll
;         for (int j = 0; j < 4; ++j) { s += (v[j][0] + v[j][1]) + (v[j][2] + v[j][3]); s2 += (v[j][0] * v[j][0] + v[j][1] * v[j][1]) + (v[j][2] * v[j][2] + v[j][3] * v[j][3]); }
;         wave_sum2(s, s2, F.lane);
;         const float mean = s * (1.f / D); const float rstd = 1.f / sqrtf(fmaxf(s2 * (1.f / D) - mean * mean, 0.f) + EPS);
; #pragma unroll
;         for (int j = 0; j < 4; ++j) { const f32x4 hh = ((const f32x4*)sh)[F.lane + 64 * j], cc = ((const f32x4*)sc)[F.lane + 64 * j];
;             const f32x4 o = (v[j] - mean) * rstd * (cc + 1.f) + hh; u32x2 wv; wv.x = pk2(o[0], o[1]); wv.y = pk2(o[2], o[3]);
;             ((u32x2*)hout)[F.lane + 64 * j] = wv; }
;     }
	v_mul_f32_e32 v80, v94, v80
	v_mul_f32_e32 v81, v94, v81
	v_mul_f32_e32 v82, v94, v82
	v_mul_f32_e32 v83, v94, v83
	v_mul_f32_e32 v84, v94, v84
	v_mul_f32_e32 v85, v94, v85
	v_mul_f32_e32 v86, v94, v86
	v_mul_f32_e32 v87, v94, v87
	v_mul_f32_e32 v88, v94, v88
	v_mul_f32_e32 v89, v94, v89
	v_fma_f32 v74, v74, v10, v26
	v_fma_f32 v75, v75, v11, v27
	v_fma_f32 v76, v76, v12, v28
	v_fma_f32 v77, v77, v13, v29
	v_fma_f32 v78, v78, v14, v30
	v_fma_f32 v79, v79, v15, v31
	v_fma_f32 v80, v80, v16, v32
	v_fma_f32 v81, v81, v17, v33
	v_fma_f32 v82, v82, v18, v34
	v_fma_f32 v83, v83, v19, v35
	v_fma_f32 v84, v84, v20, v36
	v_fma_f32 v85, v85, v21, v37
	v_fma_f32 v86, v86, v22, v38
	v_fma_f32 v87, v87, v23, v39
	v_fma_f32 v88, v88, v24, v40
	v_fma_f32 v89, v89, v25, v41
	v_add_f32_e32 v9, v74, v75
	v_add_f32_e32 v91, v76, v77
	v_mul_f32_e32 v90, v74, v74
	v_mul_f32_e32 v92, v75, v75
	v_add_f32_e32 v9, v9, v78
	v_add_f32_e32 v91, v91, v79
	v_add_f32_e32 v9, v9, v80
	v_add_f32_e32 v91, v91, v81
	v_add_f32_e32 v9, v9, v82
	v_add_f32_e32 v91, v91, v83
	v_add_f32_e32 v9, v9, v84
	v_add_f32_e32 v91, v91, v85
	v_add_f32_e32 v9, v9, v86
	v_add_f32_e32 v91, v91, v87
	v_add_f32_e32 v9, v9, v88
	v_add_f32_e32 v91, v91, v89
	v_fmac_f32_e32 v90, v76, v76
	v_fmac_f32_e32 v92, v77, v77
	v_fmac_f32_e32 v90, v78, v78
	v_fmac_f32_e32 v92, v79, v79
	v_fmac_f32_e32 v90, v80, v80
	v_fmac_f32_e32 v92, v81, v81
	v_fmac_f32_e32 v90, v82, v82
	v_fmac_f32_e32 v92, v83, v83
	v_fmac_f32_e32 v90, v84, v84
	v_fmac_f32_e32 v92, v85, v85
	v_fmac_f32_e32 v90, v86, v86
	v_fmac_f32_e32 v92, v87, v87
	v_fmac_f32_e32 v90, v88, v88
	v_fmac_f32_e32 v92, v89, v89
	v_add_f32_e32 v9, v9, v91
	v_add_f32_e32 v90, v90, v92
	s_nop 1
	v_add_f32_dpp v9, v9, v9 quad_perm:[1,0,3,2] row_mask:0xf bank_mask:0xf
	v_add_f32_dpp v90, v90, v90 quad_perm:[1,0,3,2] row_mask:0xf bank_mask:0xf
	s_nop 0
	v_add_f32_dpp v9, v9, v9 quad_perm:[2,3,0,1] row_mask:0xf bank_mask:0xf
	v_add_f32_dpp v90, v90, v90 quad_perm:[2,3,0,1] row_mask:0xf bank_mask:0xf
	s_nop 0
	v_add_f32_dpp v9, v9, v9 row_half_mirror row_mask:0xf bank_mask:0xf
	v_add_f32_dpp v90, v90, v90 row_half_mirror row_mask:0xf bank_mask:0xf
	s_nop 0
	v_add_f32_dpp v9, v9, v9 row_mirror row_mask:0xf bank_mask:0xf
	v_add_f32_dpp v90, v90, v90 row_mirror row_mask:0xf bank_mask:0xf
	s_nop 0
	v_add_f32_dpp v9, v9, v9 row_bcast:15 row_mask:0xa bank_mask:0xf
	v_add_f32_dpp v90, v90, v90 row_bcast:15 row_mask:0xa bank_mask:0xf
	s_nop 0
	v_add_f32_dpp v9, v9, v9 row_bcast:31 row_mask:0xc bank_mask:0xf
	v_add_f32_dpp v90, v90, v90 row_bcast:31 row_mask:0xc bank_mask:0xf
	s_nop 0
	v_readlane_b32 s2, v9, 63
	v_readlane_b32 s3, v90, 63
	s_nop 1
	v_mov_b32_e32 v9, s2
	v_mov_b32_e32 v90, s3
	v_mul_f32_e32 v93, 0x3a800000, v9
	v_mul_f32_e32 v91, 0x3a800000, v90
	v_fma_f32 v91, -v93, v93, v91
	v_max_f32_e32 v91, 0, v91
	v_add_f32_e32 v91, 0x358637bd, v91
	v_rsq_f32_e32 v94, v91
	v_mul_f32_e32 v91, 0.5, v91
	v_mul_f32_e32 v92, v94, v94
	v_fma_f32 v92, -v91, v92, 0.5
	v_fma_f32 v94, v94, v92, v94
	v_sub_f32_e32 v74, v74, v93
	v_sub_f32_e32 v75, v75, v93
	v_sub_f32_e32 v76, v76, v93
	v_sub_f32_e32 v77, v77, v93
	v_sub_f32_e32 v78, v78, v93
	v_sub_f32_e32 v79, v79, v93
	v_sub_f32_e32 v80, v80, v93
	v_sub_f32_e32 v81, v81, v93
	v_sub_f32_e32 v82, v82, v93
	v_sub_f32_e32 v83, v83, v93
	v_sub_f32_e32 v84, v84, v93
	v_sub_f32_e32 v85, v85, v93
	v_sub_f32_e32 v86, v86, v93
	v_sub_f32_e32 v87, v87, v93
	v_sub_f32_e32 v88, v88, v93
	v_sub_f32_e32 v89, v89, v93
	v_mul_f32_e32 v74, v94, v74
	v_mul_f32_e32 v75, v94, v75
	v_mul_f32_e32 v76, v94, v76
	v_mul_f32_e32 v77, v94, v77
	v_mul_f32_e32 v78, v94, v78
	v_mul_f32_e32 v79, v94, v79
	v_mul_f32_e32 v80, v94, v80
	v_mul_f32_e32 v81, v94, v81
	v_mul_f32_e32 v82, v94, v82
	v_mul_f32_e32 v83, v94, v83
	v_mul_f32_e32 v84, v94, v84
	v_mul_f32_e32 v85, v94, v85
	v_mul_f32_e32 v86, v94, v86
	v_mul_f32_e32 v87, v94, v87
	v_mul_f32_e32 v88, v94, v88
	v_mul_f32_e32 v89, v94, v89
	v_fma_f32 v74, v74, v130, v114
	v_fma_f32 v75, v75, v131, v115
	v_fma_f32 v76, v76, v132, v116
	v_fma_f32 v77, v77, v133, v117
	v_fma_f32 v78, v78, v134, v118
	v_fma_f32 v79, v79, v135, v119
	v_fma_f32 v80, v80, v136, v120
	v_fma_f32 v81, v81, v137, v121
	v_fma_f32 v82, v82, v138, v122
	v_fma_f32 v83, v83, v139, v123
	v_fma_f32 v84, v84, v140, v124
	v_fma_f32 v85, v85, v141, v125
	v_fma_f32 v86, v86, v142, v126
	v_fma_f32 v87, v87, v143, v127
	v_fma_f32 v88, v88, v144, v128
	v_fma_f32 v89, v89, v145, v129
	v_cvt_pk_bf16_f32 v190, v74, v75
	v_cvt_pk_bf16_f32 v191, v76, v77
	v_cvt_pk_bf16_f32 v192, v78, v79
	v_cvt_pk_bf16_f32 v193, v80, v81
	v_cvt_pk_bf16_f32 v194, v82, v83
	v_cvt_pk_bf16_f32 v195, v84, v85
	v_cvt_pk_bf16_f32 v196, v86, v87
	v_cvt_pk_bf16_f32 v197, v88, v89
	s_add_u32 s2, s10, 0x1000
	s_addc_u32 s3, s11, 0
	global_store_dwordx4 v1, v[190:193], s[2:3]
	global_store_dwordx4 v1, v[194:197], s[2:3] offset:1024
	s_add_u32 s2, s8, 0x6000
	s_addc_u32 s3, s9, 0
	global_load_dwordx4 v[74:77], v0, s[2:3]
	global_load_dwordx4 v[78:81], v0, s[2:3] offset:16
	global_load_dwordx4 v[82:85], v0, s[2:3] offset:2048
	global_load_dwordx4 v[86:89], v0, s[2:3] offset:2064
	s_waitcnt vmcnt(21)
; DI void ln_row_v(const Frame& F, f32x4 (&v)[4], float* xout, const float* g, const float* b, const float* sh, const float* sc, bf16_t* hout, const float* slab, const float* gres, float* stat = nullptr) {
;     ...
;         float s = 0.f, s2 = 0.f;
; #pragma unroll
;         for (int j = 0; j < 4; ++j) { s += (v[j][0] + v[j][1]) + (v[j][2] + v[j][3]); s2 += (v[j][0] * v[j][0] + v[j][1] * v[j][1]) + (v[j][2] * v[j][2] + v[j][3] * v[j][3]); }
;         wave_sum2(s, s2, F.lane);
;         const float mean = s * (1.f / D); const float rstd = 1.f / sqrtf(fmaxf(s2 * (1.f / D) - mean * mean, 0.f) + EPS);
;         if (stat && F.lane == 0) { f32x2 sv = {mean, rstd}; *(f32x2*)stat = sv; }
; #pragma unroll
;         for (int j = 0; j < 4; ++j) { const f32x4 gg = ((const f32x4*)g)[F.lane + 64 * j], bb = ((const f32x4*)b)[F.lane + 64 * j];
;             v[j] = (v[j] - mean) * rstd * gg + bb; if (xout) ((f32x4*)xout)[F.lane + 64 * j] = v[j]; }
;     }
;     if (hout) {
;         float s = 0.f, s2 = 0.f;
; #pragma unroll
;         for (int j = 0; j < 4; ++j) { s += (v[j][0] + v[j][1]) + (v[j][2] + v[j][3]); s2 += (v[j][0] * v[j][0] + v[j][1] * v[j][1]) + (v[j][2] * v[j][2] + v[j][3] * v[j][3]); }
;         wave_sum2(s, s2, F.lane);
	v_add_f32_e32 v9, v98, v99
	v_add_f32_e32 v91, v100, v101
	v_mul_f32_e32 v90, v98, v98
	v_mul_f32_e32 v92, v99, v99
	v_add_f32_e32 v9, v9, v102
	v_add_f32_e32 v91, v91, v103
	v_add_f32_e32 v9, v9, v104
	v_add_f32_e32 v91, v91, v105
	v_add_f32_e32 v9, v9, v106
	v_add_f32_e32 v91, v91, v107
	v_add_f32_e32 v9, v9, v108
	v_add_f32_e32 v91, v91, v109
	v_add_f32_e32 v9, v9, v110
	v_add_f32_e32 v91, v91, v111
	v_add_f32_e32 v9, v9, v112
	v_add_f32_e32 v91, v91, v113
	v_fmac_f32_e32 v90, v100, v100
	v_fmac_f32_e32 v92, v101, v101
	v_fmac_f32_e32 v90, v102, v102
	v_fmac_f32_e32 v92, v103, v103
	v_fmac_f32_e32 v90, v104, v104
	v_fmac_f32_e32 v92, v105, v105
	v_fmac_f32_e32 v90, v106, v106
	v_fmac_f32_e32 v92, v107, v107
	v_fmac_f32_e32 v90, v108, v108
	v_fmac_f32_e32 v92, v109, v109
	v_fmac_f32_e32 v90, v110, v110
	v_fmac_f32_e32 v92, v111, v111
	v_fmac_f32_e32 v90, v112, v112
	v_fmac_f32_e32 v92, v113, v113
	v_add_f32_e32 v9, v9, v91
	v_add_f32_e32 v90, v90, v92
	s_nop 1
	v_add_f32_dpp v9, v9, v9 quad_perm:[1,0,3,2] row_mask:0xf bank_mask:0xf
	v_add_f32_dpp v90, v90, v90 quad_perm:[1,0,3,2] row_mask:0xf bank_mask:0xf
	s_nop 0
	v_add_f32_dpp v9, v9, v9 quad_perm:[2,3,0,1] row_mask:0xf bank_mask:0xf
	v_add_f32_dpp v90, v90, v90 quad_perm:[2,3,0,1] row_mask:0xf bank_mask:0xf
	s_nop 0
	v_add_f32_dpp v9, v9, v9 row_half_mirror row_mask:0xf bank_mask:0xf
	v_add_f32_dpp v90, v90, v90 row_half_mirror row_mask:0xf bank_mask:0xf
	s_nop 0
	v_add_f32_dpp v9, v9, v9 row_mirror row_mask:0xf bank_mask:0xf
	v_add_f32_dpp v90, v90, v90 row_mirror row_mask:0xf bank_mask:0xf
	s_nop 0
	v_add_f32_dpp v9, v9, v9 row_bcast:15 row_mask:0xa bank_mask:0xf
	v_add_f32_dpp v90, v90, v90 row_bcast:15 row_mask:0xa bank_mask:0xf
	s_nop 0
	v_add_f32_dpp v9, v9, v9 row_bcast:31 row_mask:0xc bank_mask:0xf
	v_add_f32_dpp v90, v90, v90 row_bcast:31 row_mask:0xc bank_mask:0xf
	s_nop 0
	v_readlane_b32 s2, v9, 63
	v_readlane_b32 s3, v90, 63
	s_nop 1
	v_mov_b32_e32 v9, s2
	v_mov_b32_e32 v90, s3
	v_mul_f32_e32 v93, 0x3a800000, v9
	v_mul_f32_e32 v91, 0x3a800000, v90
	v_fma_f32 v91, -v93, v93, v91
	v_max_f32_e32 v91, 0, v91
	v_add_f32_e32 v91, 0x358637bd, v91
	v_rsq_f32_e32 v94, v91
	v_mul_f32_e32 v91, 0.5, v91
	v_mul_f32_e32 v92, v94, v94
	v_fma_f32 v92, -v91, v92, 0.5
	v_fma_f32 v94, v94, v92, v94
	s_add_u32 s2, s12, 0x18
	s_addc_u32 s3, s13, 0
	v_mov_b32_e32 v188, v93
	v_mov_b32_e32 v189, v94
	s_mov_b64 exec, 1
	global_store_dwordx2 v97, v[188:189], s[2:3]
	s_mov_b64 exec, -1
	v_sub_f32_e32 v98, v98, v93
	v_sub_f32_e32 v99, v99, v93
	v_sub_f32_e32 v100, v100, v93
	v_sub_f32_e32 v101, v101, v93
	v_sub_f32_e32 v102, v102, v93
	v_sub_f32_e32 v103, v103, v93
	v_sub_f32_e32 v104, v104, v93
	v_sub_f32_e32 v105, v105, v93
	v_sub_f32_e32 v106, v106, v93
	v_sub_f32_e32 v107, v107, v93
	v_sub_f32_e32 v108, v108, v93
	v_sub_f32_e32 v109, v109, v93
	v_sub_f32_e32 v110, v110, v93
	v_sub_f32_e32 v111, v111, v93
	v_sub_f32_e32 v112, v112, v93
	v_sub_f32_e32 v113, v113, v93
	v_mul_f32_e32 v98, v94, v98
	v_mul_f32_e32 v99, v94, v99
	v_mul_f32_e32 v100, v94, v100
	v_mul_f32_e32 v101, v94, v101
	v_mul_f32_e32 v102, v94, v102
	v_mul_f32_e32 v103, v94, v103
	v_mul_f32_e32 v104, v94, v104
	v_mul_f32_e32 v105, v94, v105
	v_mul_f32_e32 v106, v94, v106
	v_mul_f32_e32 v107, v94, v107
	v_mul_f32_e32 v108, v94, v108
	v_mul_f32_e32 v109, v94, v109
	v_mul_f32_e32 v110, v94, v110
	v_mul_f32_e32 v111, v94, v111
	v_mul_f32_e32 v112, v94, v112
	v_mul_f32_e32 v113, v94, v113
	v_fma_f32 v98, v98, v10, v26
	v_fma_f32 v99, v99, v11, v27
	v_fma_f32 v100, v100, v12, v28
	v_fma_f32 v101, v101, v13, v29
	v_fma_f32 v102, v102, v14, v30
	v_fma_f32 v103, v103, v15, v31
	v_fma_f32 v104, v104, v16, v32
	v_fma_f32 v105, v105, v17, v33
	v_fma_f32 v106, v106, v18, v34
	v_fma_f32 v107, v107, v19, v35
	v_fma_f32 v108, v108, v20, v36
	v_fma_f32 v109, v109, v21, v37
	v_fma_f32 v110, v110, v22, v38
	v_fma_f32 v111, v111, v23, v39
	v_fma_f32 v112, v112, v24, v40
	v_fma_f32 v113, v113, v25, v41
	v_add_f32_e32 v9, v98, v99
	v_add_f32_e32 v91, v100, v101
	v_mul_f32_e32 v90, v98, v98
	v_mul_f32_e32 v92, v99, v99
	v_add_f32_e32 v9, v9, v102
	v_add_f32_e32 v91, v91, v103
	v_add_f32_e32 v9, v9, v104
	v_add_f32_e32 v91, v91, v105
	v_add_f32_e32 v9, v9, v106
	v_add_f32_e32 v91, v91, v107
	v_add_f32_e32 v9, v9, v108
	v_add_f32_e32 v91, v91, v109
	v_add_f32_e32 v9, v9, v110
	v_add_f32_e32 v91, v91, v111
	v_add_f32_e32 v9, v9, v112
	v_add_f32_e32 v91, v91, v113
	v_fmac_f32_e32 v90, v100, v100
	v_fmac_f32_e32 v92, v101, v101
	v_fmac_f32_e32 v90, v102, v102
	v_fmac_f32_e32 v92, v103, v103
	v_fmac_f32_e32 v90, v104, v104
	v_fmac_f32_e32 v92, v105, v105
	v_fmac_f32_e32 v90, v106, v106
	v_fmac_f32_e32 v92, v107, v107
	v_fmac_f32_e32 v90, v108, v108
	v_fmac_f32_e32 v92, v109, v109
	v_fmac_f32_e32 v90, v110, v110
	v_fmac_f32_e32 v92, v111, v111
	v_fmac_f32_e32 v90, v112, v112
	v_fmac_f32_e32 v92, v113, v113
	v_add_f32_e32 v9, v9, v91
	v_add_f32_e32 v90, v90, v92
	s_nop 1
	v_add_f32_dpp v9, v9, v9 quad_perm:[1,0,3,2] row_mask:0xf bank_mask:0xf
	v_add_f32_dpp v90, v90, v90 quad_perm:[1,0,3,2] row_mask:0xf bank_mask:0xf
	s_nop 0
	v_add_f32_dpp v9, v9, v9 quad_perm:[2,3,0,1] row_mask:0xf bank_mask:0xf
	v_add_f32_dpp v90, v90, v90 quad_perm:[2,3,0,1] row_mask:0xf bank_mask:0xf
	s_nop 0
	v_add_f32_dpp v9, v9, v9 row_half_mirror row_mask:0xf bank_mask:0xf
	v_add_f32_dpp v90, v90, v90 row_half_mirror row_mask:0xf bank_mask:0xf
	s_nop 0
	v_add_f32_dpp v9, v9, v9 row_mirror row_mask:0xf bank_mask:0xf
	v_add_f32_dpp v90, v90, v90 row_mirror row_mask:0xf bank_mask:0xf
	s_nop 0
	v_add_f32_dpp v9, v9, v9 row_bcast:15 row_mask:0xa bank_mask:0xf
; DI unsigned pk2(float lo, float hi) { f32x2 v = {lo, hi}; bf16x2_t b = __builtin_convertvector(v, bf16x2_t); return __builtin_bit_cast(unsigned, b); }
; DI void ln_row_v(const Frame& F, f32x4 (&v)[4], float* xout, const float* g, const float* b, const float* sh, const float* sc, bf16_t* hout, const float* slab, const float* gres, float* stat = nullptr) {
;     ...
;         float s = 0.f, s2 = 0.f;
; #pragma unroll
;         for (int j = 0; j < 4; ++j) { s += (v[j][0] + v[j][1]) + (v[j][2] + v[j][3]); s2 += (v[j][0] * v[j][0] + v[j][1] * v[j][1]) + (v[j][2] * v[j][2] + v[j][3] * v[j][3]); }
;         wave_sum2(s, s2, F.lane);
;         const float mean = s * (1.f / D); const float rstd = 1.f / sqrtf(fmaxf(s2 * (1.f / D) - mean * mean, 0.f) + EPS);
;         if (stat && F.lane == 0) { f32x2 sv = {mean, rstd}; *(f32x2*)stat = sv; }
;     ...
;     if (hout) {
;         float s = 0.f, s2 = 0.f;
; #pragma unroll
;         for (int j = 0; j < 4; ++j) { s += (v[j][0] + v[j][1]) + (v[j][2] + v[j][3]); s2 += (v[j][0] * v[j][0] + v[j][1] * v[j][1]) + (v[j][2] * v[j][2] + v[j][3] * v[j][3]); }
;         wave_sum2(s, s2, F.lane);
;         const float mean = s * (1.f / D); const float rstd = 1.f / sqrtf(fmaxf(s2 * (1.f / D) - mean * mean, 0.f) + EPS);
; #pragma unroll
;         for (int j = 0; j < 4; ++j) { const f32x4 hh = ((const f32x4*)sh)[F.lane + 64 * j], cc = ((const f32x4*)sc)[F.lane + 64 * j];
;             const f32x4 o = (v[j] - mean) * rstd * (cc + 1.f) + hh; u32x2 wv; wv.x = pk2(o[0], o[1]); wv.y = pk2(o[2], o[3]);
;             ((u32x2*)hout)[F.lane + 64 * j] = wv; }
;     }
	v_add_f32_dpp v90, v90, v90 row_bcast:15 row_mask:0xa bank_mask:0xf
	s_nop 0
	v_add_f32_dpp v9, v9, v9 row_bcast:31 row_mask:0xc bank_mask:0xf
	v_add_f32_dpp v90, v90, v90 row_bcast:31 row_mask:0xc bank_mask:0xf
	s_nop 0
	v_readlane_b32 s2, v9, 63
	v_readlane_b32 s3, v90, 63
	s_nop 1
	v_mov_b32_e32 v9, s2
	v_mov_b32_e32 v90, s3
	v_mul_f32_e32 v93, 0x3a800000, v9
	v_mul_f32_e32 v91, 0x3a800000, v90
	v_fma_f32 v91, -v93, v93, v91
	v_max_f32_e32 v91, 0, v91
	v_add_f32_e32 v91, 0x358637bd, v91
	v_rsq_f32_e32 v94, v91
	v_mul_f32_e32 v91, 0.5, v91
	v_mul_f32_e32 v92, v94, v94
	v_fma_f32 v92, -v91, v92, 0.5
	v_fma_f32 v94, v94, v92, v94
	v_sub_f32_e32 v98, v98, v93
	v_sub_f32_e32 v99, v99, v93
	v_sub_f32_e32 v100, v100, v93
	v_sub_f32_e32 v101, v101, v93
	v_sub_f32_e32 v102, v102, v93
	v_sub_f32_e32 v103, v103, v93
	v_sub_f32_e32 v104, v104, v93
	v_sub_f32_e32 v105, v105, v93
	v_sub_f32_e32 v106, v106, v93
	v_sub_f32_e32 v107, v107, v93
	v_sub_f32_e32 v108, v108, v93
	v_sub_f32_e32 v109, v109, v93
	v_sub_f32_e32 v110, v110, v93
	v_sub_f32_e32 v111, v111, v93
	v_sub_f32_e32 v112, v112, v93
	v_sub_f32_e32 v113, v113, v93
	v_mul_f32_e32 v98, v94, v98
	v_mul_f32_e32 v99, v94, v99
	v_mul_f32_e32 v100, v94, v100
	v_mul_f32_e32 v101, v94, v101
	v_mul_f32_e32 v102, v94, v102
	v_mul_f32_e32 v103, v94, v103
	v_mul_f32_e32 v104, v94, v104
	v_mul_f32_e32 v105, v94, v105
	v_mul_f32_e32 v106, v94, v106
	v_mul_f32_e32 v107, v94, v107
	v_mul_f32_e32 v108, v94, v108
	v_mul_f32_e32 v109, v94, v109
	v_mul_f32_e32 v110, v94, v110
	v_mul_f32_e32 v111, v94, v111
	v_mul_f32_e32 v112, v94, v112
	v_mul_f32_e32 v113, v94, v113
	v_fma_f32 v98, v98, v130, v114
	v_fma_f32 v99, v99, v131, v115
	v_fma_f32 v100, v100, v132, v116
	v_fma_f32 v101, v101, v133, v117
	v_fma_f32 v102, v102, v134, v118
	v_fma_f32 v103, v103, v135, v119
	v_fma_f32 v104, v104, v136, v120
	v_fma_f32 v105, v105, v137, v121
	v_fma_f32 v106, v106, v138, v122
	v_fma_f32 v107, v107, v139, v123
	v_fma_f32 v108, v108, v140, v124
	v_fma_f32 v109, v109, v141, v125
	v_fma_f32 v110, v110, v142, v126
	v_fma_f32 v111, v111, v143, v127
	v_fma_f32 v112, v112, v144, v128
	v_fma_f32 v113, v113, v145, v129
	v_cvt_pk_bf16_f32 v190, v98, v99
	v_cvt_pk_bf16_f32 v191, v100, v101
	v_cvt_pk_bf16_f32 v192, v102, v103
	v_cvt_pk_bf16_f32 v193, v104, v105
	v_cvt_pk_bf16_f32 v194, v106, v107
	v_cvt_pk_bf16_f32 v195, v108, v109
	v_cvt_pk_bf16_f32 v196, v110, v111
	v_cvt_pk_bf16_f32 v197, v112, v113
	s_add_u32 s2, s10, 0x1800
	s_addc_u32 s3, s11, 0
	global_store_dwordx4 v1, v[190:193], s[2:3]
	global_store_dwordx4 v1, v[194:197], s[2:3] offset:1024
	s_add_u32 s2, s8, 0x7000
	s_addc_u32 s3, s9, 0
	global_load_dwordx4 v[98:101], v0, s[2:3]
	global_load_dwordx4 v[102:105], v0, s[2:3] offset:16
	global_load_dwordx4 v[106:109], v0, s[2:3] offset:2048
	global_load_dwordx4 v[110:113], v0, s[2:3] offset:2064
	s_waitcnt vmcnt(21)
	v_add_f32_e32 v9, v42, v43
	v_add_f32_e32 v91, v44, v45
	v_mul_f32_e32 v90, v42, v42
	v_mul_f32_e32 v92, v43, v43
	v_add_f32_e32 v9, v9, v46
	v_add_f32_e32 v91, v91, v47
	v_add_f32_e32 v9, v9, v48
	v_add_f32_e32 v91, v91, v49
	v_add_f32_e32 v9, v9, v50
	v_add_f32_e32 v91, v91, v51
	v_add_f32_e32 v9, v9, v52
	v_add_f32_e32 v91, v91, v53
	v_add_f32_e32 v9, v9, v54
	v_add_f32_e32 v91, v91, v55
	v_add_f32_e32 v9, v9, v56
	v_add_f32_e32 v91, v91, v57
	v_fmac_f32_e32 v90, v44, v44
	v_fmac_f32_e32 v92, v45, v45
	v_fmac_f32_e32 v90, v46, v46
	v_fmac_f32_e32 v92, v47, v47
	v_fmac_f32_e32 v90, v48, v48
	v_fmac_f32_e32 v92, v49, v49
	v_fmac_f32_e32 v90, v50, v50
	v_fmac_f32_e32 v92, v51, v51
	v_fmac_f32_e32 v90, v52, v52
	v_fmac_f32_e32 v92, v53, v53
	v_fmac_f32_e32 v90, v54, v54
	v_fmac_f32_e32 v92, v55, v55
	v_fmac_f32_e32 v90, v56, v56
	v_fmac_f32_e32 v92, v57, v57
	v_add_f32_e32 v9, v9, v91
	v_add_f32_e32 v90, v90, v92
	s_nop 1
	v_add_f32_dpp v9, v9, v9 quad_perm:[1,0,3,2] row_mask:0xf bank_mask:0xf
	v_add_f32_dpp v90, v90, v90 quad_perm:[1,0,3,2] row_mask:0xf bank_mask:0xf
	s_nop 0
	v_add_f32_dpp v9, v9, v9 quad_perm:[2,3,0,1] row_mask:0xf bank_mask:0xf
	v_add_f32_dpp v90, v90, v90 quad_perm:[2,3,0,1] row_mask:0xf bank_mask:0xf
	s_nop 0
	v_add_f32_dpp v9, v9, v9 row_half_mirror row_mask:0xf bank_mask:0xf
	v_add_f32_dpp v90, v90, v90 row_half_mirror row_mask:0xf bank_mask:0xf
	s_nop 0
	v_add_f32_dpp v9, v9, v9 row_mirror row_mask:0xf bank_mask:0xf
	v_add_f32_dpp v90, v90, v90 row_mirror row_mask:0xf bank_mask:0xf
	s_nop 0
	v_add_f32_dpp v9, v9, v9 row_bcast:15 row_mask:0xa bank_mask:0xf
	v_add_f32_dpp v90, v90, v90 row_bcast:15 row_mask:0xa bank_mask:0xf
	s_nop 0
	v_add_f32_dpp v9, v9, v9 row_bcast:31 row_mask:0xc bank_mask:0xf
	v_add_f32_dpp v90, v90, v90 row_bcast:31 row_mask:0xc bank_mask:0xf
	s_nop 0
	v_readlane_b32 s2, v9, 63
	v_readlane_b32 s3, v90, 63
	s_nop 1
	v_mov_b32_e32 v9, s2
	v_mov_b32_e32 v90, s3
	v_mul_f32_e32 v93, 0x3a800000, v9
	v_mul_f32_e32 v91, 0x3a800000, v90
	v_fma_f32 v91, -v93, v93, v91
	v_max_f32_e32 v91, 0, v91
	v_add_f32_e32 v91, 0x358637bd, v91
	v_rsq_f32_e32 v94, v91
	v_mul_f32_e32 v91, 0.5, v91
	v_mul_f32_e32 v92, v94, v94
	v_fma_f32 v92, -v91, v92, 0.5
	v_fma_f32 v94, v94, v92, v94
	s_add_u32 s2, s12, 0x20
	s_addc_u32 s3, s13, 0
	v_mov_b32_e32 v188, v93
	v_mov_b32_e32 v189, v94
	s_mov_b64 exec, 1
	global_store_dwordx2 v97, v[188:189], s[2:3]
	s_mov_b64 exec, -1
	v_sub_f32_e32 v42, v42, v93
	v_sub_f32_e32 v43, v43, v93
	v_sub_f32_e32 v44, v44, v93
	v_sub_f32_e32 v45, v45, v93
	v_sub_f32_e32 v46, v46, v93
	v_sub_f32_e32 v47, v47, v93
	v_sub_f32_e32 v48, v48, v93
	v_sub_f32_e32 v49, v49, v93
	v_sub_f32_e32 v50, v50, v93
	v_sub_f32_e32 v51, v51, v93
	v_sub_f32_e32 v52, v52, v93
; DI unsigned pk2(float lo, float hi) { f32x2 v = {lo, hi}; bf16x2_t b = __builtin_convertvector(v, bf16x2_t); return __builtin_bit_cast(unsigned, b); }
; DI void ln_row_v(const Frame& F, f32x4 (&v)[4], float* xout, const float* g, const float* b, const float* sh, const float* sc, bf16_t* hout, const float* slab, const float* gres, float* stat = nullptr) {
;     ...
;         float s = 0.f, s2 = 0.f;
; #pragma unroll
;         for (int j = 0; j < 4; ++j) { s += (v[j][0] + v[j][1]) + (v[j][2] + v[j][3]); s2 += (v[j][0] * v[j][0] + v[j][1] * v[j][1]) + (v[j][2] * v[j][2] + v[j][3] * v[j][3]); }
;         wave_sum2(s, s2, F.lane);
;         const float mean = s * (1.f / D); const float rstd = 1.f / sqrtf(fmaxf(s2 * (1.f / D) - mean * mean, 0.f) + EPS);
;         if (stat && F.lane == 0) { f32x2 sv = {mean, rstd}; *(f32x2*)stat = sv; }
; #pragma unroll
;         for (int j = 0; j < 4; ++j) { const f32x4 gg = ((const f32x4*)g)[F.lane + 64 * j], bb = ((const f32x4*)b)[F.lane + 64 * j];
;             v[j] = (v[j] - mean) * rstd * gg + bb; if (xout) ((f32x4*)xout)[F.lane + 64 * j] = v[j]; }
;     }
;     if (hout) {
;         float s = 0.f, s2 = 0.f;
; #pragma unroll
;         for (int j = 0; j < 4; ++j) { s += (v[j][0] + v[j][1]) + (v[j][2] + v[j][3]); s2 += (v[j][0] * v[j][0] + v[j][1] * v[j][1]) + (v[j][2] * v[j][2] + v[j][3] * v[j][3]); }
;         wave_sum2(s, s2, F.lane);
;         const float mean = s * (1.f / D); const float rstd = 1.f / sqrtf(fmaxf(s2 * (1.f / D) - mean * mean, 0.f) + EPS);
; #pragma unroll
;         for (int j = 0; j < 4; ++j) { const f32x4 hh = ((const f32x4*)sh)[F.lane + 64 * j], cc = ((const f32x4*)sc)[F.lane + 64 * j];
;             const f32x4 o = (v[j] - mean) * rstd * (cc + 1.f) + hh; u32x2 wv; wv.x = pk2(o[0], o[1]); wv.y = pk2(o[2], o[3]);
;             ((u32x2*)hout)[F.lane + 64 * j] = wv; }
;     }
	v_sub_f32_e32 v53, v53, v93
	v_sub_f32_e32 v54, v54, v93
	v_sub_f32_e32 v55, v55, v93
	v_sub_f32_e32 v56, v56, v93
	v_sub_f32_e32 v57, v57, v93
	v_mul_f32_e32 v42, v94, v42
	v_mul_f32_e32 v43, v94, v43
	v_mul_f32_e32 v44, v94, v44
	v_mul_f32_e32 v45, v94, v45
	v_mul_f32_e32 v46, v94, v46
	v_mul_f32_e32 v47, v94, v47
	v_mul_f32_e32 v48, v94, v48
	v_mul_f32_e32 v49, v94, v49
	v_mul_f32_e32 v50, v94, v50
	v_mul_f32_e32 v51, v94, v51
	v_mul_f32_e32 v52, v94, v52
	v_mul_f32_e32 v53, v94, v53
	v_mul_f32_e32 v54, v94, v54
	v_mul_f32_e32 v55, v94, v55
	v_mul_f32_e32 v56, v94, v56
	v_mul_f32_e32 v57, v94, v57
	v_fma_f32 v42, v42, v10, v26
	v_fma_f32 v43, v43, v11, v27
	v_fma_f32 v44, v44, v12, v28
	v_fma_f32 v45, v45, v13, v29
	v_fma_f32 v46, v46, v14, v30
	v_fma_f32 v47, v47, v15, v31
	v_fma_f32 v48, v48, v16, v32
	v_fma_f32 v49, v49, v17, v33
	v_fma_f32 v50, v50, v18, v34
	v_fma_f32 v51, v51, v19, v35
	v_fma_f32 v52, v52, v20, v36
	v_fma_f32 v53, v53, v21, v37
	v_fma_f32 v54, v54, v22, v38
	v_fma_f32 v55, v55, v23, v39
	v_fma_f32 v56, v56, v24, v40
	v_fma_f32 v57, v57, v25, v41
	v_add_f32_e32 v9, v42, v43
	v_add_f32_e32 v91, v44, v45
	v_mul_f32_e32 v90, v42, v42
	v_mul_f32_e32 v92, v43, v43
	v_add_f32_e32 v9, v9, v46
	v_add_f32_e32 v91, v91, v47
	v_add_f32_e32 v9, v9, v48
	v_add_f32_e32 v91, v91, v49
	v_add_f32_e32 v9, v9, v50
	v_add_f32_e32 v91, v91, v51
	v_add_f32_e32 v9, v9, v52
	v_add_f32_e32 v91, v91, v53
	v_add_f32_e32 v9, v9, v54
	v_add_f32_e32 v91, v91, v55
	v_add_f32_e32 v9, v9, v56
	v_add_f32_e32 v91, v91, v57
	v_fmac_f32_e32 v90, v44, v44
	v_fmac_f32_e32 v92, v45, v45
	v_fmac_f32_e32 v90, v46, v46
	v_fmac_f32_e32 v92, v47, v47
	v_fmac_f32_e32 v90, v48, v48
	v_fmac_f32_e32 v92, v49, v49
	v_fmac_f32_e32 v90, v50, v50
	v_fmac_f32_e32 v92, v51, v51
	v_fmac_f32_e32 v90, v52, v52
	v_fmac_f32_e32 v92, v53, v53
	v_fmac_f32_e32 v90, v54, v54
	v_fmac_f32_e32 v92, v55, v55
	v_fmac_f32_e32 v90, v56, v56
	v_fmac_f32_e32 v92, v57, v57
	v_add_f32_e32 v9, v9, v91
	v_add_f32_e32 v90, v90, v92
	s_nop 1
	v_add_f32_dpp v9, v9, v9 quad_perm:[1,0,3,2] row_mask:0xf bank_mask:0xf
	v_add_f32_dpp v90, v90, v90 quad_perm:[1,0,3,2] row_mask:0xf bank_mask:0xf
	s_nop 0
	v_add_f32_dpp v9, v9, v9 quad_perm:[2,3,0,1] row_mask:0xf bank_mask:0xf
	v_add_f32_dpp v90, v90, v90 quad_perm:[2,3,0,1] row_mask:0xf bank_mask:0xf
	s_nop 0
	v_add_f32_dpp v9, v9, v9 row_half_mirror row_mask:0xf bank_mask:0xf
	v_add_f32_dpp v90, v90, v90 row_half_mirror row_mask:0xf bank_mask:0xf
	s_nop 0
	v_add_f32_dpp v9, v9, v9 row_mirror row_mask:0xf bank_mask:0xf
	v_add_f32_dpp v90, v90, v90 row_mirror row_mask:0xf bank_mask:0xf
	s_nop 0
	v_add_f32_dpp v9, v9, v9 row_bcast:15 row_mask:0xa bank_mask:0xf
	v_add_f32_dpp v90, v90, v90 row_bcast:15 row_mask:0xa bank_mask:0xf
	s_nop 0
	v_add_f32_dpp v9, v9, v9 row_bcast:31 row_mask:0xc bank_mask:0xf
	v_add_f32_dpp v90, v90, v90 row_bcast:31 row_mask:0xc bank_mask:0xf
	s_nop 0
	v_readlane_b32 s2, v9, 63
	v_readlane_b32 s3, v90, 63
	s_nop 1
	v_mov_b32_e32 v9, s2
	v_mov_b32_e32 v90, s3
	v_mul_f32_e32 v93, 0x3a800000, v9
	v_mul_f32_e32 v91, 0x3a800000, v90
	v_fma_f32 v91, -v93, v93, v91
	v_max_f32_e32 v91, 0, v91
	v_add_f32_e32 v91, 0x358637bd, v91
	v_rsq_f32_e32 v94, v91
	v_mul_f32_e32 v91, 0.5, v91
	v_mul_f32_e32 v92, v94, v94
	v_fma_f32 v92, -v91, v92, 0.5
	v_fma_f32 v94, v94, v92, v94
	v_sub_f32_e32 v42, v42, v93
	v_sub_f32_e32 v43, v43, v93
	v_sub_f32_e32 v44, v44, v93
	v_sub_f32_e32 v45, v45, v93
	v_sub_f32_e32 v46, v46, v93
	v_sub_f32_e32 v47, v47, v93
	v_sub_f32_e32 v48, v48, v93
	v_sub_f32_e32 v49, v49, v93
	v_sub_f32_e32 v50, v50, v93
	v_sub_f32_e32 v51, v51, v93
	v_sub_f32_e32 v52, v52, v93
	v_sub_f32_e32 v53, v53, v93
	v_sub_f32_e32 v54, v54, v93
	v_sub_f32_e32 v55, v55, v93
	v_sub_f32_e32 v56, v56, v93
	v_sub_f32_e32 v57, v57, v93
	v_mul_f32_e32 v42, v94, v42
	v_mul_f32_e32 v43, v94, v43
	v_mul_f32_e32 v44, v94, v44
	v_mul_f32_e32 v45, v94, v45
	v_mul_f32_e32 v46, v94, v46
	v_mul_f32_e32 v47, v94, v47
	v_mul_f32_e32 v48, v94, v48
	v_mul_f32_e32 v49, v94, v49
	v_mul_f32_e32 v50, v94, v50
	v_mul_f32_e32 v51, v94, v51
	v_mul_f32_e32 v52, v94, v52
	v_mul_f32_e32 v53, v94, v53
	v_mul_f32_e32 v54, v94, v54
	v_mul_f32_e32 v55, v94, v55
	v_mul_f32_e32 v56, v94, v56
	v_mul_f32_e32 v57, v94, v57
	v_fma_f32 v42, v42, v130, v114
	v_fma_f32 v43, v43, v131, v115
	v_fma_f32 v44, v44, v132, v116
	v_fma_f32 v45, v45, v133, v117
	v_fma_f32 v46, v46, v134, v118
	v_fma_f32 v47, v47, v135, v119
	v_fma_f32 v48, v48, v136, v120
	v_fma_f32 v49, v49, v137, v121
	v_fma_f32 v50, v50, v138, v122
	v_fma_f32 v51, v51, v139, v123
	v_fma_f32 v52, v52, v140, v124
	v_fma_f32 v53, v53, v141, v125
	v_fma_f32 v54, v54, v142, v126
	v_fma_f32 v55, v55, v143, v127
	v_fma_f32 v56, v56, v144, v128
	v_fma_f32 v57, v57, v145, v129
	v_cvt_pk_bf16_f32 v190, v42, v43
	v_cvt_pk_bf16_f32 v191, v44, v45
	v_cvt_pk_bf16_f32 v192, v46, v47
	v_cvt_pk_bf16_f32 v193, v48, v49
	v_cvt_pk_bf16_f32 v194, v50, v51
	v_cvt_pk_bf16_f32 v195, v52, v53
	v_cvt_pk_bf16_f32 v196, v54, v55
	v_cvt_pk_bf16_f32 v197, v56, v57
	s_add_u32 s2, s10, 0x2000
	s_addc_u32 s3, s11, 0
	global_store_dwordx4 v1, v[190:193], s[2:3]
	global_store_dwordx4 v1, v[194:197], s[2:3] offset:1024
	s_mov_b64 s[2:3], s[20:21]
	global_load_dwordx4 v[42:45], v0, s[2:3]
	global_load_dwordx4 v[46:49], v0, s[2:3] offset:16
	global_load_dwordx4 v[50:53], v0, s[2:3] offset:2048
	global_load_dwordx4 v[54:57], v0, s[2:3] offset:2064
	s_waitcnt vmcnt(21)
; DI void ln_row_v(const Frame& F, f32x4 (&v)[4], float* xout, const float* g, const float* b, const float* sh, const float* sc, bf16_t* hout, const float* slab, const float* gres, float* stat = nullptr) {
;     ...
;         float s = 0.f, s2 = 0.f;
; #pragma unroll
;         for (int j = 0; j < 4; ++j) { s += (v[j][0] + v[j][1]) + (v[j][2] + v[j][3]); s2 += (v[j][0] * v[j][0] + v[j][1] * v[j][1]) + (v[j][2] * v[j][2] + v[j][3] * v[j][3]); }
;         wave_sum2(s, s2, F.lane);
;         const float mean = s * (1.f / D); const float rstd = 1.f / sqrtf(fmaxf(s2 * (1.f / D) - mean * mean, 0.f) + EPS);
;         if (stat && F.lane == 0) { f32x2 sv = {mean, rstd}; *(f32x2*)stat = sv; }
; #pragma unroll
;         for (int j = 0; j < 4; ++j) { const f32x4 gg = ((const f32x4*)g)[F.lane + 64 * j], bb = ((const f32x4*)b)[F.lane + 64 * j];
;             v[j] = (v[j] - mean) * rstd * gg + bb; if (xout) ((f32x4*)xout)[F.lane + 64 * j] = v[j]; }
;     }
;     if (hout) {
;         float s = 0.f, s2 = 0.f;
; #pragma unroll
;         for (int j = 0; j < 4; ++j) { s += (v[j][0] + v[j][1]) + (v[j][2] + v[j][3]); s2 += (v[j][0] * v[j][0] + v[j][1] * v[j][1]) + (v[j][2] * v[j][2] + v[j][3] * v[j][3]); }
;         wave_sum2(s, s2, F.lane);
	v_add_f32_e32 v9, v58, v59
	v_add_f32_e32 v91, v60, v61
	v_mul_f32_e32 v90, v58, v58
	v_mul_f32_e32 v92, v59, v59
	v_add_f32_e32 v9, v9, v62
	v_add_f32_e32 v91, v91, v63
	v_add_f32_e32 v9, v9, v64
	v_add_f32_e32 v91, v91, v65
	v_add_f32_e32 v9, v9, v66
	v_add_f32_e32 v91, v91, v67
	v_add_f32_e32 v9, v9, v68
	v_add_f32_e32 v91, v91, v69
	v_add_f32_e32 v9, v9, v70
	v_add_f32_e32 v91, v91, v71
	v_add_f32_e32 v9, v9, v72
	v_add_f32_e32 v91, v91, v73
	v_fmac_f32_e32 v90, v60, v60
	v_fmac_f32_e32 v92, v61, v61
	v_fmac_f32_e32 v90, v62, v62
	v_fmac_f32_e32 v92, v63, v63
	v_fmac_f32_e32 v90, v64, v64
	v_fmac_f32_e32 v92, v65, v65
	v_fmac_f32_e32 v90, v66, v66
	v_fmac_f32_e32 v92, v67, v67
	v_fmac_f32_e32 v90, v68, v68
	v_fmac_f32_e32 v92, v69, v69
	v_fmac_f32_e32 v90, v70, v70
	v_fmac_f32_e32 v92, v71, v71
	v_fmac_f32_e32 v90, v72, v72
	v_fmac_f32_e32 v92, v73, v73
	v_add_f32_e32 v9, v9, v91
	v_add_f32_e32 v90, v90, v92
	s_nop 1
	v_add_f32_dpp v9, v9, v9 quad_perm:[1,0,3,2] row_mask:0xf bank_mask:0xf
	v_add_f32_dpp v90, v90, v90 quad_perm:[1,0,3,2] row_mask:0xf bank_mask:0xf
	s_nop 0
	v_add_f32_dpp v9, v9, v9 quad_perm:[2,3,0,1] row_mask:0xf bank_mask:0xf
	v_add_f32_dpp v90, v90, v90 quad_perm:[2,3,0,1] row_mask:0xf bank_mask:0xf
	s_nop 0
	v_add_f32_dpp v9, v9, v9 row_half_mirror row_mask:0xf bank_mask:0xf
	v_add_f32_dpp v90, v90, v90 row_half_mirror row_mask:0xf bank_mask:0xf
	s_nop 0
	v_add_f32_dpp v9, v9, v9 row_mirror row_mask:0xf bank_mask:0xf
	v_add_f32_dpp v90, v90, v90 row_mirror row_mask:0xf bank_mask:0xf
	s_nop 0
	v_add_f32_dpp v9, v9, v9 row_bcast:15 row_mask:0xa bank_mask:0xf
	v_add_f32_dpp v90, v90, v90 row_bcast:15 row_mask:0xa bank_mask:0xf
	s_nop 0
	v_add_f32_dpp v9, v9, v9 row_bcast:31 row_mask:0xc bank_mask:0xf
	v_add_f32_dpp v90, v90, v90 row_bcast:31 row_mask:0xc bank_mask:0xf
	s_nop 0
	v_readlane_b32 s2, v9, 63
	v_readlane_b32 s3, v90, 63
	s_nop 1
	v_mov_b32_e32 v9, s2
	v_mov_b32_e32 v90, s3
	v_mul_f32_e32 v93, 0x3a800000, v9
	v_mul_f32_e32 v91, 0x3a800000, v90
	v_fma_f32 v91, -v93, v93, v91
	v_max_f32_e32 v91, 0, v91
	v_add_f32_e32 v91, 0x358637bd, v91
	v_rsq_f32_e32 v94, v91
	v_mul_f32_e32 v91, 0.5, v91
	v_mul_f32_e32 v92, v94, v94
	v_fma_f32 v92, -v91, v92, 0.5
	v_fma_f32 v94, v94, v92, v94
	s_add_u32 s2, s12, 0x28
	s_addc_u32 s3, s13, 0
	v_mov_b32_e32 v188, v93
	v_mov_b32_e32 v189, v94
	s_mov_b64 exec, 1
	global_store_dwordx2 v97, v[188:189], s[2:3]
	s_mov_b64 exec, -1
	v_sub_f32_e32 v58, v58, v93
	v_sub_f32_e32 v59, v59, v93
	v_sub_f32_e32 v60, v60, v93
	v_sub_f32_e32 v61, v61, v93
	v_sub_f32_e32 v62, v62, v93
	v_sub_f32_e32 v63, v63, v93
	v_sub_f32_e32 v64, v64, v93
	v_sub_f32_e32 v65, v65, v93
	v_sub_f32_e32 v66, v66, v93
	v_sub_f32_e32 v67, v67, v93
	v_sub_f32_e32 v68, v68, v93
	v_sub_f32_e32 v69, v69, v93
	v_sub_f32_e32 v70, v70, v93
	v_sub_f32_e32 v71, v71, v93
	v_sub_f32_e32 v72, v72, v93
	v_sub_f32_e32 v73, v73, v93
	v_mul_f32_e32 v58, v94, v58
	v_mul_f32_e32 v59, v94, v59
	v_mul_f32_e32 v60, v94, v60
	v_mul_f32_e32 v61, v94, v61
	v_mul_f32_e32 v62, v94, v62
	v_mul_f32_e32 v63, v94, v63
	v_mul_f32_e32 v64, v94, v64
	v_mul_f32_e32 v65, v94, v65
	v_mul_f32_e32 v66, v94, v66
	v_mul_f32_e32 v67, v94, v67
	v_mul_f32_e32 v68, v94, v68
	v_mul_f32_e32 v69, v94, v69
	v_mul_f32_e32 v70, v94, v70
	v_mul_f32_e32 v71, v94, v71
	v_mul_f32_e32 v72, v94, v72
	v_mul_f32_e32 v73, v94, v73
	v_fma_f32 v58, v58, v10, v26
	v_fma_f32 v59, v59, v11, v27
	v_fma_f32 v60, v60, v12, v28
	v_fma_f32 v61, v61, v13, v29
	v_fma_f32 v62, v62, v14, v30
	v_fma_f32 v63, v63, v15, v31
	v_fma_f32 v64, v64, v16, v32
	v_fma_f32 v65, v65, v17, v33
	v_fma_f32 v66, v66, v18, v34
	v_fma_f32 v67, v67, v19, v35
	v_fma_f32 v68, v68, v20, v36
	v_fma_f32 v69, v69, v21, v37
	v_fma_f32 v70, v70, v22, v38
	v_fma_f32 v71, v71, v23, v39
	v_fma_f32 v72, v72, v24, v40
	v_fma_f32 v73, v73, v25, v41
	v_add_f32_e32 v9, v58, v59
	v_add_f32_e32 v91, v60, v61
	v_mul_f32_e32 v90, v58, v58
	v_mul_f32_e32 v92, v59, v59
	v_add_f32_e32 v9, v9, v62
	v_add_f32_e32 v91, v91, v63
	v_add_f32_e32 v9, v9, v64
	v_add_f32_e32 v91, v91, v65
	v_add_f32_e32 v9, v9, v66
	v_add_f32_e32 v91, v91, v67
	v_add_f32_e32 v9, v9, v68
	v_add_f32_e32 v91, v91, v69
	v_add_f32_e32 v9, v9, v70
	v_add_f32_e32 v91, v91, v71
	v_add_f32_e32 v9, v9, v72
	v_add_f32_e32 v91, v91, v73
	v_fmac_f32_e32 v90, v60, v60
	v_fmac_f32_e32 v92, v61, v61
	v_fmac_f32_e32 v90, v62, v62
	v_fmac_f32_e32 v92, v63, v63
	v_fmac_f32_e32 v90, v64, v64
	v_fmac_f32_e32 v92, v65, v65
	v_fmac_f32_e32 v90, v66, v66
	v_fmac_f32_e32 v92, v67, v67
	v_fmac_f32_e32 v90, v68, v68
	v_fmac_f32_e32 v92, v69, v69
	v_fmac_f32_e32 v90, v70, v70
	v_fmac_f32_e32 v92, v71, v71
	v_fmac_f32_e32 v90, v72, v72
	v_fmac_f32_e32 v92, v73, v73
	v_add_f32_e32 v9, v9, v91
	v_add_f32_e32 v90, v90, v92
	s_nop 1
	v_add_f32_dpp v9, v9, v9 quad_perm:[1,0,3,2] row_mask:0xf bank_mask:0xf
	v_add_f32_dpp v90, v90, v90 quad_perm:[1,0,3,2] row_mask:0xf bank_mask:0xf
	s_nop 0
	v_add_f32_dpp v9, v9, v9 quad_perm:[2,3,0,1] row_mask:0xf bank_mask:0xf
	v_add_f32_dpp v90, v90, v90 quad_perm:[2,3,0,1] row_mask:0xf bank_mask:0xf
	s_nop 0
	v_add_f32_dpp v9, v9, v9 row_half_mirror row_mask:0xf bank_mask:0xf
	v_add_f32_dpp v90, v90, v90 row_half_mirror row_mask:0xf bank_mask:0xf
	s_nop 0
	v_add_f32_dpp v9, v9, v9 row_mirror row_mask:0xf bank_mask:0xf
	v_add_f32_dpp v90, v90, v90 row_mirror row_mask:0xf bank_mask:0xf
	s_nop 0
	v_add_f32_dpp v9, v9, v9 row_bcast:15 row_mask:0xa bank_mask:0xf
	v_add_f32_dpp v90, v90, v90 row_bcast:15 row_mask:0xa bank_mask:0xf
	s_nop 0
	v_add_f32_dpp v9, v9, v9 row_bcast:31 row_mask:0xc bank_mask:0xf
	v_add_f32_dpp v90, v90, v90 row_bcast:31 row_mask:0xc bank_mask:0xf
; DI unsigned pk2(float lo, float hi) { f32x2 v = {lo, hi}; bf16x2_t b = __builtin_convertvector(v, bf16x2_t); return __builtin_bit_cast(unsigned, b); }
; DI void ln_row_v(const Frame& F, f32x4 (&v)[4], float* xout, const float* g, const float* b, const float* sh, const float* sc, bf16_t* hout, const float* slab, const float* gres, float* stat = nullptr) {
;     ...
;         float s = 0.f, s2 = 0.f;
; #pragma unroll
;         for (int j = 0; j < 4; ++j) { s += (v[j][0] + v[j][1]) + (v[j][2] + v[j][3]); s2 += (v[j][0] * v[j][0] + v[j][1] * v[j][1]) + (v[j][2] * v[j][2] + v[j][3] * v[j][3]); }
;         wave_sum2(s, s2, F.lane);
;         const float mean = s * (1.f / D); const float rstd = 1.f / sqrtf(fmaxf(s2 * (1.f / D) - mean * mean, 0.f) + EPS);
;         if (stat && F.lane == 0) { f32x2 sv = {mean, rstd}; *(f32x2*)stat = sv; }
;     ...
;     if (hout) {
;         float s = 0.f, s2 = 0.f;
; #pragma unroll
;         for (int j = 0; j < 4; ++j) { s += (v[j][0] + v[j][1]) + (v[j][2] + v[j][3]); s2 += (v[j][0] * v[j][0] + v[j][1] * v[j][1]) + (v[j][2] * v[j][2] + v[j][3] * v[j][3]); }
;         wave_sum2(s, s2, F.lane);
;         const float mean = s * (1.f / D); const float rstd = 1.f / sqrtf(fmaxf(s2 * (1.f / D) - mean * mean, 0.f) + EPS);
; #pragma unroll
;         for (int j = 0; j < 4; ++j) { const f32x4 hh = ((const f32x4*)sh)[F.lane + 64 * j], cc = ((const f32x4*)sc)[F.lane + 64 * j];
;             const f32x4 o = (v[j] - mean) * rstd * (cc + 1.f) + hh; u32x2 wv; wv.x = pk2(o[0], o[1]); wv.y = pk2(o[2], o[3]);
;             ((u32x2*)hout)[F.lane + 64 * j] = wv; }
;     }
	s_nop 0
	v_readlane_b32 s2, v9, 63
	v_readlane_b32 s3, v90, 63
	s_nop 1
	v_mov_b32_e32 v9, s2
	v_mov_b32_e32 v90, s3
	v_mul_f32_e32 v93, 0x3a800000, v9
	v_mul_f32_e32 v91, 0x3a800000, v90
	v_fma_f32 v91, -v93, v93, v91
	v_max_f32_e32 v91, 0, v91
	v_add_f32_e32 v91, 0x358637bd, v91
	v_rsq_f32_e32 v94, v91
	v_mul_f32_e32 v91, 0.5, v91
	v_mul_f32_e32 v92, v94, v94
	v_fma_f32 v92, -v91, v92, 0.5
	v_fma_f32 v94, v94, v92, v94
	v_sub_f32_e32 v58, v58, v93
	v_sub_f32_e32 v59, v59, v93
	v_sub_f32_e32 v60, v60, v93
	v_sub_f32_e32 v61, v61, v93
	v_sub_f32_e32 v62, v62, v93
	v_sub_f32_e32 v63, v63, v93
	v_sub_f32_e32 v64, v64, v93
	v_sub_f32_e32 v65, v65, v93
	v_sub_f32_e32 v66, v66, v93
	v_sub_f32_e32 v67, v67, v93
	v_sub_f32_e32 v68, v68, v93
	v_sub_f32_e32 v69, v69, v93
	v_sub_f32_e32 v70, v70, v93
	v_sub_f32_e32 v71, v71, v93
	v_sub_f32_e32 v72, v72, v93
	v_sub_f32_e32 v73, v73, v93
	v_mul_f32_e32 v58, v94, v58
	v_mul_f32_e32 v59, v94, v59
	v_mul_f32_e32 v60, v94, v60
	v_mul_f32_e32 v61, v94, v61
	v_mul_f32_e32 v62, v94, v62
	v_mul_f32_e32 v63, v94, v63
	v_mul_f32_e32 v64, v94, v64
	v_mul_f32_e32 v65, v94, v65
	v_mul_f32_e32 v66, v94, v66
	v_mul_f32_e32 v67, v94, v67
	v_mul_f32_e32 v68, v94, v68
	v_mul_f32_e32 v69, v94, v69
	v_mul_f32_e32 v70, v94, v70
	v_mul_f32_e32 v71, v94, v71
	v_mul_f32_e32 v72, v94, v72
	v_mul_f32_e32 v73, v94, v73
	v_fma_f32 v58, v58, v130, v114
	v_fma_f32 v59, v59, v131, v115
	v_fma_f32 v60, v60, v132, v116
	v_fma_f32 v61, v61, v133, v117
	v_fma_f32 v62, v62, v134, v118
	v_fma_f32 v63, v63, v135, v119
	v_fma_f32 v64, v64, v136, v120
	v_fma_f32 v65, v65, v137, v121
	v_fma_f32 v66, v66, v138, v122
	v_fma_f32 v67, v67, v139, v123
	v_fma_f32 v68, v68, v140, v124
	v_fma_f32 v69, v69, v141, v125
	v_fma_f32 v70, v70, v142, v126
	v_fma_f32 v71, v71, v143, v127
	v_fma_f32 v72, v72, v144, v128
	v_fma_f32 v73, v73, v145, v129
	v_cvt_pk_bf16_f32 v190, v58, v59
	v_cvt_pk_bf16_f32 v191, v60, v61
	v_cvt_pk_bf16_f32 v192, v62, v63
	v_cvt_pk_bf16_f32 v193, v64, v65
	v_cvt_pk_bf16_f32 v194, v66, v67
	v_cvt_pk_bf16_f32 v195, v68, v69
	v_cvt_pk_bf16_f32 v196, v70, v71
	v_cvt_pk_bf16_f32 v197, v72, v73
	s_add_u32 s2, s10, 0x2800
	s_addc_u32 s3, s11, 0
	global_store_dwordx4 v1, v[190:193], s[2:3]
	global_store_dwordx4 v1, v[194:197], s[2:3] offset:1024
	s_waitcnt vmcnt(17)
	v_add_f32_e32 v9, v74, v75
	v_add_f32_e32 v91, v76, v77
	v_mul_f32_e32 v90, v74, v74
	v_mul_f32_e32 v92, v75, v75
	v_add_f32_e32 v9, v9, v78
	v_add_f32_e32 v91, v91, v79
	v_add_f32_e32 v9, v9, v80
	v_add_f32_e32 v91, v91, v81
	v_add_f32_e32 v9, v9, v82
	v_add_f32_e32 v91, v91, v83
	v_add_f32_e32 v9, v9, v84
	v_add_f32_e32 v91, v91, v85
	v_add_f32_e32 v9, v9, v86
	v_add_f32_e32 v91, v91, v87
	v_add_f32_e32 v9, v9, v88
	v_add_f32_e32 v91, v91, v89
	v_fmac_f32_e32 v90, v76, v76
	v_fmac_f32_e32 v92, v77, v77
	v_fmac_f32_e32 v90, v78, v78
	v_fmac_f32_e32 v92, v79, v79
	v_fmac_f32_e32 v90, v80, v80
	v_fmac_f32_e32 v92, v81, v81
	v_fmac_f32_e32 v90, v82, v82
	v_fmac_f32_e32 v92, v83, v83
	v_fmac_f32_e32 v90, v84, v84
	v_fmac_f32_e32 v92, v85, v85
	v_fmac_f32_e32 v90, v86, v86
	v_fmac_f32_e32 v92, v87, v87
	v_fmac_f32_e32 v90, v88, v88
	v_fmac_f32_e32 v92, v89, v89
	v_add_f32_e32 v9, v9, v91
	v_add_f32_e32 v90, v90, v92
	s_nop 1
	v_add_f32_dpp v9, v9, v9 quad_perm:[1,0,3,2] row_mask:0xf bank_mask:0xf
	v_add_f32_dpp v90, v90, v90 quad_perm:[1,0,3,2] row_mask:0xf bank_mask:0xf
	s_nop 0
	v_add_f32_dpp v9, v9, v9 quad_perm:[2,3,0,1] row_mask:0xf bank_mask:0xf
	v_add_f32_dpp v90, v90, v90 quad_perm:[2,3,0,1] row_mask:0xf bank_mask:0xf
	s_nop 0
	v_add_f32_dpp v9, v9, v9 row_half_mirror row_mask:0xf bank_mask:0xf
	v_add_f32_dpp v90, v90, v90 row_half_mirror row_mask:0xf bank_mask:0xf
	s_nop 0
	v_add_f32_dpp v9, v9, v9 row_mirror row_mask:0xf bank_mask:0xf
	v_add_f32_dpp v90, v90, v90 row_mirror row_mask:0xf bank_mask:0xf
	s_nop 0
	v_add_f32_dpp v9, v9, v9 row_bcast:15 row_mask:0xa bank_mask:0xf
	v_add_f32_dpp v90, v90, v90 row_bcast:15 row_mask:0xa bank_mask:0xf
	s_nop 0
	v_add_f32_dpp v9, v9, v9 row_bcast:31 row_mask:0xc bank_mask:0xf
	v_add_f32_dpp v90, v90, v90 row_bcast:31 row_mask:0xc bank_mask:0xf
	s_nop 0
	v_readlane_b32 s2, v9, 63
	v_readlane_b32 s3, v90, 63
	s_nop 1
	v_mov_b32_e32 v9, s2
	v_mov_b32_e32 v90, s3
	v_mul_f32_e32 v93, 0x3a800000, v9
	v_mul_f32_e32 v91, 0x3a800000, v90
	v_fma_f32 v91, -v93, v93, v91
	v_max_f32_e32 v91, 0, v91
	v_add_f32_e32 v91, 0x358637bd, v91
	v_rsq_f32_e32 v94, v91
	v_mul_f32_e32 v91, 0.5, v91
	v_mul_f32_e32 v92, v94, v94
	v_fma_f32 v92, -v91, v92, 0.5
	v_fma_f32 v94, v94, v92, v94
	s_add_u32 s2, s12, 0x30
	s_addc_u32 s3, s13, 0
	v_mov_b32_e32 v188, v93
	v_mov_b32_e32 v189, v94
	s_mov_b64 exec, 1
	global_store_dwordx2 v97, v[188:189], s[2:3]
	s_mov_b64 exec, -1
	v_sub_f32_e32 v74, v74, v93
	v_sub_f32_e32 v75, v75, v93
	v_sub_f32_e32 v76, v76, v93
	v_sub_f32_e32 v77, v77, v93
	v_sub_f32_e32 v78, v78, v93
	v_sub_f32_e32 v79, v79, v93
	v_sub_f32_e32 v80, v80, v93
	v_sub_f32_e32 v81, v81, v93
	v_sub_f32_e32 v82, v82, v93
	v_sub_f32_e32 v83, v83, v93
	v_sub_f32_e32 v84, v84, v93
	v_sub_f32_e32 v85, v85, v93
	v_sub_f32_e32 v86, v86, v93
	v_sub_f32_e32 v87, v87, v93
	v_sub_f32_e32 v88, v88, v93
	v_sub_f32_e32 v89, v89, v93
	v_mul_f32_e32 v74, v94, v74
	v_mul_f32_e32 v75, v94, v75
	v_mul_f32_e32 v76, v94, v76
	v_mul_f32_e32 v77, v94, v77
	v_mul_f32_e32 v78, v94, v78
	v_mul_f32_e32 v79, v94, v79
	v_mul_f32_e32 v80, v94, v80
	v_mul_f32_e32 v81, v94, v81
	v_mul_f32_e32 v82, v94, v82
	v_mul_f32_e32 v83, v94, v83
	v_mul_f32_e32 v84, v94, v84
	v_mul_f32_e32 v85, v94, v85
	v_mul_f32_e32 v86, v94, v86
	v_mul_f32_e32 v87, v94, v87
	v_mul_f32_e32 v88, v94, v88
; DI unsigned pk2(float lo, float hi) { f32x2 v = {lo, hi}; bf16x2_t b = __builtin_convertvector(v, bf16x2_t); return __builtin_bit_cast(unsigned, b); }
; DI void ln_row_v(const Frame& F, f32x4 (&v)[4], float* xout, const float* g, const float* b, const float* sh, const float* sc, bf16_t* hout, const float* slab, const float* gres, float* stat = nullptr) {
;     ...
;         float s = 0.f, s2 = 0.f;
; #pragma unroll
;         for (int j = 0; j < 4; ++j) { s += (v[j][0] + v[j][1]) + (v[j][2] + v[j][3]); s2 += (v[j][0] * v[j][0] + v[j][1] * v[j][1]) + (v[j][2] * v[j][2] + v[j][3] * v[j][3]); }
;         wave_sum2(s, s2, F.lane);
;         const float mean = s * (1.f / D); const float rstd = 1.f / sqrtf(fmaxf(s2 * (1.f / D) - mean * mean, 0.f) + EPS);
;         if (stat && F.lane == 0) { f32x2 sv = {mean, rstd}; *(f32x2*)stat = sv; }
; #pragma unroll
;         for (int j = 0; j < 4; ++j) { const f32x4 gg = ((const f32x4*)g)[F.lane + 64 * j], bb = ((const f32x4*)b)[F.lane + 64 * j];
;             v[j] = (v[j] - mean) * rstd * gg + bb; if (xout) ((f32x4*)xout)[F.lane + 64 * j] = v[j]; }
;     }
;     if (hout) {
;         float s = 0.f, s2 = 0.f;
; #pragma unroll
;         for (int j = 0; j < 4; ++j) { s += (v[j][0] + v[j][1]) + (v[j][2] + v[j][3]); s2 += (v[j][0] * v[j][0] + v[j][1] * v[j][1]) + (v[j][2] * v[j][2] + v[j][3] * v[j][3]); }
;         wave_sum2(s, s2, F.lane);
;         const float mean = s * (1.f / D); const float rstd = 1.f / sqrtf(fmaxf(s2 * (1.f / D) - mean * mean, 0.f) + EPS);
; #pragma unroll
;         for (int j = 0; j < 4; ++j) { const f32x4 hh = ((const f32x4*)sh)[F.lane + 64 * j], cc = ((const f32x4*)sc)[F.lane + 64 * j];
;             const f32x4 o = (v[j] - mean) * rstd * (cc + 1.f) + hh; u32x2 wv; wv.x = pk2(o[0], o[1]); wv.y = pk2(o[2], o[3]);
;             ((u32x2*)hout)[F.lane + 64 * j] = wv; }
;     }
	v_mul_f32_e32 v89, v94, v89
	v_fma_f32 v74, v74, v10, v26
	v_fma_f32 v75, v75, v11, v27
	v_fma_f32 v76, v76, v12, v28
	v_fma_f32 v77, v77, v13, v29
	v_fma_f32 v78, v78, v14, v30
	v_fma_f32 v79, v79, v15, v31
	v_fma_f32 v80, v80, v16, v32
	v_fma_f32 v81, v81, v17, v33
	v_fma_f32 v82, v82, v18, v34
	v_fma_f32 v83, v83, v19, v35
	v_fma_f32 v84, v84, v20, v36
	v_fma_f32 v85, v85, v21, v37
	v_fma_f32 v86, v86, v22, v38
	v_fma_f32 v87, v87, v23, v39
	v_fma_f32 v88, v88, v24, v40
	v_fma_f32 v89, v89, v25, v41
	v_add_f32_e32 v9, v74, v75
	v_add_f32_e32 v91, v76, v77
	v_mul_f32_e32 v90, v74, v74
	v_mul_f32_e32 v92, v75, v75
	v_add_f32_e32 v9, v9, v78
	v_add_f32_e32 v91, v91, v79
	v_add_f32_e32 v9, v9, v80
	v_add_f32_e32 v91, v91, v81
	v_add_f32_e32 v9, v9, v82
	v_add_f32_e32 v91, v91, v83
	v_add_f32_e32 v9, v9, v84
	v_add_f32_e32 v91, v91, v85
	v_add_f32_e32 v9, v9, v86
	v_add_f32_e32 v91, v91, v87
	v_add_f32_e32 v9, v9, v88
	v_add_f32_e32 v91, v91, v89
	v_fmac_f32_e32 v90, v76, v76
	v_fmac_f32_e32 v92, v77, v77
	v_fmac_f32_e32 v90, v78, v78
	v_fmac_f32_e32 v92, v79, v79
	v_fmac_f32_e32 v90, v80, v80
	v_fmac_f32_e32 v92, v81, v81
	v_fmac_f32_e32 v90, v82, v82
	v_fmac_f32_e32 v92, v83, v83
	v_fmac_f32_e32 v90, v84, v84
	v_fmac_f32_e32 v92, v85, v85
	v_fmac_f32_e32 v90, v86, v86
	v_fmac_f32_e32 v92, v87, v87
	v_fmac_f32_e32 v90, v88, v88
	v_fmac_f32_e32 v92, v89, v89
	v_add_f32_e32 v9, v9, v91
	v_add_f32_e32 v90, v90, v92
	s_nop 1
	v_add_f32_dpp v9, v9, v9 quad_perm:[1,0,3,2] row_mask:0xf bank_mask:0xf
	v_add_f32_dpp v90, v90, v90 quad_perm:[1,0,3,2] row_mask:0xf bank_mask:0xf
	s_nop 0
	v_add_f32_dpp v9, v9, v9 quad_perm:[2,3,0,1] row_mask:0xf bank_mask:0xf
	v_add_f32_dpp v90, v90, v90 quad_perm:[2,3,0,1] row_mask:0xf bank_mask:0xf
	s_nop 0
	v_add_f32_dpp v9, v9, v9 row_half_mirror row_mask:0xf bank_mask:0xf
	v_add_f32_dpp v90, v90, v90 row_half_mirror row_mask:0xf bank_mask:0xf
	s_nop 0
	v_add_f32_dpp v9, v9, v9 row_mirror row_mask:0xf bank_mask:0xf
	v_add_f32_dpp v90, v90, v90 row_mirror row_mask:0xf bank_mask:0xf
	s_nop 0
	v_add_f32_dpp v9, v9, v9 row_bcast:15 row_mask:0xa bank_mask:0xf
	v_add_f32_dpp v90, v90, v90 row_bcast:15 row_mask:0xa bank_mask:0xf
	s_nop 0
	v_add_f32_dpp v9, v9, v9 row_bcast:31 row_mask:0xc bank_mask:0xf
	v_add_f32_dpp v90, v90, v90 row_bcast:31 row_mask:0xc bank_mask:0xf
	s_nop 0
	v_readlane_b32 s2, v9, 63
	v_readlane_b32 s3, v90, 63
	s_nop 1
	v_mov_b32_e32 v9, s2
	v_mov_b32_e32 v90, s3
	v_mul_f32_e32 v93, 0x3a800000, v9
	v_mul_f32_e32 v91, 0x3a800000, v90
	v_fma_f32 v91, -v93, v93, v91
	v_max_f32_e32 v91, 0, v91
	v_add_f32_e32 v91, 0x358637bd, v91
	v_rsq_f32_e32 v94, v91
	v_mul_f32_e32 v91, 0.5, v91
	v_mul_f32_e32 v92, v94, v94
	v_fma_f32 v92, -v91, v92, 0.5
	v_fma_f32 v94, v94, v92, v94
	v_sub_f32_e32 v74, v74, v93
	v_sub_f32_e32 v75, v75, v93
	v_sub_f32_e32 v76, v76, v93
	v_sub_f32_e32 v77, v77, v93
	v_sub_f32_e32 v78, v78, v93
	v_sub_f32_e32 v79, v79, v93
	v_sub_f32_e32 v80, v80, v93
	v_sub_f32_e32 v81, v81, v93
	v_sub_f32_e32 v82, v82, v93
	v_sub_f32_e32 v83, v83, v93
	v_sub_f32_e32 v84, v84, v93
	v_sub_f32_e32 v85, v85, v93
	v_sub_f32_e32 v86, v86, v93
	v_sub_f32_e32 v87, v87, v93
	v_sub_f32_e32 v88, v88, v93
	v_sub_f32_e32 v89, v89, v93
	v_mul_f32_e32 v74, v94, v74
	v_mul_f32_e32 v75, v94, v75
	v_mul_f32_e32 v76, v94, v76
	v_mul_f32_e32 v77, v94, v77
	v_mul_f32_e32 v78, v94, v78
	v_mul_f32_e32 v79, v94, v79
	v_mul_f32_e32 v80, v94, v80
	v_mul_f32_e32 v81, v94, v81
	v_mul_f32_e32 v82, v94, v82
	v_mul_f32_e32 v83, v94, v83
	v_mul_f32_e32 v84, v94, v84
	v_mul_f32_e32 v85, v94, v85
	v_mul_f32_e32 v86, v94, v86
	v_mul_f32_e32 v87, v94, v87
	v_mul_f32_e32 v88, v94, v88
	v_mul_f32_e32 v89, v94, v89
	v_fma_f32 v74, v74, v130, v114
	v_fma_f32 v75, v75, v131, v115
	v_fma_f32 v76, v76, v132, v116
	v_fma_f32 v77, v77, v133, v117
	v_fma_f32 v78, v78, v134, v118
	v_fma_f32 v79, v79, v135, v119
	v_fma_f32 v80, v80, v136, v120
	v_fma_f32 v81, v81, v137, v121
	v_fma_f32 v82, v82, v138, v122
	v_fma_f32 v83, v83, v139, v123
	v_fma_f32 v84, v84, v140, v124
	v_fma_f32 v85, v85, v141, v125
	v_fma_f32 v86, v86, v142, v126
	v_fma_f32 v87, v87, v143, v127
	v_fma_f32 v88, v88, v144, v128
	v_fma_f32 v89, v89, v145, v129
	v_cvt_pk_bf16_f32 v190, v74, v75
	v_cvt_pk_bf16_f32 v191, v76, v77
	v_cvt_pk_bf16_f32 v192, v78, v79
	v_cvt_pk_bf16_f32 v193, v80, v81
	v_cvt_pk_bf16_f32 v194, v82, v83
	v_cvt_pk_bf16_f32 v195, v84, v85
	v_cvt_pk_bf16_f32 v196, v86, v87
	v_cvt_pk_bf16_f32 v197, v88, v89
	s_add_u32 s2, s10, 0x3000
	s_addc_u32 s3, s11, 0
	global_store_dwordx4 v1, v[190:193], s[2:3]
	global_store_dwordx4 v1, v[194:197], s[2:3] offset:1024
	s_waitcnt vmcnt(13)
; DI void ln_row_v(const Frame& F, f32x4 (&v)[4], float* xout, const float* g, const float* b, const float* sh, const float* sc, bf16_t* hout, const float* slab, const float* gres, float* stat = nullptr) {
;     ...
;         float s = 0.f, s2 = 0.f;
; #pragma unroll
;         for (int j = 0; j < 4; ++j) { s += (v[j][0] + v[j][1]) + (v[j][2] + v[j][3]); s2 += (v[j][0] * v[j][0] + v[j][1] * v[j][1]) + (v[j][2] * v[j][2] + v[j][3] * v[j][3]); }
;         wave_sum2(s, s2, F.lane);
;         const float mean = s * (1.f / D); const float rstd = 1.f / sqrtf(fmaxf(s2 * (1.f / D) - mean * mean, 0.f) + EPS);
;         if (stat && F.lane == 0) { f32x2 sv = {mean, rstd}; *(f32x2*)stat = sv; }
; #pragma unroll
;         for (int j = 0; j < 4; ++j) { const f32x4 gg = ((const f32x4*)g)[F.lane + 64 * j], bb = ((const f32x4*)b)[F.lane + 64 * j];
;             v[j] = (v[j] - mean) * rstd * gg + bb; if (xout) ((f32x4*)xout)[F.lane + 64 * j] = v[j]; }
;     }
;     if (hout) {
;         float s = 0.f, s2 = 0.f;
; #pragma unroll
;         for (int j = 0; j < 4; ++j) { s += (v[j][0] + v[j][1]) + (v[j][2] + v[j][3]); s2 += (v[j][0] * v[j][0] + v[j][1] * v[j][1]) + (v[j][2] * v[j][2] + v[j][3] * v[j][3]); }
;         wave_sum2(s, s2, F.lane);
	v_add_f32_e32 v9, v98, v99
	v_add_f32_e32 v91, v100, v101
	v_mul_f32_e32 v90, v98, v98
	v_mul_f32_e32 v92, v99, v99
	v_add_f32_e32 v9, v9, v102
	v_add_f32_e32 v91, v91, v103
	v_add_f32_e32 v9, v9, v104
	v_add_f32_e32 v91, v91, v105
	v_add_f32_e32 v9, v9, v106
	v_add_f32_e32 v91, v91, v107
	v_add_f32_e32 v9, v9, v108
	v_add_f32_e32 v91, v91, v109
	v_add_f32_e32 v9, v9, v110
	v_add_f32_e32 v91, v91, v111
	v_add_f32_e32 v9, v9, v112
	v_add_f32_e32 v91, v91, v113
	v_fmac_f32_e32 v90, v100, v100
	v_fmac_f32_e32 v92, v101, v101
	v_fmac_f32_e32 v90, v102, v102
	v_fmac_f32_e32 v92, v103, v103
	v_fmac_f32_e32 v90, v104, v104
	v_fmac_f32_e32 v92, v105, v105
	v_fmac_f32_e32 v90, v106, v106
	v_fmac_f32_e32 v92, v107, v107
	v_fmac_f32_e32 v90, v108, v108
	v_fmac_f32_e32 v92, v109, v109
	v_fmac_f32_e32 v90, v110, v110
	v_fmac_f32_e32 v92, v111, v111
	v_fmac_f32_e32 v90, v112, v112
	v_fmac_f32_e32 v92, v113, v113
	v_add_f32_e32 v9, v9, v91
	v_add_f32_e32 v90, v90, v92
	s_nop 1
	v_add_f32_dpp v9, v9, v9 quad_perm:[1,0,3,2] row_mask:0xf bank_mask:0xf
	v_add_f32_dpp v90, v90, v90 quad_perm:[1,0,3,2] row_mask:0xf bank_mask:0xf
	s_nop 0
	v_add_f32_dpp v9, v9, v9 quad_perm:[2,3,0,1] row_mask:0xf bank_mask:0xf
	v_add_f32_dpp v90, v90, v90 quad_perm:[2,3,0,1] row_mask:0xf bank_mask:0xf
	s_nop 0
	v_add_f32_dpp v9, v9, v9 row_half_mirror row_mask:0xf bank_mask:0xf
	v_add_f32_dpp v90, v90, v90 row_half_mirror row_mask:0xf bank_mask:0xf
	s_nop 0
	v_add_f32_dpp v9, v9, v9 row_mirror row_mask:0xf bank_mask:0xf
	v_add_f32_dpp v90, v90, v90 row_mirror row_mask:0xf bank_mask:0xf
	s_nop 0
	v_add_f32_dpp v9, v9, v9 row_bcast:15 row_mask:0xa bank_mask:0xf
	v_add_f32_dpp v90, v90, v90 row_bcast:15 row_mask:0xa bank_mask:0xf
	s_nop 0
	v_add_f32_dpp v9, v9, v9 row_bcast:31 row_mask:0xc bank_mask:0xf
	v_add_f32_dpp v90, v90, v90 row_bcast:31 row_mask:0xc bank_mask:0xf
	s_nop 0
	v_readlane_b32 s2, v9, 63
	v_readlane_b32 s3, v90, 63
	s_nop 1
	v_mov_b32_e32 v9, s2
	v_mov_b32_e32 v90, s3
	v_mul_f32_e32 v93, 0x3a800000, v9
	v_mul_f32_e32 v91, 0x3a800000, v90
	v_fma_f32 v91, -v93, v93, v91
	v_max_f32_e32 v91, 0, v91
	v_add_f32_e32 v91, 0x358637bd, v91
	v_rsq_f32_e32 v94, v91
	v_mul_f32_e32 v91, 0.5, v91
	v_mul_f32_e32 v92, v94, v94
	v_fma_f32 v92, -v91, v92, 0.5
	v_fma_f32 v94, v94, v92, v94
	s_add_u32 s2, s12, 0x38
	s_addc_u32 s3, s13, 0
	v_mov_b32_e32 v188, v93
	v_mov_b32_e32 v189, v94
	s_mov_b64 exec, 1
	global_store_dwordx2 v97, v[188:189], s[2:3]
	s_mov_b64 exec, -1
	v_sub_f32_e32 v98, v98, v93
	v_sub_f32_e32 v99, v99, v93
	v_sub_f32_e32 v100, v100, v93
	v_sub_f32_e32 v101, v101, v93
	v_sub_f32_e32 v102, v102, v93
	v_sub_f32_e32 v103, v103, v93
	v_sub_f32_e32 v104, v104, v93
	v_sub_f32_e32 v105, v105, v93
	v_sub_f32_e32 v106, v106, v93
	v_sub_f32_e32 v107, v107, v93
	v_sub_f32_e32 v108, v108, v93
	v_sub_f32_e32 v109, v109, v93
	v_sub_f32_e32 v110, v110, v93
	v_sub_f32_e32 v111, v111, v93
	v_sub_f32_e32 v112, v112, v93
	v_sub_f32_e32 v113, v113, v93
	v_mul_f32_e32 v98, v94, v98
	v_mul_f32_e32 v99, v94, v99
	v_mul_f32_e32 v100, v94, v100
	v_mul_f32_e32 v101, v94, v101
	v_mul_f32_e32 v102, v94, v102
	v_mul_f32_e32 v103, v94, v103
	v_mul_f32_e32 v104, v94, v104
	v_mul_f32_e32 v105, v94, v105
	v_mul_f32_e32 v106, v94, v106
	v_mul_f32_e32 v107, v94, v107
	v_mul_f32_e32 v108, v94, v108
	v_mul_f32_e32 v109, v94, v109
	v_mul_f32_e32 v110, v94, v110
	v_mul_f32_e32 v111, v94, v111
	v_mul_f32_e32 v112, v94, v112
	v_mul_f32_e32 v113, v94, v113
	v_fma_f32 v98, v98, v10, v26
	v_fma_f32 v99, v99, v11, v27
	v_fma_f32 v100, v100, v12, v28
	v_fma_f32 v101, v101, v13, v29
	v_fma_f32 v102, v102, v14, v30
	v_fma_f32 v103, v103, v15, v31
	v_fma_f32 v104, v104, v16, v32
	v_fma_f32 v105, v105, v17, v33
	v_fma_f32 v106, v106, v18, v34
	v_fma_f32 v107, v107, v19, v35
	v_fma_f32 v108, v108, v20, v36
	v_fma_f32 v109, v109, v21, v37
	v_fma_f32 v110, v110, v22, v38
	v_fma_f32 v111, v111, v23, v39
	v_fma_f32 v112, v112, v24, v40
	v_fma_f32 v113, v113, v25, v41
	v_add_f32_e32 v9, v98, v99
	v_add_f32_e32 v91, v100, v101
	v_mul_f32_e32 v90, v98, v98
	v_mul_f32_e32 v92, v99, v99
	v_add_f32_e32 v9, v9, v102
	v_add_f32_e32 v91, v91, v103
	v_add_f32_e32 v9, v9, v104
	v_add_f32_e32 v91, v91, v105
	v_add_f32_e32 v9, v9, v106
	v_add_f32_e32 v91, v91, v107
	v_add_f32_e32 v9, v9, v108
	v_add_f32_e32 v91, v91, v109
	v_add_f32_e32 v9, v9, v110
	v_add_f32_e32 v91, v91, v111
	v_add_f32_e32 v9, v9, v112
	v_add_f32_e32 v91, v91, v113
	v_fmac_f32_e32 v90, v100, v100
	v_fmac_f32_e32 v92, v101, v101
	v_fmac_f32_e32 v90, v102, v102
	v_fmac_f32_e32 v92, v103, v103
	v_fmac_f32_e32 v90, v104, v104
	v_fmac_f32_e32 v92, v105, v105
	v_fmac_f32_e32 v90, v106, v106
	v_fmac_f32_e32 v92, v107, v107
	v_fmac_f32_e32 v90, v108, v108
	v_fmac_f32_e32 v92, v109, v109
	v_fmac_f32_e32 v90, v110, v110
	v_fmac_f32_e32 v92, v111, v111
	v_fmac_f32_e32 v90, v112, v112
	v_fmac_f32_e32 v92, v113, v113
	v_add_f32_e32 v9, v9, v91
	v_add_f32_e32 v90, v90, v92
	s_nop 1
	v_add_f32_dpp v9, v9, v9 quad_perm:[1,0,3,2] row_mask:0xf bank_mask:0xf
	v_add_f32_dpp v90, v90, v90 quad_perm:[1,0,3,2] row_mask:0xf bank_mask:0xf
	s_nop 0
	v_add_f32_dpp v9, v9, v9 quad_perm:[2,3,0,1] row_mask:0xf bank_mask:0xf
	v_add_f32_dpp v90, v90, v90 quad_perm:[2,3,0,1] row_mask:0xf bank_mask:0xf
	s_nop 0
	v_add_f32_dpp v9, v9, v9 row_half_mirror row_mask:0xf bank_mask:0xf
	v_add_f32_dpp v90, v90, v90 row_half_mirror row_mask:0xf bank_mask:0xf
	s_nop 0
	v_add_f32_dpp v9, v9, v9 row_mirror row_mask:0xf bank_mask:0xf
	v_add_f32_dpp v90, v90, v90 row_mirror row_mask:0xf bank_mask:0xf
	s_nop 0
	v_add_f32_dpp v9, v9, v9 row_bcast:15 row_mask:0xa bank_mask:0xf
; DI unsigned pk2(float lo, float hi) { f32x2 v = {lo, hi}; bf16x2_t b = __builtin_convertvector(v, bf16x2_t); return __builtin_bit_cast(unsigned, b); }
; DI void ln_row_v(const Frame& F, f32x4 (&v)[4], float* xout, const float* g, const float* b, const float* sh, const float* sc, bf16_t* hout, const float* slab, const float* gres, float* stat = nullptr) {
;     if (slab) {
; #pragma unroll
;         for (int j = 0; j < 4; ++j) { f32x4 a = ((const f32x4*)slab)[F.lane + 64 * j];
; #pragma unroll
;             for (int z = 1; z < 8; ++z) a += ((const f32x4*)(slab + (size_t)z * MC * 1024))[F.lane + 64 * j];
;             v[j] = v[j] * ALPHA + ((const f32x4*)gres)[F.lane + 64 * j] * a; }
;     }
;     ...
;     if (hout) {
;         float s = 0.f, s2 = 0.f;
; #pragma unroll
;         for (int j = 0; j < 4; ++j) { s += (v[j][0] + v[j][1]) + (v[j][2] + v[j][3]); s2 += (v[j][0] * v[j][0] + v[j][1] * v[j][1]) + (v[j][2] * v[j][2] + v[j][3] * v[j][3]); }
;         wave_sum2(s, s2, F.lane);
;         const float mean = s * (1.f / D); const float rstd = 1.f / sqrtf(fmaxf(s2 * (1.f / D) - mean * mean, 0.f) + EPS);
; #pragma unroll
;         for (int j = 0; j < 4; ++j) { const f32x4 hh = ((const f32x4*)sh)[F.lane + 64 * j], cc = ((const f32x4*)sc)[F.lane + 64 * j];
;             const f32x4 o = (v[j] - mean) * rstd * (cc + 1.f) + hh; u32x2 wv; wv.x = pk2(o[0], o[1]); wv.y = pk2(o[2], o[3]);
;             ((u32x2*)hout)[F.lane + 64 * j] = wv; }
;     }
	v_add_f32_dpp v90, v90, v90 row_bcast:15 row_mask:0xa bank_mask:0xf
	s_nop 0
	v_add_f32_dpp v9, v9, v9 row_bcast:31 row_mask:0xc bank_mask:0xf
	v_add_f32_dpp v90, v90, v90 row_bcast:31 row_mask:0xc bank_mask:0xf
	s_nop 0
	v_readlane_b32 s2, v9, 63
	v_readlane_b32 s3, v90, 63
	s_nop 1
	v_mov_b32_e32 v9, s2
	v_mov_b32_e32 v90, s3
	v_mul_f32_e32 v93, 0x3a800000, v9
	v_mul_f32_e32 v91, 0x3a800000, v90
	v_fma_f32 v91, -v93, v93, v91
	v_max_f32_e32 v91, 0, v91
	v_add_f32_e32 v91, 0x358637bd, v91
	v_rsq_f32_e32 v94, v91
	v_mul_f32_e32 v91, 0.5, v91
	v_mul_f32_e32 v92, v94, v94
	v_fma_f32 v92, -v91, v92, 0.5
	v_fma_f32 v94, v94, v92, v94
	v_sub_f32_e32 v98, v98, v93
	v_sub_f32_e32 v99, v99, v93
	v_sub_f32_e32 v100, v100, v93
	v_sub_f32_e32 v101, v101, v93
	v_sub_f32_e32 v102, v102, v93
	v_sub_f32_e32 v103, v103, v93
	v_sub_f32_e32 v104, v104, v93
	v_sub_f32_e32 v105, v105, v93
	v_sub_f32_e32 v106, v106, v93
	v_sub_f32_e32 v107, v107, v93
	v_sub_f32_e32 v108, v108, v93
	v_sub_f32_e32 v109, v109, v93
	v_sub_f32_e32 v110, v110, v93
	v_sub_f32_e32 v111, v111, v93
	v_sub_f32_e32 v112, v112, v93
	v_sub_f32_e32 v113, v113, v93
	v_mul_f32_e32 v98, v94, v98
	v_mul_f32_e32 v99, v94, v99
	v_mul_f32_e32 v100, v94, v100
	v_mul_f32_e32 v101, v94, v101
	v_mul_f32_e32 v102, v94, v102
	v_mul_f32_e32 v103, v94, v103
	v_mul_f32_e32 v104, v94, v104
	v_mul_f32_e32 v105, v94, v105
	v_mul_f32_e32 v106, v94, v106
	v_mul_f32_e32 v107, v94, v107
	v_mul_f32_e32 v108, v94, v108
	v_mul_f32_e32 v109, v94, v109
	v_mul_f32_e32 v110, v94, v110
	v_mul_f32_e32 v111, v94, v111
	v_mul_f32_e32 v112, v94, v112
	v_mul_f32_e32 v113, v94, v113
	v_fma_f32 v98, v98, v130, v114
	v_fma_f32 v99, v99, v131, v115
	v_fma_f32 v100, v100, v132, v116
	v_fma_f32 v101, v101, v133, v117
	v_fma_f32 v102, v102, v134, v118
	v_fma_f32 v103, v103, v135, v119
	v_fma_f32 v104, v104, v136, v120
	v_fma_f32 v105, v105, v137, v121
	v_fma_f32 v106, v106, v138, v122
	v_fma_f32 v107, v107, v139, v123
	v_fma_f32 v108, v108, v140, v124
	v_fma_f32 v109, v109, v141, v125
	v_fma_f32 v110, v110, v142, v126
	v_fma_f32 v111, v111, v143, v127
	v_fma_f32 v112, v112, v144, v128
	v_fma_f32 v113, v113, v145, v129
	v_cvt_pk_bf16_f32 v190, v98, v99
	v_cvt_pk_bf16_f32 v191, v100, v101
	v_cvt_pk_bf16_f32 v192, v102, v103
	v_cvt_pk_bf16_f32 v193, v104, v105
	v_cvt_pk_bf16_f32 v194, v106, v107
	v_cvt_pk_bf16_f32 v195, v108, v109
	v_cvt_pk_bf16_f32 v196, v110, v111
	v_cvt_pk_bf16_f32 v197, v112, v113
	s_add_u32 s2, s10, 0x3800
	s_addc_u32 s3, s11, 0
	global_store_dwordx4 v1, v[190:193], s[2:3]
	global_store_dwordx4 v1, v[194:197], s[2:3] offset:1024
	s_cmp_eq_u32 s22, 3
	s_cbranch_scc1 .Lln_b_noctx
	s_add_u32 s2, s24, 0x0
	s_addc_u32 s3, s25, 0
	global_load_dwordx4 v[58:61], v0, s[2:3]
	global_load_dwordx4 v[62:65], v0, s[2:3] offset:16
	global_load_dwordx4 v[66:69], v0, s[2:3] offset:2048
	global_load_dwordx4 v[70:73], v0, s[2:3] offset:2064
	s_add_u32 s2, s24, 0x800000
	s_addc_u32 s3, s25, 0
	global_load_dwordx4 v[74:77], v0, s[2:3]
	global_load_dwordx4 v[78:81], v0, s[2:3] offset:16
	global_load_dwordx4 v[82:85], v0, s[2:3] offset:2048
	global_load_dwordx4 v[86:89], v0, s[2:3] offset:2064
	s_add_u32 s2, s24, 0x1000000
	s_addc_u32 s3, s25, 0
	global_load_dwordx4 v[98:101], v0, s[2:3]
	global_load_dwordx4 v[102:105], v0, s[2:3] offset:16
	global_load_dwordx4 v[106:109], v0, s[2:3] offset:2048
	global_load_dwordx4 v[110:113], v0, s[2:3] offset:2064
	s_add_u32 s2, s24, 0x1800000
	s_addc_u32 s3, s25, 0
	global_load_dwordx4 v[146:149], v0, s[2:3]
	global_load_dwordx4 v[150:153], v0, s[2:3] offset:16
	global_load_dwordx4 v[154:157], v0, s[2:3] offset:2048
	global_load_dwordx4 v[158:161], v0, s[2:3] offset:2064
	s_add_u32 s2, s24, 0x2000000
	s_addc_u32 s3, s25, 0
	global_load_dwordx4 v[162:165], v0, s[2:3]
	global_load_dwordx4 v[166:169], v0, s[2:3] offset:16
	global_load_dwordx4 v[170:173], v0, s[2:3] offset:2048
	global_load_dwordx4 v[174:177], v0, s[2:3] offset:2064
	s_mov_b64 s[2:3], s[26:27]
	global_load_dwordx4 v[226:229], v0, s[2:3]
	global_load_dwordx4 v[230:233], v0, s[2:3] offset:16
	global_load_dwordx4 v[234:237], v0, s[2:3] offset:2048
	global_load_dwordx4 v[238:241], v0, s[2:3] offset:2064
	s_waitcnt vmcnt(16)
	v_add_f32_e32 v58, v58, v74
	v_add_f32_e32 v59, v59, v75
	v_add_f32_e32 v60, v60, v76
	v_add_f32_e32 v61, v61, v77
	v_add_f32_e32 v62, v62, v78
	v_add_f32_e32 v63, v63, v79
	v_add_f32_e32 v64, v64, v80
	v_add_f32_e32 v65, v65, v81
	v_add_f32_e32 v66, v66, v82
	v_add_f32_e32 v67, v67, v83
	v_add_f32_e32 v68, v68, v84
	v_add_f32_e32 v69, v69, v85
	v_add_f32_e32 v70, v70, v86
	v_add_f32_e32 v71, v71, v87
	v_add_f32_e32 v72, v72, v88
	v_add_f32_e32 v73, v73, v89
	s_add_u32 s2, s24, 0x2800000
	s_addc_u32 s3, s25, 0
	global_load_dwordx4 v[74:77], v0, s[2:3]
	global_load_dwordx4 v[78:81], v0, s[2:3] offset:16
	global_load_dwordx4 v[82:85], v0, s[2:3] offset:2048
	global_load_dwordx4 v[86:89], v0, s[2:3] offset:2064
	s_waitcnt vmcnt(16)
	v_add_f32_e32 v58, v58, v98
	v_add_f32_e32 v59, v59, v99
	v_add_f32_e32 v60, v60, v100
	v_add_f32_e32 v61, v61, v101
	v_add_f32_e32 v62, v62, v102
	v_add_f32_e32 v63, v63, v103
	v_add_f32_e32 v64, v64, v104
	v_add_f32_e32 v65, v65, v105
	v_add_f32_e32 v66, v66, v106
	v_add_f32_e32 v67, v67, v107
	v_add_f32_e32 v68, v68, v108
	v_add_f32_e32 v69, v69, v109
	v_add_f32_e32 v70, v70, v110
	v_add_f32_e32 v71, v71, v111
	v_add_f32_e32 v72, v72, v112
	v_add_f32_e32 v73, v73, v113
	s_add_u32 s2, s24, 0x3000000
	s_addc_u32 s3, s25, 0
	global_load_dwordx4 v[98:101], v0, s[2:3]
	global_load_dwordx4 v[102:105], v0, s[2:3] offset:16
	global_load_dwordx4 v[106:109], v0, s[2:3] offset:2048
	global_load_dwordx4 v[110:113], v0, s[2:3] offset:2064
	s_waitcnt vmcnt(16)
; DI void ln_row_v(const Frame& F, f32x4 (&v)[4], float* xout, const float* g, const float* b, const float* sh, const float* sc, bf16_t* hout, const float* slab, const float* gres, float* stat = nullptr) {
;     if (slab) {
; #pragma unroll
;         for (int j = 0; j < 4; ++j) { f32x4 a = ((const f32x4*)slab)[F.lane + 64 * j];
; #pragma unroll
;             for (int z = 1; z < 8; ++z) a += ((const f32x4*)(slab + (size_t)z * MC * 1024))[F.lane + 64 * j];
;             v[j] = v[j] * ALPHA + ((const f32x4*)gres)[F.lane + 64 * j] * a; }
;     }
;     if (g) {
;         float s = 0.f, s2 = 0.f;
; #pragma unroll
;         for (int j = 0; j < 4; ++j) { s += (v[j][0] + v[j][1]) + (v[j][2] + v[j][3]); s2 += (v[j][0] * v[j][0] + v[j][1] * v[j][1]) + (v[j][2] * v[j][2] + v[j][3] * v[j][3]); }
;         wave_sum2(s, s2, F.lane);
	v_add_f32_e32 v58, v58, v146
	v_add_f32_e32 v59, v59, v147
	v_add_f32_e32 v60, v60, v148
	v_add_f32_e32 v61, v61, v149
	v_add_f32_e32 v62, v62, v150
	v_add_f32_e32 v63, v63, v151
	v_add_f32_e32 v64, v64, v152
	v_add_f32_e32 v65, v65, v153
	v_add_f32_e32 v66, v66, v154
	v_add_f32_e32 v67, v67, v155
	v_add_f32_e32 v68, v68, v156
	v_add_f32_e32 v69, v69, v157
	v_add_f32_e32 v70, v70, v158
	v_add_f32_e32 v71, v71, v159
	v_add_f32_e32 v72, v72, v160
	v_add_f32_e32 v73, v73, v161
	s_add_u32 s2, s24, 0x3800000
	s_addc_u32 s3, s25, 0
	global_load_dwordx4 v[146:149], v0, s[2:3]
	global_load_dwordx4 v[150:153], v0, s[2:3] offset:16
	global_load_dwordx4 v[154:157], v0, s[2:3] offset:2048
	global_load_dwordx4 v[158:161], v0, s[2:3] offset:2064
	s_waitcnt vmcnt(16)
	v_add_f32_e32 v58, v58, v162
	v_add_f32_e32 v59, v59, v163
	v_add_f32_e32 v60, v60, v164
	v_add_f32_e32 v61, v61, v165
	v_add_f32_e32 v62, v62, v166
	v_add_f32_e32 v63, v63, v167
	v_add_f32_e32 v64, v64, v168
	v_add_f32_e32 v65, v65, v169
	v_add_f32_e32 v66, v66, v170
	v_add_f32_e32 v67, v67, v171
	v_add_f32_e32 v68, v68, v172
	v_add_f32_e32 v69, v69, v173
	v_add_f32_e32 v70, v70, v174
	v_add_f32_e32 v71, v71, v175
	v_add_f32_e32 v72, v72, v176
	v_add_f32_e32 v73, v73, v177
	s_waitcnt vmcnt(8)
	v_add_f32_e32 v58, v58, v74
	v_add_f32_e32 v59, v59, v75
	v_add_f32_e32 v60, v60, v76
	v_add_f32_e32 v61, v61, v77
	v_add_f32_e32 v62, v62, v78
	v_add_f32_e32 v63, v63, v79
	v_add_f32_e32 v64, v64, v80
	v_add_f32_e32 v65, v65, v81
	v_add_f32_e32 v66, v66, v82
	v_add_f32_e32 v67, v67, v83
	v_add_f32_e32 v68, v68, v84
	v_add_f32_e32 v69, v69, v85
	v_add_f32_e32 v70, v70, v86
	v_add_f32_e32 v71, v71, v87
	v_add_f32_e32 v72, v72, v88
	v_add_f32_e32 v73, v73, v89
	s_waitcnt vmcnt(4)
	v_add_f32_e32 v58, v58, v98
	v_add_f32_e32 v59, v59, v99
	v_add_f32_e32 v60, v60, v100
	v_add_f32_e32 v61, v61, v101
	v_add_f32_e32 v62, v62, v102
	v_add_f32_e32 v63, v63, v103
	v_add_f32_e32 v64, v64, v104
	v_add_f32_e32 v65, v65, v105
	v_add_f32_e32 v66, v66, v106
	v_add_f32_e32 v67, v67, v107
	v_add_f32_e32 v68, v68, v108
	v_add_f32_e32 v69, v69, v109
	v_add_f32_e32 v70, v70, v110
	v_add_f32_e32 v71, v71, v111
	v_add_f32_e32 v72, v72, v112
	v_add_f32_e32 v73, v73, v113
	s_waitcnt vmcnt(0)
	v_add_f32_e32 v58, v58, v146
	v_add_f32_e32 v59, v59, v147
	v_add_f32_e32 v60, v60, v148
	v_add_f32_e32 v61, v61, v149
	v_add_f32_e32 v62, v62, v150
	v_add_f32_e32 v63, v63, v151
	v_add_f32_e32 v64, v64, v152
	v_add_f32_e32 v65, v65, v153
	v_add_f32_e32 v66, v66, v154
	v_add_f32_e32 v67, v67, v155
	v_add_f32_e32 v68, v68, v156
	v_add_f32_e32 v69, v69, v157
	v_add_f32_e32 v70, v70, v158
	v_add_f32_e32 v71, v71, v159
	v_add_f32_e32 v72, v72, v160
	v_add_f32_e32 v73, v73, v161
	s_mov_b32 s23, 0x30000
	s_add_u32 s2, s14, s23
	s_addc_u32 s3, s15, 0
	global_load_dwordx4 v[146:149], v0, s[2:3]
	global_load_dwordx4 v[150:153], v0, s[2:3] offset:16
	global_load_dwordx4 v[154:157], v0, s[2:3] offset:2048
	global_load_dwordx4 v[158:161], v0, s[2:3] offset:2064
	s_add_u32 s2, s18, s23
	s_addc_u32 s3, s19, 0
	global_load_dwordx4 v[162:165], v0, s[2:3]
	global_load_dwordx4 v[166:169], v0, s[2:3] offset:16
	global_load_dwordx4 v[170:173], v0, s[2:3] offset:2048
	global_load_dwordx4 v[174:177], v0, s[2:3] offset:2064
	v_mul_f32_e32 v42, 0x3fd744fd, v42
	v_mul_f32_e32 v43, 0x3fd744fd, v43
	v_mul_f32_e32 v44, 0x3fd744fd, v44
	v_mul_f32_e32 v45, 0x3fd744fd, v45
	v_mul_f32_e32 v46, 0x3fd744fd, v46
	v_mul_f32_e32 v47, 0x3fd744fd, v47
	v_mul_f32_e32 v48, 0x3fd744fd, v48
	v_mul_f32_e32 v49, 0x3fd744fd, v49
	v_mul_f32_e32 v50, 0x3fd744fd, v50
	v_mul_f32_e32 v51, 0x3fd744fd, v51
	v_mul_f32_e32 v52, 0x3fd744fd, v52
	v_mul_f32_e32 v53, 0x3fd744fd, v53
	v_mul_f32_e32 v54, 0x3fd744fd, v54
	v_mul_f32_e32 v55, 0x3fd744fd, v55
	v_mul_f32_e32 v56, 0x3fd744fd, v56
	v_mul_f32_e32 v57, 0x3fd744fd, v57
	v_fmac_f32_e32 v42, v226, v58
	v_fmac_f32_e32 v43, v227, v59
	v_fmac_f32_e32 v44, v228, v60
	v_fmac_f32_e32 v45, v229, v61
	v_fmac_f32_e32 v46, v230, v62
	v_fmac_f32_e32 v47, v231, v63
	v_fmac_f32_e32 v48, v232, v64
	v_fmac_f32_e32 v49, v233, v65
	v_fmac_f32_e32 v50, v234, v66
	v_fmac_f32_e32 v51, v235, v67
	v_fmac_f32_e32 v52, v236, v68
	v_fmac_f32_e32 v53, v237, v69
	v_fmac_f32_e32 v54, v238, v70
	v_fmac_f32_e32 v55, v239, v71
	v_fmac_f32_e32 v56, v240, v72
	v_fmac_f32_e32 v57, v241, v73
	v_add_f32_e32 v9, v42, v43
	v_add_f32_e32 v91, v44, v45
	v_mul_f32_e32 v90, v42, v42
	v_mul_f32_e32 v92, v43, v43
	v_add_f32_e32 v9, v9, v46
	v_add_f32_e32 v91, v91, v47
	v_add_f32_e32 v9, v9, v48
	v_add_f32_e32 v91, v91, v49
	v_add_f32_e32 v9, v9, v50
	v_add_f32_e32 v91, v91, v51
	v_add_f32_e32 v9, v9, v52
	v_add_f32_e32 v91, v91, v53
	v_add_f32_e32 v9, v9, v54
	v_add_f32_e32 v91, v91, v55
	v_add_f32_e32 v9, v9, v56
	v_add_f32_e32 v91, v91, v57
	v_fmac_f32_e32 v90, v44, v44
	v_fmac_f32_e32 v92, v45, v45
	v_fmac_f32_e32 v90, v46, v46
	v_fmac_f32_e32 v92, v47, v47
	v_fmac_f32_e32 v90, v48, v48
	v_fmac_f32_e32 v92, v49, v49
	v_fmac_f32_e32 v90, v50, v50
	v_fmac_f32_e32 v92, v51, v51
	v_fmac_f32_e32 v90, v52, v52
	v_fmac_f32_e32 v92, v53, v53
	v_fmac_f32_e32 v90, v54, v54
	v_fmac_f32_e32 v92, v55, v55
	v_fmac_f32_e32 v90, v56, v56
	v_fmac_f32_e32 v92, v57, v57
	v_add_f32_e32 v9, v9, v91
	v_add_f32_e32 v90, v90, v92
	s_nop 1
	v_add_f32_dpp v9, v9, v9 quad_perm:[1,0,3,2] row_mask:0xf bank_mask:0xf
	v_add_f32_dpp v90, v90, v90 quad_perm:[1,0,3,2] row_mask:0xf bank_mask:0xf
	s_nop 0
	v_add_f32_dpp v9, v9, v9 quad_perm:[2,3,0,1] row_mask:0xf bank_mask:0xf
	v_add_f32_dpp v90, v90, v90 quad_perm:[2,3,0,1] row_mask:0xf bank_mask:0xf
	s_nop 0
	v_add_f32_dpp v9, v9, v9 row_half_mirror row_mask:0xf bank_mask:0xf
; DI void ln_row_v(const Frame& F, f32x4 (&v)[4], float* xout, const float* g, const float* b, const float* sh, const float* sc, bf16_t* hout, const float* slab, const float* gres, float* stat = nullptr) {
;     ...
;         float s = 0.f, s2 = 0.f;
; #pragma unroll
;         for (int j = 0; j < 4; ++j) { s += (v[j][0] + v[j][1]) + (v[j][2] + v[j][3]); s2 += (v[j][0] * v[j][0] + v[j][1] * v[j][1]) + (v[j][2] * v[j][2] + v[j][3] * v[j][3]); }
;         wave_sum2(s, s2, F.lane);
;         const float mean = s * (1.f / D); const float rstd = 1.f / sqrtf(fmaxf(s2 * (1.f / D) - mean * mean, 0.f) + EPS);
;         if (stat && F.lane == 0) { f32x2 sv = {mean, rstd}; *(f32x2*)stat = sv; }
; #pragma unroll
;         for (int j = 0; j < 4; ++j) { const f32x4 gg = ((const f32x4*)g)[F.lane + 64 * j], bb = ((const f32x4*)b)[F.lane + 64 * j];
;             v[j] = (v[j] - mean) * rstd * gg + bb; if (xout) ((f32x4*)xout)[F.lane + 64 * j] = v[j]; }
;     }
;     if (hout) {
;         float s = 0.f, s2 = 0.f;
; #pragma unroll
;         for (int j = 0; j < 4; ++j) { s += (v[j][0] + v[j][1]) + (v[j][2] + v[j][3]); s2 += (v[j][0] * v[j][0] + v[j][1] * v[j][1]) + (v[j][2] * v[j][2] + v[j][3] * v[j][3]); }
;         wave_sum2(s, s2, F.lane);
;         const float mean = s * (1.f / D); const float rstd = 1.f / sqrtf(fmaxf(s2 * (1.f / D) - mean * mean, 0.f) + EPS);
	v_add_f32_dpp v90, v90, v90 row_half_mirror row_mask:0xf bank_mask:0xf
	s_nop 0
	v_add_f32_dpp v9, v9, v9 row_mirror row_mask:0xf bank_mask:0xf
	v_add_f32_dpp v90, v90, v90 row_mirror row_mask:0xf bank_mask:0xf
	s_nop 0
	v_add_f32_dpp v9, v9, v9 row_bcast:15 row_mask:0xa bank_mask:0xf
	v_add_f32_dpp v90, v90, v90 row_bcast:15 row_mask:0xa bank_mask:0xf
	s_nop 0
	v_add_f32_dpp v9, v9, v9 row_bcast:31 row_mask:0xc bank_mask:0xf
	v_add_f32_dpp v90, v90, v90 row_bcast:31 row_mask:0xc bank_mask:0xf
	s_nop 0
	v_readlane_b32 s2, v9, 63
	v_readlane_b32 s3, v90, 63
	s_nop 1
	v_mov_b32_e32 v9, s2
	v_mov_b32_e32 v90, s3
	v_mul_f32_e32 v93, 0x3a800000, v9
	v_mul_f32_e32 v91, 0x3a800000, v90
	v_fma_f32 v91, -v93, v93, v91
	v_max_f32_e32 v91, 0, v91
	v_add_f32_e32 v91, 0x358637bd, v91
	v_rsq_f32_e32 v94, v91
	v_mul_f32_e32 v91, 0.5, v91
	v_mul_f32_e32 v92, v94, v94
	v_fma_f32 v92, -v91, v92, 0.5
	v_fma_f32 v94, v94, v92, v94
	v_sub_f32_e32 v42, v42, v93
	v_sub_f32_e32 v43, v43, v93
	v_sub_f32_e32 v44, v44, v93
	v_sub_f32_e32 v45, v45, v93
	v_sub_f32_e32 v46, v46, v93
	v_sub_f32_e32 v47, v47, v93
	v_sub_f32_e32 v48, v48, v93
	v_sub_f32_e32 v49, v49, v93
	v_sub_f32_e32 v50, v50, v93
	v_sub_f32_e32 v51, v51, v93
	v_sub_f32_e32 v52, v52, v93
	v_sub_f32_e32 v53, v53, v93
	v_sub_f32_e32 v54, v54, v93
	v_sub_f32_e32 v55, v55, v93
	v_sub_f32_e32 v56, v56, v93
	v_sub_f32_e32 v57, v57, v93
	v_mul_f32_e32 v42, v94, v42
	v_mul_f32_e32 v43, v94, v43
	v_mul_f32_e32 v44, v94, v44
	v_mul_f32_e32 v45, v94, v45
	v_mul_f32_e32 v46, v94, v46
	v_mul_f32_e32 v47, v94, v47
	v_mul_f32_e32 v48, v94, v48
	v_mul_f32_e32 v49, v94, v49
	v_mul_f32_e32 v50, v94, v50
	v_mul_f32_e32 v51, v94, v51
	v_mul_f32_e32 v52, v94, v52
	v_mul_f32_e32 v53, v94, v53
	v_mul_f32_e32 v54, v94, v54
	v_mul_f32_e32 v55, v94, v55
	v_mul_f32_e32 v56, v94, v56
	v_mul_f32_e32 v57, v94, v57
	v_fma_f32 v42, v42, v10, v26
	v_fma_f32 v43, v43, v11, v27
	v_fma_f32 v44, v44, v12, v28
	v_fma_f32 v45, v45, v13, v29
	v_fma_f32 v46, v46, v14, v30
	v_fma_f32 v47, v47, v15, v31
	v_fma_f32 v48, v48, v16, v32
	v_fma_f32 v49, v49, v17, v33
	v_fma_f32 v50, v50, v18, v34
	v_fma_f32 v51, v51, v19, v35
	v_fma_f32 v52, v52, v20, v36
	v_fma_f32 v53, v53, v21, v37
	v_fma_f32 v54, v54, v22, v38
	v_fma_f32 v55, v55, v23, v39
	v_fma_f32 v56, v56, v24, v40
	v_fma_f32 v57, v57, v25, v41
	s_mov_b64 s[2:3], s[20:21]
	global_store_dwordx4 v0, v[42:45], s[2:3]
	global_store_dwordx4 v0, v[46:49], s[2:3] offset:16
	global_store_dwordx4 v0, v[50:53], s[2:3] offset:2048
	global_store_dwordx4 v0, v[54:57], s[2:3] offset:2064
	v_add_f32_e32 v9, v42, v43
	v_add_f32_e32 v91, v44, v45
	v_mul_f32_e32 v90, v42, v42
	v_mul_f32_e32 v92, v43, v43
	v_add_f32_e32 v9, v9, v46
	v_add_f32_e32 v91, v91, v47
	v_add_f32_e32 v9, v9, v48
	v_add_f32_e32 v91, v91, v49
	v_add_f32_e32 v9, v9, v50
	v_add_f32_e32 v91, v91, v51
	v_add_f32_e32 v9, v9, v52
	v_add_f32_e32 v91, v91, v53
	v_add_f32_e32 v9, v9, v54
	v_add_f32_e32 v91, v91, v55
	v_add_f32_e32 v9, v9, v56
	v_add_f32_e32 v91, v91, v57
	v_fmac_f32_e32 v90, v44, v44
	v_fmac_f32_e32 v92, v45, v45
	v_fmac_f32_e32 v90, v46, v46
	v_fmac_f32_e32 v92, v47, v47
	v_fmac_f32_e32 v90, v48, v48
	v_fmac_f32_e32 v92, v49, v49
	v_fmac_f32_e32 v90, v50, v50
	v_fmac_f32_e32 v92, v51, v51
	v_fmac_f32_e32 v90, v52, v52
	v_fmac_f32_e32 v92, v53, v53
	v_fmac_f32_e32 v90, v54, v54
	v_fmac_f32_e32 v92, v55, v55
	v_fmac_f32_e32 v90, v56, v56
	v_fmac_f32_e32 v92, v57, v57
	v_add_f32_e32 v9, v9, v91
	v_add_f32_e32 v90, v90, v92
	s_nop 1
	v_add_f32_dpp v9, v9, v9 quad_perm:[1,0,3,2] row_mask:0xf bank_mask:0xf
	v_add_f32_dpp v90, v90, v90 quad_perm:[1,0,3,2] row_mask:0xf bank_mask:0xf
	s_nop 0
	v_add_f32_dpp v9, v9, v9 quad_perm:[2,3,0,1] row_mask:0xf bank_mask:0xf
	v_add_f32_dpp v90, v90, v90 quad_perm:[2,3,0,1] row_mask:0xf bank_mask:0xf
	s_nop 0
	v_add_f32_dpp v9, v9, v9 row_half_mirror row_mask:0xf bank_mask:0xf
	v_add_f32_dpp v90, v90, v90 row_half_mirror row_mask:0xf bank_mask:0xf
	s_nop 0
	v_add_f32_dpp v9, v9, v9 row_mirror row_mask:0xf bank_mask:0xf
	v_add_f32_dpp v90, v90, v90 row_mirror row_mask:0xf bank_mask:0xf
	s_nop 0
	v_add_f32_dpp v9, v9, v9 row_bcast:15 row_mask:0xa bank_mask:0xf
	v_add_f32_dpp v90, v90, v90 row_bcast:15 row_mask:0xa bank_mask:0xf
	s_nop 0
	v_add_f32_dpp v9, v9, v9 row_bcast:31 row_mask:0xc bank_mask:0xf
	v_add_f32_dpp v90, v90, v90 row_bcast:31 row_mask:0xc bank_mask:0xf
	s_nop 0
	v_readlane_b32 s2, v9, 63
	v_readlane_b32 s3, v90, 63
	s_nop 1
	v_mov_b32_e32 v9, s2
	v_mov_b32_e32 v90, s3
	v_mul_f32_e32 v93, 0x3a800000, v9
	v_mul_f32_e32 v91, 0x3a800000, v90
	v_fma_f32 v91, -v93, v93, v91
	v_max_f32_e32 v91, 0, v91
	v_add_f32_e32 v91, 0x358637bd, v91
	v_rsq_f32_e32 v94, v91
	v_mul_f32_e32 v91, 0.5, v91
	v_mul_f32_e32 v92, v94, v94
	v_fma_f32 v92, -v91, v92, 0.5
	v_fma_f32 v94, v94, v92, v94
	s_waitcnt vmcnt(4)
; DI unsigned pk2(float lo, float hi) { f32x2 v = {lo, hi}; bf16x2_t b = __builtin_convertvector(v, bf16x2_t); return __builtin_bit_cast(unsigned, b); }
; DI void ln_row_v(const Frame& F, f32x4 (&v)[4], float* xout, const float* g, const float* b, const float* sh, const float* sc, bf16_t* hout, const float* slab, const float* gres, float* stat = nullptr) {
;     ...
;     if (hout) {
;         float s = 0.f, s2 = 0.f;
; #pragma unroll
;         for (int j = 0; j < 4; ++j) { s += (v[j][0] + v[j][1]) + (v[j][2] + v[j][3]); s2 += (v[j][0] * v[j][0] + v[j][1] * v[j][1]) + (v[j][2] * v[j][2] + v[j][3] * v[j][3]); }
;         wave_sum2(s, s2, F.lane);
;         const float mean = s * (1.f / D); const float rstd = 1.f / sqrtf(fmaxf(s2 * (1.f / D) - mean * mean, 0.f) + EPS);
; #pragma unroll
;         for (int j = 0; j < 4; ++j) { const f32x4 hh = ((const f32x4*)sh)[F.lane + 64 * j], cc = ((const f32x4*)sc)[F.lane + 64 * j];
;             const f32x4 o = (v[j] - mean) * rstd * (cc + 1.f) + hh; u32x2 wv; wv.x = pk2(o[0], o[1]); wv.y = pk2(o[2], o[3]);
;             ((u32x2*)hout)[F.lane + 64 * j] = wv; }
;     }
	v_sub_f32_e32 v42, v42, v93
	v_sub_f32_e32 v43, v43, v93
	v_sub_f32_e32 v44, v44, v93
	v_sub_f32_e32 v45, v45, v93
	v_sub_f32_e32 v46, v46, v93
	v_sub_f32_e32 v47, v47, v93
	v_sub_f32_e32 v48, v48, v93
	v_sub_f32_e32 v49, v49, v93
	v_sub_f32_e32 v50, v50, v93
	v_sub_f32_e32 v51, v51, v93
	v_sub_f32_e32 v52, v52, v93
	v_sub_f32_e32 v53, v53, v93
	v_sub_f32_e32 v54, v54, v93
	v_sub_f32_e32 v55, v55, v93
	v_sub_f32_e32 v56, v56, v93
	v_sub_f32_e32 v57, v57, v93
	v_add_f32_e32 v162, 1.0, v162
	v_add_f32_e32 v163, 1.0, v163
	v_add_f32_e32 v164, 1.0, v164
	v_add_f32_e32 v165, 1.0, v165
	v_add_f32_e32 v166, 1.0, v166
	v_add_f32_e32 v167, 1.0, v167
	v_add_f32_e32 v168, 1.0, v168
	v_add_f32_e32 v169, 1.0, v169
	v_add_f32_e32 v170, 1.0, v170
	v_add_f32_e32 v171, 1.0, v171
	v_add_f32_e32 v172, 1.0, v172
	v_add_f32_e32 v173, 1.0, v173
	v_add_f32_e32 v174, 1.0, v174
	v_add_f32_e32 v175, 1.0, v175
	v_add_f32_e32 v176, 1.0, v176
	v_add_f32_e32 v177, 1.0, v177
	v_mul_f32_e32 v42, v94, v42
	v_mul_f32_e32 v43, v94, v43
	v_mul_f32_e32 v44, v94, v44
	v_mul_f32_e32 v45, v94, v45
	v_mul_f32_e32 v46, v94, v46
	v_mul_f32_e32 v47, v94, v47
	v_mul_f32_e32 v48, v94, v48
	v_mul_f32_e32 v49, v94, v49
	v_mul_f32_e32 v50, v94, v50
	v_mul_f32_e32 v51, v94, v51
	v_mul_f32_e32 v52, v94, v52
	v_mul_f32_e32 v53, v94, v53
	v_mul_f32_e32 v54, v94, v54
	v_mul_f32_e32 v55, v94, v55
	v_mul_f32_e32 v56, v94, v56
	v_mul_f32_e32 v57, v94, v57
	v_fma_f32 v42, v42, v162, v146
	v_fma_f32 v43, v43, v163, v147
	v_fma_f32 v44, v44, v164, v148
	v_fma_f32 v45, v45, v165, v149
	v_fma_f32 v46, v46, v166, v150
	v_fma_f32 v47, v47, v167, v151
	v_fma_f32 v48, v48, v168, v152
	v_fma_f32 v49, v49, v169, v153
	v_fma_f32 v50, v50, v170, v154
	v_fma_f32 v51, v51, v171, v155
	v_fma_f32 v52, v52, v172, v156
	v_fma_f32 v53, v53, v173, v157
	v_fma_f32 v54, v54, v174, v158
	v_fma_f32 v55, v55, v175, v159
	v_fma_f32 v56, v56, v176, v160
	v_fma_f32 v57, v57, v177, v161
	v_cvt_pk_bf16_f32 v190, v42, v43
	v_cvt_pk_bf16_f32 v191, v44, v45
	v_cvt_pk_bf16_f32 v192, v46, v47
	v_cvt_pk_bf16_f32 v193, v48, v49
	v_cvt_pk_bf16_f32 v194, v50, v51
	v_cvt_pk_bf16_f32 v195, v52, v53
	v_cvt_pk_bf16_f32 v196, v54, v55
	v_cvt_pk_bf16_f32 v197, v56, v57
	s_lshl_b32 s2, s16, 11
	s_add_u32 s2, s94, s2
	s_addc_u32 s3, s95, 0
	s_add_u32 s2, s2, 0x5e00000
	s_addc_u32 s3, s3, 0
	global_store_dwordx4 v1, v[190:193], s[2:3]
	global_store_dwordx4 v1, v[194:197], s[2:3] offset:1024

; DI void ln_row_v(const Frame& F, f32x4 (&v)[4], float* xout, const float* g, const float* b, const float* sh, const float* sc, bf16_t* hout, const float* slab, const float* gres, float* stat = nullptr) {
;     ...
;         float s = 0.f, s2 = 0.f;
; #pragma unroll
;         for (int j = 0; j < 4; ++j) { s += (v[j][0] + v[j][1]) + (v[j][2] + v[j][3]); s2 += (v[j][0] * v[j][0] + v[j][1] * v[j][1]) + (v[j][2] * v[j][2] + v[j][3] * v[j][3]); }
;         wave_sum2(s, s2, F.lane);
;         const float mean = s * (1.f / D); const float rstd = 1.f / sqrtf(fmaxf(s2 * (1.f / D) - mean * mean, 0.f) + EPS);
;         if (stat && F.lane == 0) { f32x2 sv = {mean, rstd}; *(f32x2*)stat = sv; }
; #pragma unroll
;         for (int j = 0; j < 4; ++j) { const f32x4 gg = ((const f32x4*)g)[F.lane + 64 * j], bb = ((const f32x4*)b)[F.lane + 64 * j];
;             v[j] = (v[j] - mean) * rstd * gg + bb; if (xout) ((f32x4*)xout)[F.lane + 64 * j] = v[j]; }
;     }
.Lln_b_final:
	global_load_dwordx4 v[10:13], v0, s[4:5]
	global_load_dwordx4 v[14:17], v0, s[4:5] offset:16
	global_load_dwordx4 v[18:21], v0, s[4:5] offset:2048
	global_load_dwordx4 v[22:25], v0, s[4:5] offset:2064
	global_load_dwordx4 v[26:29], v0, s[6:7]
	global_load_dwordx4 v[30:33], v0, s[6:7] offset:16
	global_load_dwordx4 v[34:37], v0, s[6:7] offset:2048
	global_load_dwordx4 v[38:41], v0, s[6:7] offset:2064
	s_add_u32 s2, s8, 0x0
	s_addc_u32 s3, s9, 0
	global_load_dwordx4 v[42:45], v0, s[2:3]
	global_load_dwordx4 v[46:49], v0, s[2:3] offset:16
	global_load_dwordx4 v[50:53], v0, s[2:3] offset:2048
	global_load_dwordx4 v[54:57], v0, s[2:3] offset:2064
	s_add_u32 s2, s8, 0x1000
	s_addc_u32 s3, s9, 0
	global_load_dwordx4 v[58:61], v0, s[2:3]
	global_load_dwordx4 v[62:65], v0, s[2:3] offset:16
	global_load_dwordx4 v[66:69], v0, s[2:3] offset:2048
	global_load_dwordx4 v[70:73], v0, s[2:3] offset:2064
	s_add_u32 s2, s8, 0x2000
	s_addc_u32 s3, s9, 0
	global_load_dwordx4 v[74:77], v0, s[2:3]
	global_load_dwordx4 v[78:81], v0, s[2:3] offset:16
	global_load_dwordx4 v[82:85], v0, s[2:3] offset:2048
	global_load_dwordx4 v[86:89], v0, s[2:3] offset:2064
	s_add_u32 s2, s8, 0x3000
	s_addc_u32 s3, s9, 0
	global_load_dwordx4 v[98:101], v0, s[2:3]
	global_load_dwordx4 v[102:105], v0, s[2:3] offset:16
	global_load_dwordx4 v[106:109], v0, s[2:3] offset:2048
	global_load_dwordx4 v[110:113], v0, s[2:3] offset:2064
	s_waitcnt vmcnt(12)
	v_add_f32_e32 v9, v42, v43
	v_add_f32_e32 v91, v44, v45
	v_mul_f32_e32 v90, v42, v42
	v_mul_f32_e32 v92, v43, v43
	v_add_f32_e32 v9, v9, v46
	v_add_f32_e32 v91, v91, v47
	v_add_f32_e32 v9, v9, v48
	v_add_f32_e32 v91, v91, v49
	v_add_f32_e32 v9, v9, v50
	v_add_f32_e32 v91, v91, v51
	v_add_f32_e32 v9, v9, v52
	v_add_f32_e32 v91, v91, v53
	v_add_f32_e32 v9, v9, v54
	v_add_f32_e32 v91, v91, v55
	v_add_f32_e32 v9, v9, v56
	v_add_f32_e32 v91, v91, v57
	v_fmac_f32_e32 v90, v44, v44
	v_fmac_f32_e32 v92, v45, v45
	v_fmac_f32_e32 v90, v46, v46
	v_fmac_f32_e32 v92, v47, v47
	v_fmac_f32_e32 v90, v48, v48
	v_fmac_f32_e32 v92, v49, v49
	v_fmac_f32_e32 v90, v50, v50
	v_fmac_f32_e32 v92, v51, v51
	v_fmac_f32_e32 v90, v52, v52
	v_fmac_f32_e32 v92, v53, v53
	v_fmac_f32_e32 v90, v54, v54
	v_fmac_f32_e32 v92, v55, v55
	v_fmac_f32_e32 v90, v56, v56
	v_fmac_f32_e32 v92, v57, v57
	v_add_f32_e32 v9, v9, v91
	v_add_f32_e32 v90, v90, v92
	s_nop 1
	v_add_f32_dpp v9, v9, v9 quad_perm:[1,0,3,2] row_mask:0xf bank_mask:0xf
	v_add_f32_dpp v90, v90, v90 quad_perm:[1,0,3,2] row_mask:0xf bank_mask:0xf
	s_nop 0
	v_add_f32_dpp v9, v9, v9 quad_perm:[2,3,0,1] row_mask:0xf bank_mask:0xf
	v_add_f32_dpp v90, v90, v90 quad_perm:[2,3,0,1] row_mask:0xf bank_mask:0xf
	s_nop 0
	v_add_f32_dpp v9, v9, v9 row_half_mirror row_mask:0xf bank_mask:0xf
	v_add_f32_dpp v90, v90, v90 row_half_mirror row_mask:0xf bank_mask:0xf
	s_nop 0
	v_add_f32_dpp v9, v9, v9 row_mirror row_mask:0xf bank_mask:0xf
	v_add_f32_dpp v90, v90, v90 row_mirror row_mask:0xf bank_mask:0xf
	s_nop 0
	v_add_f32_dpp v9, v9, v9 row_bcast:15 row_mask:0xa bank_mask:0xf
	v_add_f32_dpp v90, v90, v90 row_bcast:15 row_mask:0xa bank_mask:0xf
	s_nop 0
	v_add_f32_dpp v9, v9, v9 row_bcast:31 row_mask:0xc bank_mask:0xf
	v_add_f32_dpp v90, v90, v90 row_bcast:31 row_mask:0xc bank_mask:0xf
	s_nop 0
	v_readlane_b32 s2, v9, 63
	v_readlane_b32 s3, v90, 63
	s_nop 1
	v_mov_b32_e32 v9, s2
	v_mov_b32_e32 v90, s3
	v_mul_f32_e32 v93, 0x3a800000, v9
	v_mul_f32_e32 v91, 0x3a800000, v90
	v_fma_f32 v91, -v93, v93, v91
	v_max_f32_e32 v91, 0, v91
	v_add_f32_e32 v91, 0x358637bd, v91
	v_rsq_f32_e32 v94, v91
	v_mul_f32_e32 v91, 0.5, v91
	v_mul_f32_e32 v92, v94, v94
	v_fma_f32 v92, -v91, v92, 0.5
	v_fma_f32 v94, v94, v92, v94
	v_sub_f32_e32 v42, v42, v93
	v_sub_f32_e32 v43, v43, v93
	v_sub_f32_e32 v44, v44, v93
	v_sub_f32_e32 v45, v45, v93
	v_sub_f32_e32 v46, v46, v93
	v_sub_f32_e32 v47, v47, v93
	v_sub_f32_e32 v48, v48, v93
	v_sub_f32_e32 v49, v49, v93
	v_sub_f32_e32 v50, v50, v93
	v_sub_f32_e32 v51, v51, v93
	v_sub_f32_e32 v52, v52, v93
	v_sub_f32_e32 v53, v53, v93
	v_sub_f32_e32 v54, v54, v93
	v_sub_f32_e32 v55, v55, v93
	v_sub_f32_e32 v56, v56, v93
	v_sub_f32_e32 v57, v57, v93
	v_mul_f32_e32 v42, v94, v42
	v_mul_f32_e32 v43, v94, v43
	v_mul_f32_e32 v44, v94, v44
	v_mul_f32_e32 v45, v94, v45
	v_mul_f32_e32 v46, v94, v46
	v_mul_f32_e32 v47, v94, v47
	v_mul_f32_e32 v48, v94, v48
	v_mul_f32_e32 v49, v94, v49
	v_mul_f32_e32 v50, v94, v50
	v_mul_f32_e32 v51, v94, v51
	v_mul_f32_e32 v52, v94, v52
	v_mul_f32_e32 v53, v94, v53
	v_mul_f32_e32 v54, v94, v54
	v_mul_f32_e32 v55, v94, v55
	v_mul_f32_e32 v56, v94, v56
	v_mul_f32_e32 v57, v94, v57
	v_fma_f32 v42, v42, v10, v26
	v_fma_f32 v43, v43, v11, v27
	v_fma_f32 v44, v44, v12, v28
	v_fma_f32 v45, v45, v13, v29
	v_fma_f32 v46, v46, v14, v30
	v_fma_f32 v47, v47, v15, v31
	v_fma_f32 v48, v48, v16, v32
	v_fma_f32 v49, v49, v17, v33
	v_fma_f32 v50, v50, v18, v34
	v_fma_f32 v51, v51, v19, v35
	v_fma_f32 v52, v52, v20, v36
	v_fma_f32 v53, v53, v21, v37
	v_fma_f32 v54, v54, v22, v38
	v_fma_f32 v55, v55, v23, v39
	v_fma_f32 v56, v56, v24, v40
	v_fma_f32 v57, v57, v25, v41
	s_add_u32 s2, s8, 0x0
	s_addc_u32 s3, s9, 0
	global_store_dwordx4 v0, v[42:45], s[2:3]
	global_store_dwordx4 v0, v[46:49], s[2:3] offset:16
	global_store_dwordx4 v0, v[50:53], s[2:3] offset:2048
	global_store_dwordx4 v0, v[54:57], s[2:3] offset:2064
	s_add_u32 s2, s8, 0x4000
	s_addc_u32 s3, s9, 0
	global_load_dwordx4 v[42:45], v0, s[2:3]
	global_load_dwordx4 v[46:49], v0, s[2:3] offset:16
	global_load_dwordx4 v[50:53], v0, s[2:3] offset:2048
	global_load_dwordx4 v[54:57], v0, s[2:3] offset:2064
	s_waitcnt vmcnt(16)
; DI void ln_row_v(const Frame& F, f32x4 (&v)[4], float* xout, const float* g, const float* b, const float* sh, const float* sc, bf16_t* hout, const float* slab, const float* gres, float* stat = nullptr) {
;     ...
;         float s = 0.f, s2 = 0.f;
; #pragma unroll
;         for (int j = 0; j < 4; ++j) { s += (v[j][0] + v[j][1]) + (v[j][2] + v[j][3]); s2 += (v[j][0] * v[j][0] + v[j][1] * v[j][1]) + (v[j][2] * v[j][2] + v[j][3] * v[j][3]); }
;         wave_sum2(s, s2, F.lane);
;         const float mean = s * (1.f / D); const float rstd = 1.f / sqrtf(fmaxf(s2 * (1.f / D) - mean * mean, 0.f) + EPS);
;         if (stat && F.lane == 0) { f32x2 sv = {mean, rstd}; *(f32x2*)stat = sv; }
; #pragma unroll
;         for (int j = 0; j < 4; ++j) { const f32x4 gg = ((const f32x4*)g)[F.lane + 64 * j], bb = ((const f32x4*)b)[F.lane + 64 * j];
;             v[j] = (v[j] - mean) * rstd * gg + bb; if (xout) ((f32x4*)xout)[F.lane + 64 * j] = v[j]; }
;     }
	v_add_f32_e32 v9, v58, v59
	v_add_f32_e32 v91, v60, v61
	v_mul_f32_e32 v90, v58, v58
	v_mul_f32_e32 v92, v59, v59
	v_add_f32_e32 v9, v9, v62
	v_add_f32_e32 v91, v91, v63
	v_add_f32_e32 v9, v9, v64
	v_add_f32_e32 v91, v91, v65
	v_add_f32_e32 v9, v9, v66
	v_add_f32_e32 v91, v91, v67
	v_add_f32_e32 v9, v9, v68
	v_add_f32_e32 v91, v91, v69
	v_add_f32_e32 v9, v9, v70
	v_add_f32_e32 v91, v91, v71
	v_add_f32_e32 v9, v9, v72
	v_add_f32_e32 v91, v91, v73
	v_fmac_f32_e32 v90, v60, v60
	v_fmac_f32_e32 v92, v61, v61
	v_fmac_f32_e32 v90, v62, v62
	v_fmac_f32_e32 v92, v63, v63
	v_fmac_f32_e32 v90, v64, v64
	v_fmac_f32_e32 v92, v65, v65
	v_fmac_f32_e32 v90, v66, v66
	v_fmac_f32_e32 v92, v67, v67
	v_fmac_f32_e32 v90, v68, v68
	v_fmac_f32_e32 v92, v69, v69
	v_fmac_f32_e32 v90, v70, v70
	v_fmac_f32_e32 v92, v71, v71
	v_fmac_f32_e32 v90, v72, v72
	v_fmac_f32_e32 v92, v73, v73
	v_add_f32_e32 v9, v9, v91
	v_add_f32_e32 v90, v90, v92
	s_nop 1
	v_add_f32_dpp v9, v9, v9 quad_perm:[1,0,3,2] row_mask:0xf bank_mask:0xf
	v_add_f32_dpp v90, v90, v90 quad_perm:[1,0,3,2] row_mask:0xf bank_mask:0xf
	s_nop 0
	v_add_f32_dpp v9, v9, v9 quad_perm:[2,3,0,1] row_mask:0xf bank_mask:0xf
	v_add_f32_dpp v90, v90, v90 quad_perm:[2,3,0,1] row_mask:0xf bank_mask:0xf
	s_nop 0
	v_add_f32_dpp v9, v9, v9 row_half_mirror row_mask:0xf bank_mask:0xf
	v_add_f32_dpp v90, v90, v90 row_half_mirror row_mask:0xf bank_mask:0xf
	s_nop 0
	v_add_f32_dpp v9, v9, v9 row_mirror row_mask:0xf bank_mask:0xf
	v_add_f32_dpp v90, v90, v90 row_mirror row_mask:0xf bank_mask:0xf
	s_nop 0
	v_add_f32_dpp v9, v9, v9 row_bcast:15 row_mask:0xa bank_mask:0xf
	v_add_f32_dpp v90, v90, v90 row_bcast:15 row_mask:0xa bank_mask:0xf
	s_nop 0
	v_add_f32_dpp v9, v9, v9 row_bcast:31 row_mask:0xc bank_mask:0xf
	v_add_f32_dpp v90, v90, v90 row_bcast:31 row_mask:0xc bank_mask:0xf
	s_nop 0
	v_readlane_b32 s2, v9, 63
	v_readlane_b32 s3, v90, 63
	s_nop 1
	v_mov_b32_e32 v9, s2
	v_mov_b32_e32 v90, s3
	v_mul_f32_e32 v93, 0x3a800000, v9
	v_mul_f32_e32 v91, 0x3a800000, v90
	v_fma_f32 v91, -v93, v93, v91
	v_max_f32_e32 v91, 0, v91
	v_add_f32_e32 v91, 0x358637bd, v91
	v_rsq_f32_e32 v94, v91
	v_mul_f32_e32 v91, 0.5, v91
	v_mul_f32_e32 v92, v94, v94
	v_fma_f32 v92, -v91, v92, 0.5
	v_fma_f32 v94, v94, v92, v94
	v_sub_f32_e32 v58, v58, v93
	v_sub_f32_e32 v59, v59, v93
	v_sub_f32_e32 v60, v60, v93
	v_sub_f32_e32 v61, v61, v93
	v_sub_f32_e32 v62, v62, v93
	v_sub_f32_e32 v63, v63, v93
	v_sub_f32_e32 v64, v64, v93
	v_sub_f32_e32 v65, v65, v93
	v_sub_f32_e32 v66, v66, v93
	v_sub_f32_e32 v67, v67, v93
	v_sub_f32_e32 v68, v68, v93
	v_sub_f32_e32 v69, v69, v93
	v_sub_f32_e32 v70, v70, v93
	v_sub_f32_e32 v71, v71, v93
	v_sub_f32_e32 v72, v72, v93
	v_sub_f32_e32 v73, v73, v93
	v_mul_f32_e32 v58, v94, v58
	v_mul_f32_e32 v59, v94, v59
	v_mul_f32_e32 v60, v94, v60
	v_mul_f32_e32 v61, v94, v61
	v_mul_f32_e32 v62, v94, v62
	v_mul_f32_e32 v63, v94, v63
	v_mul_f32_e32 v64, v94, v64
	v_mul_f32_e32 v65, v94, v65
	v_mul_f32_e32 v66, v94, v66
	v_mul_f32_e32 v67, v94, v67
	v_mul_f32_e32 v68, v94, v68
	v_mul_f32_e32 v69, v94, v69
	v_mul_f32_e32 v70, v94, v70
	v_mul_f32_e32 v71, v94, v71
	v_mul_f32_e32 v72, v94, v72
	v_mul_f32_e32 v73, v94, v73
	v_fma_f32 v58, v58, v10, v26
	v_fma_f32 v59, v59, v11, v27
	v_fma_f32 v60, v60, v12, v28
	v_fma_f32 v61, v61, v13, v29
	v_fma_f32 v62, v62, v14, v30
	v_fma_f32 v63, v63, v15, v31
	v_fma_f32 v64, v64, v16, v32
	v_fma_f32 v65, v65, v17, v33
	v_fma_f32 v66, v66, v18, v34
	v_fma_f32 v67, v67, v19, v35
	v_fma_f32 v68, v68, v20, v36
	v_fma_f32 v69, v69, v21, v37
	v_fma_f32 v70, v70, v22, v38
	v_fma_f32 v71, v71, v23, v39
	v_fma_f32 v72, v72, v24, v40
	v_fma_f32 v73, v73, v25, v41
	s_add_u32 s2, s8, 0x1000
	s_addc_u32 s3, s9, 0
	global_store_dwordx4 v0, v[58:61], s[2:3]
	global_store_dwordx4 v0, v[62:65], s[2:3] offset:16
	global_store_dwordx4 v0, v[66:69], s[2:3] offset:2048
	global_store_dwordx4 v0, v[70:73], s[2:3] offset:2064
	s_add_u32 s2, s8, 0x5000
	s_addc_u32 s3, s9, 0
	global_load_dwordx4 v[58:61], v0, s[2:3]
	global_load_dwordx4 v[62:65], v0, s[2:3] offset:16
	global_load_dwordx4 v[66:69], v0, s[2:3] offset:2048
	global_load_dwordx4 v[70:73], v0, s[2:3] offset:2064
	s_waitcnt vmcnt(20)
	v_add_f32_e32 v9, v74, v75
	v_add_f32_e32 v91, v76, v77
	v_mul_f32_e32 v90, v74, v74
	v_mul_f32_e32 v92, v75, v75
	v_add_f32_e32 v9, v9, v78
	v_add_f32_e32 v91, v91, v79
	v_add_f32_e32 v9, v9, v80
	v_add_f32_e32 v91, v91, v81
	v_add_f32_e32 v9, v9, v82
	v_add_f32_e32 v91, v91, v83
	v_add_f32_e32 v9, v9, v84
	v_add_f32_e32 v91, v91, v85
	v_add_f32_e32 v9, v9, v86
	v_add_f32_e32 v91, v91, v87
	v_add_f32_e32 v9, v9, v88
	v_add_f32_e32 v91, v91, v89
	v_fmac_f32_e32 v90, v76, v76
	v_fmac_f32_e32 v92, v77, v77
	v_fmac_f32_e32 v90, v78, v78
	v_fmac_f32_e32 v92, v79, v79
	v_fmac_f32_e32 v90, v80, v80
	v_fmac_f32_e32 v92, v81, v81
	v_fmac_f32_e32 v90, v82, v82
	v_fmac_f32_e32 v92, v83, v83
	v_fmac_f32_e32 v90, v84, v84
	v_fmac_f32_e32 v92, v85, v85
	v_fmac_f32_e32 v90, v86, v86
	v_fmac_f32_e32 v92, v87, v87
	v_fmac_f32_e32 v90, v88, v88
	v_fmac_f32_e32 v92, v89, v89
	v_add_f32_e32 v9, v9, v91
	v_add_f32_e32 v90, v90, v92
	s_nop 1
	v_add_f32_dpp v9, v9, v9 quad_perm:[1,0,3,2] row_mask:0xf bank_mask:0xf
	v_add_f32_dpp v90, v90, v90 quad_perm:[1,0,3,2] row_mask:0xf bank_mask:0xf
	s_nop 0
	v_add_f32_dpp v9, v9, v9 quad_perm:[2,3,0,1] row_mask:0xf bank_mask:0xf
	v_add_f32_dpp v90, v90, v90 quad_perm:[2,3,0,1] row_mask:0xf bank_mask:0xf
	s_nop 0
	v_add_f32_dpp v9, v9, v9 row_half_mirror row_mask:0xf bank_mask:0xf
	v_add_f32_dpp v90, v90, v90 row_half_mirror row_mask:0xf bank_mask:0xf
	s_nop 0
	v_add_f32_dpp v9, v9, v9 row_mirror row_mask:0xf bank_mask:0xf
; DI void ln_row_v(const Frame& F, f32x4 (&v)[4], float* xout, const float* g, const float* b, const float* sh, const float* sc, bf16_t* hout, const float* slab, const float* gres, float* stat = nullptr) {
;     ...
;         float s = 0.f, s2 = 0.f;
; #pragma unroll
;         for (int j = 0; j < 4; ++j) { s += (v[j][0] + v[j][1]) + (v[j][2] + v[j][3]); s2 += (v[j][0] * v[j][0] + v[j][1] * v[j][1]) + (v[j][2] * v[j][2] + v[j][3] * v[j][3]); }
;         wave_sum2(s, s2, F.lane);
;         const float mean = s * (1.f / D); const float rstd = 1.f / sqrtf(fmaxf(s2 * (1.f / D) - mean * mean, 0.f) + EPS);
;         if (stat && F.lane == 0) { f32x2 sv = {mean, rstd}; *(f32x2*)stat = sv; }
; #pragma unroll
;         for (int j = 0; j < 4; ++j) { const f32x4 gg = ((const f32x4*)g)[F.lane + 64 * j], bb = ((const f32x4*)b)[F.lane + 64 * j];
;             v[j] = (v[j] - mean) * rstd * gg + bb; if (xout) ((f32x4*)xout)[F.lane + 64 * j] = v[j]; }
;     }
	v_add_f32_dpp v90, v90, v90 row_mirror row_mask:0xf bank_mask:0xf
	s_nop 0
	v_add_f32_dpp v9, v9, v9 row_bcast:15 row_mask:0xa bank_mask:0xf
	v_add_f32_dpp v90, v90, v90 row_bcast:15 row_mask:0xa bank_mask:0xf
	s_nop 0
	v_add_f32_dpp v9, v9, v9 row_bcast:31 row_mask:0xc bank_mask:0xf
	v_add_f32_dpp v90, v90, v90 row_bcast:31 row_mask:0xc bank_mask:0xf
	s_nop 0
	v_readlane_b32 s2, v9, 63
	v_readlane_b32 s3, v90, 63
	s_nop 1
	v_mov_b32_e32 v9, s2
	v_mov_b32_e32 v90, s3
	v_mul_f32_e32 v93, 0x3a800000, v9
	v_mul_f32_e32 v91, 0x3a800000, v90
	v_fma_f32 v91, -v93, v93, v91
	v_max_f32_e32 v91, 0, v91
	v_add_f32_e32 v91, 0x358637bd, v91
	v_rsq_f32_e32 v94, v91
	v_mul_f32_e32 v91, 0.5, v91
	v_mul_f32_e32 v92, v94, v94
	v_fma_f32 v92, -v91, v92, 0.5
	v_fma_f32 v94, v94, v92, v94
	v_sub_f32_e32 v74, v74, v93
	v_sub_f32_e32 v75, v75, v93
	v_sub_f32_e32 v76, v76, v93
	v_sub_f32_e32 v77, v77, v93
	v_sub_f32_e32 v78, v78, v93
	v_sub_f32_e32 v79, v79, v93
	v_sub_f32_e32 v80, v80, v93
	v_sub_f32_e32 v81, v81, v93
	v_sub_f32_e32 v82, v82, v93
	v_sub_f32_e32 v83, v83, v93
	v_sub_f32_e32 v84, v84, v93
	v_sub_f32_e32 v85, v85, v93
	v_sub_f32_e32 v86, v86, v93
	v_sub_f32_e32 v87, v87, v93
	v_sub_f32_e32 v88, v88, v93
	v_sub_f32_e32 v89, v89, v93
	v_mul_f32_e32 v74, v94, v74
	v_mul_f32_e32 v75, v94, v75
	v_mul_f32_e32 v76, v94, v76
	v_mul_f32_e32 v77, v94, v77
	v_mul_f32_e32 v78, v94, v78
	v_mul_f32_e32 v79, v94, v79
	v_mul_f32_e32 v80, v94, v80
	v_mul_f32_e32 v81, v94, v81
	v_mul_f32_e32 v82, v94, v82
	v_mul_f32_e32 v83, v94, v83
	v_mul_f32_e32 v84, v94, v84
	v_mul_f32_e32 v85, v94, v85
	v_mul_f32_e32 v86, v94, v86
	v_mul_f32_e32 v87, v94, v87
	v_mul_f32_e32 v88, v94, v88
	v_mul_f32_e32 v89, v94, v89
	v_fma_f32 v74, v74, v10, v26
	v_fma_f32 v75, v75, v11, v27
	v_fma_f32 v76, v76, v12, v28
	v_fma_f32 v77, v77, v13, v29
	v_fma_f32 v78, v78, v14, v30
	v_fma_f32 v79, v79, v15, v31
	v_fma_f32 v80, v80, v16, v32
	v_fma_f32 v81, v81, v17, v33
	v_fma_f32 v82, v82, v18, v34
	v_fma_f32 v83, v83, v19, v35
	v_fma_f32 v84, v84, v20, v36
	v_fma_f32 v85, v85, v21, v37
	v_fma_f32 v86, v86, v22, v38
	v_fma_f32 v87, v87, v23, v39
	v_fma_f32 v88, v88, v24, v40
	v_fma_f32 v89, v89, v25, v41
	s_add_u32 s2, s8, 0x2000
	s_addc_u32 s3, s9, 0
	global_store_dwordx4 v0, v[74:77], s[2:3]
	global_store_dwordx4 v0, v[78:81], s[2:3] offset:16
	global_store_dwordx4 v0, v[82:85], s[2:3] offset:2048
	global_store_dwordx4 v0, v[86:89], s[2:3] offset:2064
	s_add_u32 s2, s8, 0x6000
	s_addc_u32 s3, s9, 0
	global_load_dwordx4 v[74:77], v0, s[2:3]
	global_load_dwordx4 v[78:81], v0, s[2:3] offset:16
	global_load_dwordx4 v[82:85], v0, s[2:3] offset:2048
	global_load_dwordx4 v[86:89], v0, s[2:3] offset:2064
	s_waitcnt vmcnt(24)
	v_add_f32_e32 v9, v98, v99
	v_add_f32_e32 v91, v100, v101
	v_mul_f32_e32 v90, v98, v98
	v_mul_f32_e32 v92, v99, v99
	v_add_f32_e32 v9, v9, v102
	v_add_f32_e32 v91, v91, v103
	v_add_f32_e32 v9, v9, v104
	v_add_f32_e32 v91, v91, v105
	v_add_f32_e32 v9, v9, v106
	v_add_f32_e32 v91, v91, v107
	v_add_f32_e32 v9, v9, v108
	v_add_f32_e32 v91, v91, v109
	v_add_f32_e32 v9, v9, v110
	v_add_f32_e32 v91, v91, v111
	v_add_f32_e32 v9, v9, v112
	v_add_f32_e32 v91, v91, v113
	v_fmac_f32_e32 v90, v100, v100
	v_fmac_f32_e32 v92, v101, v101
	v_fmac_f32_e32 v90, v102, v102
	v_fmac_f32_e32 v92, v103, v103
	v_fmac_f32_e32 v90, v104, v104
	v_fmac_f32_e32 v92, v105, v105
	v_fmac_f32_e32 v90, v106, v106
	v_fmac_f32_e32 v92, v107, v107
	v_fmac_f32_e32 v90, v108, v108
	v_fmac_f32_e32 v92, v109, v109
	v_fmac_f32_e32 v90, v110, v110
	v_fmac_f32_e32 v92, v111, v111
	v_fmac_f32_e32 v90, v112, v112
	v_fmac_f32_e32 v92, v113, v113
	v_add_f32_e32 v9, v9, v91
	v_add_f32_e32 v90, v90, v92
	s_nop 1
	v_add_f32_dpp v9, v9, v9 quad_perm:[1,0,3,2] row_mask:0xf bank_mask:0xf
	v_add_f32_dpp v90, v90, v90 quad_perm:[1,0,3,2] row_mask:0xf bank_mask:0xf
	s_nop 0
	v_add_f32_dpp v9, v9, v9 quad_perm:[2,3,0,1] row_mask:0xf bank_mask:0xf
	v_add_f32_dpp v90, v90, v90 quad_perm:[2,3,0,1] row_mask:0xf bank_mask:0xf
	s_nop 0
	v_add_f32_dpp v9, v9, v9 row_half_mirror row_mask:0xf bank_mask:0xf
	v_add_f32_dpp v90, v90, v90 row_half_mirror row_mask:0xf bank_mask:0xf
	s_nop 0
	v_add_f32_dpp v9, v9, v9 row_mirror row_mask:0xf bank_mask:0xf
	v_add_f32_dpp v90, v90, v90 row_mirror row_mask:0xf bank_mask:0xf
	s_nop 0
	v_add_f32_dpp v9, v9, v9 row_bcast:15 row_mask:0xa bank_mask:0xf
	v_add_f32_dpp v90, v90, v90 row_bcast:15 row_mask:0xa bank_mask:0xf
	s_nop 0
	v_add_f32_dpp v9, v9, v9 row_bcast:31 row_mask:0xc bank_mask:0xf
	v_add_f32_dpp v90, v90, v90 row_bcast:31 row_mask:0xc bank_mask:0xf
	s_nop 0
	v_readlane_b32 s2, v9, 63
	v_readlane_b32 s3, v90, 63
	s_nop 1
	v_mov_b32_e32 v9, s2
	v_mov_b32_e32 v90, s3
	v_mul_f32_e32 v93, 0x3a800000, v9
	v_mul_f32_e32 v91, 0x3a800000, v90
	v_fma_f32 v91, -v93, v93, v91
	v_max_f32_e32 v91, 0, v91
	v_add_f32_e32 v91, 0x358637bd, v91
	v_rsq_f32_e32 v94, v91
	v_mul_f32_e32 v91, 0.5, v91
	v_mul_f32_e32 v92, v94, v94
	v_fma_f32 v92, -v91, v92, 0.5
	v_fma_f32 v94, v94, v92, v94
	v_sub_f32_e32 v98, v98, v93
	v_sub_f32_e32 v99, v99, v93
	v_sub_f32_e32 v100, v100, v93
	v_sub_f32_e32 v101, v101, v93
	v_sub_f32_e32 v102, v102, v93
	v_sub_f32_e32 v103, v103, v93
	v_sub_f32_e32 v104, v104, v93
	v_sub_f32_e32 v105, v105, v93
	v_sub_f32_e32 v106, v106, v93
	v_sub_f32_e32 v107, v107, v93
	v_sub_f32_e32 v108, v108, v93
	v_sub_f32_e32 v109, v109, v93
	v_sub_f32_e32 v110, v110, v93
	v_sub_f32_e32 v111, v111, v93
	v_sub_f32_e32 v112, v112, v93
	v_sub_f32_e32 v113, v113, v93
	v_mul_f32_e32 v98, v94, v98
	v_mul_f32_e32 v99, v94, v99
	v_mul_f32_e32 v100, v94, v100
	v_mul_f32_e32 v101, v94, v101
	v_mul_f32_e32 v102, v94, v102
	v_mul_f32_e32 v103, v94, v103
	v_mul_f32_e32 v104, v94, v104
	v_mul_f32_e32 v105, v94, v105
	v_mul_f32_e32 v106, v94, v106
	v_mul_f32_e32 v107, v94, v107
	v_mul_f32_e32 v108, v94, v108
	v_mul_f32_e32 v109, v94, v109
	v_mul_f32_e32 v110, v94, v110
	v_mul_f32_e32 v111, v94, v111
	v_mul_f32_e32 v112, v94, v112
	v_mul_f32_e32 v113, v94, v113
	v_fma_f32 v98, v98, v10, v26
	v_fma_f32 v99, v99, v11, v27
	v_fma_f32 v100, v100, v12, v28
	v_fma_f32 v101, v101, v13, v29
	v_fma_f32 v102, v102, v14, v30
	v_fma_f32 v103, v103, v15, v31
	v_fma_f32 v104, v104, v16, v32
	v_fma_f32 v105, v105, v17, v33
	v_fma_f32 v106, v106, v18, v34
	v_fma_f32 v107, v107, v19, v35
	v_fma_f32 v108, v108, v20, v36
	v_fma_f32 v109, v109, v21, v37
	v_fma_f32 v110, v110, v22, v38
	v_fma_f32 v111, v111, v23, v39
	v_fma_f32 v112, v112, v24, v40
	v_fma_f32 v113, v113, v25, v41
	s_add_u32 s2, s8, 0x3000
	s_addc_u32 s3, s9, 0
	global_store_dwordx4 v0, v[98:101], s[2:3]
	global_store_dwordx4 v0, v[102:105], s[2:3] offset:16
	global_store_dwordx4 v0, v[106:109], s[2:3] offset:2048
	global_store_dwordx4 v0, v[110:113], s[2:3] offset:2064
	s_add_u32 s2, s8, 0x7000
	s_addc_u32 s3, s9, 0
	global_load_dwordx4 v[98:101], v0, s[2:3]
	global_load_dwordx4 v[102:105], v0, s[2:3] offset:16
	global_load_dwordx4 v[106:109], v0, s[2:3] offset:2048
	global_load_dwordx4 v[110:113], v0, s[2:3] offset:2064
	s_waitcnt vmcnt(24)
; DI void ln_row_v(const Frame& F, f32x4 (&v)[4], float* xout, const float* g, const float* b, const float* sh, const float* sc, bf16_t* hout, const float* slab, const float* gres, float* stat = nullptr) {
;     ...
;         float s = 0.f, s2 = 0.f;
; #pragma unroll
;         for (int j = 0; j < 4; ++j) { s += (v[j][0] + v[j][1]) + (v[j][2] + v[j][3]); s2 += (v[j][0] * v[j][0] + v[j][1] * v[j][1]) + (v[j][2] * v[j][2] + v[j][3] * v[j][3]); }
;         wave_sum2(s, s2, F.lane);
;         const float mean = s * (1.f / D); const float rstd = 1.f / sqrtf(fmaxf(s2 * (1.f / D) - mean * mean, 0.f) + EPS);
;         if (stat && F.lane == 0) { f32x2 sv = {mean, rstd}; *(f32x2*)stat = sv; }
; #pragma unroll
;         for (int j = 0; j < 4; ++j) { const f32x4 gg = ((const f32x4*)g)[F.lane + 64 * j], bb = ((const f32x4*)b)[F.lane + 64 * j];
;             v[j] = (v[j] - mean) * rstd * gg + bb; if (xout) ((f32x4*)xout)[F.lane + 64 * j] = v[j]; }
;     }
	v_add_f32_e32 v9, v42, v43
	v_add_f32_e32 v91, v44, v45
	v_mul_f32_e32 v90, v42, v42
	v_mul_f32_e32 v92, v43, v43
	v_add_f32_e32 v9, v9, v46
	v_add_f32_e32 v91, v91, v47
	v_add_f32_e32 v9, v9, v48
	v_add_f32_e32 v91, v91, v49
	v_add_f32_e32 v9, v9, v50
	v_add_f32_e32 v91, v91, v51
	v_add_f32_e32 v9, v9, v52
	v_add_f32_e32 v91, v91, v53
	v_add_f32_e32 v9, v9, v54
	v_add_f32_e32 v91, v91, v55
	v_add_f32_e32 v9, v9, v56
	v_add_f32_e32 v91, v91, v57
	v_fmac_f32_e32 v90, v44, v44
	v_fmac_f32_e32 v92, v45, v45
	v_fmac_f32_e32 v90, v46, v46
	v_fmac_f32_e32 v92, v47, v47
	v_fmac_f32_e32 v90, v48, v48
	v_fmac_f32_e32 v92, v49, v49
	v_fmac_f32_e32 v90, v50, v50
	v_fmac_f32_e32 v92, v51, v51
	v_fmac_f32_e32 v90, v52, v52
	v_fmac_f32_e32 v92, v53, v53
	v_fmac_f32_e32 v90, v54, v54
	v_fmac_f32_e32 v92, v55, v55
	v_fmac_f32_e32 v90, v56, v56
	v_fmac_f32_e32 v92, v57, v57
	v_add_f32_e32 v9, v9, v91
	v_add_f32_e32 v90, v90, v92
	s_nop 1
	v_add_f32_dpp v9, v9, v9 quad_perm:[1,0,3,2] row_mask:0xf bank_mask:0xf
	v_add_f32_dpp v90, v90, v90 quad_perm:[1,0,3,2] row_mask:0xf bank_mask:0xf
	s_nop 0
	v_add_f32_dpp v9, v9, v9 quad_perm:[2,3,0,1] row_mask:0xf bank_mask:0xf
	v_add_f32_dpp v90, v90, v90 quad_perm:[2,3,0,1] row_mask:0xf bank_mask:0xf
	s_nop 0
	v_add_f32_dpp v9, v9, v9 row_half_mirror row_mask:0xf bank_mask:0xf
	v_add_f32_dpp v90, v90, v90 row_half_mirror row_mask:0xf bank_mask:0xf
	s_nop 0
	v_add_f32_dpp v9, v9, v9 row_mirror row_mask:0xf bank_mask:0xf
	v_add_f32_dpp v90, v90, v90 row_mirror row_mask:0xf bank_mask:0xf
	s_nop 0
	v_add_f32_dpp v9, v9, v9 row_bcast:15 row_mask:0xa bank_mask:0xf
	v_add_f32_dpp v90, v90, v90 row_bcast:15 row_mask:0xa bank_mask:0xf
	s_nop 0
	v_add_f32_dpp v9, v9, v9 row_bcast:31 row_mask:0xc bank_mask:0xf
	v_add_f32_dpp v90, v90, v90 row_bcast:31 row_mask:0xc bank_mask:0xf
	s_nop 0
	v_readlane_b32 s2, v9, 63
	v_readlane_b32 s3, v90, 63
	s_nop 1
	v_mov_b32_e32 v9, s2
	v_mov_b32_e32 v90, s3
	v_mul_f32_e32 v93, 0x3a800000, v9
	v_mul_f32_e32 v91, 0x3a800000, v90
	v_fma_f32 v91, -v93, v93, v91
	v_max_f32_e32 v91, 0, v91
	v_add_f32_e32 v91, 0x358637bd, v91
	v_rsq_f32_e32 v94, v91
	v_mul_f32_e32 v91, 0.5, v91
	v_mul_f32_e32 v92, v94, v94
	v_fma_f32 v92, -v91, v92, 0.5
	v_fma_f32 v94, v94, v92, v94
	v_sub_f32_e32 v42, v42, v93
	v_sub_f32_e32 v43, v43, v93
	v_sub_f32_e32 v44, v44, v93
	v_sub_f32_e32 v45, v45, v93
	v_sub_f32_e32 v46, v46, v93
	v_sub_f32_e32 v47, v47, v93
	v_sub_f32_e32 v48, v48, v93
	v_sub_f32_e32 v49, v49, v93
	v_sub_f32_e32 v50, v50, v93
	v_sub_f32_e32 v51, v51, v93
	v_sub_f32_e32 v52, v52, v93
	v_sub_f32_e32 v53, v53, v93
	v_sub_f32_e32 v54, v54, v93
	v_sub_f32_e32 v55, v55, v93
	v_sub_f32_e32 v56, v56, v93
	v_sub_f32_e32 v57, v57, v93
	v_mul_f32_e32 v42, v94, v42
	v_mul_f32_e32 v43, v94, v43
	v_mul_f32_e32 v44, v94, v44
	v_mul_f32_e32 v45, v94, v45
	v_mul_f32_e32 v46, v94, v46
	v_mul_f32_e32 v47, v94, v47
	v_mul_f32_e32 v48, v94, v48
	v_mul_f32_e32 v49, v94, v49
	v_mul_f32_e32 v50, v94, v50
	v_mul_f32_e32 v51, v94, v51
	v_mul_f32_e32 v52, v94, v52
	v_mul_f32_e32 v53, v94, v53
	v_mul_f32_e32 v54, v94, v54
	v_mul_f32_e32 v55, v94, v55
	v_mul_f32_e32 v56, v94, v56
	v_mul_f32_e32 v57, v94, v57
	v_fma_f32 v42, v42, v10, v26
	v_fma_f32 v43, v43, v11, v27
	v_fma_f32 v44, v44, v12, v28
	v_fma_f32 v45, v45, v13, v29
	v_fma_f32 v46, v46, v14, v30
	v_fma_f32 v47, v47, v15, v31
	v_fma_f32 v48, v48, v16, v32
	v_fma_f32 v49, v49, v17, v33
	v_fma_f32 v50, v50, v18, v34
	v_fma_f32 v51, v51, v19, v35
	v_fma_f32 v52, v52, v20, v36
	v_fma_f32 v53, v53, v21, v37
	v_fma_f32 v54, v54, v22, v38
	v_fma_f32 v55, v55, v23, v39
	v_fma_f32 v56, v56, v24, v40
	v_fma_f32 v57, v57, v25, v41
	s_add_u32 s2, s8, 0x4000
	s_addc_u32 s3, s9, 0
	global_store_dwordx4 v0, v[42:45], s[2:3]
	global_store_dwordx4 v0, v[46:49], s[2:3] offset:16
	global_store_dwordx4 v0, v[50:53], s[2:3] offset:2048
	global_store_dwordx4 v0, v[54:57], s[2:3] offset:2064
	s_waitcnt vmcnt(20)
	v_add_f32_e32 v9, v58, v59
	v_add_f32_e32 v91, v60, v61
	v_mul_f32_e32 v90, v58, v58
	v_mul_f32_e32 v92, v59, v59
	v_add_f32_e32 v9, v9, v62
	v_add_f32_e32 v91, v91, v63
	v_add_f32_e32 v9, v9, v64
	v_add_f32_e32 v91, v91, v65
	v_add_f32_e32 v9, v9, v66
	v_add_f32_e32 v91, v91, v67
	v_add_f32_e32 v9, v9, v68
	v_add_f32_e32 v91, v91, v69
	v_add_f32_e32 v9, v9, v70
	v_add_f32_e32 v91, v91, v71
	v_add_f32_e32 v9, v9, v72
	v_add_f32_e32 v91, v91, v73
	v_fmac_f32_e32 v90, v60, v60
	v_fmac_f32_e32 v92, v61, v61
	v_fmac_f32_e32 v90, v62, v62
	v_fmac_f32_e32 v92, v63, v63
	v_fmac_f32_e32 v90, v64, v64
	v_fmac_f32_e32 v92, v65, v65
	v_fmac_f32_e32 v90, v66, v66
	v_fmac_f32_e32 v92, v67, v67
	v_fmac_f32_e32 v90, v68, v68
	v_fmac_f32_e32 v92, v69, v69
	v_fmac_f32_e32 v90, v70, v70
	v_fmac_f32_e32 v92, v71, v71
	v_fmac_f32_e32 v90, v72, v72
	v_fmac_f32_e32 v92, v73, v73
	v_add_f32_e32 v9, v9, v91
	v_add_f32_e32 v90, v90, v92
	s_nop 1
	v_add_f32_dpp v9, v9, v9 quad_perm:[1,0,3,2] row_mask:0xf bank_mask:0xf
	v_add_f32_dpp v90, v90, v90 quad_perm:[1,0,3,2] row_mask:0xf bank_mask:0xf
	s_nop 0
	v_add_f32_dpp v9, v9, v9 quad_perm:[2,3,0,1] row_mask:0xf bank_mask:0xf
	v_add_f32_dpp v90, v90, v90 quad_perm:[2,3,0,1] row_mask:0xf bank_mask:0xf
	s_nop 0
	v_add_f32_dpp v9, v9, v9 row_half_mirror row_mask:0xf bank_mask:0xf
	v_add_f32_dpp v90, v90, v90 row_half_mirror row_mask:0xf bank_mask:0xf
	s_nop 0
	v_add_f32_dpp v9, v9, v9 row_mirror row_mask:0xf bank_mask:0xf
	v_add_f32_dpp v90, v90, v90 row_mirror row_mask:0xf bank_mask:0xf
	s_nop 0
	v_add_f32_dpp v9, v9, v9 row_bcast:15 row_mask:0xa bank_mask:0xf
	v_add_f32_dpp v90, v90, v90 row_bcast:15 row_mask:0xa bank_mask:0xf
	s_nop 0
; DI void ln_row_v(const Frame& F, f32x4 (&v)[4], float* xout, const float* g, const float* b, const float* sh, const float* sc, bf16_t* hout, const float* slab, const float* gres, float* stat = nullptr) {
;     ...
;     if (g) {
;         float s = 0.f, s2 = 0.f;
; #pragma unroll
;         for (int j = 0; j < 4; ++j) { s += (v[j][0] + v[j][1]) + (v[j][2] + v[j][3]); s2 += (v[j][0] * v[j][0] + v[j][1] * v[j][1]) + (v[j][2] * v[j][2] + v[j][3] * v[j][3]); }
;         wave_sum2(s, s2, F.lane);
;         const float mean = s * (1.f / D); const float rstd = 1.f / sqrtf(fmaxf(s2 * (1.f / D) - mean * mean, 0.f) + EPS);
;         if (stat && F.lane == 0) { f32x2 sv = {mean, rstd}; *(f32x2*)stat = sv; }
; #pragma unroll
;         for (int j = 0; j < 4; ++j) { const f32x4 gg = ((const f32x4*)g)[F.lane + 64 * j], bb = ((const f32x4*)b)[F.lane + 64 * j];
;             v[j] = (v[j] - mean) * rstd * gg + bb; if (xout) ((f32x4*)xout)[F.lane + 64 * j] = v[j]; }
;     }
	v_add_f32_dpp v9, v9, v9 row_bcast:31 row_mask:0xc bank_mask:0xf
	v_add_f32_dpp v90, v90, v90 row_bcast:31 row_mask:0xc bank_mask:0xf
	s_nop 0
	v_readlane_b32 s2, v9, 63
	v_readlane_b32 s3, v90, 63
	s_nop 1
	v_mov_b32_e32 v9, s2
	v_mov_b32_e32 v90, s3
	v_mul_f32_e32 v93, 0x3a800000, v9
	v_mul_f32_e32 v91, 0x3a800000, v90
	v_fma_f32 v91, -v93, v93, v91
	v_max_f32_e32 v91, 0, v91
	v_add_f32_e32 v91, 0x358637bd, v91
	v_rsq_f32_e32 v94, v91
	v_mul_f32_e32 v91, 0.5, v91
	v_mul_f32_e32 v92, v94, v94
	v_fma_f32 v92, -v91, v92, 0.5
	v_fma_f32 v94, v94, v92, v94
	v_sub_f32_e32 v58, v58, v93
	v_sub_f32_e32 v59, v59, v93
	v_sub_f32_e32 v60, v60, v93
	v_sub_f32_e32 v61, v61, v93
	v_sub_f32_e32 v62, v62, v93
	v_sub_f32_e32 v63, v63, v93
	v_sub_f32_e32 v64, v64, v93
	v_sub_f32_e32 v65, v65, v93
	v_sub_f32_e32 v66, v66, v93
	v_sub_f32_e32 v67, v67, v93
	v_sub_f32_e32 v68, v68, v93
	v_sub_f32_e32 v69, v69, v93
	v_sub_f32_e32 v70, v70, v93
	v_sub_f32_e32 v71, v71, v93
	v_sub_f32_e32 v72, v72, v93
	v_sub_f32_e32 v73, v73, v93
	v_mul_f32_e32 v58, v94, v58
	v_mul_f32_e32 v59, v94, v59
	v_mul_f32_e32 v60, v94, v60
	v_mul_f32_e32 v61, v94, v61
	v_mul_f32_e32 v62, v94, v62
	v_mul_f32_e32 v63, v94, v63
	v_mul_f32_e32 v64, v94, v64
	v_mul_f32_e32 v65, v94, v65
	v_mul_f32_e32 v66, v94, v66
	v_mul_f32_e32 v67, v94, v67
	v_mul_f32_e32 v68, v94, v68
	v_mul_f32_e32 v69, v94, v69
	v_mul_f32_e32 v70, v94, v70
	v_mul_f32_e32 v71, v94, v71
	v_mul_f32_e32 v72, v94, v72
	v_mul_f32_e32 v73, v94, v73
	v_fma_f32 v58, v58, v10, v26
	v_fma_f32 v59, v59, v11, v27
	v_fma_f32 v60, v60, v12, v28
	v_fma_f32 v61, v61, v13, v29
	v_fma_f32 v62, v62, v14, v30
	v_fma_f32 v63, v63, v15, v31
	v_fma_f32 v64, v64, v16, v32
	v_fma_f32 v65, v65, v17, v33
	v_fma_f32 v66, v66, v18, v34
	v_fma_f32 v67, v67, v19, v35
	v_fma_f32 v68, v68, v20, v36
	v_fma_f32 v69, v69, v21, v37
	v_fma_f32 v70, v70, v22, v38
	v_fma_f32 v71, v71, v23, v39
	v_fma_f32 v72, v72, v24, v40
	v_fma_f32 v73, v73, v25, v41
	s_add_u32 s2, s8, 0x5000
	s_addc_u32 s3, s9, 0
	global_store_dwordx4 v0, v[58:61], s[2:3]
	global_store_dwordx4 v0, v[62:65], s[2:3] offset:16
	global_store_dwordx4 v0, v[66:69], s[2:3] offset:2048
	global_store_dwordx4 v0, v[70:73], s[2:3] offset:2064
	s_waitcnt vmcnt(16)
	v_add_f32_e32 v9, v74, v75
	v_add_f32_e32 v91, v76, v77
	v_mul_f32_e32 v90, v74, v74
	v_mul_f32_e32 v92, v75, v75
	v_add_f32_e32 v9, v9, v78
	v_add_f32_e32 v91, v91, v79
	v_add_f32_e32 v9, v9, v80
	v_add_f32_e32 v91, v91, v81
	v_add_f32_e32 v9, v9, v82
	v_add_f32_e32 v91, v91, v83
	v_add_f32_e32 v9, v9, v84
	v_add_f32_e32 v91, v91, v85
	v_add_f32_e32 v9, v9, v86
	v_add_f32_e32 v91, v91, v87
	v_add_f32_e32 v9, v9, v88
	v_add_f32_e32 v91, v91, v89
	v_fmac_f32_e32 v90, v76, v76
	v_fmac_f32_e32 v92, v77, v77
	v_fmac_f32_e32 v90, v78, v78
	v_fmac_f32_e32 v92, v79, v79
	v_fmac_f32_e32 v90, v80, v80
	v_fmac_f32_e32 v92, v81, v81
	v_fmac_f32_e32 v90, v82, v82
	v_fmac_f32_e32 v92, v83, v83
	v_fmac_f32_e32 v90, v84, v84
	v_fmac_f32_e32 v92, v85, v85
	v_fmac_f32_e32 v90, v86, v86
	v_fmac_f32_e32 v92, v87, v87
	v_fmac_f32_e32 v90, v88, v88
	v_fmac_f32_e32 v92, v89, v89
	v_add_f32_e32 v9, v9, v91
	v_add_f32_e32 v90, v90, v92
	s_nop 1
	v_add_f32_dpp v9, v9, v9 quad_perm:[1,0,3,2] row_mask:0xf bank_mask:0xf
	v_add_f32_dpp v90, v90, v90 quad_perm:[1,0,3,2] row_mask:0xf bank_mask:0xf
	s_nop 0
	v_add_f32_dpp v9, v9, v9 quad_perm:[2,3,0,1] row_mask:0xf bank_mask:0xf
	v_add_f32_dpp v90, v90, v90 quad_perm:[2,3,0,1] row_mask:0xf bank_mask:0xf
	s_nop 0
	v_add_f32_dpp v9, v9, v9 row_half_mirror row_mask:0xf bank_mask:0xf
	v_add_f32_dpp v90, v90, v90 row_half_mirror row_mask:0xf bank_mask:0xf
	s_nop 0
	v_add_f32_dpp v9, v9, v9 row_mirror row_mask:0xf bank_mask:0xf
	v_add_f32_dpp v90, v90, v90 row_mirror row_mask:0xf bank_mask:0xf
	s_nop 0
	v_add_f32_dpp v9, v9, v9 row_bcast:15 row_mask:0xa bank_mask:0xf
	v_add_f32_dpp v90, v90, v90 row_bcast:15 row_mask:0xa bank_mask:0xf
	s_nop 0
	v_add_f32_dpp v9, v9, v9 row_bcast:31 row_mask:0xc bank_mask:0xf
	v_add_f32_dpp v90, v90, v90 row_bcast:31 row_mask:0xc bank_mask:0xf
	s_nop 0
	v_readlane_b32 s2, v9, 63
	v_readlane_b32 s3, v90, 63
	s_nop 1
	v_mov_b32_e32 v9, s2
	v_mov_b32_e32 v90, s3
	v_mul_f32_e32 v93, 0x3a800000, v9
	v_mul_f32_e32 v91, 0x3a800000, v90
	v_fma_f32 v91, -v93, v93, v91
	v_max_f32_e32 v91, 0, v91
	v_add_f32_e32 v91, 0x358637bd, v91
	v_rsq_f32_e32 v94, v91
	v_mul_f32_e32 v91, 0.5, v91
	v_mul_f32_e32 v92, v94, v94
	v_fma_f32 v92, -v91, v92, 0.5
	v_fma_f32 v94, v94, v92, v94
	v_sub_f32_e32 v74, v74, v93
	v_sub_f32_e32 v75, v75, v93
	v_sub_f32_e32 v76, v76, v93
	v_sub_f32_e32 v77, v77, v93
	v_sub_f32_e32 v78, v78, v93
	v_sub_f32_e32 v79, v79, v93
	v_sub_f32_e32 v80, v80, v93
	v_sub_f32_e32 v81, v81, v93
	v_sub_f32_e32 v82, v82, v93
	v_sub_f32_e32 v83, v83, v93
	v_sub_f32_e32 v84, v84, v93
	v_sub_f32_e32 v85, v85, v93
	v_sub_f32_e32 v86, v86, v93
	v_sub_f32_e32 v87, v87, v93
	v_sub_f32_e32 v88, v88, v93
	v_sub_f32_e32 v89, v89, v93
	v_mul_f32_e32 v74, v94, v74
	v_mul_f32_e32 v75, v94, v75
	v_mul_f32_e32 v76, v94, v76
	v_mul_f32_e32 v77, v94, v77
	v_mul_f32_e32 v78, v94, v78
	v_mul_f32_e32 v79, v94, v79
	v_mul_f32_e32 v80, v94, v80
	v_mul_f32_e32 v81, v94, v81
	v_mul_f32_e32 v82, v94, v82
	v_mul_f32_e32 v83, v94, v83
	v_mul_f32_e32 v84, v94, v84
	v_mul_f32_e32 v85, v94, v85
	v_mul_f32_e32 v86, v94, v86
	v_mul_f32_e32 v87, v94, v87
	v_mul_f32_e32 v88, v94, v88
	v_mul_f32_e32 v89, v94, v89
	v_fma_f32 v74, v74, v10, v26
	v_fma_f32 v75, v75, v11, v27
	v_fma_f32 v76, v76, v12, v28
	v_fma_f32 v77, v77, v13, v29
	v_fma_f32 v78, v78, v14, v30
	v_fma_f32 v79, v79, v15, v31
	v_fma_f32 v80, v80, v16, v32
	v_fma_f32 v81, v81, v17, v33
	v_fma_f32 v82, v82, v18, v34
	v_fma_f32 v83, v83, v19, v35
	v_fma_f32 v84, v84, v20, v36
	v_fma_f32 v85, v85, v21, v37
	v_fma_f32 v86, v86, v22, v38
	v_fma_f32 v87, v87, v23, v39
	v_fma_f32 v88, v88, v24, v40
	v_fma_f32 v89, v89, v25, v41
	s_add_u32 s2, s8, 0x6000
	s_addc_u32 s3, s9, 0
	global_store_dwordx4 v0, v[74:77], s[2:3]
	global_store_dwordx4 v0, v[78:81], s[2:3] offset:16
	global_store_dwordx4 v0, v[82:85], s[2:3] offset:2048
	global_store_dwordx4 v0, v[86:89], s[2:3] offset:2064
	s_waitcnt vmcnt(12)
; DI void ln_row_v(const Frame& F, f32x4 (&v)[4], float* xout, const float* g, const float* b, const float* sh, const float* sc, bf16_t* hout, const float* slab, const float* gres, float* stat = nullptr) {
;     ...
;     if (g) {
;         float s = 0.f, s2 = 0.f;
; #pragma unroll
;         for (int j = 0; j < 4; ++j) { s += (v[j][0] + v[j][1]) + (v[j][2] + v[j][3]); s2 += (v[j][0] * v[j][0] + v[j][1] * v[j][1]) + (v[j][2] * v[j][2] + v[j][3] * v[j][3]); }
;         wave_sum2(s, s2, F.lane);
;         const float mean = s * (1.f / D); const float rstd = 1.f / sqrtf(fmaxf(s2 * (1.f / D) - mean * mean, 0.f) + EPS);
;         if (stat && F.lane == 0) { f32x2 sv = {mean, rstd}; *(f32x2*)stat = sv; }
; #pragma unroll
;         for (int j = 0; j < 4; ++j) { const f32x4 gg = ((const f32x4*)g)[F.lane + 64 * j], bb = ((const f32x4*)b)[F.lane + 64 * j];
;             v[j] = (v[j] - mean) * rstd * gg + bb; if (xout) ((f32x4*)xout)[F.lane + 64 * j] = v[j]; }
;     }
	v_add_f32_e32 v9, v98, v99
	v_add_f32_e32 v91, v100, v101
	v_mul_f32_e32 v90, v98, v98
	v_mul_f32_e32 v92, v99, v99
	v_add_f32_e32 v9, v9, v102
	v_add_f32_e32 v91, v91, v103
	v_add_f32_e32 v9, v9, v104
	v_add_f32_e32 v91, v91, v105
	v_add_f32_e32 v9, v9, v106
	v_add_f32_e32 v91, v91, v107
	v_add_f32_e32 v9, v9, v108
	v_add_f32_e32 v91, v91, v109
	v_add_f32_e32 v9, v9, v110
	v_add_f32_e32 v91, v91, v111
	v_add_f32_e32 v9, v9, v112
	v_add_f32_e32 v91, v91, v113
	v_fmac_f32_e32 v90, v100, v100
	v_fmac_f32_e32 v92, v101, v101
	v_fmac_f32_e32 v90, v102, v102
	v_fmac_f32_e32 v92, v103, v103
	v_fmac_f32_e32 v90, v104, v104
	v_fmac_f32_e32 v92, v105, v105
	v_fmac_f32_e32 v90, v106, v106
	v_fmac_f32_e32 v92, v107, v107
	v_fmac_f32_e32 v90, v108, v108
	v_fmac_f32_e32 v92, v109, v109
	v_fmac_f32_e32 v90, v110, v110
	v_fmac_f32_e32 v92, v111, v111
	v_fmac_f32_e32 v90, v112, v112
	v_fmac_f32_e32 v92, v113, v113
	v_add_f32_e32 v9, v9, v91
	v_add_f32_e32 v90, v90, v92
	s_nop 1
	v_add_f32_dpp v9, v9, v9 quad_perm:[1,0,3,2] row_mask:0xf bank_mask:0xf
	v_add_f32_dpp v90, v90, v90 quad_perm:[1,0,3,2] row_mask:0xf bank_mask:0xf
	s_nop 0
	v_add_f32_dpp v9, v9, v9 quad_perm:[2,3,0,1] row_mask:0xf bank_mask:0xf
	v_add_f32_dpp v90, v90, v90 quad_perm:[2,3,0,1] row_mask:0xf bank_mask:0xf
	s_nop 0
	v_add_f32_dpp v9, v9, v9 row_half_mirror row_mask:0xf bank_mask:0xf
	v_add_f32_dpp v90, v90, v90 row_half_mirror row_mask:0xf bank_mask:0xf
	s_nop 0
	v_add_f32_dpp v9, v9, v9 row_mirror row_mask:0xf bank_mask:0xf
	v_add_f32_dpp v90, v90, v90 row_mirror row_mask:0xf bank_mask:0xf
	s_nop 0
	v_add_f32_dpp v9, v9, v9 row_bcast:15 row_mask:0xa bank_mask:0xf
	v_add_f32_dpp v90, v90, v90 row_bcast:15 row_mask:0xa bank_mask:0xf
	s_nop 0
	v_add_f32_dpp v9, v9, v9 row_bcast:31 row_mask:0xc bank_mask:0xf
	v_add_f32_dpp v90, v90, v90 row_bcast:31 row_mask:0xc bank_mask:0xf
	s_nop 0
	v_readlane_b32 s2, v9, 63
	v_readlane_b32 s3, v90, 63
	s_nop 1
	v_mov_b32_e32 v9, s2
	v_mov_b32_e32 v90, s3
	v_mul_f32_e32 v93, 0x3a800000, v9
	v_mul_f32_e32 v91, 0x3a800000, v90
	v_fma_f32 v91, -v93, v93, v91
	v_max_f32_e32 v91, 0, v91
	v_add_f32_e32 v91, 0x358637bd, v91
	v_rsq_f32_e32 v94, v91
	v_mul_f32_e32 v91, 0.5, v91
	v_mul_f32_e32 v92, v94, v94
	v_fma_f32 v92, -v91, v92, 0.5
	v_fma_f32 v94, v94, v92, v94
	v_sub_f32_e32 v98, v98, v93
	v_sub_f32_e32 v99, v99, v93
	v_sub_f32_e32 v100, v100, v93
	v_sub_f32_e32 v101, v101, v93
	v_sub_f32_e32 v102, v102, v93
	v_sub_f32_e32 v103, v103, v93
	v_sub_f32_e32 v104, v104, v93
	v_sub_f32_e32 v105, v105, v93
	v_sub_f32_e32 v106, v106, v93
	v_sub_f32_e32 v107, v107, v93
	v_sub_f32_e32 v108, v108, v93
	v_sub_f32_e32 v109, v109, v93
	v_sub_f32_e32 v110, v110, v93
	v_sub_f32_e32 v111, v111, v93
	v_sub_f32_e32 v112, v112, v93
	v_sub_f32_e32 v113, v113, v93
	v_mul_f32_e32 v98, v94, v98
	v_mul_f32_e32 v99, v94, v99
	v_mul_f32_e32 v100, v94, v100
	v_mul_f32_e32 v101, v94, v101
	v_mul_f32_e32 v102, v94, v102
	v_mul_f32_e32 v103, v94, v103
	v_mul_f32_e32 v104, v94, v104
	v_mul_f32_e32 v105, v94, v105
	v_mul_f32_e32 v106, v94, v106
	v_mul_f32_e32 v107, v94, v107
	v_mul_f32_e32 v108, v94, v108
	v_mul_f32_e32 v109, v94, v109
	v_mul_f32_e32 v110, v94, v110
	v_mul_f32_e32 v111, v94, v111
	v_mul_f32_e32 v112, v94, v112
	v_mul_f32_e32 v113, v94, v113
	v_fma_f32 v98, v98, v10, v26
	v_fma_f32 v99, v99, v11, v27
	v_fma_f32 v100, v100, v12, v28
	v_fma_f32 v101, v101, v13, v29
	v_fma_f32 v102, v102, v14, v30
	v_fma_f32 v103, v103, v15, v31
	v_fma_f32 v104, v104, v16, v32
	v_fma_f32 v105, v105, v17, v33
	v_fma_f32 v106, v106, v18, v34
	v_fma_f32 v107, v107, v19, v35
	v_fma_f32 v108, v108, v20, v36
	v_fma_f32 v109, v109, v21, v37
	v_fma_f32 v110, v110, v22, v38
	v_fma_f32 v111, v111, v23, v39
	v_fma_f32 v112, v112, v24, v40
	v_fma_f32 v113, v113, v25, v41
	s_add_u32 s2, s8, 0x7000
	s_addc_u32 s3, s9, 0
	global_store_dwordx4 v0, v[98:101], s[2:3]
	global_store_dwordx4 v0, v[102:105], s[2:3] offset:16
	global_store_dwordx4 v0, v[106:109], s[2:3] offset:2048
	global_store_dwordx4 v0, v[110:113], s[2:3] offset:2064
	s_waitcnt vmcnt(0)

; DI const float* modp(const Frame& F, int l, int mr, int which) { return (const float*)(F.ws + WS_MOD) + ((size_t)(l * 9 + mr) * 6 + which) * 1024; }
; DI void ln_load(const Frame& F, const float* xin, f32x4 (&v)[4]) {
;     const f32x4* xr = (const f32x4*)xin + F.lane;
; #pragma unroll
;     for (int j = 0; j < 4; ++j) v[j] = xr[64 * j];
; }
; DI void prologue_b(const Frame& F) {
;     const int gw = F.vcu * 8 + F.wave, NGW = F.G * 8;
;     bf16_t* H = (bf16_t*)(F.ws + WS_HB);
;     for (int row = gw; row < MT; row += NGW) {
;         const int mr = row < ML ? (row >> 11) : 8;
;         const float* xi = row < ML ? pin(F, I_X) + (size_t)row * D : pin(F, I_CTX) + (size_t)(row - ML) * D;
;         ln_row(F, xi, nullptr, nullptr, nullptr, modp(F, 0, mr, 0), modp(F, 0, mr, 1), H + (size_t)row * D);
;     }
; }
.LBB0_663:
	s_and_b64 vcc, exec, s[2:3]
	s_cbranch_vccz .LBB0_671
	v_readlane_b32 s2, v255, 29
	s_lshl_b32 s2, s2, 3
	v_readlane_b32 s3, v255, 31
	s_add_i32 s16, s3, s2
	v_lshlrev_b32_e32 v0, 5, v186
	v_lshlrev_b32_e32 v1, 4, v186
	v_lshlrev_b32_e32 v96, 2, v186
	v_xor_b32_e32 v3, 4, v96
	v_xor_b32_e32 v4, 8, v96
	v_xor_b32_e32 v5, 16, v96
	v_xor_b32_e32 v6, 32, v96
	v_xor_b32_e32 v7, 64, v96
	v_xor_b32_e32 v8, 128, v96
	s_load_dwordx2 s[8:9], s[62:63], 0x0
	s_load_dwordx2 s[20:21], s[62:63], 0x10
	s_mov_b32 s22, 0
	s_lshl_b32 s2, s16, 12
	s_lshl_b32 s3, s16, 15
	s_waitcnt lgkmcnt(0)
	s_add_u32 s8, s8, s3
	s_addc_u32 s9, s9, 0
	s_add_u32 s20, s20, s2
	s_addc_u32 s21, s21, 0
	s_lshl_b32 s2, s16, 14
	s_add_u32 s10, s94, s2
	s_addc_u32 s11, s95, 0
	s_add_u32 s10, s10, 0x3e00000
	s_addc_u32 s11, s11, 0
	s_lshl_b32 s2, s16, 6
	s_add_u32 s12, s94, s2
	s_addc_u32 s13, s95, 0
	s_add_u32 s12, s12, 0x4c0000
	s_addc_u32 s13, s13, 0
	s_mov_b32 s3, 0
	s_mul_i32 s3, s3, 0x36000
	s_add_u32 s14, s94, s3
	s_addc_u32 s15, s95, 0
	s_add_u32 s14, s14, 0x100000
	s_addc_u32 s15, s15, 0
	s_add_u32 s18, s14, 0x1000
	s_addc_u32 s19, s15, 0
	s_add_u32 s2, s8, 0x0
	s_addc_u32 s3, s9, 0
	global_load_dwordx4 v[42:45], v0, s[2:3]
	global_load_dwordx4 v[46:49], v0, s[2:3] offset:16
	global_load_dwordx4 v[50:53], v0, s[2:3] offset:2048
	global_load_dwordx4 v[54:57], v0, s[2:3] offset:2064
	s_lshr_b32 s23, s16, 8
	s_mul_i32 s23, s23, 0x6000
	s_add_u32 s2, s14, s23
	s_addc_u32 s3, s15, 0
	global_load_dwordx4 v[114:117], v0, s[2:3]
	global_load_dwordx4 v[118:121], v0, s[2:3] offset:16
	global_load_dwordx4 v[122:125], v0, s[2:3] offset:2048
	global_load_dwordx4 v[126:129], v0, s[2:3] offset:2064
	s_add_u32 s2, s18, s23
	s_addc_u32 s3, s19, 0
	global_load_dwordx4 v[130:133], v0, s[2:3]
	global_load_dwordx4 v[134:137], v0, s[2:3] offset:16
	global_load_dwordx4 v[138:141], v0, s[2:3] offset:2048
	global_load_dwordx4 v[142:145], v0, s[2:3] offset:2064
	s_add_u32 s2, s8, 0x1000
	s_addc_u32 s3, s9, 0
	global_load_dwordx4 v[58:61], v0, s[2:3]
	global_load_dwordx4 v[62:65], v0, s[2:3] offset:16
	global_load_dwordx4 v[66:69], v0, s[2:3] offset:2048
	global_load_dwordx4 v[70:73], v0, s[2:3] offset:2064
	s_mov_b32 s23, 0x30000
	s_add_u32 s2, s14, s23
	s_addc_u32 s3, s15, 0
	global_load_dwordx4 v[146:149], v0, s[2:3]
	global_load_dwordx4 v[150:153], v0, s[2:3] offset:16
	global_load_dwordx4 v[154:157], v0, s[2:3] offset:2048
	global_load_dwordx4 v[158:161], v0, s[2:3] offset:2064
	s_add_u32 s2, s18, s23
	s_addc_u32 s3, s19, 0
	global_load_dwordx4 v[162:165], v0, s[2:3]
	global_load_dwordx4 v[166:169], v0, s[2:3] offset:16
	global_load_dwordx4 v[170:173], v0, s[2:3] offset:2048
	global_load_dwordx4 v[174:177], v0, s[2:3] offset:2064
	s_add_u32 s2, s8, 0x2000
	s_addc_u32 s3, s9, 0
	global_load_dwordx4 v[74:77], v0, s[2:3]
	global_load_dwordx4 v[78:81], v0, s[2:3] offset:16
	global_load_dwordx4 v[82:85], v0, s[2:3] offset:2048
	global_load_dwordx4 v[86:89], v0, s[2:3] offset:2064
	s_add_u32 s2, s8, 0x3000
	s_addc_u32 s3, s9, 0
	global_load_dwordx4 v[98:101], v0, s[2:3]
	global_load_dwordx4 v[102:105], v0, s[2:3] offset:16
	global_load_dwordx4 v[106:109], v0, s[2:3] offset:2048
	global_load_dwordx4 v[110:113], v0, s[2:3] offset:2064
	s_waitcnt vmcnt(28)
	v_add_f32_e32 v9, v42, v43
	v_add_f32_e32 v91, v44, v45
	v_mul_f32_e32 v90, v42, v42
	v_mul_f32_e32 v92, v43, v43
	v_add_f32_e32 v9, v9, v46
	v_add_f32_e32 v91, v91, v47
	v_add_f32_e32 v9, v9, v48
	v_add_f32_e32 v91, v91, v49
	v_add_f32_e32 v9, v9, v50
	v_add_f32_e32 v91, v91, v51
	v_add_f32_e32 v9, v9, v52
	v_add_f32_e32 v91, v91, v53
	v_add_f32_e32 v9, v9, v54
	v_add_f32_e32 v91, v91, v55
	v_add_f32_e32 v9, v9, v56
	v_add_f32_e32 v91, v91, v57
	v_fmac_f32_e32 v90, v44, v44
	v_fmac_f32_e32 v92, v45, v45
	v_fmac_f32_e32 v90, v46, v46
	v_fmac_f32_e32 v92, v47, v47
	v_fmac_f32_e32 v90, v48, v48
	v_fmac_f32_e32 v92, v49, v49
	v_fmac_f32_e32 v90, v50, v50
	v_fmac_f32_e32 v92, v51, v51
	v_fmac_f32_e32 v90, v52, v52
	v_fmac_f32_e32 v92, v53, v53
	v_fmac_f32_e32 v90, v54, v54
	v_fmac_f32_e32 v92, v55, v55
	v_fmac_f32_e32 v90, v56, v56
	v_fmac_f32_e32 v92, v57, v57
	v_add_f32_e32 v9, v9, v91
	v_add_f32_e32 v90, v90, v92
	s_nop 1
	v_add_f32_dpp v9, v9, v9 quad_perm:[1,0,3,2] row_mask:0xf bank_mask:0xf
	v_add_f32_dpp v90, v90, v90 quad_perm:[1,0,3,2] row_mask:0xf bank_mask:0xf
	s_nop 0
	v_add_f32_dpp v9, v9, v9 quad_perm:[2,3,0,1] row_mask:0xf bank_mask:0xf
	v_add_f32_dpp v90, v90, v90 quad_perm:[2,3,0,1] row_mask:0xf bank_mask:0xf
	s_nop 0
	v_add_f32_dpp v9, v9, v9 row_half_mirror row_mask:0xf bank_mask:0xf
	v_add_f32_dpp v90, v90, v90 row_half_mirror row_mask:0xf bank_mask:0xf
	s_nop 0
	v_add_f32_dpp v9, v9, v9 row_mirror row_mask:0xf bank_mask:0xf
	v_add_f32_dpp v90, v90, v90 row_mirror row_mask:0xf bank_mask:0xf
	s_nop 0
	v_add_f32_dpp v9, v9, v9 row_bcast:15 row_mask:0xa bank_mask:0xf
	v_add_f32_dpp v90, v90, v90 row_bcast:15 row_mask:0xa bank_mask:0xf
	s_nop 0
	v_add_f32_dpp v9, v9, v9 row_bcast:31 row_mask:0xc bank_mask:0xf
	v_add_f32_dpp v90, v90, v90 row_bcast:31 row_mask:0xc bank_mask:0xf
	s_nop 0
	v_readlane_b32 s2, v9, 63
	v_readlane_b32 s3, v90, 63
	s_nop 1
	v_mov_b32_e32 v9, s2
	v_mov_b32_e32 v90, s3
	v_mul_f32_e32 v93, 0x3a800000, v9
	v_mul_f32_e32 v91, 0x3a800000, v90
	v_fma_f32 v91, -v93, v93, v91
	v_max_f32_e32 v91, 0, v91
	v_add_f32_e32 v91, 0x358637bd, v91
	v_rsq_f32_e32 v94, v91
	v_mul_f32_e32 v91, 0.5, v91
	v_mul_f32_e32 v92, v94, v94
	v_fma_f32 v92, -v91, v92, 0.5
	v_fma_f32 v94, v94, v92, v94
	s_waitcnt vmcnt(20)
; DI unsigned pk2(float lo, float hi) { f32x2 v = {lo, hi}; bf16x2_t b = __builtin_convertvector(v, bf16x2_t); return __builtin_bit_cast(unsigned, b); }
; DI void ln_row_v(const Frame& F, f32x4 (&v)[4], float* xout, const float* g, const float* b, const float* sh, const float* sc, bf16_t* hout, const float* slab, const float* gres, float* stat = nullptr) {
;     ...
;     if (hout) {
;         float s = 0.f, s2 = 0.f;
; #pragma unroll
;         for (int j = 0; j < 4; ++j) { s += (v[j][0] + v[j][1]) + (v[j][2] + v[j][3]); s2 += (v[j][0] * v[j][0] + v[j][1] * v[j][1]) + (v[j][2] * v[j][2] + v[j][3] * v[j][3]); }
;         wave_sum2(s, s2, F.lane);
;         const float mean = s * (1.f / D); const float rstd = 1.f / sqrtf(fmaxf(s2 * (1.f / D) - mean * mean, 0.f) + EPS);
; #pragma unroll
;         for (int j = 0; j < 4; ++j) { const f32x4 hh = ((const f32x4*)sh)[F.lane + 64 * j], cc = ((const f32x4*)sc)[F.lane + 64 * j];
;             const f32x4 o = (v[j] - mean) * rstd * (cc + 1.f) + hh; u32x2 wv; wv.x = pk2(o[0], o[1]); wv.y = pk2(o[2], o[3]);
;             ((u32x2*)hout)[F.lane + 64 * j] = wv; }
;     }
	v_sub_f32_e32 v42, v42, v93
	v_sub_f32_e32 v43, v43, v93
	v_sub_f32_e32 v44, v44, v93
	v_sub_f32_e32 v45, v45, v93
	v_sub_f32_e32 v46, v46, v93
	v_sub_f32_e32 v47, v47, v93
	v_sub_f32_e32 v48, v48, v93
	v_sub_f32_e32 v49, v49, v93
	v_sub_f32_e32 v50, v50, v93
	v_sub_f32_e32 v51, v51, v93
	v_sub_f32_e32 v52, v52, v93
	v_sub_f32_e32 v53, v53, v93
	v_sub_f32_e32 v54, v54, v93
	v_sub_f32_e32 v55, v55, v93
	v_sub_f32_e32 v56, v56, v93
	v_sub_f32_e32 v57, v57, v93
	v_add_f32_e32 v130, 1.0, v130
	v_add_f32_e32 v131, 1.0, v131
	v_add_f32_e32 v132, 1.0, v132
	v_add_f32_e32 v133, 1.0, v133
	v_add_f32_e32 v134, 1.0, v134
	v_add_f32_e32 v135, 1.0, v135
	v_add_f32_e32 v136, 1.0, v136
	v_add_f32_e32 v137, 1.0, v137
	v_add_f32_e32 v138, 1.0, v138
	v_add_f32_e32 v139, 1.0, v139
	v_add_f32_e32 v140, 1.0, v140
	v_add_f32_e32 v141, 1.0, v141
	v_add_f32_e32 v142, 1.0, v142
	v_add_f32_e32 v143, 1.0, v143
	v_add_f32_e32 v144, 1.0, v144
	v_add_f32_e32 v145, 1.0, v145
	v_mul_f32_e32 v42, v94, v42
	v_mul_f32_e32 v43, v94, v43
	v_mul_f32_e32 v44, v94, v44
	v_mul_f32_e32 v45, v94, v45
	v_mul_f32_e32 v46, v94, v46
	v_mul_f32_e32 v47, v94, v47
	v_mul_f32_e32 v48, v94, v48
	v_mul_f32_e32 v49, v94, v49
	v_mul_f32_e32 v50, v94, v50
	v_mul_f32_e32 v51, v94, v51
	v_mul_f32_e32 v52, v94, v52
	v_mul_f32_e32 v53, v94, v53
	v_mul_f32_e32 v54, v94, v54
	v_mul_f32_e32 v55, v94, v55
	v_mul_f32_e32 v56, v94, v56
	v_mul_f32_e32 v57, v94, v57
	v_fma_f32 v42, v42, v130, v114
	v_fma_f32 v43, v43, v131, v115
	v_fma_f32 v44, v44, v132, v116
	v_fma_f32 v45, v45, v133, v117
	v_fma_f32 v46, v46, v134, v118
	v_fma_f32 v47, v47, v135, v119
	v_fma_f32 v48, v48, v136, v120
	v_fma_f32 v49, v49, v137, v121
	v_fma_f32 v50, v50, v138, v122
	v_fma_f32 v51, v51, v139, v123
	v_fma_f32 v52, v52, v140, v124
	v_fma_f32 v53, v53, v141, v125
	v_fma_f32 v54, v54, v142, v126
	v_fma_f32 v55, v55, v143, v127
	v_fma_f32 v56, v56, v144, v128
	v_fma_f32 v57, v57, v145, v129
	v_cvt_pk_bf16_f32 v190, v42, v43
	v_cvt_pk_bf16_f32 v191, v44, v45
	v_cvt_pk_bf16_f32 v192, v46, v47
	v_cvt_pk_bf16_f32 v193, v48, v49
	v_cvt_pk_bf16_f32 v194, v50, v51
	v_cvt_pk_bf16_f32 v195, v52, v53
	v_cvt_pk_bf16_f32 v196, v54, v55
	v_cvt_pk_bf16_f32 v197, v56, v57
	s_add_u32 s2, s10, 0x0
	s_addc_u32 s3, s11, 0
	global_store_dwordx4 v1, v[190:193], s[2:3]
	global_store_dwordx4 v1, v[194:197], s[2:3] offset:1024
	s_add_u32 s2, s8, 0x4000
	s_addc_u32 s3, s9, 0
	global_load_dwordx4 v[42:45], v0, s[2:3]
	global_load_dwordx4 v[46:49], v0, s[2:3] offset:16
	global_load_dwordx4 v[50:53], v0, s[2:3] offset:2048
	global_load_dwordx4 v[54:57], v0, s[2:3] offset:2064
	s_waitcnt vmcnt(22)
	v_add_f32_e32 v9, v58, v59
	v_add_f32_e32 v91, v60, v61
	v_mul_f32_e32 v90, v58, v58
	v_mul_f32_e32 v92, v59, v59
	v_add_f32_e32 v9, v9, v62
	v_add_f32_e32 v91, v91, v63
	v_add_f32_e32 v9, v9, v64
	v_add_f32_e32 v91, v91, v65
	v_add_f32_e32 v9, v9, v66
	v_add_f32_e32 v91, v91, v67
	v_add_f32_e32 v9, v9, v68
	v_add_f32_e32 v91, v91, v69
	v_add_f32_e32 v9, v9, v70
	v_add_f32_e32 v91, v91, v71
	v_add_f32_e32 v9, v9, v72
	v_add_f32_e32 v91, v91, v73
	v_fmac_f32_e32 v90, v60, v60
	v_fmac_f32_e32 v92, v61, v61
	v_fmac_f32_e32 v90, v62, v62
	v_fmac_f32_e32 v92, v63, v63
	v_fmac_f32_e32 v90, v64, v64
	v_fmac_f32_e32 v92, v65, v65
	v_fmac_f32_e32 v90, v66, v66
	v_fmac_f32_e32 v92, v67, v67
	v_fmac_f32_e32 v90, v68, v68
	v_fmac_f32_e32 v92, v69, v69
	v_fmac_f32_e32 v90, v70, v70
	v_fmac_f32_e32 v92, v71, v71
	v_fmac_f32_e32 v90, v72, v72
	v_fmac_f32_e32 v92, v73, v73
	v_add_f32_e32 v9, v9, v91
	v_add_f32_e32 v90, v90, v92
	s_nop 1
	v_add_f32_dpp v9, v9, v9 quad_perm:[1,0,3,2] row_mask:0xf bank_mask:0xf
	v_add_f32_dpp v90, v90, v90 quad_perm:[1,0,3,2] row_mask:0xf bank_mask:0xf
	s_nop 0
	v_add_f32_dpp v9, v9, v9 quad_perm:[2,3,0,1] row_mask:0xf bank_mask:0xf
	v_add_f32_dpp v90, v90, v90 quad_perm:[2,3,0,1] row_mask:0xf bank_mask:0xf
	s_nop 0
	v_add_f32_dpp v9, v9, v9 row_half_mirror row_mask:0xf bank_mask:0xf
	v_add_f32_dpp v90, v90, v90 row_half_mirror row_mask:0xf bank_mask:0xf
	s_nop 0
	v_add_f32_dpp v9, v9, v9 row_mirror row_mask:0xf bank_mask:0xf
	v_add_f32_dpp v90, v90, v90 row_mirror row_mask:0xf bank_mask:0xf
	s_nop 0
	v_add_f32_dpp v9, v9, v9 row_bcast:15 row_mask:0xa bank_mask:0xf
	v_add_f32_dpp v90, v90, v90 row_bcast:15 row_mask:0xa bank_mask:0xf
	s_nop 0
	v_add_f32_dpp v9, v9, v9 row_bcast:31 row_mask:0xc bank_mask:0xf
	v_add_f32_dpp v90, v90, v90 row_bcast:31 row_mask:0xc bank_mask:0xf
	s_nop 0
	v_readlane_b32 s2, v9, 63
	v_readlane_b32 s3, v90, 63
	s_nop 1
	v_mov_b32_e32 v9, s2
	v_mov_b32_e32 v90, s3
	v_mul_f32_e32 v93, 0x3a800000, v9
	v_mul_f32_e32 v91, 0x3a800000, v90
	v_fma_f32 v91, -v93, v93, v91
	v_max_f32_e32 v91, 0, v91
	v_add_f32_e32 v91, 0x358637bd, v91
	v_rsq_f32_e32 v94, v91
	v_mul_f32_e32 v91, 0.5, v91
	v_mul_f32_e32 v92, v94, v94
	v_fma_f32 v92, -v91, v92, 0.5
	v_fma_f32 v94, v94, v92, v94
	v_sub_f32_e32 v58, v58, v93
	v_sub_f32_e32 v59, v59, v93
	v_sub_f32_e32 v60, v60, v93
	v_sub_f32_e32 v61, v61, v93
	v_sub_f32_e32 v62, v62, v93
	v_sub_f32_e32 v63, v63, v93
	v_sub_f32_e32 v64, v64, v93
	v_sub_f32_e32 v65, v65, v93
	v_sub_f32_e32 v66, v66, v93
	v_sub_f32_e32 v67, v67, v93
	v_sub_f32_e32 v68, v68, v93
	v_sub_f32_e32 v69, v69, v93
	v_sub_f32_e32 v70, v70, v93
	v_sub_f32_e32 v71, v71, v93
	v_sub_f32_e32 v72, v72, v93
	v_sub_f32_e32 v73, v73, v93
	v_mul_f32_e32 v58, v94, v58
	v_mul_f32_e32 v59, v94, v59
	v_mul_f32_e32 v60, v94, v60
	v_mul_f32_e32 v61, v94, v61
	v_mul_f32_e32 v62, v94, v62
	v_mul_f32_e32 v63, v94, v63
	v_mul_f32_e32 v64, v94, v64
	v_mul_f32_e32 v65, v94, v65
	v_mul_f32_e32 v66, v94, v66
	v_mul_f32_e32 v67, v94, v67
	v_mul_f32_e32 v68, v94, v68
	v_mul_f32_e32 v69, v94, v69
	v_mul_f32_e32 v70, v94, v70
	v_mul_f32_e32 v71, v94, v71
	v_mul_f32_e32 v72, v94, v72
	v_mul_f32_e32 v73, v94, v73
	v_fma_f32 v58, v58, v130, v114
	v_fma_f32 v59, v59, v131, v115
	v_fma_f32 v60, v60, v132, v116
	v_fma_f32 v61, v61, v133, v117
	v_fma_f32 v62, v62, v134, v118
	v_fma_f32 v63, v63, v135, v119
	v_fma_f32 v64, v64, v136, v120
	v_fma_f32 v65, v65, v137, v121
	v_fma_f32 v66, v66, v138, v122
	v_fma_f32 v67, v67, v139, v123
	v_fma_f32 v68, v68, v140, v124
	v_fma_f32 v69, v69, v141, v125
	v_fma_f32 v70, v70, v142, v126
	v_fma_f32 v71, v71, v143, v127
	v_fma_f32 v72, v72, v144, v128
	v_fma_f32 v73, v73, v145, v129
	v_cvt_pk_bf16_f32 v190, v58, v59
	v_cvt_pk_bf16_f32 v191, v60, v61
	v_cvt_pk_bf16_f32 v192, v62, v63
	v_cvt_pk_bf16_f32 v193, v64, v65
	v_cvt_pk_bf16_f32 v194, v66, v67
	v_cvt_pk_bf16_f32 v195, v68, v69
	v_cvt_pk_bf16_f32 v196, v70, v71
	v_cvt_pk_bf16_f32 v197, v72, v73
	s_add_u32 s2, s10, 0x800
	s_addc_u32 s3, s11, 0
	global_store_dwordx4 v1, v[190:193], s[2:3]
	global_store_dwordx4 v1, v[194:197], s[2:3] offset:1024
	s_add_u32 s2, s8, 0x5000
	s_addc_u32 s3, s9, 0
	global_load_dwordx4 v[58:61], v0, s[2:3]
	global_load_dwordx4 v[62:65], v0, s[2:3] offset:16
	global_load_dwordx4 v[66:69], v0, s[2:3] offset:2048
	global_load_dwordx4 v[70:73], v0, s[2:3] offset:2064
	s_waitcnt vmcnt(16)
; DI unsigned pk2(float lo, float hi) { f32x2 v = {lo, hi}; bf16x2_t b = __builtin_convertvector(v, bf16x2_t); return __builtin_bit_cast(unsigned, b); }
; DI void ln_row_v(const Frame& F, f32x4 (&v)[4], float* xout, const float* g, const float* b, const float* sh, const float* sc, bf16_t* hout, const float* slab, const float* gres, float* stat = nullptr) {
;     ...
;     if (hout) {
;         float s = 0.f, s2 = 0.f;
; #pragma unroll
;         for (int j = 0; j < 4; ++j) { s += (v[j][0] + v[j][1]) + (v[j][2] + v[j][3]); s2 += (v[j][0] * v[j][0] + v[j][1] * v[j][1]) + (v[j][2] * v[j][2] + v[j][3] * v[j][3]); }
;         wave_sum2(s, s2, F.lane);
;         const float mean = s * (1.f / D); const float rstd = 1.f / sqrtf(fmaxf(s2 * (1.f / D) - mean * mean, 0.f) + EPS);
; #pragma unroll
;         for (int j = 0; j < 4; ++j) { const f32x4 hh = ((const f32x4*)sh)[F.lane + 64 * j], cc = ((const f32x4*)sc)[F.lane + 64 * j];
;             const f32x4 o = (v[j] - mean) * rstd * (cc + 1.f) + hh; u32x2 wv; wv.x = pk2(o[0], o[1]); wv.y = pk2(o[2], o[3]);
;             ((u32x2*)hout)[F.lane + 64 * j] = wv; }
;     }
	v_add_f32_e32 v9, v74, v75
	v_add_f32_e32 v91, v76, v77
	v_mul_f32_e32 v90, v74, v74
	v_mul_f32_e32 v92, v75, v75
	v_add_f32_e32 v9, v9, v78
	v_add_f32_e32 v91, v91, v79
	v_add_f32_e32 v9, v9, v80
	v_add_f32_e32 v91, v91, v81
	v_add_f32_e32 v9, v9, v82
	v_add_f32_e32 v91, v91, v83
	v_add_f32_e32 v9, v9, v84
	v_add_f32_e32 v91, v91, v85
	v_add_f32_e32 v9, v9, v86
	v_add_f32_e32 v91, v91, v87
	v_add_f32_e32 v9, v9, v88
	v_add_f32_e32 v91, v91, v89
	v_fmac_f32_e32 v90, v76, v76
	v_fmac_f32_e32 v92, v77, v77
	v_fmac_f32_e32 v90, v78, v78
	v_fmac_f32_e32 v92, v79, v79
	v_fmac_f32_e32 v90, v80, v80
	v_fmac_f32_e32 v92, v81, v81
	v_fmac_f32_e32 v90, v82, v82
	v_fmac_f32_e32 v92, v83, v83
	v_fmac_f32_e32 v90, v84, v84
	v_fmac_f32_e32 v92, v85, v85
	v_fmac_f32_e32 v90, v86, v86
	v_fmac_f32_e32 v92, v87, v87
	v_fmac_f32_e32 v90, v88, v88
	v_fmac_f32_e32 v92, v89, v89
	v_add_f32_e32 v9, v9, v91
	v_add_f32_e32 v90, v90, v92
	s_nop 1
	v_add_f32_dpp v9, v9, v9 quad_perm:[1,0,3,2] row_mask:0xf bank_mask:0xf
	v_add_f32_dpp v90, v90, v90 quad_perm:[1,0,3,2] row_mask:0xf bank_mask:0xf
	s_nop 0
	v_add_f32_dpp v9, v9, v9 quad_perm:[2,3,0,1] row_mask:0xf bank_mask:0xf
	v_add_f32_dpp v90, v90, v90 quad_perm:[2,3,0,1] row_mask:0xf bank_mask:0xf
	s_nop 0
	v_add_f32_dpp v9, v9, v9 row_half_mirror row_mask:0xf bank_mask:0xf
	v_add_f32_dpp v90, v90, v90 row_half_mirror row_mask:0xf bank_mask:0xf
	s_nop 0
	v_add_f32_dpp v9, v9, v9 row_mirror row_mask:0xf bank_mask:0xf
	v_add_f32_dpp v90, v90, v90 row_mirror row_mask:0xf bank_mask:0xf
	s_nop 0
	v_add_f32_dpp v9, v9, v9 row_bcast:15 row_mask:0xa bank_mask:0xf
	v_add_f32_dpp v90, v90, v90 row_bcast:15 row_mask:0xa bank_mask:0xf
	s_nop 0
	v_add_f32_dpp v9, v9, v9 row_bcast:31 row_mask:0xc bank_mask:0xf
	v_add_f32_dpp v90, v90, v90 row_bcast:31 row_mask:0xc bank_mask:0xf
	s_nop 0
	v_readlane_b32 s2, v9, 63
	v_readlane_b32 s3, v90, 63
	s_nop 1
	v_mov_b32_e32 v9, s2
	v_mov_b32_e32 v90, s3
	v_mul_f32_e32 v93, 0x3a800000, v9
	v_mul_f32_e32 v91, 0x3a800000, v90
	v_fma_f32 v91, -v93, v93, v91
	v_max_f32_e32 v91, 0, v91
	v_add_f32_e32 v91, 0x358637bd, v91
	v_rsq_f32_e32 v94, v91
	v_mul_f32_e32 v91, 0.5, v91
	v_mul_f32_e32 v92, v94, v94
	v_fma_f32 v92, -v91, v92, 0.5
	v_fma_f32 v94, v94, v92, v94
	v_sub_f32_e32 v74, v74, v93
	v_sub_f32_e32 v75, v75, v93
	v_sub_f32_e32 v76, v76, v93
	v_sub_f32_e32 v77, v77, v93
	v_sub_f32_e32 v78, v78, v93
	v_sub_f32_e32 v79, v79, v93
	v_sub_f32_e32 v80, v80, v93
	v_sub_f32_e32 v81, v81, v93
	v_sub_f32_e32 v82, v82, v93
	v_sub_f32_e32 v83, v83, v93
	v_sub_f32_e32 v84, v84, v93
	v_sub_f32_e32 v85, v85, v93
	v_sub_f32_e32 v86, v86, v93
	v_sub_f32_e32 v87, v87, v93
	v_sub_f32_e32 v88, v88, v93
	v_sub_f32_e32 v89, v89, v93
	v_mul_f32_e32 v74, v94, v74
	v_mul_f32_e32 v75, v94, v75
	v_mul_f32_e32 v76, v94, v76
	v_mul_f32_e32 v77, v94, v77
	v_mul_f32_e32 v78, v94, v78
	v_mul_f32_e32 v79, v94, v79
	v_mul_f32_e32 v80, v94, v80
	v_mul_f32_e32 v81, v94, v81
	v_mul_f32_e32 v82, v94, v82
	v_mul_f32_e32 v83, v94, v83
	v_mul_f32_e32 v84, v94, v84
	v_mul_f32_e32 v85, v94, v85
	v_mul_f32_e32 v86, v94, v86
	v_mul_f32_e32 v87, v94, v87
	v_mul_f32_e32 v88, v94, v88
	v_mul_f32_e32 v89, v94, v89
	v_fma_f32 v74, v74, v130, v114
	v_fma_f32 v75, v75, v131, v115
	v_fma_f32 v76, v76, v132, v116
	v_fma_f32 v77, v77, v133, v117
	v_fma_f32 v78, v78, v134, v118
	v_fma_f32 v79, v79, v135, v119
	v_fma_f32 v80, v80, v136, v120
	v_fma_f32 v81, v81, v137, v121
	v_fma_f32 v82, v82, v138, v122
	v_fma_f32 v83, v83, v139, v123
	v_fma_f32 v84, v84, v140, v124
	v_fma_f32 v85, v85, v141, v125
	v_fma_f32 v86, v86, v142, v126
	v_fma_f32 v87, v87, v143, v127
	v_fma_f32 v88, v88, v144, v128
	v_fma_f32 v89, v89, v145, v129
	v_cvt_pk_bf16_f32 v190, v74, v75
	v_cvt_pk_bf16_f32 v191, v76, v77
	v_cvt_pk_bf16_f32 v192, v78, v79
	v_cvt_pk_bf16_f32 v193, v80, v81
	v_cvt_pk_bf16_f32 v194, v82, v83
	v_cvt_pk_bf16_f32 v195, v84, v85
	v_cvt_pk_bf16_f32 v196, v86, v87
	v_cvt_pk_bf16_f32 v197, v88, v89
	s_add_u32 s2, s10, 0x1000
	s_addc_u32 s3, s11, 0
	global_store_dwordx4 v1, v[190:193], s[2:3]
	global_store_dwordx4 v1, v[194:197], s[2:3] offset:1024
	s_add_u32 s2, s8, 0x6000
	s_addc_u32 s3, s9, 0
	global_load_dwordx4 v[74:77], v0, s[2:3]
	global_load_dwordx4 v[78:81], v0, s[2:3] offset:16
	global_load_dwordx4 v[82:85], v0, s[2:3] offset:2048
	global_load_dwordx4 v[86:89], v0, s[2:3] offset:2064
	s_waitcnt vmcnt(18)
; DI unsigned pk2(float lo, float hi) { f32x2 v = {lo, hi}; bf16x2_t b = __builtin_convertvector(v, bf16x2_t); return __builtin_bit_cast(unsigned, b); }
; DI void ln_row_v(const Frame& F, f32x4 (&v)[4], float* xout, const float* g, const float* b, const float* sh, const float* sc, bf16_t* hout, const float* slab, const float* gres, float* stat = nullptr) {
;     ...
;     if (hout) {
;         float s = 0.f, s2 = 0.f;
; #pragma unroll
;         for (int j = 0; j < 4; ++j) { s += (v[j][0] + v[j][1]) + (v[j][2] + v[j][3]); s2 += (v[j][0] * v[j][0] + v[j][1] * v[j][1]) + (v[j][2] * v[j][2] + v[j][3] * v[j][3]); }
;         wave_sum2(s, s2, F.lane);
;         const float mean = s * (1.f / D); const float rstd = 1.f / sqrtf(fmaxf(s2 * (1.f / D) - mean * mean, 0.f) + EPS);
; #pragma unroll
;         for (int j = 0; j < 4; ++j) { const f32x4 hh = ((const f32x4*)sh)[F.lane + 64 * j], cc = ((const f32x4*)sc)[F.lane + 64 * j];
;             const f32x4 o = (v[j] - mean) * rstd * (cc + 1.f) + hh; u32x2 wv; wv.x = pk2(o[0], o[1]); wv.y = pk2(o[2], o[3]);
;             ((u32x2*)hout)[F.lane + 64 * j] = wv; }
;     }
	v_add_f32_e32 v9, v98, v99
	v_add_f32_e32 v91, v100, v101
	v_mul_f32_e32 v90, v98, v98
	v_mul_f32_e32 v92, v99, v99
	v_add_f32_e32 v9, v9, v102
	v_add_f32_e32 v91, v91, v103
	v_add_f32_e32 v9, v9, v104
	v_add_f32_e32 v91, v91, v105
	v_add_f32_e32 v9, v9, v106
	v_add_f32_e32 v91, v91, v107
	v_add_f32_e32 v9, v9, v108
	v_add_f32_e32 v91, v91, v109
	v_add_f32_e32 v9, v9, v110
	v_add_f32_e32 v91, v91, v111
	v_add_f32_e32 v9, v9, v112
	v_add_f32_e32 v91, v91, v113
	v_fmac_f32_e32 v90, v100, v100
	v_fmac_f32_e32 v92, v101, v101
	v_fmac_f32_e32 v90, v102, v102
	v_fmac_f32_e32 v92, v103, v103
	v_fmac_f32_e32 v90, v104, v104
	v_fmac_f32_e32 v92, v105, v105
	v_fmac_f32_e32 v90, v106, v106
	v_fmac_f32_e32 v92, v107, v107
	v_fmac_f32_e32 v90, v108, v108
	v_fmac_f32_e32 v92, v109, v109
	v_fmac_f32_e32 v90, v110, v110
	v_fmac_f32_e32 v92, v111, v111
	v_fmac_f32_e32 v90, v112, v112
	v_fmac_f32_e32 v92, v113, v113
	v_add_f32_e32 v9, v9, v91
	v_add_f32_e32 v90, v90, v92
	s_nop 1
	v_add_f32_dpp v9, v9, v9 quad_perm:[1,0,3,2] row_mask:0xf bank_mask:0xf
	v_add_f32_dpp v90, v90, v90 quad_perm:[1,0,3,2] row_mask:0xf bank_mask:0xf
	s_nop 0
	v_add_f32_dpp v9, v9, v9 quad_perm:[2,3,0,1] row_mask:0xf bank_mask:0xf
	v_add_f32_dpp v90, v90, v90 quad_perm:[2,3,0,1] row_mask:0xf bank_mask:0xf
	s_nop 0
	v_add_f32_dpp v9, v9, v9 row_half_mirror row_mask:0xf bank_mask:0xf
	v_add_f32_dpp v90, v90, v90 row_half_mirror row_mask:0xf bank_mask:0xf
	s_nop 0
	v_add_f32_dpp v9, v9, v9 row_mirror row_mask:0xf bank_mask:0xf
	v_add_f32_dpp v90, v90, v90 row_mirror row_mask:0xf bank_mask:0xf
	s_nop 0
	v_add_f32_dpp v9, v9, v9 row_bcast:15 row_mask:0xa bank_mask:0xf
	v_add_f32_dpp v90, v90, v90 row_bcast:15 row_mask:0xa bank_mask:0xf
	s_nop 0
	v_add_f32_dpp v9, v9, v9 row_bcast:31 row_mask:0xc bank_mask:0xf
	v_add_f32_dpp v90, v90, v90 row_bcast:31 row_mask:0xc bank_mask:0xf
	s_nop 0
	v_readlane_b32 s2, v9, 63
	v_readlane_b32 s3, v90, 63
	s_nop 1
	v_mov_b32_e32 v9, s2
	v_mov_b32_e32 v90, s3
	v_mul_f32_e32 v93, 0x3a800000, v9
	v_mul_f32_e32 v91, 0x3a800000, v90
	v_fma_f32 v91, -v93, v93, v91
	v_max_f32_e32 v91, 0, v91
	v_add_f32_e32 v91, 0x358637bd, v91
	v_rsq_f32_e32 v94, v91
	v_mul_f32_e32 v91, 0.5, v91
	v_mul_f32_e32 v92, v94, v94
	v_fma_f32 v92, -v91, v92, 0.5
	v_fma_f32 v94, v94, v92, v94
	v_sub_f32_e32 v98, v98, v93
	v_sub_f32_e32 v99, v99, v93
	v_sub_f32_e32 v100, v100, v93
	v_sub_f32_e32 v101, v101, v93
	v_sub_f32_e32 v102, v102, v93
	v_sub_f32_e32 v103, v103, v93
	v_sub_f32_e32 v104, v104, v93
	v_sub_f32_e32 v105, v105, v93
	v_sub_f32_e32 v106, v106, v93
	v_sub_f32_e32 v107, v107, v93
	v_sub_f32_e32 v108, v108, v93
	v_sub_f32_e32 v109, v109, v93
	v_sub_f32_e32 v110, v110, v93
	v_sub_f32_e32 v111, v111, v93
	v_sub_f32_e32 v112, v112, v93
	v_sub_f32_e32 v113, v113, v93
	v_mul_f32_e32 v98, v94, v98
	v_mul_f32_e32 v99, v94, v99
	v_mul_f32_e32 v100, v94, v100
	v_mul_f32_e32 v101, v94, v101
	v_mul_f32_e32 v102, v94, v102
	v_mul_f32_e32 v103, v94, v103
	v_mul_f32_e32 v104, v94, v104
	v_mul_f32_e32 v105, v94, v105
	v_mul_f32_e32 v106, v94, v106
	v_mul_f32_e32 v107, v94, v107
	v_mul_f32_e32 v108, v94, v108
	v_mul_f32_e32 v109, v94, v109
	v_mul_f32_e32 v110, v94, v110
	v_mul_f32_e32 v111, v94, v111
	v_mul_f32_e32 v112, v94, v112
	v_mul_f32_e32 v113, v94, v113
	v_fma_f32 v98, v98, v130, v114
	v_fma_f32 v99, v99, v131, v115
	v_fma_f32 v100, v100, v132, v116
	v_fma_f32 v101, v101, v133, v117
	v_fma_f32 v102, v102, v134, v118
	v_fma_f32 v103, v103, v135, v119
	v_fma_f32 v104, v104, v136, v120
	v_fma_f32 v105, v105, v137, v121
	v_fma_f32 v106, v106, v138, v122
	v_fma_f32 v107, v107, v139, v123
	v_fma_f32 v108, v108, v140, v124
	v_fma_f32 v109, v109, v141, v125
	v_fma_f32 v110, v110, v142, v126
	v_fma_f32 v111, v111, v143, v127
	v_fma_f32 v112, v112, v144, v128
	v_fma_f32 v113, v113, v145, v129
	v_cvt_pk_bf16_f32 v190, v98, v99
	v_cvt_pk_bf16_f32 v191, v100, v101
	v_cvt_pk_bf16_f32 v192, v102, v103
	v_cvt_pk_bf16_f32 v193, v104, v105
	v_cvt_pk_bf16_f32 v194, v106, v107
	v_cvt_pk_bf16_f32 v195, v108, v109
	v_cvt_pk_bf16_f32 v196, v110, v111
	v_cvt_pk_bf16_f32 v197, v112, v113
	s_add_u32 s2, s10, 0x1800
	s_addc_u32 s3, s11, 0
	global_store_dwordx4 v1, v[190:193], s[2:3]
	global_store_dwordx4 v1, v[194:197], s[2:3] offset:1024
	s_add_u32 s2, s8, 0x7000
	s_addc_u32 s3, s9, 0
	global_load_dwordx4 v[98:101], v0, s[2:3]
	global_load_dwordx4 v[102:105], v0, s[2:3] offset:16
	global_load_dwordx4 v[106:109], v0, s[2:3] offset:2048
	global_load_dwordx4 v[110:113], v0, s[2:3] offset:2064
	s_waitcnt vmcnt(18)
; DI unsigned pk2(float lo, float hi) { f32x2 v = {lo, hi}; bf16x2_t b = __builtin_convertvector(v, bf16x2_t); return __builtin_bit_cast(unsigned, b); }
; DI const float* modp(const Frame& F, int l, int mr, int which) { return (const float*)(F.ws + WS_MOD) + ((size_t)(l * 9 + mr) * 6 + which) * 1024; }
; DI void ln_row_v(const Frame& F, f32x4 (&v)[4], float* xout, const float* g, const float* b, const float* sh, const float* sc, bf16_t* hout, const float* slab, const float* gres, float* stat = nullptr) {
;     ...
;     if (hout) {
;         float s = 0.f, s2 = 0.f;
; #pragma unroll
;         for (int j = 0; j < 4; ++j) { s += (v[j][0] + v[j][1]) + (v[j][2] + v[j][3]); s2 += (v[j][0] * v[j][0] + v[j][1] * v[j][1]) + (v[j][2] * v[j][2] + v[j][3] * v[j][3]); }
;         wave_sum2(s, s2, F.lane);
;         const float mean = s * (1.f / D); const float rstd = 1.f / sqrtf(fmaxf(s2 * (1.f / D) - mean * mean, 0.f) + EPS);
; #pragma unroll
;         for (int j = 0; j < 4; ++j) { const f32x4 hh = ((const f32x4*)sh)[F.lane + 64 * j], cc = ((const f32x4*)sc)[F.lane + 64 * j];
;             const f32x4 o = (v[j] - mean) * rstd * (cc + 1.f) + hh; u32x2 wv; wv.x = pk2(o[0], o[1]); wv.y = pk2(o[2], o[3]);
;             ((u32x2*)hout)[F.lane + 64 * j] = wv; }
;     }
; DI void prologue_b(const Frame& F) {
;     ...
;         const int mr = row < ML ? (row >> 11) : 8;
;         const float* xi = row < ML ? pin(F, I_X) + (size_t)row * D : pin(F, I_CTX) + (size_t)(row - ML) * D;
;         ln_row(F, xi, nullptr, nullptr, nullptr, modp(F, 0, mr, 0), modp(F, 0, mr, 1), H + (size_t)row * D);
	v_add_f32_e32 v9, v42, v43
	v_add_f32_e32 v91, v44, v45
	v_mul_f32_e32 v90, v42, v42
	v_mul_f32_e32 v92, v43, v43
	v_add_f32_e32 v9, v9, v46
	v_add_f32_e32 v91, v91, v47
	v_add_f32_e32 v9, v9, v48
	v_add_f32_e32 v91, v91, v49
	v_add_f32_e32 v9, v9, v50
	v_add_f32_e32 v91, v91, v51
	v_add_f32_e32 v9, v9, v52
	v_add_f32_e32 v91, v91, v53
	v_add_f32_e32 v9, v9, v54
	v_add_f32_e32 v91, v91, v55
	v_add_f32_e32 v9, v9, v56
	v_add_f32_e32 v91, v91, v57
	v_fmac_f32_e32 v90, v44, v44
	v_fmac_f32_e32 v92, v45, v45
	v_fmac_f32_e32 v90, v46, v46
	v_fmac_f32_e32 v92, v47, v47
	v_fmac_f32_e32 v90, v48, v48
	v_fmac_f32_e32 v92, v49, v49
	v_fmac_f32_e32 v90, v50, v50
	v_fmac_f32_e32 v92, v51, v51
	v_fmac_f32_e32 v90, v52, v52
	v_fmac_f32_e32 v92, v53, v53
	v_fmac_f32_e32 v90, v54, v54
	v_fmac_f32_e32 v92, v55, v55
	v_fmac_f32_e32 v90, v56, v56
	v_fmac_f32_e32 v92, v57, v57
	v_add_f32_e32 v9, v9, v91
	v_add_f32_e32 v90, v90, v92
	s_nop 1
	v_add_f32_dpp v9, v9, v9 quad_perm:[1,0,3,2] row_mask:0xf bank_mask:0xf
	v_add_f32_dpp v90, v90, v90 quad_perm:[1,0,3,2] row_mask:0xf bank_mask:0xf
	s_nop 0
	v_add_f32_dpp v9, v9, v9 quad_perm:[2,3,0,1] row_mask:0xf bank_mask:0xf
	v_add_f32_dpp v90, v90, v90 quad_perm:[2,3,0,1] row_mask:0xf bank_mask:0xf
	s_nop 0
	v_add_f32_dpp v9, v9, v9 row_half_mirror row_mask:0xf bank_mask:0xf
	v_add_f32_dpp v90, v90, v90 row_half_mirror row_mask:0xf bank_mask:0xf
	s_nop 0
	v_add_f32_dpp v9, v9, v9 row_mirror row_mask:0xf bank_mask:0xf
	v_add_f32_dpp v90, v90, v90 row_mirror row_mask:0xf bank_mask:0xf
	s_nop 0
	v_add_f32_dpp v9, v9, v9 row_bcast:15 row_mask:0xa bank_mask:0xf
	v_add_f32_dpp v90, v90, v90 row_bcast:15 row_mask:0xa bank_mask:0xf
	s_nop 0
	v_add_f32_dpp v9, v9, v9 row_bcast:31 row_mask:0xc bank_mask:0xf
	v_add_f32_dpp v90, v90, v90 row_bcast:31 row_mask:0xc bank_mask:0xf
	s_nop 0
	v_readlane_b32 s2, v9, 63
	v_readlane_b32 s3, v90, 63
	s_nop 1
	v_mov_b32_e32 v9, s2
	v_mov_b32_e32 v90, s3
	v_mul_f32_e32 v93, 0x3a800000, v9
	v_mul_f32_e32 v91, 0x3a800000, v90
	v_fma_f32 v91, -v93, v93, v91
	v_max_f32_e32 v91, 0, v91
	v_add_f32_e32 v91, 0x358637bd, v91
	v_rsq_f32_e32 v94, v91
	v_mul_f32_e32 v91, 0.5, v91
	v_mul_f32_e32 v92, v94, v94
	v_fma_f32 v92, -v91, v92, 0.5
	v_fma_f32 v94, v94, v92, v94
	v_sub_f32_e32 v42, v42, v93
	v_sub_f32_e32 v43, v43, v93
	v_sub_f32_e32 v44, v44, v93
	v_sub_f32_e32 v45, v45, v93
	v_sub_f32_e32 v46, v46, v93
	v_sub_f32_e32 v47, v47, v93
	v_sub_f32_e32 v48, v48, v93
	v_sub_f32_e32 v49, v49, v93
	v_sub_f32_e32 v50, v50, v93
	v_sub_f32_e32 v51, v51, v93
	v_sub_f32_e32 v52, v52, v93
	v_sub_f32_e32 v53, v53, v93
	v_sub_f32_e32 v54, v54, v93
	v_sub_f32_e32 v55, v55, v93
	v_sub_f32_e32 v56, v56, v93
	v_sub_f32_e32 v57, v57, v93
	v_mul_f32_e32 v42, v94, v42
	v_mul_f32_e32 v43, v94, v43
	v_mul_f32_e32 v44, v94, v44
	v_mul_f32_e32 v45, v94, v45
	v_mul_f32_e32 v46, v94, v46
	v_mul_f32_e32 v47, v94, v47
	v_mul_f32_e32 v48, v94, v48
	v_mul_f32_e32 v49, v94, v49
	v_mul_f32_e32 v50, v94, v50
	v_mul_f32_e32 v51, v94, v51
	v_mul_f32_e32 v52, v94, v52
	v_mul_f32_e32 v53, v94, v53
	v_mul_f32_e32 v54, v94, v54
	v_mul_f32_e32 v55, v94, v55
	v_mul_f32_e32 v56, v94, v56
	v_mul_f32_e32 v57, v94, v57
	v_fma_f32 v42, v42, v130, v114
	v_fma_f32 v43, v43, v131, v115
	v_fma_f32 v44, v44, v132, v116
	v_fma_f32 v45, v45, v133, v117
	v_fma_f32 v46, v46, v134, v118
	v_fma_f32 v47, v47, v135, v119
	v_fma_f32 v48, v48, v136, v120
	v_fma_f32 v49, v49, v137, v121
	v_fma_f32 v50, v50, v138, v122
	v_fma_f32 v51, v51, v139, v123
	v_fma_f32 v52, v52, v140, v124
	v_fma_f32 v53, v53, v141, v125
	v_fma_f32 v54, v54, v142, v126
	v_fma_f32 v55, v55, v143, v127
	v_fma_f32 v56, v56, v144, v128
	v_fma_f32 v57, v57, v145, v129
	v_cvt_pk_bf16_f32 v190, v42, v43
	v_cvt_pk_bf16_f32 v191, v44, v45
	v_cvt_pk_bf16_f32 v192, v46, v47
	v_cvt_pk_bf16_f32 v193, v48, v49
	v_cvt_pk_bf16_f32 v194, v50, v51
	v_cvt_pk_bf16_f32 v195, v52, v53
	v_cvt_pk_bf16_f32 v196, v54, v55
	v_cvt_pk_bf16_f32 v197, v56, v57
	s_add_u32 s2, s10, 0x2000
	s_addc_u32 s3, s11, 0
	global_store_dwordx4 v1, v[190:193], s[2:3]
	global_store_dwordx4 v1, v[194:197], s[2:3] offset:1024
	s_mov_b64 s[2:3], s[20:21]
	global_load_dwordx4 v[42:45], v0, s[2:3]
	global_load_dwordx4 v[46:49], v0, s[2:3] offset:16
	global_load_dwordx4 v[50:53], v0, s[2:3] offset:2048
	global_load_dwordx4 v[54:57], v0, s[2:3] offset:2064
	s_waitcnt vmcnt(18)
; DI unsigned pk2(float lo, float hi) { f32x2 v = {lo, hi}; bf16x2_t b = __builtin_convertvector(v, bf16x2_t); return __builtin_bit_cast(unsigned, b); }
; DI void ln_row_v(const Frame& F, f32x4 (&v)[4], float* xout, const float* g, const float* b, const float* sh, const float* sc, bf16_t* hout, const float* slab, const float* gres, float* stat = nullptr) {
;     ...
;     if (hout) {
;         float s = 0.f, s2 = 0.f;
; #pragma unroll
;         for (int j = 0; j < 4; ++j) { s += (v[j][0] + v[j][1]) + (v[j][2] + v[j][3]); s2 += (v[j][0] * v[j][0] + v[j][1] * v[j][1]) + (v[j][2] * v[j][2] + v[j][3] * v[j][3]); }
;         wave_sum2(s, s2, F.lane);
;         const float mean = s * (1.f / D); const float rstd = 1.f / sqrtf(fmaxf(s2 * (1.f / D) - mean * mean, 0.f) + EPS);
; #pragma unroll
;         for (int j = 0; j < 4; ++j) { const f32x4 hh = ((const f32x4*)sh)[F.lane + 64 * j], cc = ((const f32x4*)sc)[F.lane + 64 * j];
;             const f32x4 o = (v[j] - mean) * rstd * (cc + 1.f) + hh; u32x2 wv; wv.x = pk2(o[0], o[1]); wv.y = pk2(o[2], o[3]);
;             ((u32x2*)hout)[F.lane + 64 * j] = wv; }
;     }
	v_add_f32_e32 v9, v58, v59
	v_add_f32_e32 v91, v60, v61
	v_mul_f32_e32 v90, v58, v58
	v_mul_f32_e32 v92, v59, v59
	v_add_f32_e32 v9, v9, v62
	v_add_f32_e32 v91, v91, v63
	v_add_f32_e32 v9, v9, v64
	v_add_f32_e32 v91, v91, v65
	v_add_f32_e32 v9, v9, v66
	v_add_f32_e32 v91, v91, v67
	v_add_f32_e32 v9, v9, v68
	v_add_f32_e32 v91, v91, v69
	v_add_f32_e32 v9, v9, v70
	v_add_f32_e32 v91, v91, v71
	v_add_f32_e32 v9, v9, v72
	v_add_f32_e32 v91, v91, v73
	v_fmac_f32_e32 v90, v60, v60
	v_fmac_f32_e32 v92, v61, v61
	v_fmac_f32_e32 v90, v62, v62
	v_fmac_f32_e32 v92, v63, v63
	v_fmac_f32_e32 v90, v64, v64
	v_fmac_f32_e32 v92, v65, v65
	v_fmac_f32_e32 v90, v66, v66
	v_fmac_f32_e32 v92, v67, v67
	v_fmac_f32_e32 v90, v68, v68
	v_fmac_f32_e32 v92, v69, v69
	v_fmac_f32_e32 v90, v70, v70
	v_fmac_f32_e32 v92, v71, v71
	v_fmac_f32_e32 v90, v72, v72
	v_fmac_f32_e32 v92, v73, v73
	v_add_f32_e32 v9, v9, v91
	v_add_f32_e32 v90, v90, v92
	s_nop 1
	v_add_f32_dpp v9, v9, v9 quad_perm:[1,0,3,2] row_mask:0xf bank_mask:0xf
	v_add_f32_dpp v90, v90, v90 quad_perm:[1,0,3,2] row_mask:0xf bank_mask:0xf
	s_nop 0
	v_add_f32_dpp v9, v9, v9 quad_perm:[2,3,0,1] row_mask:0xf bank_mask:0xf
	v_add_f32_dpp v90, v90, v90 quad_perm:[2,3,0,1] row_mask:0xf bank_mask:0xf
	s_nop 0
	v_add_f32_dpp v9, v9, v9 row_half_mirror row_mask:0xf bank_mask:0xf
	v_add_f32_dpp v90, v90, v90 row_half_mirror row_mask:0xf bank_mask:0xf
	s_nop 0
	v_add_f32_dpp v9, v9, v9 row_mirror row_mask:0xf bank_mask:0xf
	v_add_f32_dpp v90, v90, v90 row_mirror row_mask:0xf bank_mask:0xf
	s_nop 0
	v_add_f32_dpp v9, v9, v9 row_bcast:15 row_mask:0xa bank_mask:0xf
	v_add_f32_dpp v90, v90, v90 row_bcast:15 row_mask:0xa bank_mask:0xf
	s_nop 0
	v_add_f32_dpp v9, v9, v9 row_bcast:31 row_mask:0xc bank_mask:0xf
	v_add_f32_dpp v90, v90, v90 row_bcast:31 row_mask:0xc bank_mask:0xf
	s_nop 0
	v_readlane_b32 s2, v9, 63
	v_readlane_b32 s3, v90, 63
	s_nop 1
	v_mov_b32_e32 v9, s2
	v_mov_b32_e32 v90, s3
	v_mul_f32_e32 v93, 0x3a800000, v9
	v_mul_f32_e32 v91, 0x3a800000, v90
	v_fma_f32 v91, -v93, v93, v91
	v_max_f32_e32 v91, 0, v91
	v_add_f32_e32 v91, 0x358637bd, v91
	v_rsq_f32_e32 v94, v91
	v_mul_f32_e32 v91, 0.5, v91
	v_mul_f32_e32 v92, v94, v94
	v_fma_f32 v92, -v91, v92, 0.5
	v_fma_f32 v94, v94, v92, v94
	v_sub_f32_e32 v58, v58, v93
	v_sub_f32_e32 v59, v59, v93
	v_sub_f32_e32 v60, v60, v93
	v_sub_f32_e32 v61, v61, v93
	v_sub_f32_e32 v62, v62, v93
	v_sub_f32_e32 v63, v63, v93
	v_sub_f32_e32 v64, v64, v93
	v_sub_f32_e32 v65, v65, v93
	v_sub_f32_e32 v66, v66, v93
	v_sub_f32_e32 v67, v67, v93
	v_sub_f32_e32 v68, v68, v93
	v_sub_f32_e32 v69, v69, v93
	v_sub_f32_e32 v70, v70, v93
	v_sub_f32_e32 v71, v71, v93
	v_sub_f32_e32 v72, v72, v93
	v_sub_f32_e32 v73, v73, v93
	v_mul_f32_e32 v58, v94, v58
	v_mul_f32_e32 v59, v94, v59
	v_mul_f32_e32 v60, v94, v60
	v_mul_f32_e32 v61, v94, v61
	v_mul_f32_e32 v62, v94, v62
	v_mul_f32_e32 v63, v94, v63
	v_mul_f32_e32 v64, v94, v64
	v_mul_f32_e32 v65, v94, v65
	v_mul_f32_e32 v66, v94, v66
	v_mul_f32_e32 v67, v94, v67
	v_mul_f32_e32 v68, v94, v68
	v_mul_f32_e32 v69, v94, v69
	v_mul_f32_e32 v70, v94, v70
	v_mul_f32_e32 v71, v94, v71
	v_mul_f32_e32 v72, v94, v72
	v_mul_f32_e32 v73, v94, v73
	v_fma_f32 v58, v58, v130, v114
	v_fma_f32 v59, v59, v131, v115
	v_fma_f32 v60, v60, v132, v116
	v_fma_f32 v61, v61, v133, v117
	v_fma_f32 v62, v62, v134, v118
	v_fma_f32 v63, v63, v135, v119
	v_fma_f32 v64, v64, v136, v120
	v_fma_f32 v65, v65, v137, v121
	v_fma_f32 v66, v66, v138, v122
	v_fma_f32 v67, v67, v139, v123
	v_fma_f32 v68, v68, v140, v124
	v_fma_f32 v69, v69, v141, v125
	v_fma_f32 v70, v70, v142, v126
	v_fma_f32 v71, v71, v143, v127
	v_fma_f32 v72, v72, v144, v128
	v_fma_f32 v73, v73, v145, v129
	v_cvt_pk_bf16_f32 v190, v58, v59
	v_cvt_pk_bf16_f32 v191, v60, v61
	v_cvt_pk_bf16_f32 v192, v62, v63
	v_cvt_pk_bf16_f32 v193, v64, v65
	v_cvt_pk_bf16_f32 v194, v66, v67
	v_cvt_pk_bf16_f32 v195, v68, v69
	v_cvt_pk_bf16_f32 v196, v70, v71
	v_cvt_pk_bf16_f32 v197, v72, v73
	s_add_u32 s2, s10, 0x2800
	s_addc_u32 s3, s11, 0
	global_store_dwordx4 v1, v[190:193], s[2:3]
	global_store_dwordx4 v1, v[194:197], s[2:3] offset:1024
	s_waitcnt vmcnt(14)
	v_add_f32_e32 v9, v74, v75
	v_add_f32_e32 v91, v76, v77
	v_mul_f32_e32 v90, v74, v74
	v_mul_f32_e32 v92, v75, v75
	v_add_f32_e32 v9, v9, v78
	v_add_f32_e32 v91, v91, v79
	v_add_f32_e32 v9, v9, v80
	v_add_f32_e32 v91, v91, v81
	v_add_f32_e32 v9, v9, v82
	v_add_f32_e32 v91, v91, v83
	v_add_f32_e32 v9, v9, v84
	v_add_f32_e32 v91, v91, v85
	v_add_f32_e32 v9, v9, v86
	v_add_f32_e32 v91, v91, v87
	v_add_f32_e32 v9, v9, v88
	v_add_f32_e32 v91, v91, v89
	v_fmac_f32_e32 v90, v76, v76
	v_fmac_f32_e32 v92, v77, v77
	v_fmac_f32_e32 v90, v78, v78
	v_fmac_f32_e32 v92, v79, v79
	v_fmac_f32_e32 v90, v80, v80
	v_fmac_f32_e32 v92, v81, v81
	v_fmac_f32_e32 v90, v82, v82
	v_fmac_f32_e32 v92, v83, v83
	v_fmac_f32_e32 v90, v84, v84
	v_fmac_f32_e32 v92, v85, v85
	v_fmac_f32_e32 v90, v86, v86
	v_fmac_f32_e32 v92, v87, v87
	v_fmac_f32_e32 v90, v88, v88
	v_fmac_f32_e32 v92, v89, v89
	v_add_f32_e32 v9, v9, v91
	v_add_f32_e32 v90, v90, v92
	s_nop 1
	v_add_f32_dpp v9, v9, v9 quad_perm:[1,0,3,2] row_mask:0xf bank_mask:0xf
	v_add_f32_dpp v90, v90, v90 quad_perm:[1,0,3,2] row_mask:0xf bank_mask:0xf
	s_nop 0
	v_add_f32_dpp v9, v9, v9 quad_perm:[2,3,0,1] row_mask:0xf bank_mask:0xf
	v_add_f32_dpp v90, v90, v90 quad_perm:[2,3,0,1] row_mask:0xf bank_mask:0xf
	s_nop 0
	v_add_f32_dpp v9, v9, v9 row_half_mirror row_mask:0xf bank_mask:0xf
	v_add_f32_dpp v90, v90, v90 row_half_mirror row_mask:0xf bank_mask:0xf
	s_nop 0
	v_add_f32_dpp v9, v9, v9 row_mirror row_mask:0xf bank_mask:0xf
	v_add_f32_dpp v90, v90, v90 row_mirror row_mask:0xf bank_mask:0xf
; DI unsigned pk2(float lo, float hi) { f32x2 v = {lo, hi}; bf16x2_t b = __builtin_convertvector(v, bf16x2_t); return __builtin_bit_cast(unsigned, b); }
; DI void ln_row_v(const Frame& F, f32x4 (&v)[4], float* xout, const float* g, const float* b, const float* sh, const float* sc, bf16_t* hout, const float* slab, const float* gres, float* stat = nullptr) {
;     ...
;     if (hout) {
;         float s = 0.f, s2 = 0.f;
; #pragma unroll
;         for (int j = 0; j < 4; ++j) { s += (v[j][0] + v[j][1]) + (v[j][2] + v[j][3]); s2 += (v[j][0] * v[j][0] + v[j][1] * v[j][1]) + (v[j][2] * v[j][2] + v[j][3] * v[j][3]); }
;         wave_sum2(s, s2, F.lane);
;         const float mean = s * (1.f / D); const float rstd = 1.f / sqrtf(fmaxf(s2 * (1.f / D) - mean * mean, 0.f) + EPS);
; #pragma unroll
;         for (int j = 0; j < 4; ++j) { const f32x4 hh = ((const f32x4*)sh)[F.lane + 64 * j], cc = ((const f32x4*)sc)[F.lane + 64 * j];
;             const f32x4 o = (v[j] - mean) * rstd * (cc + 1.f) + hh; u32x2 wv; wv.x = pk2(o[0], o[1]); wv.y = pk2(o[2], o[3]);
;             ((u32x2*)hout)[F.lane + 64 * j] = wv; }
;     }
	s_nop 0
	v_add_f32_dpp v9, v9, v9 row_bcast:15 row_mask:0xa bank_mask:0xf
	v_add_f32_dpp v90, v90, v90 row_bcast:15 row_mask:0xa bank_mask:0xf
	s_nop 0
	v_add_f32_dpp v9, v9, v9 row_bcast:31 row_mask:0xc bank_mask:0xf
	v_add_f32_dpp v90, v90, v90 row_bcast:31 row_mask:0xc bank_mask:0xf
	s_nop 0
	v_readlane_b32 s2, v9, 63
	v_readlane_b32 s3, v90, 63
	s_nop 1
	v_mov_b32_e32 v9, s2
	v_mov_b32_e32 v90, s3
	v_mul_f32_e32 v93, 0x3a800000, v9
	v_mul_f32_e32 v91, 0x3a800000, v90
	v_fma_f32 v91, -v93, v93, v91
	v_max_f32_e32 v91, 0, v91
	v_add_f32_e32 v91, 0x358637bd, v91
	v_rsq_f32_e32 v94, v91
	v_mul_f32_e32 v91, 0.5, v91
	v_mul_f32_e32 v92, v94, v94
	v_fma_f32 v92, -v91, v92, 0.5
	v_fma_f32 v94, v94, v92, v94
	v_sub_f32_e32 v74, v74, v93
	v_sub_f32_e32 v75, v75, v93
	v_sub_f32_e32 v76, v76, v93
	v_sub_f32_e32 v77, v77, v93
	v_sub_f32_e32 v78, v78, v93
	v_sub_f32_e32 v79, v79, v93
	v_sub_f32_e32 v80, v80, v93
	v_sub_f32_e32 v81, v81, v93
	v_sub_f32_e32 v82, v82, v93
	v_sub_f32_e32 v83, v83, v93
	v_sub_f32_e32 v84, v84, v93
	v_sub_f32_e32 v85, v85, v93
	v_sub_f32_e32 v86, v86, v93
	v_sub_f32_e32 v87, v87, v93
	v_sub_f32_e32 v88, v88, v93
	v_sub_f32_e32 v89, v89, v93
	v_mul_f32_e32 v74, v94, v74
	v_mul_f32_e32 v75, v94, v75
	v_mul_f32_e32 v76, v94, v76
	v_mul_f32_e32 v77, v94, v77
	v_mul_f32_e32 v78, v94, v78
	v_mul_f32_e32 v79, v94, v79
	v_mul_f32_e32 v80, v94, v80
	v_mul_f32_e32 v81, v94, v81
	v_mul_f32_e32 v82, v94, v82
	v_mul_f32_e32 v83, v94, v83
	v_mul_f32_e32 v84, v94, v84
	v_mul_f32_e32 v85, v94, v85
	v_mul_f32_e32 v86, v94, v86
	v_mul_f32_e32 v87, v94, v87
	v_mul_f32_e32 v88, v94, v88
	v_mul_f32_e32 v89, v94, v89
	v_fma_f32 v74, v74, v130, v114
	v_fma_f32 v75, v75, v131, v115
	v_fma_f32 v76, v76, v132, v116
	v_fma_f32 v77, v77, v133, v117
	v_fma_f32 v78, v78, v134, v118
	v_fma_f32 v79, v79, v135, v119
	v_fma_f32 v80, v80, v136, v120
	v_fma_f32 v81, v81, v137, v121
	v_fma_f32 v82, v82, v138, v122
	v_fma_f32 v83, v83, v139, v123
	v_fma_f32 v84, v84, v140, v124
	v_fma_f32 v85, v85, v141, v125
	v_fma_f32 v86, v86, v142, v126
	v_fma_f32 v87, v87, v143, v127
	v_fma_f32 v88, v88, v144, v128
	v_fma_f32 v89, v89, v145, v129
	v_cvt_pk_bf16_f32 v190, v74, v75
	v_cvt_pk_bf16_f32 v191, v76, v77
	v_cvt_pk_bf16_f32 v192, v78, v79
	v_cvt_pk_bf16_f32 v193, v80, v81
	v_cvt_pk_bf16_f32 v194, v82, v83
	v_cvt_pk_bf16_f32 v195, v84, v85
	v_cvt_pk_bf16_f32 v196, v86, v87
	v_cvt_pk_bf16_f32 v197, v88, v89
	s_add_u32 s2, s10, 0x3000
	s_addc_u32 s3, s11, 0
	global_store_dwordx4 v1, v[190:193], s[2:3]
	global_store_dwordx4 v1, v[194:197], s[2:3] offset:1024
	s_waitcnt vmcnt(10)
	v_add_f32_e32 v9, v98, v99
	v_add_f32_e32 v91, v100, v101
	v_mul_f32_e32 v90, v98, v98
	v_mul_f32_e32 v92, v99, v99
	v_add_f32_e32 v9, v9, v102
	v_add_f32_e32 v91, v91, v103
	v_add_f32_e32 v9, v9, v104
	v_add_f32_e32 v91, v91, v105
	v_add_f32_e32 v9, v9, v106
	v_add_f32_e32 v91, v91, v107
	v_add_f32_e32 v9, v9, v108
	v_add_f32_e32 v91, v91, v109
	v_add_f32_e32 v9, v9, v110
	v_add_f32_e32 v91, v91, v111
	v_add_f32_e32 v9, v9, v112
	v_add_f32_e32 v91, v91, v113
	v_fmac_f32_e32 v90, v100, v100
	v_fmac_f32_e32 v92, v101, v101
	v_fmac_f32_e32 v90, v102, v102
	v_fmac_f32_e32 v92, v103, v103
	v_fmac_f32_e32 v90, v104, v104
	v_fmac_f32_e32 v92, v105, v105
	v_fmac_f32_e32 v90, v106, v106
	v_fmac_f32_e32 v92, v107, v107
	v_fmac_f32_e32 v90, v108, v108
	v_fmac_f32_e32 v92, v109, v109
	v_fmac_f32_e32 v90, v110, v110
	v_fmac_f32_e32 v92, v111, v111
	v_fmac_f32_e32 v90, v112, v112
	v_fmac_f32_e32 v92, v113, v113
	v_add_f32_e32 v9, v9, v91
	v_add_f32_e32 v90, v90, v92
	s_nop 1
	v_add_f32_dpp v9, v9, v9 quad_perm:[1,0,3,2] row_mask:0xf bank_mask:0xf
	v_add_f32_dpp v90, v90, v90 quad_perm:[1,0,3,2] row_mask:0xf bank_mask:0xf
	s_nop 0
	v_add_f32_dpp v9, v9, v9 quad_perm:[2,3,0,1] row_mask:0xf bank_mask:0xf
	v_add_f32_dpp v90, v90, v90 quad_perm:[2,3,0,1] row_mask:0xf bank_mask:0xf
	s_nop 0
	v_add_f32_dpp v9, v9, v9 row_half_mirror row_mask:0xf bank_mask:0xf
	v_add_f32_dpp v90, v90, v90 row_half_mirror row_mask:0xf bank_mask:0xf
	s_nop 0
	v_add_f32_dpp v9, v9, v9 row_mirror row_mask:0xf bank_mask:0xf
	v_add_f32_dpp v90, v90, v90 row_mirror row_mask:0xf bank_mask:0xf
	s_nop 0
	v_add_f32_dpp v9, v9, v9 row_bcast:15 row_mask:0xa bank_mask:0xf
	v_add_f32_dpp v90, v90, v90 row_bcast:15 row_mask:0xa bank_mask:0xf
	s_nop 0
	v_add_f32_dpp v9, v9, v9 row_bcast:31 row_mask:0xc bank_mask:0xf
	v_add_f32_dpp v90, v90, v90 row_bcast:31 row_mask:0xc bank_mask:0xf
	s_nop 0
	v_readlane_b32 s2, v9, 63
	v_readlane_b32 s3, v90, 63
	s_nop 1
	v_mov_b32_e32 v9, s2
	v_mov_b32_e32 v90, s3
	v_mul_f32_e32 v93, 0x3a800000, v9
	v_mul_f32_e32 v91, 0x3a800000, v90
	v_fma_f32 v91, -v93, v93, v91
	v_max_f32_e32 v91, 0, v91
	v_add_f32_e32 v91, 0x358637bd, v91
	v_rsq_f32_e32 v94, v91
	v_mul_f32_e32 v91, 0.5, v91
	v_mul_f32_e32 v92, v94, v94
	v_fma_f32 v92, -v91, v92, 0.5
	v_fma_f32 v94, v94, v92, v94
	v_sub_f32_e32 v98, v98, v93
	v_sub_f32_e32 v99, v99, v93
	v_sub_f32_e32 v100, v100, v93
	v_sub_f32_e32 v101, v101, v93
	v_sub_f32_e32 v102, v102, v93
	v_sub_f32_e32 v103, v103, v93
	v_sub_f32_e32 v104, v104, v93
	v_sub_f32_e32 v105, v105, v93
	v_sub_f32_e32 v106, v106, v93
	v_sub_f32_e32 v107, v107, v93
	v_sub_f32_e32 v108, v108, v93
	v_sub_f32_e32 v109, v109, v93
	v_sub_f32_e32 v110, v110, v93
	v_sub_f32_e32 v111, v111, v93
	v_sub_f32_e32 v112, v112, v93
	v_sub_f32_e32 v113, v113, v93
	v_mul_f32_e32 v98, v94, v98
	v_mul_f32_e32 v99, v94, v99
	v_mul_f32_e32 v100, v94, v100
	v_mul_f32_e32 v101, v94, v101
	v_mul_f32_e32 v102, v94, v102
	v_mul_f32_e32 v103, v94, v103
	v_mul_f32_e32 v104, v94, v104
	v_mul_f32_e32 v105, v94, v105
	v_mul_f32_e32 v106, v94, v106
	v_mul_f32_e32 v107, v94, v107
	v_mul_f32_e32 v108, v94, v108
	v_mul_f32_e32 v109, v94, v109
	v_mul_f32_e32 v110, v94, v110
	v_mul_f32_e32 v111, v94, v111
	v_mul_f32_e32 v112, v94, v112
	v_mul_f32_e32 v113, v94, v113
	v_fma_f32 v98, v98, v130, v114
	v_fma_f32 v99, v99, v131, v115
	v_fma_f32 v100, v100, v132, v116
	v_fma_f32 v101, v101, v133, v117
	v_fma_f32 v102, v102, v134, v118
	v_fma_f32 v103, v103, v135, v119
	v_fma_f32 v104, v104, v136, v120
	v_fma_f32 v105, v105, v137, v121
	v_fma_f32 v106, v106, v138, v122
	v_fma_f32 v107, v107, v139, v123
	v_fma_f32 v108, v108, v140, v124
	v_fma_f32 v109, v109, v141, v125
	v_fma_f32 v110, v110, v142, v126
	v_fma_f32 v111, v111, v143, v127
	v_fma_f32 v112, v112, v144, v128
	v_fma_f32 v113, v113, v145, v129
	v_cvt_pk_bf16_f32 v190, v98, v99
	v_cvt_pk_bf16_f32 v191, v100, v101
	v_cvt_pk_bf16_f32 v192, v102, v103
	v_cvt_pk_bf16_f32 v193, v104, v105
	v_cvt_pk_bf16_f32 v194, v106, v107
	v_cvt_pk_bf16_f32 v195, v108, v109
	v_cvt_pk_bf16_f32 v196, v110, v111
	v_cvt_pk_bf16_f32 v197, v112, v113
	s_add_u32 s2, s10, 0x3800
	s_addc_u32 s3, s11, 0
	global_store_dwordx4 v1, v[190:193], s[2:3]
	global_store_dwordx4 v1, v[194:197], s[2:3] offset:1024
	s_waitcnt vmcnt(6)
; DI unsigned pk2(float lo, float hi) { f32x2 v = {lo, hi}; bf16x2_t b = __builtin_convertvector(v, bf16x2_t); return __builtin_bit_cast(unsigned, b); }
; DI const float* modp(const Frame& F, int l, int mr, int which) { return (const float*)(F.ws + WS_MOD) + ((size_t)(l * 9 + mr) * 6 + which) * 1024; }
; DI void ln_row_v(const Frame& F, f32x4 (&v)[4], float* xout, const float* g, const float* b, const float* sh, const float* sc, bf16_t* hout, const float* slab, const float* gres, float* stat = nullptr) {
;     ...
;     if (hout) {
;         float s = 0.f, s2 = 0.f;
; #pragma unroll
;         for (int j = 0; j < 4; ++j) { s += (v[j][0] + v[j][1]) + (v[j][2] + v[j][3]); s2 += (v[j][0] * v[j][0] + v[j][1] * v[j][1]) + (v[j][2] * v[j][2] + v[j][3] * v[j][3]); }
;         wave_sum2(s, s2, F.lane);
;         const float mean = s * (1.f / D); const float rstd = 1.f / sqrtf(fmaxf(s2 * (1.f / D) - mean * mean, 0.f) + EPS);
; #pragma unroll
;         for (int j = 0; j < 4; ++j) { const f32x4 hh = ((const f32x4*)sh)[F.lane + 64 * j], cc = ((const f32x4*)sc)[F.lane + 64 * j];
;             const f32x4 o = (v[j] - mean) * rstd * (cc + 1.f) + hh; u32x2 wv; wv.x = pk2(o[0], o[1]); wv.y = pk2(o[2], o[3]);
;             ((u32x2*)hout)[F.lane + 64 * j] = wv; }
;     }
; DI void prologue_b(const Frame& F) {
;     const int gw = F.vcu * 8 + F.wave, NGW = F.G * 8;
;     bf16_t* H = (bf16_t*)(F.ws + WS_HB);
;     for (int row = gw; row < MT; row += NGW) {
;         const int mr = row < ML ? (row >> 11) : 8;
;         const float* xi = row < ML ? pin(F, I_X) + (size_t)row * D : pin(F, I_CTX) + (size_t)(row - ML) * D;
;         ln_row(F, xi, nullptr, nullptr, nullptr, modp(F, 0, mr, 0), modp(F, 0, mr, 1), H + (size_t)row * D);
;     }
; }
	v_add_f32_e32 v9, v42, v43
	v_add_f32_e32 v91, v44, v45
	v_mul_f32_e32 v90, v42, v42
	v_mul_f32_e32 v92, v43, v43
	v_add_f32_e32 v9, v9, v46
	v_add_f32_e32 v91, v91, v47
	v_add_f32_e32 v9, v9, v48
	v_add_f32_e32 v91, v91, v49
	v_add_f32_e32 v9, v9, v50
	v_add_f32_e32 v91, v91, v51
	v_add_f32_e32 v9, v9, v52
	v_add_f32_e32 v91, v91, v53
	v_add_f32_e32 v9, v9, v54
	v_add_f32_e32 v91, v91, v55
	v_add_f32_e32 v9, v9, v56
	v_add_f32_e32 v91, v91, v57
	v_fmac_f32_e32 v90, v44, v44
	v_fmac_f32_e32 v92, v45, v45
	v_fmac_f32_e32 v90, v46, v46
	v_fmac_f32_e32 v92, v47, v47
	v_fmac_f32_e32 v90, v48, v48
	v_fmac_f32_e32 v92, v49, v49
	v_fmac_f32_e32 v90, v50, v50
	v_fmac_f32_e32 v92, v51, v51
	v_fmac_f32_e32 v90, v52, v52
	v_fmac_f32_e32 v92, v53, v53
	v_fmac_f32_e32 v90, v54, v54
	v_fmac_f32_e32 v92, v55, v55
	v_fmac_f32_e32 v90, v56, v56
	v_fmac_f32_e32 v92, v57, v57
	v_add_f32_e32 v9, v9, v91
	v_add_f32_e32 v90, v90, v92
	s_nop 1
	v_add_f32_dpp v9, v9, v9 quad_perm:[1,0,3,2] row_mask:0xf bank_mask:0xf
	v_add_f32_dpp v90, v90, v90 quad_perm:[1,0,3,2] row_mask:0xf bank_mask:0xf
	s_nop 0
	v_add_f32_dpp v9, v9, v9 quad_perm:[2,3,0,1] row_mask:0xf bank_mask:0xf
	v_add_f32_dpp v90, v90, v90 quad_perm:[2,3,0,1] row_mask:0xf bank_mask:0xf
	s_nop 0
	v_add_f32_dpp v9, v9, v9 row_half_mirror row_mask:0xf bank_mask:0xf
	v_add_f32_dpp v90, v90, v90 row_half_mirror row_mask:0xf bank_mask:0xf
	s_nop 0
	v_add_f32_dpp v9, v9, v9 row_mirror row_mask:0xf bank_mask:0xf
	v_add_f32_dpp v90, v90, v90 row_mirror row_mask:0xf bank_mask:0xf
	s_nop 0
	v_add_f32_dpp v9, v9, v9 row_bcast:15 row_mask:0xa bank_mask:0xf
	v_add_f32_dpp v90, v90, v90 row_bcast:15 row_mask:0xa bank_mask:0xf
	s_nop 0
	v_add_f32_dpp v9, v9, v9 row_bcast:31 row_mask:0xc bank_mask:0xf
	v_add_f32_dpp v90, v90, v90 row_bcast:31 row_mask:0xc bank_mask:0xf
	s_nop 0
	v_readlane_b32 s2, v9, 63
	v_readlane_b32 s3, v90, 63
	s_nop 1
	v_mov_b32_e32 v9, s2
	v_mov_b32_e32 v90, s3
	v_mul_f32_e32 v93, 0x3a800000, v9
	v_mul_f32_e32 v91, 0x3a800000, v90
	v_fma_f32 v91, -v93, v93, v91
	v_max_f32_e32 v91, 0, v91
	v_add_f32_e32 v91, 0x358637bd, v91
	v_rsq_f32_e32 v94, v91
	v_mul_f32_e32 v91, 0.5, v91
	v_mul_f32_e32 v92, v94, v94
	v_fma_f32 v92, -v91, v92, 0.5
	v_fma_f32 v94, v94, v92, v94
	v_sub_f32_e32 v42, v42, v93
	v_sub_f32_e32 v43, v43, v93
	v_sub_f32_e32 v44, v44, v93
	v_sub_f32_e32 v45, v45, v93
	v_sub_f32_e32 v46, v46, v93
	v_sub_f32_e32 v47, v47, v93
	v_sub_f32_e32 v48, v48, v93
	v_sub_f32_e32 v49, v49, v93
	v_sub_f32_e32 v50, v50, v93
	v_sub_f32_e32 v51, v51, v93
	v_sub_f32_e32 v52, v52, v93
	v_sub_f32_e32 v53, v53, v93
	v_sub_f32_e32 v54, v54, v93
	v_sub_f32_e32 v55, v55, v93
	v_sub_f32_e32 v56, v56, v93
	v_sub_f32_e32 v57, v57, v93
	v_add_f32_e32 v162, 1.0, v162
	v_add_f32_e32 v163, 1.0, v163
	v_add_f32_e32 v164, 1.0, v164
	v_add_f32_e32 v165, 1.0, v165
	v_add_f32_e32 v166, 1.0, v166
	v_add_f32_e32 v167, 1.0, v167
	v_add_f32_e32 v168, 1.0, v168
	v_add_f32_e32 v169, 1.0, v169
	v_add_f32_e32 v170, 1.0, v170
	v_add_f32_e32 v171, 1.0, v171
	v_add_f32_e32 v172, 1.0, v172
	v_add_f32_e32 v173, 1.0, v173
	v_add_f32_e32 v174, 1.0, v174
	v_add_f32_e32 v175, 1.0, v175
	v_add_f32_e32 v176, 1.0, v176
	v_add_f32_e32 v177, 1.0, v177
	v_mul_f32_e32 v42, v94, v42
	v_mul_f32_e32 v43, v94, v43
	v_mul_f32_e32 v44, v94, v44
	v_mul_f32_e32 v45, v94, v45
	v_mul_f32_e32 v46, v94, v46
	v_mul_f32_e32 v47, v94, v47
	v_mul_f32_e32 v48, v94, v48
	v_mul_f32_e32 v49, v94, v49
	v_mul_f32_e32 v50, v94, v50
	v_mul_f32_e32 v51, v94, v51
	v_mul_f32_e32 v52, v94, v52
	v_mul_f32_e32 v53, v94, v53
	v_mul_f32_e32 v54, v94, v54
	v_mul_f32_e32 v55, v94, v55
	v_mul_f32_e32 v56, v94, v56
	v_mul_f32_e32 v57, v94, v57
	v_fma_f32 v42, v42, v162, v146
	v_fma_f32 v43, v43, v163, v147
	v_fma_f32 v44, v44, v164, v148
	v_fma_f32 v45, v45, v165, v149
	v_fma_f32 v46, v46, v166, v150
	v_fma_f32 v47, v47, v167, v151
	v_fma_f32 v48, v48, v168, v152
	v_fma_f32 v49, v49, v169, v153
	v_fma_f32 v50, v50, v170, v154
	v_fma_f32 v51, v51, v171, v155
	v_fma_f32 v52, v52, v172, v156
	v_fma_f32 v53, v53, v173, v157
	v_fma_f32 v54, v54, v174, v158
	v_fma_f32 v55, v55, v175, v159
	v_fma_f32 v56, v56, v176, v160
	v_fma_f32 v57, v57, v177, v161
	v_cvt_pk_bf16_f32 v190, v42, v43
	v_cvt_pk_bf16_f32 v191, v44, v45
	v_cvt_pk_bf16_f32 v192, v46, v47
	v_cvt_pk_bf16_f32 v193, v48, v49
	v_cvt_pk_bf16_f32 v194, v50, v51
	v_cvt_pk_bf16_f32 v195, v52, v53
	v_cvt_pk_bf16_f32 v196, v54, v55
	v_cvt_pk_bf16_f32 v197, v56, v57
	s_lshl_b32 s2, s16, 11
	s_add_u32 s2, s94, s2
	s_addc_u32 s3, s95, 0
	s_add_u32 s2, s2, 0x5e00000
	s_addc_u32 s3, s3, 0
	global_store_dwordx4 v1, v[190:193], s[2:3]
	global_store_dwordx4 v1, v[194:197], s[2:3] offset:1024
	s_waitcnt vmcnt(0)
	s_add_i32 s16, s16, 0x4800
	s_cmpk_gt_u32 s16, 0x47ff
	s_cbranch_scc1 .LBB0_671
	s_lshl_b64 s[2:3], s[44:45], 3
	s_add_u32 s4, s62, s2
	s_addc_u32 s5, s63, s3
	v_lshlrev_b32_e32 v0, 2, v186
	v_lshlrev_b32_e32 v96, 3, v186
	s_add_u32 s18, s94, 0x100000
	v_xor_b32_e32 v18, 4, v0
	v_xor_b32_e32 v19, 8, v0
	v_xor_b32_e32 v20, 16, v0
	v_xor_b32_e32 v21, 32, v0
	v_xor_b32_e32 v22, 64, v0
	v_xor_b32_e32 v23, 0x80, v0
	v_or_b32_e32 v0, 64, v186
	v_or_b32_e32 v2, 0x80, v186
	v_or_b32_e32 v4, 0xc0, v186
	v_lshl_add_u64 v[6:7], s[94:95], 0, v[96:97]
	s_mov_b64 s[2:3], 0x3e00000
	s_addc_u32 s19, s95, 0
	v_lshl_add_u64 v[16:17], v[6:7], 0, s[2:3]
	s_lshl_b32 s20, s93, 3
	s_lshl_b64 s[6:7], s[16:17], 12
	s_lshl_b32 s21, s93, 15
	v_lshlrev_b32_e32 v24, 4, v186
	v_lshlrev_b32_e32 v25, 4, v0
	v_lshlrev_b32_e32 v26, 4, v2
	v_lshlrev_b32_e32 v27, 4, v4
	s_mov_b64 s[8:9], s[16:17]
	s_branch .LBB0_668
